# speedup vs baseline: 1.0587x; 1.0050x over previous
; __device__ __forceinline__ void pool_window(const bf16_t* __restrict__ U  , bf16_t* __restrict__ A3, const int gtid, const int nthr) {
;     ...
;     for (int it = gtid; it < (T / 32) * 256; it += nthr) {
;         const int cg8 = it & 255, tb = it >> 8, c = cg8 * 8, g = c >> 9, w = 2 << g, t0 = tb * 32, s0 = t0 & (SEQ - 1);
;         float sum[8];
; #pragma unroll
;         for (int e = 0; e < 8; ++e) sum[e] = 0.f;
;         if (s0 > 0) {
;             for (int k = 1; k < w; ++k) { const u32x4 uu = *(const u32x4*)(U + (size_t)(t0 - k) * LDU + c);
;                 sum[0] += bflo(uu.x); sum[1] += bfhi(uu.x); sum[2] += bflo(uu.y); sum[3] += bfhi(uu.y); sum[4] += bflo(uu.z); sum[5] += bfhi(uu.z); sum[6] += bflo(uu.w); sum[7] += bfhi(uu.w); }
;         }
.LBB0_1332:
	v_lshlrev_b32_e32 v8, 3, v22
	v_ashrrev_i32_e32 v3, 3, v22
	v_lshlrev_b32_e32 v0, 1, v23
	v_bfe_u32 v2, v8, 9, 2
	v_and_b32_e32 v4, 0xffffffe0, v3
	v_and_b32_e32 v25, 0x1fe0, v3
	v_and_b32_e32 v0, 0xff0, v0
	v_lshlrev_b32_e64 v24, v2, 2
	v_cmp_ne_u32_e32 vcc, 0, v25
	v_ashrrev_i32_e32 v5, 31, v4
	s_xor_b64 s[24:25], vcc, exec
	s_cmp_eq_u64 s[24:25], 0
	s_cbranch_scc1 .Lpw_fast
	s_cmp_eq_u64 vcc, 0
	s_cbranch_scc1 .Lpw_fast0
	s_and_saveexec_b64 s[0:1], vcc
	s_xor_b64 s[14:15], exec, s[0:1]
	s_cbranch_execz .LBB0_1336
	v_lshlrev_b64 v[6:7], 13, v[4:5]
	v_or_b32_e32 v2, v6, v0
	v_mov_b32_e32 v3, v7
	v_mov_b32_e32 v12, 0
	v_add_u32_e32 v9, -1, v24
	v_lshl_add_u64 v[2:3], s[4:5], 0, v[2:3]
	v_mov_b64_e32 v[42:43], v[2:3]
	global_load_dword v44, v[42:43], off
	v_lshl_add_u64 v[42:43], v[42:43], 0, s[8:9]
	global_load_dword v44, v[42:43], off
	v_lshl_add_u64 v[42:43], v[42:43], 0, s[8:9]
	global_load_dword v44, v[42:43], off
	v_lshl_add_u64 v[42:43], v[42:43], 0, s[8:9]
	global_load_dword v44, v[42:43], off
	v_lshl_add_u64 v[42:43], v[42:43], 0, s[8:9]
	global_load_dword v44, v[42:43], off
	v_lshl_add_u64 v[42:43], v[42:43], 0, s[8:9]
	global_load_dword v44, v[42:43], off
	v_lshl_add_u64 v[42:43], v[42:43], 0, s[8:9]
	global_load_dword v44, v[42:43], off
	v_lshl_add_u64 v[42:43], v[42:43], 0, s[8:9]
	global_load_dword v44, v[42:43], off
	v_lshl_add_u64 v[42:43], v[42:43], 0, s[8:9]
	global_load_dword v44, v[42:43], off
	v_lshl_add_u64 v[42:43], v[42:43], 0, s[8:9]
	global_load_dword v44, v[42:43], off
	v_lshl_add_u64 v[42:43], v[42:43], 0, s[8:9]
	global_load_dword v44, v[42:43], off
	v_lshl_add_u64 v[42:43], v[42:43], 0, s[8:9]
	global_load_dword v44, v[42:43], off
	v_lshl_add_u64 v[42:43], v[42:43], 0, s[8:9]
	global_load_dword v44, v[42:43], off
	v_lshl_add_u64 v[42:43], v[42:43], 0, s[8:9]
	global_load_dword v44, v[42:43], off
	v_lshl_add_u64 v[42:43], v[42:43], 0, s[8:9]
	global_load_dword v44, v[42:43], off
	v_lshl_add_u64 v[42:43], v[2:3], 0, s[22:23]
	global_load_dword v44, v[42:43], off
	v_lshl_add_u64 v[42:43], v[42:43], 0, s[22:23]
	global_load_dword v44, v[42:43], off
	v_lshl_add_u64 v[42:43], v[42:43], 0, s[22:23]
	global_load_dword v44, v[42:43], off
	v_lshl_add_u64 v[42:43], v[42:43], 0, s[22:23]
	global_load_dword v44, v[42:43], off
	v_lshl_add_u64 v[42:43], v[42:43], 0, s[22:23]
	global_load_dword v44, v[42:43], off
	v_lshl_add_u64 v[42:43], v[42:43], 0, s[22:23]
	global_load_dword v44, v[42:43], off
	v_lshl_add_u64 v[42:43], v[42:43], 0, s[22:23]
	global_load_dword v44, v[42:43], off
	v_lshl_add_u64 v[42:43], v[42:43], 0, s[22:23]
	global_load_dword v44, v[42:43], off
	s_mov_b64 s[16:17], 0
	v_mov_b32_e32 v13, v12
	v_mov_b32_e32 v14, v12
	v_mov_b32_e32 v15, v12
	v_mov_b32_e32 v16, v12
	v_mov_b32_e32 v17, v12
	v_mov_b32_e32 v18, v12
	v_mov_b32_e32 v19, v12

; __device__ __forceinline__ void pool_window(const bf16_t* __restrict__ U  , bf16_t* __restrict__ A3, const int gtid, const int nthr) {
;     ...
;         const int cg8 = it & 255, tb = it >> 8, c = cg8 * 8, g = c >> 9, w = 2 << g, t0 = tb * 32, s0 = t0 & (SEQ - 1);
;         float sum[8];
; #pragma unroll
;         for (int e = 0; e < 8; ++e) sum[e] = 0.f;
;         if (s0 > 0) {
;             for (int k = 1; k < w; ++k) { const u32x4 uu = *(const u32x4*)(U + (size_t)(t0 - k) * LDU + c);
;                 sum[0] += bflo(uu.x); sum[1] += bfhi(uu.x); sum[2] += bflo(uu.y); sum[3] += bfhi(uu.y); sum[4] += bflo(uu.z); sum[5] += bfhi(uu.z); sum[6] += bflo(uu.w); sum[7] += bfhi(uu.w); }
;         }
; #pragma unroll 8
;         for (int i = 0; i < 32; ++i) {
;             const int t = t0 + i, s = s0 + i;
;             const u32x4 uu = *(const u32x4*)(U + (size_t)t * LDU + c);
;             float cu[8] = {bflo(uu.x), bfhi(uu.x), bflo(uu.y), bfhi(uu.y), bflo(uu.z), bfhi(uu.z), bflo(uu.w), bfhi(uu.w)};
.Lpw_fast0:
	v_readfirstlane_b32 s24, v2
	v_lshlrev_b64 v[6:7], 13, v[4:5]
	v_lshl_add_u64 v[6:7], s[72:73], 0, v[6:7]
	v_lshl_add_u64 v[6:7], v[6:7], 0, v[0:1]
	s_mov_b32 s26, 0x197e2000
	s_mov_b32 s27, 0
	v_lshl_add_u64 v[8:9], v[6:7], 0, s[26:27]
	global_load_dwordx4 v[64:67], v[8:9], off
	v_lshl_add_u64 v[8:9], v[8:9], 0, s[22:23]
	global_load_dwordx4 v[68:71], v[8:9], off
	v_lshl_add_u64 v[8:9], v[8:9], 0, s[22:23]
	global_load_dwordx4 v[72:75], v[8:9], off
	v_lshl_add_u64 v[8:9], v[8:9], 0, s[22:23]
	global_load_dwordx4 v[76:79], v[8:9], off
	v_lshl_add_u64 v[8:9], v[8:9], 0, s[22:23]
	global_load_dwordx4 v[80:83], v[8:9], off
	v_lshl_add_u64 v[8:9], v[8:9], 0, s[22:23]
	global_load_dwordx4 v[84:87], v[8:9], off
	v_lshl_add_u64 v[8:9], v[8:9], 0, s[22:23]
	global_load_dwordx4 v[88:91], v[8:9], off
	v_lshl_add_u64 v[8:9], v[8:9], 0, s[22:23]
	global_load_dwordx4 v[92:95], v[8:9], off
	v_lshl_add_u64 v[8:9], v[8:9], 0, s[22:23]
	global_load_dwordx4 v[96:99], v[8:9], off
	v_lshl_add_u64 v[8:9], v[8:9], 0, s[22:23]
	global_load_dwordx4 v[100:103], v[8:9], off
	v_lshl_add_u64 v[8:9], v[8:9], 0, s[22:23]
	global_load_dwordx4 v[104:107], v[8:9], off
	v_lshl_add_u64 v[8:9], v[8:9], 0, s[22:23]
	global_load_dwordx4 v[108:111], v[8:9], off
	v_lshl_add_u64 v[8:9], v[8:9], 0, s[22:23]
	global_load_dwordx4 v[112:115], v[8:9], off
	v_lshl_add_u64 v[8:9], v[8:9], 0, s[22:23]
	global_load_dwordx4 v[116:119], v[8:9], off
	v_lshl_add_u64 v[8:9], v[8:9], 0, s[22:23]
	global_load_dwordx4 v[120:123], v[8:9], off
	v_lshl_add_u64 v[8:9], v[8:9], 0, s[22:23]
	global_load_dwordx4 v[124:127], v[8:9], off
	v_lshl_add_u64 v[8:9], v[8:9], 0, s[22:23]
	global_load_dwordx4 v[128:131], v[8:9], off
	v_lshl_add_u64 v[8:9], v[8:9], 0, s[22:23]
	global_load_dwordx4 v[132:135], v[8:9], off
	v_lshl_add_u64 v[8:9], v[8:9], 0, s[22:23]
	global_load_dwordx4 v[136:139], v[8:9], off
	v_lshl_add_u64 v[8:9], v[8:9], 0, s[22:23]
	global_load_dwordx4 v[140:143], v[8:9], off
	v_lshl_add_u64 v[8:9], v[8:9], 0, s[22:23]
	global_load_dwordx4 v[144:147], v[8:9], off
	v_lshl_add_u64 v[8:9], v[8:9], 0, s[22:23]
	global_load_dwordx4 v[148:151], v[8:9], off
	v_lshl_add_u64 v[8:9], v[8:9], 0, s[22:23]
	global_load_dwordx4 v[152:155], v[8:9], off
	v_lshl_add_u64 v[8:9], v[8:9], 0, s[22:23]
	global_load_dwordx4 v[156:159], v[8:9], off
	v_lshl_add_u64 v[8:9], v[8:9], 0, s[22:23]
	global_load_dwordx4 v[160:163], v[8:9], off
	v_lshl_add_u64 v[8:9], v[8:9], 0, s[22:23]
	global_load_dwordx4 v[164:167], v[8:9], off
	v_lshl_add_u64 v[8:9], v[8:9], 0, s[22:23]
	global_load_dwordx4 v[168:171], v[8:9], off
	v_lshl_add_u64 v[8:9], v[8:9], 0, s[22:23]
	global_load_dwordx4 v[172:175], v[8:9], off
	v_lshl_add_u64 v[8:9], v[8:9], 0, s[22:23]
	global_load_dwordx4 v[176:179], v[8:9], off
	v_lshl_add_u64 v[8:9], v[8:9], 0, s[22:23]
	global_load_dwordx4 v[180:183], v[8:9], off
	v_lshl_add_u64 v[8:9], v[8:9], 0, s[22:23]
	global_load_dwordx4 v[184:187], v[8:9], off
	v_lshl_add_u64 v[8:9], v[8:9], 0, s[22:23]
	global_load_dwordx4 v[188:191], v[8:9], off
	v_lshl_add_u64 v[8:9], v[8:9], 0, s[22:23]
	global_load_dwordx4 v[192:195], v[8:9], off
	v_lshl_add_u64 v[8:9], v[8:9], 0, s[22:23]
	global_load_dwordx4 v[196:199], v[8:9], off
	v_lshl_add_u64 v[8:9], v[8:9], 0, s[22:23]
	global_load_dwordx4 v[200:203], v[8:9], off
	v_lshl_add_u64 v[8:9], v[8:9], 0, s[22:23]
	global_load_dwordx4 v[204:207], v[8:9], off
	v_lshl_add_u64 v[8:9], v[8:9], 0, s[22:23]
	global_load_dwordx4 v[208:211], v[8:9], off
	v_lshl_add_u64 v[8:9], v[8:9], 0, s[22:23]
	global_load_dwordx4 v[214:217], v[8:9], off
	v_lshl_add_u64 v[8:9], v[8:9], 0, s[22:23]
	global_load_dwordx4 v[218:221], v[8:9], off
	v_lshl_add_u64 v[8:9], v[8:9], 0, s[22:23]
	global_load_dwordx4 v[222:225], v[8:9], off
	v_lshl_add_u64 v[8:9], v[8:9], 0, s[22:23]
	global_load_dwordx4 v[226:229], v[8:9], off
	v_lshl_add_u64 v[8:9], v[8:9], 0, s[22:23]
	global_load_dwordx4 v[230:233], v[8:9], off
	v_lshl_add_u64 v[8:9], v[8:9], 0, s[22:23]
	global_load_dwordx4 v[234:237], v[8:9], off
	v_lshl_add_u64 v[8:9], v[8:9], 0, s[22:23]
	global_load_dwordx4 v[238:241], v[8:9], off
	v_lshl_add_u64 v[8:9], v[8:9], 0, s[22:23]
	global_load_dwordx4 v[242:245], v[8:9], off
	v_lshl_add_u64 v[8:9], v[8:9], 0, s[22:23]
	global_load_dwordx4 v[246:249], v[8:9], off
	v_lshl_add_u64 v[8:9], v[8:9], 0, s[22:23]
	global_load_dwordx4 v[250:253], v[8:9], off
	v_lshlrev_b64 v[10:11], 12, v[4:5]
	v_lshl_add_u64 v[10:11], s[72:73], 0, v[10:11]
	v_lshl_add_u64 v[10:11], v[10:11], 0, v[0:1]
	s_mov_b32 s26, 0x9800000
	v_lshl_add_u64 v[10:11], v[10:11], 0, s[26:27]
	s_mov_b32 s26, 0x1000
	v_mov_b32_e32 v12, 0
	v_mov_b32_e32 v13, 0
	v_mov_b32_e32 v14, 0
	v_mov_b32_e32 v15, 0
	v_mov_b32_e32 v16, 0
	v_mov_b32_e32 v17, 0
	v_mov_b32_e32 v18, 0
	v_mov_b32_e32 v19, 0
	s_cmp_eq_u32 s24, 0
	s_cbranch_scc1 .Lpw0_w2
	s_cmp_eq_u32 s24, 1
	s_cbranch_scc1 .Lpw0_w4
	s_cmp_eq_u32 s24, 2
	s_cbranch_scc1 .Lpw0_w8
; __device__ __forceinline__ unsigned pk2(float lo, float hi) { f32x2 v = {lo, hi}; bf16x2_t b = __builtin_convertvector(v, bf16x2_t); return __builtin_bit_cast(unsigned, b); }
; __device__ __forceinline__ void pool_window(const bf16_t* __restrict__ U  , bf16_t* __restrict__ A3, const int gtid, const int nthr) {
;     ...
;         for (int i = 0; i < 32; ++i) {
;             const int t = t0 + i, s = s0 + i;
;             const u32x4 uu = *(const u32x4*)(U + (size_t)t * LDU + c);
;             float cu[8] = {bflo(uu.x), bfhi(uu.x), bflo(uu.y), bfhi(uu.y), bflo(uu.z), bfhi(uu.z), bflo(uu.w), bfhi(uu.w)};
;             const float rc = 1.0f / (float)((s + 1) < w ? (s + 1) : w);
;             float o[8];
; #pragma unroll
;             for (int e = 0; e < 8; ++e) { sum[e] += cu[e]; o[e] = sum[e] * rc - cu[e]; }
;             u32x4 ww; ww.x = pk2(o[0], o[1]); ww.y = pk2(o[2], o[3]); ww.z = pk2(o[4], o[5]); ww.w = pk2(o[6], o[7]);
;             *(u32x4*)(A3 + (size_t)t * DM + c) = ww;
	v_mov_b32_e32 v34, 0x3d800000
	s_waitcnt vmcnt(0)
	v_mov_b32_e32 v34, 0x3f800000
	v_lshlrev_b32_e32 v44, 16, v124
	v_and_b32_e32 v45, 0xffff0000, v124
	v_lshlrev_b32_e32 v46, 16, v125
	v_and_b32_e32 v47, 0xffff0000, v125
	v_lshlrev_b32_e32 v48, 16, v126
	v_and_b32_e32 v49, 0xffff0000, v126
	v_lshlrev_b32_e32 v50, 16, v127
	v_and_b32_e32 v51, 0xffff0000, v127
	v_pk_add_f32 v[14:15], v[14:15], v[44:45]
	v_pk_add_f32 v[16:17], v[16:17], v[46:47]
	v_pk_add_f32 v[18:19], v[18:19], v[48:49]
	v_pk_add_f32 v[12:13], v[12:13], v[50:51]
	v_pk_fma_f32 v[36:37], v[34:35], v[14:15], v[44:45] op_sel_hi:[0,1,1] neg_lo:[0,0,1] neg_hi:[0,0,1]
	v_pk_fma_f32 v[38:39], v[34:35], v[16:17], v[46:47] op_sel_hi:[0,1,1] neg_lo:[0,0,1] neg_hi:[0,0,1]
	v_pk_fma_f32 v[40:41], v[34:35], v[18:19], v[48:49] op_sel_hi:[0,1,1] neg_lo:[0,0,1] neg_hi:[0,0,1]
	v_pk_fma_f32 v[42:43], v[34:35], v[12:13], v[50:51] op_sel_hi:[0,1,1] neg_lo:[0,0,1] neg_hi:[0,0,1]
	v_cvt_pk_bf16_f32 v28, v36, v37
	v_cvt_pk_bf16_f32 v29, v38, v39
	v_cvt_pk_bf16_f32 v30, v40, v41
	v_cvt_pk_bf16_f32 v31, v42, v43
	global_store_dwordx4 v[10:11], v[28:31], off
	v_lshl_add_u64 v[10:11], v[10:11], 0, s[26:27]
	v_mov_b32_e32 v34, 0x3f000000
	v_lshlrev_b32_e32 v44, 16, v128
	v_and_b32_e32 v45, 0xffff0000, v128
	v_lshlrev_b32_e32 v46, 16, v129
	v_and_b32_e32 v47, 0xffff0000, v129
	v_lshlrev_b32_e32 v48, 16, v130
	v_and_b32_e32 v49, 0xffff0000, v130
	v_lshlrev_b32_e32 v50, 16, v131
	v_and_b32_e32 v51, 0xffff0000, v131
	v_pk_add_f32 v[14:15], v[14:15], v[44:45]
	v_pk_add_f32 v[16:17], v[16:17], v[46:47]
	v_pk_add_f32 v[18:19], v[18:19], v[48:49]
	v_pk_add_f32 v[12:13], v[12:13], v[50:51]
	v_pk_fma_f32 v[36:37], v[34:35], v[14:15], v[44:45] op_sel_hi:[0,1,1] neg_lo:[0,0,1] neg_hi:[0,0,1]
	v_pk_fma_f32 v[38:39], v[34:35], v[16:17], v[46:47] op_sel_hi:[0,1,1] neg_lo:[0,0,1] neg_hi:[0,0,1]
	v_pk_fma_f32 v[40:41], v[34:35], v[18:19], v[48:49] op_sel_hi:[0,1,1] neg_lo:[0,0,1] neg_hi:[0,0,1]
	v_pk_fma_f32 v[42:43], v[34:35], v[12:13], v[50:51] op_sel_hi:[0,1,1] neg_lo:[0,0,1] neg_hi:[0,0,1]
	v_cvt_pk_bf16_f32 v28, v36, v37
	v_cvt_pk_bf16_f32 v29, v38, v39
	v_cvt_pk_bf16_f32 v30, v40, v41
	v_cvt_pk_bf16_f32 v31, v42, v43
	global_store_dwordx4 v[10:11], v[28:31], off
	v_lshl_add_u64 v[10:11], v[10:11], 0, s[26:27]
	v_mov_b32_e32 v34, 0x3eaaaaab
	v_lshlrev_b32_e32 v44, 16, v132
	v_and_b32_e32 v45, 0xffff0000, v132
	v_lshlrev_b32_e32 v46, 16, v133
	v_and_b32_e32 v47, 0xffff0000, v133
	v_lshlrev_b32_e32 v48, 16, v134
	v_and_b32_e32 v49, 0xffff0000, v134
	v_lshlrev_b32_e32 v50, 16, v135
	v_and_b32_e32 v51, 0xffff0000, v135
	v_pk_add_f32 v[14:15], v[14:15], v[44:45]
	v_pk_add_f32 v[16:17], v[16:17], v[46:47]
	v_pk_add_f32 v[18:19], v[18:19], v[48:49]
	v_pk_add_f32 v[12:13], v[12:13], v[50:51]
	v_pk_fma_f32 v[36:37], v[34:35], v[14:15], v[44:45] op_sel_hi:[0,1,1] neg_lo:[0,0,1] neg_hi:[0,0,1]
	v_pk_fma_f32 v[38:39], v[34:35], v[16:17], v[46:47] op_sel_hi:[0,1,1] neg_lo:[0,0,1] neg_hi:[0,0,1]
	v_pk_fma_f32 v[40:41], v[34:35], v[18:19], v[48:49] op_sel_hi:[0,1,1] neg_lo:[0,0,1] neg_hi:[0,0,1]
	v_pk_fma_f32 v[42:43], v[34:35], v[12:13], v[50:51] op_sel_hi:[0,1,1] neg_lo:[0,0,1] neg_hi:[0,0,1]
	v_cvt_pk_bf16_f32 v28, v36, v37
	v_cvt_pk_bf16_f32 v29, v38, v39
	v_cvt_pk_bf16_f32 v30, v40, v41
	v_cvt_pk_bf16_f32 v31, v42, v43
	global_store_dwordx4 v[10:11], v[28:31], off
	v_lshl_add_u64 v[10:11], v[10:11], 0, s[26:27]
	v_mov_b32_e32 v34, 0x3e800000
	v_lshlrev_b32_e32 v44, 16, v136
	v_and_b32_e32 v45, 0xffff0000, v136
	v_lshlrev_b32_e32 v46, 16, v137
	v_and_b32_e32 v47, 0xffff0000, v137
	v_lshlrev_b32_e32 v48, 16, v138
	v_and_b32_e32 v49, 0xffff0000, v138
	v_lshlrev_b32_e32 v50, 16, v139
	v_and_b32_e32 v51, 0xffff0000, v139
	v_pk_add_f32 v[14:15], v[14:15], v[44:45]
	v_pk_add_f32 v[16:17], v[16:17], v[46:47]
	v_pk_add_f32 v[18:19], v[18:19], v[48:49]
	v_pk_add_f32 v[12:13], v[12:13], v[50:51]
	v_pk_fma_f32 v[36:37], v[34:35], v[14:15], v[44:45] op_sel_hi:[0,1,1] neg_lo:[0,0,1] neg_hi:[0,0,1]
	v_pk_fma_f32 v[38:39], v[34:35], v[16:17], v[46:47] op_sel_hi:[0,1,1] neg_lo:[0,0,1] neg_hi:[0,0,1]
	v_pk_fma_f32 v[40:41], v[34:35], v[18:19], v[48:49] op_sel_hi:[0,1,1] neg_lo:[0,0,1] neg_hi:[0,0,1]
	v_pk_fma_f32 v[42:43], v[34:35], v[12:13], v[50:51] op_sel_hi:[0,1,1] neg_lo:[0,0,1] neg_hi:[0,0,1]
	v_cvt_pk_bf16_f32 v28, v36, v37
	v_cvt_pk_bf16_f32 v29, v38, v39
	v_cvt_pk_bf16_f32 v30, v40, v41
	v_cvt_pk_bf16_f32 v31, v42, v43
	global_store_dwordx4 v[10:11], v[28:31], off
	v_lshl_add_u64 v[10:11], v[10:11], 0, s[26:27]
	v_mov_b32_e32 v34, 0x3e4ccccd
	v_lshlrev_b32_e32 v44, 16, v140
	v_and_b32_e32 v45, 0xffff0000, v140
	v_lshlrev_b32_e32 v46, 16, v141
	v_and_b32_e32 v47, 0xffff0000, v141
	v_lshlrev_b32_e32 v48, 16, v142
	v_and_b32_e32 v49, 0xffff0000, v142
	v_lshlrev_b32_e32 v50, 16, v143
	v_and_b32_e32 v51, 0xffff0000, v143
	v_pk_add_f32 v[14:15], v[14:15], v[44:45]
	v_pk_add_f32 v[16:17], v[16:17], v[46:47]
	v_pk_add_f32 v[18:19], v[18:19], v[48:49]
	v_pk_add_f32 v[12:13], v[12:13], v[50:51]
	v_pk_fma_f32 v[36:37], v[34:35], v[14:15], v[44:45] op_sel_hi:[0,1,1] neg_lo:[0,0,1] neg_hi:[0,0,1]
	v_pk_fma_f32 v[38:39], v[34:35], v[16:17], v[46:47] op_sel_hi:[0,1,1] neg_lo:[0,0,1] neg_hi:[0,0,1]
	v_pk_fma_f32 v[40:41], v[34:35], v[18:19], v[48:49] op_sel_hi:[0,1,1] neg_lo:[0,0,1] neg_hi:[0,0,1]
	v_pk_fma_f32 v[42:43], v[34:35], v[12:13], v[50:51] op_sel_hi:[0,1,1] neg_lo:[0,0,1] neg_hi:[0,0,1]
	v_cvt_pk_bf16_f32 v28, v36, v37
	v_cvt_pk_bf16_f32 v29, v38, v39
	v_cvt_pk_bf16_f32 v30, v40, v41
	v_cvt_pk_bf16_f32 v31, v42, v43
	global_store_dwordx4 v[10:11], v[28:31], off
	v_lshl_add_u64 v[10:11], v[10:11], 0, s[26:27]
	v_mov_b32_e32 v34, 0x3e2aaaab
; __device__ __forceinline__ unsigned pk2(float lo, float hi) { f32x2 v = {lo, hi}; bf16x2_t b = __builtin_convertvector(v, bf16x2_t); return __builtin_bit_cast(unsigned, b); }
; __device__ __forceinline__ void pool_window(const bf16_t* __restrict__ U  , bf16_t* __restrict__ A3, const int gtid, const int nthr) {
;     ...
;         for (int i = 0; i < 32; ++i) {
;             const int t = t0 + i, s = s0 + i;
;             const u32x4 uu = *(const u32x4*)(U + (size_t)t * LDU + c);
;             float cu[8] = {bflo(uu.x), bfhi(uu.x), bflo(uu.y), bfhi(uu.y), bflo(uu.z), bfhi(uu.z), bflo(uu.w), bfhi(uu.w)};
;             const float rc = 1.0f / (float)((s + 1) < w ? (s + 1) : w);
;             float o[8];
; #pragma unroll
;             for (int e = 0; e < 8; ++e) { sum[e] += cu[e]; o[e] = sum[e] * rc - cu[e]; }
;             u32x4 ww; ww.x = pk2(o[0], o[1]); ww.y = pk2(o[2], o[3]); ww.z = pk2(o[4], o[5]); ww.w = pk2(o[6], o[7]);
;             *(u32x4*)(A3 + (size_t)t * DM + c) = ww;
	v_lshlrev_b32_e32 v44, 16, v144
	v_and_b32_e32 v45, 0xffff0000, v144
	v_lshlrev_b32_e32 v46, 16, v145
	v_and_b32_e32 v47, 0xffff0000, v145
	v_lshlrev_b32_e32 v48, 16, v146
	v_and_b32_e32 v49, 0xffff0000, v146
	v_lshlrev_b32_e32 v50, 16, v147
	v_and_b32_e32 v51, 0xffff0000, v147
	v_pk_add_f32 v[14:15], v[14:15], v[44:45]
	v_pk_add_f32 v[16:17], v[16:17], v[46:47]
	v_pk_add_f32 v[18:19], v[18:19], v[48:49]
	v_pk_add_f32 v[12:13], v[12:13], v[50:51]
	v_pk_fma_f32 v[36:37], v[34:35], v[14:15], v[44:45] op_sel_hi:[0,1,1] neg_lo:[0,0,1] neg_hi:[0,0,1]
	v_pk_fma_f32 v[38:39], v[34:35], v[16:17], v[46:47] op_sel_hi:[0,1,1] neg_lo:[0,0,1] neg_hi:[0,0,1]
	v_pk_fma_f32 v[40:41], v[34:35], v[18:19], v[48:49] op_sel_hi:[0,1,1] neg_lo:[0,0,1] neg_hi:[0,0,1]
	v_pk_fma_f32 v[42:43], v[34:35], v[12:13], v[50:51] op_sel_hi:[0,1,1] neg_lo:[0,0,1] neg_hi:[0,0,1]
	v_cvt_pk_bf16_f32 v28, v36, v37
	v_cvt_pk_bf16_f32 v29, v38, v39
	v_cvt_pk_bf16_f32 v30, v40, v41
	v_cvt_pk_bf16_f32 v31, v42, v43
	global_store_dwordx4 v[10:11], v[28:31], off
	v_lshl_add_u64 v[10:11], v[10:11], 0, s[26:27]
	v_mov_b32_e32 v34, 0x3e124925
	v_lshlrev_b32_e32 v44, 16, v148
	v_and_b32_e32 v45, 0xffff0000, v148
	v_lshlrev_b32_e32 v46, 16, v149
	v_and_b32_e32 v47, 0xffff0000, v149
	v_lshlrev_b32_e32 v48, 16, v150
	v_and_b32_e32 v49, 0xffff0000, v150
	v_lshlrev_b32_e32 v50, 16, v151
	v_and_b32_e32 v51, 0xffff0000, v151
	v_pk_add_f32 v[14:15], v[14:15], v[44:45]
	v_pk_add_f32 v[16:17], v[16:17], v[46:47]
	v_pk_add_f32 v[18:19], v[18:19], v[48:49]
	v_pk_add_f32 v[12:13], v[12:13], v[50:51]
	v_pk_fma_f32 v[36:37], v[34:35], v[14:15], v[44:45] op_sel_hi:[0,1,1] neg_lo:[0,0,1] neg_hi:[0,0,1]
	v_pk_fma_f32 v[38:39], v[34:35], v[16:17], v[46:47] op_sel_hi:[0,1,1] neg_lo:[0,0,1] neg_hi:[0,0,1]
	v_pk_fma_f32 v[40:41], v[34:35], v[18:19], v[48:49] op_sel_hi:[0,1,1] neg_lo:[0,0,1] neg_hi:[0,0,1]
	v_pk_fma_f32 v[42:43], v[34:35], v[12:13], v[50:51] op_sel_hi:[0,1,1] neg_lo:[0,0,1] neg_hi:[0,0,1]
	v_cvt_pk_bf16_f32 v28, v36, v37
	v_cvt_pk_bf16_f32 v29, v38, v39
	v_cvt_pk_bf16_f32 v30, v40, v41
	v_cvt_pk_bf16_f32 v31, v42, v43
	global_store_dwordx4 v[10:11], v[28:31], off
	v_lshl_add_u64 v[10:11], v[10:11], 0, s[26:27]
	v_mov_b32_e32 v34, 0x3e000000
	v_lshlrev_b32_e32 v44, 16, v152
	v_and_b32_e32 v45, 0xffff0000, v152
	v_lshlrev_b32_e32 v46, 16, v153
	v_and_b32_e32 v47, 0xffff0000, v153
	v_lshlrev_b32_e32 v48, 16, v154
	v_and_b32_e32 v49, 0xffff0000, v154
	v_lshlrev_b32_e32 v50, 16, v155
	v_and_b32_e32 v51, 0xffff0000, v155
	v_pk_add_f32 v[14:15], v[14:15], v[44:45]
	v_pk_add_f32 v[16:17], v[16:17], v[46:47]
	v_pk_add_f32 v[18:19], v[18:19], v[48:49]
	v_pk_add_f32 v[12:13], v[12:13], v[50:51]
	v_pk_fma_f32 v[36:37], v[34:35], v[14:15], v[44:45] op_sel_hi:[0,1,1] neg_lo:[0,0,1] neg_hi:[0,0,1]
	v_pk_fma_f32 v[38:39], v[34:35], v[16:17], v[46:47] op_sel_hi:[0,1,1] neg_lo:[0,0,1] neg_hi:[0,0,1]
	v_pk_fma_f32 v[40:41], v[34:35], v[18:19], v[48:49] op_sel_hi:[0,1,1] neg_lo:[0,0,1] neg_hi:[0,0,1]
	v_pk_fma_f32 v[42:43], v[34:35], v[12:13], v[50:51] op_sel_hi:[0,1,1] neg_lo:[0,0,1] neg_hi:[0,0,1]
	v_cvt_pk_bf16_f32 v28, v36, v37
	v_cvt_pk_bf16_f32 v29, v38, v39
	v_cvt_pk_bf16_f32 v30, v40, v41
	v_cvt_pk_bf16_f32 v31, v42, v43
	global_store_dwordx4 v[10:11], v[28:31], off
	v_lshl_add_u64 v[10:11], v[10:11], 0, s[26:27]
	v_mov_b32_e32 v34, 0x3de38e39
	v_lshlrev_b32_e32 v44, 16, v156
	v_and_b32_e32 v45, 0xffff0000, v156
	v_lshlrev_b32_e32 v46, 16, v157
	v_and_b32_e32 v47, 0xffff0000, v157
	v_lshlrev_b32_e32 v48, 16, v158
	v_and_b32_e32 v49, 0xffff0000, v158
	v_lshlrev_b32_e32 v50, 16, v159
	v_and_b32_e32 v51, 0xffff0000, v159
	v_pk_add_f32 v[14:15], v[14:15], v[44:45]
	v_pk_add_f32 v[16:17], v[16:17], v[46:47]
	v_pk_add_f32 v[18:19], v[18:19], v[48:49]
	v_pk_add_f32 v[12:13], v[12:13], v[50:51]
	v_pk_fma_f32 v[36:37], v[34:35], v[14:15], v[44:45] op_sel_hi:[0,1,1] neg_lo:[0,0,1] neg_hi:[0,0,1]
	v_pk_fma_f32 v[38:39], v[34:35], v[16:17], v[46:47] op_sel_hi:[0,1,1] neg_lo:[0,0,1] neg_hi:[0,0,1]
	v_pk_fma_f32 v[40:41], v[34:35], v[18:19], v[48:49] op_sel_hi:[0,1,1] neg_lo:[0,0,1] neg_hi:[0,0,1]
	v_pk_fma_f32 v[42:43], v[34:35], v[12:13], v[50:51] op_sel_hi:[0,1,1] neg_lo:[0,0,1] neg_hi:[0,0,1]
	v_cvt_pk_bf16_f32 v28, v36, v37
	v_cvt_pk_bf16_f32 v29, v38, v39
	v_cvt_pk_bf16_f32 v30, v40, v41
	v_cvt_pk_bf16_f32 v31, v42, v43
	global_store_dwordx4 v[10:11], v[28:31], off
	v_lshl_add_u64 v[10:11], v[10:11], 0, s[26:27]
	v_mov_b32_e32 v34, 0x3dcccccd
	v_lshlrev_b32_e32 v44, 16, v160
	v_and_b32_e32 v45, 0xffff0000, v160
	v_lshlrev_b32_e32 v46, 16, v161
	v_and_b32_e32 v47, 0xffff0000, v161
	v_lshlrev_b32_e32 v48, 16, v162
	v_and_b32_e32 v49, 0xffff0000, v162
	v_lshlrev_b32_e32 v50, 16, v163
	v_and_b32_e32 v51, 0xffff0000, v163
	v_pk_add_f32 v[14:15], v[14:15], v[44:45]
	v_pk_add_f32 v[16:17], v[16:17], v[46:47]
	v_pk_add_f32 v[18:19], v[18:19], v[48:49]
	v_pk_add_f32 v[12:13], v[12:13], v[50:51]
	v_pk_fma_f32 v[36:37], v[34:35], v[14:15], v[44:45] op_sel_hi:[0,1,1] neg_lo:[0,0,1] neg_hi:[0,0,1]
	v_pk_fma_f32 v[38:39], v[34:35], v[16:17], v[46:47] op_sel_hi:[0,1,1] neg_lo:[0,0,1] neg_hi:[0,0,1]
	v_pk_fma_f32 v[40:41], v[34:35], v[18:19], v[48:49] op_sel_hi:[0,1,1] neg_lo:[0,0,1] neg_hi:[0,0,1]
	v_pk_fma_f32 v[42:43], v[34:35], v[12:13], v[50:51] op_sel_hi:[0,1,1] neg_lo:[0,0,1] neg_hi:[0,0,1]
	v_cvt_pk_bf16_f32 v28, v36, v37
	v_cvt_pk_bf16_f32 v29, v38, v39
	v_cvt_pk_bf16_f32 v30, v40, v41
	v_cvt_pk_bf16_f32 v31, v42, v43
	global_store_dwordx4 v[10:11], v[28:31], off
	v_lshl_add_u64 v[10:11], v[10:11], 0, s[26:27]
	v_mov_b32_e32 v34, 0x3dba2e8c
	v_lshlrev_b32_e32 v44, 16, v164
	v_and_b32_e32 v45, 0xffff0000, v164
; __device__ __forceinline__ unsigned pk2(float lo, float hi) { f32x2 v = {lo, hi}; bf16x2_t b = __builtin_convertvector(v, bf16x2_t); return __builtin_bit_cast(unsigned, b); }
; __device__ __forceinline__ void pool_window(const bf16_t* __restrict__ U  , bf16_t* __restrict__ A3, const int gtid, const int nthr) {
;     ...
;         for (int i = 0; i < 32; ++i) {
;             const int t = t0 + i, s = s0 + i;
;             const u32x4 uu = *(const u32x4*)(U + (size_t)t * LDU + c);
;             float cu[8] = {bflo(uu.x), bfhi(uu.x), bflo(uu.y), bfhi(uu.y), bflo(uu.z), bfhi(uu.z), bflo(uu.w), bfhi(uu.w)};
;             const float rc = 1.0f / (float)((s + 1) < w ? (s + 1) : w);
;             float o[8];
; #pragma unroll
;             for (int e = 0; e < 8; ++e) { sum[e] += cu[e]; o[e] = sum[e] * rc - cu[e]; }
;             u32x4 ww; ww.x = pk2(o[0], o[1]); ww.y = pk2(o[2], o[3]); ww.z = pk2(o[4], o[5]); ww.w = pk2(o[6], o[7]);
;             *(u32x4*)(A3 + (size_t)t * DM + c) = ww;
	v_lshlrev_b32_e32 v46, 16, v165
	v_and_b32_e32 v47, 0xffff0000, v165
	v_lshlrev_b32_e32 v48, 16, v166
	v_and_b32_e32 v49, 0xffff0000, v166
	v_lshlrev_b32_e32 v50, 16, v167
	v_and_b32_e32 v51, 0xffff0000, v167
	v_pk_add_f32 v[14:15], v[14:15], v[44:45]
	v_pk_add_f32 v[16:17], v[16:17], v[46:47]
	v_pk_add_f32 v[18:19], v[18:19], v[48:49]
	v_pk_add_f32 v[12:13], v[12:13], v[50:51]
	v_pk_fma_f32 v[36:37], v[34:35], v[14:15], v[44:45] op_sel_hi:[0,1,1] neg_lo:[0,0,1] neg_hi:[0,0,1]
	v_pk_fma_f32 v[38:39], v[34:35], v[16:17], v[46:47] op_sel_hi:[0,1,1] neg_lo:[0,0,1] neg_hi:[0,0,1]
	v_pk_fma_f32 v[40:41], v[34:35], v[18:19], v[48:49] op_sel_hi:[0,1,1] neg_lo:[0,0,1] neg_hi:[0,0,1]
	v_pk_fma_f32 v[42:43], v[34:35], v[12:13], v[50:51] op_sel_hi:[0,1,1] neg_lo:[0,0,1] neg_hi:[0,0,1]
	v_cvt_pk_bf16_f32 v28, v36, v37
	v_cvt_pk_bf16_f32 v29, v38, v39
	v_cvt_pk_bf16_f32 v30, v40, v41
	v_cvt_pk_bf16_f32 v31, v42, v43
	global_store_dwordx4 v[10:11], v[28:31], off
	v_lshl_add_u64 v[10:11], v[10:11], 0, s[26:27]
	v_mov_b32_e32 v34, 0x3daaaaab
	v_lshlrev_b32_e32 v44, 16, v168
	v_and_b32_e32 v45, 0xffff0000, v168
	v_lshlrev_b32_e32 v46, 16, v169
	v_and_b32_e32 v47, 0xffff0000, v169
	v_lshlrev_b32_e32 v48, 16, v170
	v_and_b32_e32 v49, 0xffff0000, v170
	v_lshlrev_b32_e32 v50, 16, v171
	v_and_b32_e32 v51, 0xffff0000, v171
	v_pk_add_f32 v[14:15], v[14:15], v[44:45]
	v_pk_add_f32 v[16:17], v[16:17], v[46:47]
	v_pk_add_f32 v[18:19], v[18:19], v[48:49]
	v_pk_add_f32 v[12:13], v[12:13], v[50:51]
	v_pk_fma_f32 v[36:37], v[34:35], v[14:15], v[44:45] op_sel_hi:[0,1,1] neg_lo:[0,0,1] neg_hi:[0,0,1]
	v_pk_fma_f32 v[38:39], v[34:35], v[16:17], v[46:47] op_sel_hi:[0,1,1] neg_lo:[0,0,1] neg_hi:[0,0,1]
	v_pk_fma_f32 v[40:41], v[34:35], v[18:19], v[48:49] op_sel_hi:[0,1,1] neg_lo:[0,0,1] neg_hi:[0,0,1]
	v_pk_fma_f32 v[42:43], v[34:35], v[12:13], v[50:51] op_sel_hi:[0,1,1] neg_lo:[0,0,1] neg_hi:[0,0,1]
	v_cvt_pk_bf16_f32 v28, v36, v37
	v_cvt_pk_bf16_f32 v29, v38, v39
	v_cvt_pk_bf16_f32 v30, v40, v41
	v_cvt_pk_bf16_f32 v31, v42, v43
	global_store_dwordx4 v[10:11], v[28:31], off
	v_lshl_add_u64 v[10:11], v[10:11], 0, s[26:27]
	v_mov_b32_e32 v34, 0x3d9d89d9
	v_lshlrev_b32_e32 v44, 16, v172
	v_and_b32_e32 v45, 0xffff0000, v172
	v_lshlrev_b32_e32 v46, 16, v173
	v_and_b32_e32 v47, 0xffff0000, v173
	v_lshlrev_b32_e32 v48, 16, v174
	v_and_b32_e32 v49, 0xffff0000, v174
	v_lshlrev_b32_e32 v50, 16, v175
	v_and_b32_e32 v51, 0xffff0000, v175
	v_pk_add_f32 v[14:15], v[14:15], v[44:45]
	v_pk_add_f32 v[16:17], v[16:17], v[46:47]
	v_pk_add_f32 v[18:19], v[18:19], v[48:49]
	v_pk_add_f32 v[12:13], v[12:13], v[50:51]
	v_pk_fma_f32 v[36:37], v[34:35], v[14:15], v[44:45] op_sel_hi:[0,1,1] neg_lo:[0,0,1] neg_hi:[0,0,1]
	v_pk_fma_f32 v[38:39], v[34:35], v[16:17], v[46:47] op_sel_hi:[0,1,1] neg_lo:[0,0,1] neg_hi:[0,0,1]
	v_pk_fma_f32 v[40:41], v[34:35], v[18:19], v[48:49] op_sel_hi:[0,1,1] neg_lo:[0,0,1] neg_hi:[0,0,1]
	v_pk_fma_f32 v[42:43], v[34:35], v[12:13], v[50:51] op_sel_hi:[0,1,1] neg_lo:[0,0,1] neg_hi:[0,0,1]
	v_cvt_pk_bf16_f32 v28, v36, v37
	v_cvt_pk_bf16_f32 v29, v38, v39
	v_cvt_pk_bf16_f32 v30, v40, v41
	v_cvt_pk_bf16_f32 v31, v42, v43
	global_store_dwordx4 v[10:11], v[28:31], off
	v_lshl_add_u64 v[10:11], v[10:11], 0, s[26:27]
	v_mov_b32_e32 v34, 0x3d924925
	v_lshlrev_b32_e32 v44, 16, v176
	v_and_b32_e32 v45, 0xffff0000, v176
	v_lshlrev_b32_e32 v46, 16, v177
	v_and_b32_e32 v47, 0xffff0000, v177
	v_lshlrev_b32_e32 v48, 16, v178
	v_and_b32_e32 v49, 0xffff0000, v178
	v_lshlrev_b32_e32 v50, 16, v179
	v_and_b32_e32 v51, 0xffff0000, v179
	v_pk_add_f32 v[14:15], v[14:15], v[44:45]
	v_pk_add_f32 v[16:17], v[16:17], v[46:47]
	v_pk_add_f32 v[18:19], v[18:19], v[48:49]
	v_pk_add_f32 v[12:13], v[12:13], v[50:51]
	v_pk_fma_f32 v[36:37], v[34:35], v[14:15], v[44:45] op_sel_hi:[0,1,1] neg_lo:[0,0,1] neg_hi:[0,0,1]
	v_pk_fma_f32 v[38:39], v[34:35], v[16:17], v[46:47] op_sel_hi:[0,1,1] neg_lo:[0,0,1] neg_hi:[0,0,1]
	v_pk_fma_f32 v[40:41], v[34:35], v[18:19], v[48:49] op_sel_hi:[0,1,1] neg_lo:[0,0,1] neg_hi:[0,0,1]
	v_pk_fma_f32 v[42:43], v[34:35], v[12:13], v[50:51] op_sel_hi:[0,1,1] neg_lo:[0,0,1] neg_hi:[0,0,1]
	v_cvt_pk_bf16_f32 v28, v36, v37
	v_cvt_pk_bf16_f32 v29, v38, v39
	v_cvt_pk_bf16_f32 v30, v40, v41
	v_cvt_pk_bf16_f32 v31, v42, v43
	global_store_dwordx4 v[10:11], v[28:31], off
	v_lshl_add_u64 v[10:11], v[10:11], 0, s[26:27]
	v_mov_b32_e32 v34, 0x3d888889
	v_lshlrev_b32_e32 v44, 16, v180
	v_and_b32_e32 v45, 0xffff0000, v180
	v_lshlrev_b32_e32 v46, 16, v181
	v_and_b32_e32 v47, 0xffff0000, v181
	v_lshlrev_b32_e32 v48, 16, v182
	v_and_b32_e32 v49, 0xffff0000, v182
	v_lshlrev_b32_e32 v50, 16, v183
	v_and_b32_e32 v51, 0xffff0000, v183
	v_pk_add_f32 v[14:15], v[14:15], v[44:45]
	v_pk_add_f32 v[16:17], v[16:17], v[46:47]
	v_pk_add_f32 v[18:19], v[18:19], v[48:49]
	v_pk_add_f32 v[12:13], v[12:13], v[50:51]
	v_pk_fma_f32 v[36:37], v[34:35], v[14:15], v[44:45] op_sel_hi:[0,1,1] neg_lo:[0,0,1] neg_hi:[0,0,1]
	v_pk_fma_f32 v[38:39], v[34:35], v[16:17], v[46:47] op_sel_hi:[0,1,1] neg_lo:[0,0,1] neg_hi:[0,0,1]
	v_pk_fma_f32 v[40:41], v[34:35], v[18:19], v[48:49] op_sel_hi:[0,1,1] neg_lo:[0,0,1] neg_hi:[0,0,1]
	v_pk_fma_f32 v[42:43], v[34:35], v[12:13], v[50:51] op_sel_hi:[0,1,1] neg_lo:[0,0,1] neg_hi:[0,0,1]
	v_cvt_pk_bf16_f32 v28, v36, v37
	v_cvt_pk_bf16_f32 v29, v38, v39
	v_cvt_pk_bf16_f32 v30, v40, v41
	v_cvt_pk_bf16_f32 v31, v42, v43
	global_store_dwordx4 v[10:11], v[28:31], off
	v_lshl_add_u64 v[10:11], v[10:11], 0, s[26:27]
	v_mov_b32_e32 v34, 0x3d800000
	v_lshlrev_b32_e32 v44, 16, v184
	v_and_b32_e32 v45, 0xffff0000, v184
	v_lshlrev_b32_e32 v46, 16, v185
	v_and_b32_e32 v47, 0xffff0000, v185
; __device__ __forceinline__ unsigned pk2(float lo, float hi) { f32x2 v = {lo, hi}; bf16x2_t b = __builtin_convertvector(v, bf16x2_t); return __builtin_bit_cast(unsigned, b); }
; __device__ __forceinline__ void pool_window(const bf16_t* __restrict__ U  , bf16_t* __restrict__ A3, const int gtid, const int nthr) {
;     ...
;         for (int i = 0; i < 32; ++i) {
;             const int t = t0 + i, s = s0 + i;
;             const u32x4 uu = *(const u32x4*)(U + (size_t)t * LDU + c);
;             float cu[8] = {bflo(uu.x), bfhi(uu.x), bflo(uu.y), bfhi(uu.y), bflo(uu.z), bfhi(uu.z), bflo(uu.w), bfhi(uu.w)};
;             const float rc = 1.0f / (float)((s + 1) < w ? (s + 1) : w);
;             float o[8];
; #pragma unroll
;             for (int e = 0; e < 8; ++e) { sum[e] += cu[e]; o[e] = sum[e] * rc - cu[e]; }
;             u32x4 ww; ww.x = pk2(o[0], o[1]); ww.y = pk2(o[2], o[3]); ww.z = pk2(o[4], o[5]); ww.w = pk2(o[6], o[7]);
;             *(u32x4*)(A3 + (size_t)t * DM + c) = ww;
;             if (s + 1 >= w) { const u32x4 ud = *(const u32x4*)(U + (size_t)(t - w + 1) * LDU + c);
;                 sum[0] -= bflo(ud.x); sum[1] -= bfhi(ud.x); sum[2] -= bflo(ud.y); sum[3] -= bfhi(ud.y); sum[4] -= bflo(ud.z); sum[5] -= bfhi(ud.z); sum[6] -= bflo(ud.w); sum[7] -= bfhi(ud.w); }
;         }
	v_lshlrev_b32_e32 v48, 16, v186
	v_and_b32_e32 v49, 0xffff0000, v186
	v_lshlrev_b32_e32 v50, 16, v187
	v_and_b32_e32 v51, 0xffff0000, v187
	v_pk_add_f32 v[14:15], v[14:15], v[44:45]
	v_pk_add_f32 v[16:17], v[16:17], v[46:47]
	v_pk_add_f32 v[18:19], v[18:19], v[48:49]
	v_pk_add_f32 v[12:13], v[12:13], v[50:51]
	v_pk_fma_f32 v[36:37], v[34:35], v[14:15], v[44:45] op_sel_hi:[0,1,1] neg_lo:[0,0,1] neg_hi:[0,0,1]
	v_pk_fma_f32 v[38:39], v[34:35], v[16:17], v[46:47] op_sel_hi:[0,1,1] neg_lo:[0,0,1] neg_hi:[0,0,1]
	v_pk_fma_f32 v[40:41], v[34:35], v[18:19], v[48:49] op_sel_hi:[0,1,1] neg_lo:[0,0,1] neg_hi:[0,0,1]
	v_pk_fma_f32 v[42:43], v[34:35], v[12:13], v[50:51] op_sel_hi:[0,1,1] neg_lo:[0,0,1] neg_hi:[0,0,1]
	v_cvt_pk_bf16_f32 v28, v36, v37
	v_cvt_pk_bf16_f32 v29, v38, v39
	v_cvt_pk_bf16_f32 v30, v40, v41
	v_cvt_pk_bf16_f32 v31, v42, v43
	global_store_dwordx4 v[10:11], v[28:31], off
	v_lshlrev_b32_e32 v44, 16, v124
	v_and_b32_e32 v45, 0xffff0000, v124
	v_lshlrev_b32_e32 v46, 16, v125
	v_and_b32_e32 v47, 0xffff0000, v125
	v_lshlrev_b32_e32 v48, 16, v126
	v_and_b32_e32 v49, 0xffff0000, v126
	v_lshlrev_b32_e32 v50, 16, v127
	v_and_b32_e32 v51, 0xffff0000, v127
	v_pk_add_f32 v[14:15], v[14:15], v[44:45] neg_lo:[0,1] neg_hi:[0,1]
	v_pk_add_f32 v[16:17], v[16:17], v[46:47] neg_lo:[0,1] neg_hi:[0,1]
	v_pk_add_f32 v[18:19], v[18:19], v[48:49] neg_lo:[0,1] neg_hi:[0,1]
	v_pk_add_f32 v[12:13], v[12:13], v[50:51] neg_lo:[0,1] neg_hi:[0,1]
	v_lshl_add_u64 v[10:11], v[10:11], 0, s[26:27]
	v_lshlrev_b32_e32 v44, 16, v188
	v_and_b32_e32 v45, 0xffff0000, v188
	v_lshlrev_b32_e32 v46, 16, v189
	v_and_b32_e32 v47, 0xffff0000, v189
	v_lshlrev_b32_e32 v48, 16, v190
	v_and_b32_e32 v49, 0xffff0000, v190
	v_lshlrev_b32_e32 v50, 16, v191
	v_and_b32_e32 v51, 0xffff0000, v191
	v_pk_add_f32 v[14:15], v[14:15], v[44:45]
	v_pk_add_f32 v[16:17], v[16:17], v[46:47]
	v_pk_add_f32 v[18:19], v[18:19], v[48:49]
	v_pk_add_f32 v[12:13], v[12:13], v[50:51]
	v_pk_fma_f32 v[36:37], v[34:35], v[14:15], v[44:45] op_sel_hi:[0,1,1] neg_lo:[0,0,1] neg_hi:[0,0,1]
	v_pk_fma_f32 v[38:39], v[34:35], v[16:17], v[46:47] op_sel_hi:[0,1,1] neg_lo:[0,0,1] neg_hi:[0,0,1]
	v_pk_fma_f32 v[40:41], v[34:35], v[18:19], v[48:49] op_sel_hi:[0,1,1] neg_lo:[0,0,1] neg_hi:[0,0,1]
	v_pk_fma_f32 v[42:43], v[34:35], v[12:13], v[50:51] op_sel_hi:[0,1,1] neg_lo:[0,0,1] neg_hi:[0,0,1]
	v_cvt_pk_bf16_f32 v28, v36, v37
	v_cvt_pk_bf16_f32 v29, v38, v39
	v_cvt_pk_bf16_f32 v30, v40, v41
	v_cvt_pk_bf16_f32 v31, v42, v43
	global_store_dwordx4 v[10:11], v[28:31], off
	v_lshlrev_b32_e32 v44, 16, v128
	v_and_b32_e32 v45, 0xffff0000, v128
	v_lshlrev_b32_e32 v46, 16, v129
	v_and_b32_e32 v47, 0xffff0000, v129
	v_lshlrev_b32_e32 v48, 16, v130
	v_and_b32_e32 v49, 0xffff0000, v130
	v_lshlrev_b32_e32 v50, 16, v131
	v_and_b32_e32 v51, 0xffff0000, v131
	v_pk_add_f32 v[14:15], v[14:15], v[44:45] neg_lo:[0,1] neg_hi:[0,1]
	v_pk_add_f32 v[16:17], v[16:17], v[46:47] neg_lo:[0,1] neg_hi:[0,1]
	v_pk_add_f32 v[18:19], v[18:19], v[48:49] neg_lo:[0,1] neg_hi:[0,1]
	v_pk_add_f32 v[12:13], v[12:13], v[50:51] neg_lo:[0,1] neg_hi:[0,1]
	v_lshl_add_u64 v[10:11], v[10:11], 0, s[26:27]
	v_lshlrev_b32_e32 v44, 16, v192
	v_and_b32_e32 v45, 0xffff0000, v192
	v_lshlrev_b32_e32 v46, 16, v193
	v_and_b32_e32 v47, 0xffff0000, v193
	v_lshlrev_b32_e32 v48, 16, v194
	v_and_b32_e32 v49, 0xffff0000, v194
	v_lshlrev_b32_e32 v50, 16, v195
	v_and_b32_e32 v51, 0xffff0000, v195
	v_pk_add_f32 v[14:15], v[14:15], v[44:45]
	v_pk_add_f32 v[16:17], v[16:17], v[46:47]
	v_pk_add_f32 v[18:19], v[18:19], v[48:49]
	v_pk_add_f32 v[12:13], v[12:13], v[50:51]
	v_pk_fma_f32 v[36:37], v[34:35], v[14:15], v[44:45] op_sel_hi:[0,1,1] neg_lo:[0,0,1] neg_hi:[0,0,1]
	v_pk_fma_f32 v[38:39], v[34:35], v[16:17], v[46:47] op_sel_hi:[0,1,1] neg_lo:[0,0,1] neg_hi:[0,0,1]
	v_pk_fma_f32 v[40:41], v[34:35], v[18:19], v[48:49] op_sel_hi:[0,1,1] neg_lo:[0,0,1] neg_hi:[0,0,1]
	v_pk_fma_f32 v[42:43], v[34:35], v[12:13], v[50:51] op_sel_hi:[0,1,1] neg_lo:[0,0,1] neg_hi:[0,0,1]
	v_cvt_pk_bf16_f32 v28, v36, v37
	v_cvt_pk_bf16_f32 v29, v38, v39
	v_cvt_pk_bf16_f32 v30, v40, v41
	v_cvt_pk_bf16_f32 v31, v42, v43
	global_store_dwordx4 v[10:11], v[28:31], off
	v_lshlrev_b32_e32 v44, 16, v132
	v_and_b32_e32 v45, 0xffff0000, v132
	v_lshlrev_b32_e32 v46, 16, v133
	v_and_b32_e32 v47, 0xffff0000, v133
	v_lshlrev_b32_e32 v48, 16, v134
	v_and_b32_e32 v49, 0xffff0000, v134
	v_lshlrev_b32_e32 v50, 16, v135
	v_and_b32_e32 v51, 0xffff0000, v135
	v_pk_add_f32 v[14:15], v[14:15], v[44:45] neg_lo:[0,1] neg_hi:[0,1]
	v_pk_add_f32 v[16:17], v[16:17], v[46:47] neg_lo:[0,1] neg_hi:[0,1]
	v_pk_add_f32 v[18:19], v[18:19], v[48:49] neg_lo:[0,1] neg_hi:[0,1]
	v_pk_add_f32 v[12:13], v[12:13], v[50:51] neg_lo:[0,1] neg_hi:[0,1]
	v_lshl_add_u64 v[10:11], v[10:11], 0, s[26:27]
	v_lshlrev_b32_e32 v44, 16, v196
	v_and_b32_e32 v45, 0xffff0000, v196
	v_lshlrev_b32_e32 v46, 16, v197
	v_and_b32_e32 v47, 0xffff0000, v197
	v_lshlrev_b32_e32 v48, 16, v198
	v_and_b32_e32 v49, 0xffff0000, v198
	v_lshlrev_b32_e32 v50, 16, v199
	v_and_b32_e32 v51, 0xffff0000, v199
	v_pk_add_f32 v[14:15], v[14:15], v[44:45]
	v_pk_add_f32 v[16:17], v[16:17], v[46:47]
	v_pk_add_f32 v[18:19], v[18:19], v[48:49]
	v_pk_add_f32 v[12:13], v[12:13], v[50:51]
	v_pk_fma_f32 v[36:37], v[34:35], v[14:15], v[44:45] op_sel_hi:[0,1,1] neg_lo:[0,0,1] neg_hi:[0,0,1]
	v_pk_fma_f32 v[38:39], v[34:35], v[16:17], v[46:47] op_sel_hi:[0,1,1] neg_lo:[0,0,1] neg_hi:[0,0,1]
	v_pk_fma_f32 v[40:41], v[34:35], v[18:19], v[48:49] op_sel_hi:[0,1,1] neg_lo:[0,0,1] neg_hi:[0,0,1]
	v_pk_fma_f32 v[42:43], v[34:35], v[12:13], v[50:51] op_sel_hi:[0,1,1] neg_lo:[0,0,1] neg_hi:[0,0,1]
; __device__ __forceinline__ unsigned pk2(float lo, float hi) { f32x2 v = {lo, hi}; bf16x2_t b = __builtin_convertvector(v, bf16x2_t); return __builtin_bit_cast(unsigned, b); }
; __device__ __forceinline__ void pool_window(const bf16_t* __restrict__ U  , bf16_t* __restrict__ A3, const int gtid, const int nthr) {
;     ...
;         for (int i = 0; i < 32; ++i) {
;             const int t = t0 + i, s = s0 + i;
;             const u32x4 uu = *(const u32x4*)(U + (size_t)t * LDU + c);
;             float cu[8] = {bflo(uu.x), bfhi(uu.x), bflo(uu.y), bfhi(uu.y), bflo(uu.z), bfhi(uu.z), bflo(uu.w), bfhi(uu.w)};
;             const float rc = 1.0f / (float)((s + 1) < w ? (s + 1) : w);
;             float o[8];
; #pragma unroll
;             for (int e = 0; e < 8; ++e) { sum[e] += cu[e]; o[e] = sum[e] * rc - cu[e]; }
;             u32x4 ww; ww.x = pk2(o[0], o[1]); ww.y = pk2(o[2], o[3]); ww.z = pk2(o[4], o[5]); ww.w = pk2(o[6], o[7]);
;             *(u32x4*)(A3 + (size_t)t * DM + c) = ww;
;             if (s + 1 >= w) { const u32x4 ud = *(const u32x4*)(U + (size_t)(t - w + 1) * LDU + c);
;                 sum[0] -= bflo(ud.x); sum[1] -= bfhi(ud.x); sum[2] -= bflo(ud.y); sum[3] -= bfhi(ud.y); sum[4] -= bflo(ud.z); sum[5] -= bfhi(ud.z); sum[6] -= bflo(ud.w); sum[7] -= bfhi(ud.w); }
;         }
	v_cvt_pk_bf16_f32 v28, v36, v37
	v_cvt_pk_bf16_f32 v29, v38, v39
	v_cvt_pk_bf16_f32 v30, v40, v41
	v_cvt_pk_bf16_f32 v31, v42, v43
	global_store_dwordx4 v[10:11], v[28:31], off
	v_lshlrev_b32_e32 v44, 16, v136
	v_and_b32_e32 v45, 0xffff0000, v136
	v_lshlrev_b32_e32 v46, 16, v137
	v_and_b32_e32 v47, 0xffff0000, v137
	v_lshlrev_b32_e32 v48, 16, v138
	v_and_b32_e32 v49, 0xffff0000, v138
	v_lshlrev_b32_e32 v50, 16, v139
	v_and_b32_e32 v51, 0xffff0000, v139
	v_pk_add_f32 v[14:15], v[14:15], v[44:45] neg_lo:[0,1] neg_hi:[0,1]
	v_pk_add_f32 v[16:17], v[16:17], v[46:47] neg_lo:[0,1] neg_hi:[0,1]
	v_pk_add_f32 v[18:19], v[18:19], v[48:49] neg_lo:[0,1] neg_hi:[0,1]
	v_pk_add_f32 v[12:13], v[12:13], v[50:51] neg_lo:[0,1] neg_hi:[0,1]
	v_lshl_add_u64 v[10:11], v[10:11], 0, s[26:27]
	v_lshlrev_b32_e32 v44, 16, v200
	v_and_b32_e32 v45, 0xffff0000, v200
	v_lshlrev_b32_e32 v46, 16, v201
	v_and_b32_e32 v47, 0xffff0000, v201
	v_lshlrev_b32_e32 v48, 16, v202
	v_and_b32_e32 v49, 0xffff0000, v202
	v_lshlrev_b32_e32 v50, 16, v203
	v_and_b32_e32 v51, 0xffff0000, v203
	v_pk_add_f32 v[14:15], v[14:15], v[44:45]
	v_pk_add_f32 v[16:17], v[16:17], v[46:47]
	v_pk_add_f32 v[18:19], v[18:19], v[48:49]
	v_pk_add_f32 v[12:13], v[12:13], v[50:51]
	v_pk_fma_f32 v[36:37], v[34:35], v[14:15], v[44:45] op_sel_hi:[0,1,1] neg_lo:[0,0,1] neg_hi:[0,0,1]
	v_pk_fma_f32 v[38:39], v[34:35], v[16:17], v[46:47] op_sel_hi:[0,1,1] neg_lo:[0,0,1] neg_hi:[0,0,1]
	v_pk_fma_f32 v[40:41], v[34:35], v[18:19], v[48:49] op_sel_hi:[0,1,1] neg_lo:[0,0,1] neg_hi:[0,0,1]
	v_pk_fma_f32 v[42:43], v[34:35], v[12:13], v[50:51] op_sel_hi:[0,1,1] neg_lo:[0,0,1] neg_hi:[0,0,1]
	v_cvt_pk_bf16_f32 v28, v36, v37
	v_cvt_pk_bf16_f32 v29, v38, v39
	v_cvt_pk_bf16_f32 v30, v40, v41
	v_cvt_pk_bf16_f32 v31, v42, v43
	global_store_dwordx4 v[10:11], v[28:31], off
	v_lshlrev_b32_e32 v44, 16, v140
	v_and_b32_e32 v45, 0xffff0000, v140
	v_lshlrev_b32_e32 v46, 16, v141
	v_and_b32_e32 v47, 0xffff0000, v141
	v_lshlrev_b32_e32 v48, 16, v142
	v_and_b32_e32 v49, 0xffff0000, v142
	v_lshlrev_b32_e32 v50, 16, v143
	v_and_b32_e32 v51, 0xffff0000, v143
	v_pk_add_f32 v[14:15], v[14:15], v[44:45] neg_lo:[0,1] neg_hi:[0,1]
	v_pk_add_f32 v[16:17], v[16:17], v[46:47] neg_lo:[0,1] neg_hi:[0,1]
	v_pk_add_f32 v[18:19], v[18:19], v[48:49] neg_lo:[0,1] neg_hi:[0,1]
	v_pk_add_f32 v[12:13], v[12:13], v[50:51] neg_lo:[0,1] neg_hi:[0,1]
	v_lshl_add_u64 v[10:11], v[10:11], 0, s[26:27]
	v_lshlrev_b32_e32 v44, 16, v204
	v_and_b32_e32 v45, 0xffff0000, v204
	v_lshlrev_b32_e32 v46, 16, v205
	v_and_b32_e32 v47, 0xffff0000, v205
	v_lshlrev_b32_e32 v48, 16, v206
	v_and_b32_e32 v49, 0xffff0000, v206
	v_lshlrev_b32_e32 v50, 16, v207
	v_and_b32_e32 v51, 0xffff0000, v207
	v_pk_add_f32 v[14:15], v[14:15], v[44:45]
	v_pk_add_f32 v[16:17], v[16:17], v[46:47]
	v_pk_add_f32 v[18:19], v[18:19], v[48:49]
	v_pk_add_f32 v[12:13], v[12:13], v[50:51]
	v_pk_fma_f32 v[36:37], v[34:35], v[14:15], v[44:45] op_sel_hi:[0,1,1] neg_lo:[0,0,1] neg_hi:[0,0,1]
	v_pk_fma_f32 v[38:39], v[34:35], v[16:17], v[46:47] op_sel_hi:[0,1,1] neg_lo:[0,0,1] neg_hi:[0,0,1]
	v_pk_fma_f32 v[40:41], v[34:35], v[18:19], v[48:49] op_sel_hi:[0,1,1] neg_lo:[0,0,1] neg_hi:[0,0,1]
	v_pk_fma_f32 v[42:43], v[34:35], v[12:13], v[50:51] op_sel_hi:[0,1,1] neg_lo:[0,0,1] neg_hi:[0,0,1]
	v_cvt_pk_bf16_f32 v28, v36, v37
	v_cvt_pk_bf16_f32 v29, v38, v39
	v_cvt_pk_bf16_f32 v30, v40, v41
	v_cvt_pk_bf16_f32 v31, v42, v43
	global_store_dwordx4 v[10:11], v[28:31], off
	v_lshlrev_b32_e32 v44, 16, v144
	v_and_b32_e32 v45, 0xffff0000, v144
	v_lshlrev_b32_e32 v46, 16, v145
	v_and_b32_e32 v47, 0xffff0000, v145
	v_lshlrev_b32_e32 v48, 16, v146
	v_and_b32_e32 v49, 0xffff0000, v146
	v_lshlrev_b32_e32 v50, 16, v147
	v_and_b32_e32 v51, 0xffff0000, v147
	v_pk_add_f32 v[14:15], v[14:15], v[44:45] neg_lo:[0,1] neg_hi:[0,1]
	v_pk_add_f32 v[16:17], v[16:17], v[46:47] neg_lo:[0,1] neg_hi:[0,1]
	v_pk_add_f32 v[18:19], v[18:19], v[48:49] neg_lo:[0,1] neg_hi:[0,1]
	v_pk_add_f32 v[12:13], v[12:13], v[50:51] neg_lo:[0,1] neg_hi:[0,1]
	v_lshl_add_u64 v[10:11], v[10:11], 0, s[26:27]
	v_lshlrev_b32_e32 v44, 16, v208
	v_and_b32_e32 v45, 0xffff0000, v208
	v_lshlrev_b32_e32 v46, 16, v209
	v_and_b32_e32 v47, 0xffff0000, v209
	v_lshlrev_b32_e32 v48, 16, v210
	v_and_b32_e32 v49, 0xffff0000, v210
	v_lshlrev_b32_e32 v50, 16, v211
	v_and_b32_e32 v51, 0xffff0000, v211
	v_pk_add_f32 v[14:15], v[14:15], v[44:45]
	v_pk_add_f32 v[16:17], v[16:17], v[46:47]
	v_pk_add_f32 v[18:19], v[18:19], v[48:49]
	v_pk_add_f32 v[12:13], v[12:13], v[50:51]
	v_pk_fma_f32 v[36:37], v[34:35], v[14:15], v[44:45] op_sel_hi:[0,1,1] neg_lo:[0,0,1] neg_hi:[0,0,1]
	v_pk_fma_f32 v[38:39], v[34:35], v[16:17], v[46:47] op_sel_hi:[0,1,1] neg_lo:[0,0,1] neg_hi:[0,0,1]
	v_pk_fma_f32 v[40:41], v[34:35], v[18:19], v[48:49] op_sel_hi:[0,1,1] neg_lo:[0,0,1] neg_hi:[0,0,1]
	v_pk_fma_f32 v[42:43], v[34:35], v[12:13], v[50:51] op_sel_hi:[0,1,1] neg_lo:[0,0,1] neg_hi:[0,0,1]
	v_cvt_pk_bf16_f32 v28, v36, v37
	v_cvt_pk_bf16_f32 v29, v38, v39
	v_cvt_pk_bf16_f32 v30, v40, v41
	v_cvt_pk_bf16_f32 v31, v42, v43
	global_store_dwordx4 v[10:11], v[28:31], off
	v_lshlrev_b32_e32 v44, 16, v148
	v_and_b32_e32 v45, 0xffff0000, v148
	v_lshlrev_b32_e32 v46, 16, v149
	v_and_b32_e32 v47, 0xffff0000, v149
	v_lshlrev_b32_e32 v48, 16, v150
	v_and_b32_e32 v49, 0xffff0000, v150
	v_lshlrev_b32_e32 v50, 16, v151
	v_and_b32_e32 v51, 0xffff0000, v151
	v_pk_add_f32 v[14:15], v[14:15], v[44:45] neg_lo:[0,1] neg_hi:[0,1]
	v_pk_add_f32 v[16:17], v[16:17], v[46:47] neg_lo:[0,1] neg_hi:[0,1]
	v_pk_add_f32 v[18:19], v[18:19], v[48:49] neg_lo:[0,1] neg_hi:[0,1]
	v_pk_add_f32 v[12:13], v[12:13], v[50:51] neg_lo:[0,1] neg_hi:[0,1]
; __device__ __forceinline__ unsigned pk2(float lo, float hi) { f32x2 v = {lo, hi}; bf16x2_t b = __builtin_convertvector(v, bf16x2_t); return __builtin_bit_cast(unsigned, b); }
; __device__ __forceinline__ void pool_window(const bf16_t* __restrict__ U  , bf16_t* __restrict__ A3, const int gtid, const int nthr) {
;     ...
;         for (int i = 0; i < 32; ++i) {
;             const int t = t0 + i, s = s0 + i;
;             const u32x4 uu = *(const u32x4*)(U + (size_t)t * LDU + c);
;             float cu[8] = {bflo(uu.x), bfhi(uu.x), bflo(uu.y), bfhi(uu.y), bflo(uu.z), bfhi(uu.z), bflo(uu.w), bfhi(uu.w)};
;             const float rc = 1.0f / (float)((s + 1) < w ? (s + 1) : w);
;             float o[8];
; #pragma unroll
;             for (int e = 0; e < 8; ++e) { sum[e] += cu[e]; o[e] = sum[e] * rc - cu[e]; }
;             u32x4 ww; ww.x = pk2(o[0], o[1]); ww.y = pk2(o[2], o[3]); ww.z = pk2(o[4], o[5]); ww.w = pk2(o[6], o[7]);
;             *(u32x4*)(A3 + (size_t)t * DM + c) = ww;
;             if (s + 1 >= w) { const u32x4 ud = *(const u32x4*)(U + (size_t)(t - w + 1) * LDU + c);
;                 sum[0] -= bflo(ud.x); sum[1] -= bfhi(ud.x); sum[2] -= bflo(ud.y); sum[3] -= bfhi(ud.y); sum[4] -= bflo(ud.z); sum[5] -= bfhi(ud.z); sum[6] -= bflo(ud.w); sum[7] -= bfhi(ud.w); }
;         }
	v_lshl_add_u64 v[10:11], v[10:11], 0, s[26:27]
	v_lshlrev_b32_e32 v44, 16, v214
	v_and_b32_e32 v45, 0xffff0000, v214
	v_lshlrev_b32_e32 v46, 16, v215
	v_and_b32_e32 v47, 0xffff0000, v215
	v_lshlrev_b32_e32 v48, 16, v216
	v_and_b32_e32 v49, 0xffff0000, v216
	v_lshlrev_b32_e32 v50, 16, v217
	v_and_b32_e32 v51, 0xffff0000, v217
	v_pk_add_f32 v[14:15], v[14:15], v[44:45]
	v_pk_add_f32 v[16:17], v[16:17], v[46:47]
	v_pk_add_f32 v[18:19], v[18:19], v[48:49]
	v_pk_add_f32 v[12:13], v[12:13], v[50:51]
	v_pk_fma_f32 v[36:37], v[34:35], v[14:15], v[44:45] op_sel_hi:[0,1,1] neg_lo:[0,0,1] neg_hi:[0,0,1]
	v_pk_fma_f32 v[38:39], v[34:35], v[16:17], v[46:47] op_sel_hi:[0,1,1] neg_lo:[0,0,1] neg_hi:[0,0,1]
	v_pk_fma_f32 v[40:41], v[34:35], v[18:19], v[48:49] op_sel_hi:[0,1,1] neg_lo:[0,0,1] neg_hi:[0,0,1]
	v_pk_fma_f32 v[42:43], v[34:35], v[12:13], v[50:51] op_sel_hi:[0,1,1] neg_lo:[0,0,1] neg_hi:[0,0,1]
	v_cvt_pk_bf16_f32 v28, v36, v37
	v_cvt_pk_bf16_f32 v29, v38, v39
	v_cvt_pk_bf16_f32 v30, v40, v41
	v_cvt_pk_bf16_f32 v31, v42, v43
	global_store_dwordx4 v[10:11], v[28:31], off
	v_lshlrev_b32_e32 v44, 16, v152
	v_and_b32_e32 v45, 0xffff0000, v152
	v_lshlrev_b32_e32 v46, 16, v153
	v_and_b32_e32 v47, 0xffff0000, v153
	v_lshlrev_b32_e32 v48, 16, v154
	v_and_b32_e32 v49, 0xffff0000, v154
	v_lshlrev_b32_e32 v50, 16, v155
	v_and_b32_e32 v51, 0xffff0000, v155
	v_pk_add_f32 v[14:15], v[14:15], v[44:45] neg_lo:[0,1] neg_hi:[0,1]
	v_pk_add_f32 v[16:17], v[16:17], v[46:47] neg_lo:[0,1] neg_hi:[0,1]
	v_pk_add_f32 v[18:19], v[18:19], v[48:49] neg_lo:[0,1] neg_hi:[0,1]
	v_pk_add_f32 v[12:13], v[12:13], v[50:51] neg_lo:[0,1] neg_hi:[0,1]
	v_lshl_add_u64 v[10:11], v[10:11], 0, s[26:27]
	v_lshlrev_b32_e32 v44, 16, v218
	v_and_b32_e32 v45, 0xffff0000, v218
	v_lshlrev_b32_e32 v46, 16, v219
	v_and_b32_e32 v47, 0xffff0000, v219
	v_lshlrev_b32_e32 v48, 16, v220
	v_and_b32_e32 v49, 0xffff0000, v220
	v_lshlrev_b32_e32 v50, 16, v221
	v_and_b32_e32 v51, 0xffff0000, v221
	v_pk_add_f32 v[14:15], v[14:15], v[44:45]
	v_pk_add_f32 v[16:17], v[16:17], v[46:47]
	v_pk_add_f32 v[18:19], v[18:19], v[48:49]
	v_pk_add_f32 v[12:13], v[12:13], v[50:51]
	v_pk_fma_f32 v[36:37], v[34:35], v[14:15], v[44:45] op_sel_hi:[0,1,1] neg_lo:[0,0,1] neg_hi:[0,0,1]
	v_pk_fma_f32 v[38:39], v[34:35], v[16:17], v[46:47] op_sel_hi:[0,1,1] neg_lo:[0,0,1] neg_hi:[0,0,1]
	v_pk_fma_f32 v[40:41], v[34:35], v[18:19], v[48:49] op_sel_hi:[0,1,1] neg_lo:[0,0,1] neg_hi:[0,0,1]
	v_pk_fma_f32 v[42:43], v[34:35], v[12:13], v[50:51] op_sel_hi:[0,1,1] neg_lo:[0,0,1] neg_hi:[0,0,1]
	v_cvt_pk_bf16_f32 v28, v36, v37
	v_cvt_pk_bf16_f32 v29, v38, v39
	v_cvt_pk_bf16_f32 v30, v40, v41
	v_cvt_pk_bf16_f32 v31, v42, v43
	global_store_dwordx4 v[10:11], v[28:31], off
	v_lshlrev_b32_e32 v44, 16, v156
	v_and_b32_e32 v45, 0xffff0000, v156
	v_lshlrev_b32_e32 v46, 16, v157
	v_and_b32_e32 v47, 0xffff0000, v157
	v_lshlrev_b32_e32 v48, 16, v158
	v_and_b32_e32 v49, 0xffff0000, v158
	v_lshlrev_b32_e32 v50, 16, v159
	v_and_b32_e32 v51, 0xffff0000, v159
	v_pk_add_f32 v[14:15], v[14:15], v[44:45] neg_lo:[0,1] neg_hi:[0,1]
	v_pk_add_f32 v[16:17], v[16:17], v[46:47] neg_lo:[0,1] neg_hi:[0,1]
	v_pk_add_f32 v[18:19], v[18:19], v[48:49] neg_lo:[0,1] neg_hi:[0,1]
	v_pk_add_f32 v[12:13], v[12:13], v[50:51] neg_lo:[0,1] neg_hi:[0,1]
	v_lshl_add_u64 v[10:11], v[10:11], 0, s[26:27]
	v_lshlrev_b32_e32 v44, 16, v222
	v_and_b32_e32 v45, 0xffff0000, v222
	v_lshlrev_b32_e32 v46, 16, v223
	v_and_b32_e32 v47, 0xffff0000, v223
	v_lshlrev_b32_e32 v48, 16, v224
	v_and_b32_e32 v49, 0xffff0000, v224
	v_lshlrev_b32_e32 v50, 16, v225
	v_and_b32_e32 v51, 0xffff0000, v225
	v_pk_add_f32 v[14:15], v[14:15], v[44:45]
	v_pk_add_f32 v[16:17], v[16:17], v[46:47]
	v_pk_add_f32 v[18:19], v[18:19], v[48:49]
	v_pk_add_f32 v[12:13], v[12:13], v[50:51]
	v_pk_fma_f32 v[36:37], v[34:35], v[14:15], v[44:45] op_sel_hi:[0,1,1] neg_lo:[0,0,1] neg_hi:[0,0,1]
	v_pk_fma_f32 v[38:39], v[34:35], v[16:17], v[46:47] op_sel_hi:[0,1,1] neg_lo:[0,0,1] neg_hi:[0,0,1]
	v_pk_fma_f32 v[40:41], v[34:35], v[18:19], v[48:49] op_sel_hi:[0,1,1] neg_lo:[0,0,1] neg_hi:[0,0,1]
	v_pk_fma_f32 v[42:43], v[34:35], v[12:13], v[50:51] op_sel_hi:[0,1,1] neg_lo:[0,0,1] neg_hi:[0,0,1]
	v_cvt_pk_bf16_f32 v28, v36, v37
	v_cvt_pk_bf16_f32 v29, v38, v39
	v_cvt_pk_bf16_f32 v30, v40, v41
	v_cvt_pk_bf16_f32 v31, v42, v43
	global_store_dwordx4 v[10:11], v[28:31], off
	v_lshlrev_b32_e32 v44, 16, v160
	v_and_b32_e32 v45, 0xffff0000, v160
	v_lshlrev_b32_e32 v46, 16, v161
	v_and_b32_e32 v47, 0xffff0000, v161
	v_lshlrev_b32_e32 v48, 16, v162
	v_and_b32_e32 v49, 0xffff0000, v162
	v_lshlrev_b32_e32 v50, 16, v163
	v_and_b32_e32 v51, 0xffff0000, v163
	v_pk_add_f32 v[14:15], v[14:15], v[44:45] neg_lo:[0,1] neg_hi:[0,1]
	v_pk_add_f32 v[16:17], v[16:17], v[46:47] neg_lo:[0,1] neg_hi:[0,1]
	v_pk_add_f32 v[18:19], v[18:19], v[48:49] neg_lo:[0,1] neg_hi:[0,1]
	v_pk_add_f32 v[12:13], v[12:13], v[50:51] neg_lo:[0,1] neg_hi:[0,1]
	v_lshl_add_u64 v[10:11], v[10:11], 0, s[26:27]
	v_lshlrev_b32_e32 v44, 16, v226
	v_and_b32_e32 v45, 0xffff0000, v226
	v_lshlrev_b32_e32 v46, 16, v227
	v_and_b32_e32 v47, 0xffff0000, v227
	v_lshlrev_b32_e32 v48, 16, v228
	v_and_b32_e32 v49, 0xffff0000, v228
	v_lshlrev_b32_e32 v50, 16, v229
	v_and_b32_e32 v51, 0xffff0000, v229
	v_pk_add_f32 v[14:15], v[14:15], v[44:45]
	v_pk_add_f32 v[16:17], v[16:17], v[46:47]
	v_pk_add_f32 v[18:19], v[18:19], v[48:49]
	v_pk_add_f32 v[12:13], v[12:13], v[50:51]
	v_pk_fma_f32 v[36:37], v[34:35], v[14:15], v[44:45] op_sel_hi:[0,1,1] neg_lo:[0,0,1] neg_hi:[0,0,1]
	v_pk_fma_f32 v[38:39], v[34:35], v[16:17], v[46:47] op_sel_hi:[0,1,1] neg_lo:[0,0,1] neg_hi:[0,0,1]
; __device__ __forceinline__ unsigned pk2(float lo, float hi) { f32x2 v = {lo, hi}; bf16x2_t b = __builtin_convertvector(v, bf16x2_t); return __builtin_bit_cast(unsigned, b); }
; __device__ __forceinline__ void pool_window(const bf16_t* __restrict__ U  , bf16_t* __restrict__ A3, const int gtid, const int nthr) {
;     ...
;         for (int i = 0; i < 32; ++i) {
;             const int t = t0 + i, s = s0 + i;
;             const u32x4 uu = *(const u32x4*)(U + (size_t)t * LDU + c);
;             float cu[8] = {bflo(uu.x), bfhi(uu.x), bflo(uu.y), bfhi(uu.y), bflo(uu.z), bfhi(uu.z), bflo(uu.w), bfhi(uu.w)};
;             const float rc = 1.0f / (float)((s + 1) < w ? (s + 1) : w);
;             float o[8];
; #pragma unroll
;             for (int e = 0; e < 8; ++e) { sum[e] += cu[e]; o[e] = sum[e] * rc - cu[e]; }
;             u32x4 ww; ww.x = pk2(o[0], o[1]); ww.y = pk2(o[2], o[3]); ww.z = pk2(o[4], o[5]); ww.w = pk2(o[6], o[7]);
;             *(u32x4*)(A3 + (size_t)t * DM + c) = ww;
;             if (s + 1 >= w) { const u32x4 ud = *(const u32x4*)(U + (size_t)(t - w + 1) * LDU + c);
;                 sum[0] -= bflo(ud.x); sum[1] -= bfhi(ud.x); sum[2] -= bflo(ud.y); sum[3] -= bfhi(ud.y); sum[4] -= bflo(ud.z); sum[5] -= bfhi(ud.z); sum[6] -= bflo(ud.w); sum[7] -= bfhi(ud.w); }
;         }
	v_pk_fma_f32 v[40:41], v[34:35], v[18:19], v[48:49] op_sel_hi:[0,1,1] neg_lo:[0,0,1] neg_hi:[0,0,1]
	v_pk_fma_f32 v[42:43], v[34:35], v[12:13], v[50:51] op_sel_hi:[0,1,1] neg_lo:[0,0,1] neg_hi:[0,0,1]
	v_cvt_pk_bf16_f32 v28, v36, v37
	v_cvt_pk_bf16_f32 v29, v38, v39
	v_cvt_pk_bf16_f32 v30, v40, v41
	v_cvt_pk_bf16_f32 v31, v42, v43
	global_store_dwordx4 v[10:11], v[28:31], off
	v_lshlrev_b32_e32 v44, 16, v164
	v_and_b32_e32 v45, 0xffff0000, v164
	v_lshlrev_b32_e32 v46, 16, v165
	v_and_b32_e32 v47, 0xffff0000, v165
	v_lshlrev_b32_e32 v48, 16, v166
	v_and_b32_e32 v49, 0xffff0000, v166
	v_lshlrev_b32_e32 v50, 16, v167
	v_and_b32_e32 v51, 0xffff0000, v167
	v_pk_add_f32 v[14:15], v[14:15], v[44:45] neg_lo:[0,1] neg_hi:[0,1]
	v_pk_add_f32 v[16:17], v[16:17], v[46:47] neg_lo:[0,1] neg_hi:[0,1]
	v_pk_add_f32 v[18:19], v[18:19], v[48:49] neg_lo:[0,1] neg_hi:[0,1]
	v_pk_add_f32 v[12:13], v[12:13], v[50:51] neg_lo:[0,1] neg_hi:[0,1]
	v_lshl_add_u64 v[10:11], v[10:11], 0, s[26:27]
	v_lshlrev_b32_e32 v44, 16, v230
	v_and_b32_e32 v45, 0xffff0000, v230
	v_lshlrev_b32_e32 v46, 16, v231
	v_and_b32_e32 v47, 0xffff0000, v231
	v_lshlrev_b32_e32 v48, 16, v232
	v_and_b32_e32 v49, 0xffff0000, v232
	v_lshlrev_b32_e32 v50, 16, v233
	v_and_b32_e32 v51, 0xffff0000, v233
	v_pk_add_f32 v[14:15], v[14:15], v[44:45]
	v_pk_add_f32 v[16:17], v[16:17], v[46:47]
	v_pk_add_f32 v[18:19], v[18:19], v[48:49]
	v_pk_add_f32 v[12:13], v[12:13], v[50:51]
	v_pk_fma_f32 v[36:37], v[34:35], v[14:15], v[44:45] op_sel_hi:[0,1,1] neg_lo:[0,0,1] neg_hi:[0,0,1]
	v_pk_fma_f32 v[38:39], v[34:35], v[16:17], v[46:47] op_sel_hi:[0,1,1] neg_lo:[0,0,1] neg_hi:[0,0,1]
	v_pk_fma_f32 v[40:41], v[34:35], v[18:19], v[48:49] op_sel_hi:[0,1,1] neg_lo:[0,0,1] neg_hi:[0,0,1]
	v_pk_fma_f32 v[42:43], v[34:35], v[12:13], v[50:51] op_sel_hi:[0,1,1] neg_lo:[0,0,1] neg_hi:[0,0,1]
	v_cvt_pk_bf16_f32 v28, v36, v37
	v_cvt_pk_bf16_f32 v29, v38, v39
	v_cvt_pk_bf16_f32 v30, v40, v41
	v_cvt_pk_bf16_f32 v31, v42, v43
	global_store_dwordx4 v[10:11], v[28:31], off
	v_lshlrev_b32_e32 v44, 16, v168
	v_and_b32_e32 v45, 0xffff0000, v168
	v_lshlrev_b32_e32 v46, 16, v169
	v_and_b32_e32 v47, 0xffff0000, v169
	v_lshlrev_b32_e32 v48, 16, v170
	v_and_b32_e32 v49, 0xffff0000, v170
	v_lshlrev_b32_e32 v50, 16, v171
	v_and_b32_e32 v51, 0xffff0000, v171
	v_pk_add_f32 v[14:15], v[14:15], v[44:45] neg_lo:[0,1] neg_hi:[0,1]
	v_pk_add_f32 v[16:17], v[16:17], v[46:47] neg_lo:[0,1] neg_hi:[0,1]
	v_pk_add_f32 v[18:19], v[18:19], v[48:49] neg_lo:[0,1] neg_hi:[0,1]
	v_pk_add_f32 v[12:13], v[12:13], v[50:51] neg_lo:[0,1] neg_hi:[0,1]
	v_lshl_add_u64 v[10:11], v[10:11], 0, s[26:27]
	v_lshlrev_b32_e32 v44, 16, v234
	v_and_b32_e32 v45, 0xffff0000, v234
	v_lshlrev_b32_e32 v46, 16, v235
	v_and_b32_e32 v47, 0xffff0000, v235
	v_lshlrev_b32_e32 v48, 16, v236
	v_and_b32_e32 v49, 0xffff0000, v236
	v_lshlrev_b32_e32 v50, 16, v237
	v_and_b32_e32 v51, 0xffff0000, v237
	v_pk_add_f32 v[14:15], v[14:15], v[44:45]
	v_pk_add_f32 v[16:17], v[16:17], v[46:47]
	v_pk_add_f32 v[18:19], v[18:19], v[48:49]
	v_pk_add_f32 v[12:13], v[12:13], v[50:51]
	v_pk_fma_f32 v[36:37], v[34:35], v[14:15], v[44:45] op_sel_hi:[0,1,1] neg_lo:[0,0,1] neg_hi:[0,0,1]
	v_pk_fma_f32 v[38:39], v[34:35], v[16:17], v[46:47] op_sel_hi:[0,1,1] neg_lo:[0,0,1] neg_hi:[0,0,1]
	v_pk_fma_f32 v[40:41], v[34:35], v[18:19], v[48:49] op_sel_hi:[0,1,1] neg_lo:[0,0,1] neg_hi:[0,0,1]
	v_pk_fma_f32 v[42:43], v[34:35], v[12:13], v[50:51] op_sel_hi:[0,1,1] neg_lo:[0,0,1] neg_hi:[0,0,1]
	v_cvt_pk_bf16_f32 v28, v36, v37
	v_cvt_pk_bf16_f32 v29, v38, v39
	v_cvt_pk_bf16_f32 v30, v40, v41
	v_cvt_pk_bf16_f32 v31, v42, v43
	global_store_dwordx4 v[10:11], v[28:31], off
	v_lshlrev_b32_e32 v44, 16, v172
	v_and_b32_e32 v45, 0xffff0000, v172
	v_lshlrev_b32_e32 v46, 16, v173
	v_and_b32_e32 v47, 0xffff0000, v173
	v_lshlrev_b32_e32 v48, 16, v174
	v_and_b32_e32 v49, 0xffff0000, v174
	v_lshlrev_b32_e32 v50, 16, v175
	v_and_b32_e32 v51, 0xffff0000, v175
	v_pk_add_f32 v[14:15], v[14:15], v[44:45] neg_lo:[0,1] neg_hi:[0,1]
	v_pk_add_f32 v[16:17], v[16:17], v[46:47] neg_lo:[0,1] neg_hi:[0,1]
	v_pk_add_f32 v[18:19], v[18:19], v[48:49] neg_lo:[0,1] neg_hi:[0,1]
	v_pk_add_f32 v[12:13], v[12:13], v[50:51] neg_lo:[0,1] neg_hi:[0,1]
	v_lshl_add_u64 v[10:11], v[10:11], 0, s[26:27]
	v_lshlrev_b32_e32 v44, 16, v238
	v_and_b32_e32 v45, 0xffff0000, v238
	v_lshlrev_b32_e32 v46, 16, v239
	v_and_b32_e32 v47, 0xffff0000, v239
	v_lshlrev_b32_e32 v48, 16, v240
	v_and_b32_e32 v49, 0xffff0000, v240
	v_lshlrev_b32_e32 v50, 16, v241
	v_and_b32_e32 v51, 0xffff0000, v241
	v_pk_add_f32 v[14:15], v[14:15], v[44:45]
	v_pk_add_f32 v[16:17], v[16:17], v[46:47]
	v_pk_add_f32 v[18:19], v[18:19], v[48:49]
	v_pk_add_f32 v[12:13], v[12:13], v[50:51]
	v_pk_fma_f32 v[36:37], v[34:35], v[14:15], v[44:45] op_sel_hi:[0,1,1] neg_lo:[0,0,1] neg_hi:[0,0,1]
	v_pk_fma_f32 v[38:39], v[34:35], v[16:17], v[46:47] op_sel_hi:[0,1,1] neg_lo:[0,0,1] neg_hi:[0,0,1]
	v_pk_fma_f32 v[40:41], v[34:35], v[18:19], v[48:49] op_sel_hi:[0,1,1] neg_lo:[0,0,1] neg_hi:[0,0,1]
	v_pk_fma_f32 v[42:43], v[34:35], v[12:13], v[50:51] op_sel_hi:[0,1,1] neg_lo:[0,0,1] neg_hi:[0,0,1]
	v_cvt_pk_bf16_f32 v28, v36, v37
	v_cvt_pk_bf16_f32 v29, v38, v39
	v_cvt_pk_bf16_f32 v30, v40, v41
	v_cvt_pk_bf16_f32 v31, v42, v43
	global_store_dwordx4 v[10:11], v[28:31], off
	v_lshlrev_b32_e32 v44, 16, v176
	v_and_b32_e32 v45, 0xffff0000, v176
	v_lshlrev_b32_e32 v46, 16, v177
	v_and_b32_e32 v47, 0xffff0000, v177
	v_lshlrev_b32_e32 v48, 16, v178
	v_and_b32_e32 v49, 0xffff0000, v178
	v_lshlrev_b32_e32 v50, 16, v179
	v_and_b32_e32 v51, 0xffff0000, v179
	v_pk_add_f32 v[14:15], v[14:15], v[44:45] neg_lo:[0,1] neg_hi:[0,1]
; __device__ __forceinline__ unsigned pk2(float lo, float hi) { f32x2 v = {lo, hi}; bf16x2_t b = __builtin_convertvector(v, bf16x2_t); return __builtin_bit_cast(unsigned, b); }
; __device__ __forceinline__ void pool_window(const bf16_t* __restrict__ U  , bf16_t* __restrict__ A3, const int gtid, const int nthr) {
;     ...
;         for (int i = 0; i < 32; ++i) {
;             const int t = t0 + i, s = s0 + i;
;             const u32x4 uu = *(const u32x4*)(U + (size_t)t * LDU + c);
;             float cu[8] = {bflo(uu.x), bfhi(uu.x), bflo(uu.y), bfhi(uu.y), bflo(uu.z), bfhi(uu.z), bflo(uu.w), bfhi(uu.w)};
;             const float rc = 1.0f / (float)((s + 1) < w ? (s + 1) : w);
;             float o[8];
; #pragma unroll
;             for (int e = 0; e < 8; ++e) { sum[e] += cu[e]; o[e] = sum[e] * rc - cu[e]; }
;             u32x4 ww; ww.x = pk2(o[0], o[1]); ww.y = pk2(o[2], o[3]); ww.z = pk2(o[4], o[5]); ww.w = pk2(o[6], o[7]);
;             *(u32x4*)(A3 + (size_t)t * DM + c) = ww;
;             if (s + 1 >= w) { const u32x4 ud = *(const u32x4*)(U + (size_t)(t - w + 1) * LDU + c);
;                 sum[0] -= bflo(ud.x); sum[1] -= bfhi(ud.x); sum[2] -= bflo(ud.y); sum[3] -= bfhi(ud.y); sum[4] -= bflo(ud.z); sum[5] -= bfhi(ud.z); sum[6] -= bflo(ud.w); sum[7] -= bfhi(ud.w); }
;         }
	v_pk_add_f32 v[16:17], v[16:17], v[46:47] neg_lo:[0,1] neg_hi:[0,1]
	v_pk_add_f32 v[18:19], v[18:19], v[48:49] neg_lo:[0,1] neg_hi:[0,1]
	v_pk_add_f32 v[12:13], v[12:13], v[50:51] neg_lo:[0,1] neg_hi:[0,1]
	v_lshl_add_u64 v[10:11], v[10:11], 0, s[26:27]
	v_lshlrev_b32_e32 v44, 16, v242
	v_and_b32_e32 v45, 0xffff0000, v242
	v_lshlrev_b32_e32 v46, 16, v243
	v_and_b32_e32 v47, 0xffff0000, v243
	v_lshlrev_b32_e32 v48, 16, v244
	v_and_b32_e32 v49, 0xffff0000, v244
	v_lshlrev_b32_e32 v50, 16, v245
	v_and_b32_e32 v51, 0xffff0000, v245
	v_pk_add_f32 v[14:15], v[14:15], v[44:45]
	v_pk_add_f32 v[16:17], v[16:17], v[46:47]
	v_pk_add_f32 v[18:19], v[18:19], v[48:49]
	v_pk_add_f32 v[12:13], v[12:13], v[50:51]
	v_pk_fma_f32 v[36:37], v[34:35], v[14:15], v[44:45] op_sel_hi:[0,1,1] neg_lo:[0,0,1] neg_hi:[0,0,1]
	v_pk_fma_f32 v[38:39], v[34:35], v[16:17], v[46:47] op_sel_hi:[0,1,1] neg_lo:[0,0,1] neg_hi:[0,0,1]
	v_pk_fma_f32 v[40:41], v[34:35], v[18:19], v[48:49] op_sel_hi:[0,1,1] neg_lo:[0,0,1] neg_hi:[0,0,1]
	v_pk_fma_f32 v[42:43], v[34:35], v[12:13], v[50:51] op_sel_hi:[0,1,1] neg_lo:[0,0,1] neg_hi:[0,0,1]
	v_cvt_pk_bf16_f32 v28, v36, v37
	v_cvt_pk_bf16_f32 v29, v38, v39
	v_cvt_pk_bf16_f32 v30, v40, v41
	v_cvt_pk_bf16_f32 v31, v42, v43
	global_store_dwordx4 v[10:11], v[28:31], off
	v_lshlrev_b32_e32 v44, 16, v180
	v_and_b32_e32 v45, 0xffff0000, v180
	v_lshlrev_b32_e32 v46, 16, v181
	v_and_b32_e32 v47, 0xffff0000, v181
	v_lshlrev_b32_e32 v48, 16, v182
	v_and_b32_e32 v49, 0xffff0000, v182
	v_lshlrev_b32_e32 v50, 16, v183
	v_and_b32_e32 v51, 0xffff0000, v183
	v_pk_add_f32 v[14:15], v[14:15], v[44:45] neg_lo:[0,1] neg_hi:[0,1]
	v_pk_add_f32 v[16:17], v[16:17], v[46:47] neg_lo:[0,1] neg_hi:[0,1]
	v_pk_add_f32 v[18:19], v[18:19], v[48:49] neg_lo:[0,1] neg_hi:[0,1]
	v_pk_add_f32 v[12:13], v[12:13], v[50:51] neg_lo:[0,1] neg_hi:[0,1]
	v_lshl_add_u64 v[10:11], v[10:11], 0, s[26:27]
	v_lshlrev_b32_e32 v44, 16, v246
	v_and_b32_e32 v45, 0xffff0000, v246
	v_lshlrev_b32_e32 v46, 16, v247
	v_and_b32_e32 v47, 0xffff0000, v247
	v_lshlrev_b32_e32 v48, 16, v248
	v_and_b32_e32 v49, 0xffff0000, v248
	v_lshlrev_b32_e32 v50, 16, v249
	v_and_b32_e32 v51, 0xffff0000, v249
	v_pk_add_f32 v[14:15], v[14:15], v[44:45]
	v_pk_add_f32 v[16:17], v[16:17], v[46:47]
	v_pk_add_f32 v[18:19], v[18:19], v[48:49]
	v_pk_add_f32 v[12:13], v[12:13], v[50:51]
	v_pk_fma_f32 v[36:37], v[34:35], v[14:15], v[44:45] op_sel_hi:[0,1,1] neg_lo:[0,0,1] neg_hi:[0,0,1]
	v_pk_fma_f32 v[38:39], v[34:35], v[16:17], v[46:47] op_sel_hi:[0,1,1] neg_lo:[0,0,1] neg_hi:[0,0,1]
	v_pk_fma_f32 v[40:41], v[34:35], v[18:19], v[48:49] op_sel_hi:[0,1,1] neg_lo:[0,0,1] neg_hi:[0,0,1]
	v_pk_fma_f32 v[42:43], v[34:35], v[12:13], v[50:51] op_sel_hi:[0,1,1] neg_lo:[0,0,1] neg_hi:[0,0,1]
	v_cvt_pk_bf16_f32 v28, v36, v37
	v_cvt_pk_bf16_f32 v29, v38, v39
	v_cvt_pk_bf16_f32 v30, v40, v41
	v_cvt_pk_bf16_f32 v31, v42, v43
	global_store_dwordx4 v[10:11], v[28:31], off
	v_lshlrev_b32_e32 v44, 16, v184
	v_and_b32_e32 v45, 0xffff0000, v184
	v_lshlrev_b32_e32 v46, 16, v185
	v_and_b32_e32 v47, 0xffff0000, v185
	v_lshlrev_b32_e32 v48, 16, v186
	v_and_b32_e32 v49, 0xffff0000, v186
	v_lshlrev_b32_e32 v50, 16, v187
	v_and_b32_e32 v51, 0xffff0000, v187
	v_pk_add_f32 v[14:15], v[14:15], v[44:45] neg_lo:[0,1] neg_hi:[0,1]
	v_pk_add_f32 v[16:17], v[16:17], v[46:47] neg_lo:[0,1] neg_hi:[0,1]
	v_pk_add_f32 v[18:19], v[18:19], v[48:49] neg_lo:[0,1] neg_hi:[0,1]
	v_pk_add_f32 v[12:13], v[12:13], v[50:51] neg_lo:[0,1] neg_hi:[0,1]
	v_lshl_add_u64 v[10:11], v[10:11], 0, s[26:27]
	v_lshlrev_b32_e32 v44, 16, v250
	v_and_b32_e32 v45, 0xffff0000, v250
	v_lshlrev_b32_e32 v46, 16, v251
	v_and_b32_e32 v47, 0xffff0000, v251
	v_lshlrev_b32_e32 v48, 16, v252
	v_and_b32_e32 v49, 0xffff0000, v252
	v_lshlrev_b32_e32 v50, 16, v253
	v_and_b32_e32 v51, 0xffff0000, v253
	v_pk_add_f32 v[14:15], v[14:15], v[44:45]
	v_pk_add_f32 v[16:17], v[16:17], v[46:47]
	v_pk_add_f32 v[18:19], v[18:19], v[48:49]
	v_pk_add_f32 v[12:13], v[12:13], v[50:51]
	v_pk_fma_f32 v[36:37], v[34:35], v[14:15], v[44:45] op_sel_hi:[0,1,1] neg_lo:[0,0,1] neg_hi:[0,0,1]
	v_pk_fma_f32 v[38:39], v[34:35], v[16:17], v[46:47] op_sel_hi:[0,1,1] neg_lo:[0,0,1] neg_hi:[0,0,1]
	v_pk_fma_f32 v[40:41], v[34:35], v[18:19], v[48:49] op_sel_hi:[0,1,1] neg_lo:[0,0,1] neg_hi:[0,0,1]
	v_pk_fma_f32 v[42:43], v[34:35], v[12:13], v[50:51] op_sel_hi:[0,1,1] neg_lo:[0,0,1] neg_hi:[0,0,1]
	v_cvt_pk_bf16_f32 v28, v36, v37
	v_cvt_pk_bf16_f32 v29, v38, v39
	v_cvt_pk_bf16_f32 v30, v40, v41
	v_cvt_pk_bf16_f32 v31, v42, v43
	global_store_dwordx4 v[10:11], v[28:31], off
	v_lshlrev_b32_e32 v44, 16, v188
	v_and_b32_e32 v45, 0xffff0000, v188
	v_lshlrev_b32_e32 v46, 16, v189
	v_and_b32_e32 v47, 0xffff0000, v189
	v_lshlrev_b32_e32 v48, 16, v190
	v_and_b32_e32 v49, 0xffff0000, v190
	v_lshlrev_b32_e32 v50, 16, v191
	v_and_b32_e32 v51, 0xffff0000, v191
	v_pk_add_f32 v[14:15], v[14:15], v[44:45] neg_lo:[0,1] neg_hi:[0,1]
	v_pk_add_f32 v[16:17], v[16:17], v[46:47] neg_lo:[0,1] neg_hi:[0,1]
	v_pk_add_f32 v[18:19], v[18:19], v[48:49] neg_lo:[0,1] neg_hi:[0,1]
	v_pk_add_f32 v[12:13], v[12:13], v[50:51] neg_lo:[0,1] neg_hi:[0,1]
	s_branch .LBB0_1331
; __device__ __forceinline__ unsigned pk2(float lo, float hi) { f32x2 v = {lo, hi}; bf16x2_t b = __builtin_convertvector(v, bf16x2_t); return __builtin_bit_cast(unsigned, b); }
; __device__ __forceinline__ void pool_window(const bf16_t* __restrict__ U  , bf16_t* __restrict__ A3, const int gtid, const int nthr) {
;     ...
;         for (int i = 0; i < 32; ++i) {
;             const int t = t0 + i, s = s0 + i;
;             const u32x4 uu = *(const u32x4*)(U + (size_t)t * LDU + c);
;             float cu[8] = {bflo(uu.x), bfhi(uu.x), bflo(uu.y), bfhi(uu.y), bflo(uu.z), bfhi(uu.z), bflo(uu.w), bfhi(uu.w)};
;             const float rc = 1.0f / (float)((s + 1) < w ? (s + 1) : w);
;             float o[8];
; #pragma unroll
;             for (int e = 0; e < 8; ++e) { sum[e] += cu[e]; o[e] = sum[e] * rc - cu[e]; }
;             u32x4 ww; ww.x = pk2(o[0], o[1]); ww.y = pk2(o[2], o[3]); ww.z = pk2(o[4], o[5]); ww.w = pk2(o[6], o[7]);
;             *(u32x4*)(A3 + (size_t)t * DM + c) = ww;
;             if (s + 1 >= w) { const u32x4 ud = *(const u32x4*)(U + (size_t)(t - w + 1) * LDU + c);
;                 sum[0] -= bflo(ud.x); sum[1] -= bfhi(ud.x); sum[2] -= bflo(ud.y); sum[3] -= bfhi(ud.y); sum[4] -= bflo(ud.z); sum[5] -= bfhi(ud.z); sum[6] -= bflo(ud.w); sum[7] -= bfhi(ud.w); }
;         }
.Lpw0_w2:
	v_mov_b32_e32 v34, 0.5
	s_waitcnt vmcnt(0)
	v_mov_b32_e32 v34, 0x3f800000
	v_lshlrev_b32_e32 v44, 16, v124
	v_and_b32_e32 v45, 0xffff0000, v124
	v_lshlrev_b32_e32 v46, 16, v125
	v_and_b32_e32 v47, 0xffff0000, v125
	v_lshlrev_b32_e32 v48, 16, v126
	v_and_b32_e32 v49, 0xffff0000, v126
	v_lshlrev_b32_e32 v50, 16, v127
	v_and_b32_e32 v51, 0xffff0000, v127
	v_pk_add_f32 v[14:15], v[14:15], v[44:45]
	v_pk_add_f32 v[16:17], v[16:17], v[46:47]
	v_pk_add_f32 v[18:19], v[18:19], v[48:49]
	v_pk_add_f32 v[12:13], v[12:13], v[50:51]
	v_pk_fma_f32 v[36:37], v[34:35], v[14:15], v[44:45] op_sel_hi:[0,1,1] neg_lo:[0,0,1] neg_hi:[0,0,1]
	v_pk_fma_f32 v[38:39], v[34:35], v[16:17], v[46:47] op_sel_hi:[0,1,1] neg_lo:[0,0,1] neg_hi:[0,0,1]
	v_pk_fma_f32 v[40:41], v[34:35], v[18:19], v[48:49] op_sel_hi:[0,1,1] neg_lo:[0,0,1] neg_hi:[0,0,1]
	v_pk_fma_f32 v[42:43], v[34:35], v[12:13], v[50:51] op_sel_hi:[0,1,1] neg_lo:[0,0,1] neg_hi:[0,0,1]
	v_cvt_pk_bf16_f32 v28, v36, v37
	v_cvt_pk_bf16_f32 v29, v38, v39
	v_cvt_pk_bf16_f32 v30, v40, v41
	v_cvt_pk_bf16_f32 v31, v42, v43
	global_store_dwordx4 v[10:11], v[28:31], off
	v_lshl_add_u64 v[10:11], v[10:11], 0, s[26:27]
	v_mov_b32_e32 v34, 0x3f000000
	v_lshlrev_b32_e32 v44, 16, v128
	v_and_b32_e32 v45, 0xffff0000, v128
	v_lshlrev_b32_e32 v46, 16, v129
	v_and_b32_e32 v47, 0xffff0000, v129
	v_lshlrev_b32_e32 v48, 16, v130
	v_and_b32_e32 v49, 0xffff0000, v130
	v_lshlrev_b32_e32 v50, 16, v131
	v_and_b32_e32 v51, 0xffff0000, v131
	v_pk_add_f32 v[14:15], v[14:15], v[44:45]
	v_pk_add_f32 v[16:17], v[16:17], v[46:47]
	v_pk_add_f32 v[18:19], v[18:19], v[48:49]
	v_pk_add_f32 v[12:13], v[12:13], v[50:51]
	v_pk_fma_f32 v[36:37], v[34:35], v[14:15], v[44:45] op_sel_hi:[0,1,1] neg_lo:[0,0,1] neg_hi:[0,0,1]
	v_pk_fma_f32 v[38:39], v[34:35], v[16:17], v[46:47] op_sel_hi:[0,1,1] neg_lo:[0,0,1] neg_hi:[0,0,1]
	v_pk_fma_f32 v[40:41], v[34:35], v[18:19], v[48:49] op_sel_hi:[0,1,1] neg_lo:[0,0,1] neg_hi:[0,0,1]
	v_pk_fma_f32 v[42:43], v[34:35], v[12:13], v[50:51] op_sel_hi:[0,1,1] neg_lo:[0,0,1] neg_hi:[0,0,1]
	v_cvt_pk_bf16_f32 v28, v36, v37
	v_cvt_pk_bf16_f32 v29, v38, v39
	v_cvt_pk_bf16_f32 v30, v40, v41
	v_cvt_pk_bf16_f32 v31, v42, v43
	global_store_dwordx4 v[10:11], v[28:31], off
	v_lshlrev_b32_e32 v44, 16, v124
	v_and_b32_e32 v45, 0xffff0000, v124
	v_lshlrev_b32_e32 v46, 16, v125
	v_and_b32_e32 v47, 0xffff0000, v125
	v_lshlrev_b32_e32 v48, 16, v126
	v_and_b32_e32 v49, 0xffff0000, v126
	v_lshlrev_b32_e32 v50, 16, v127
	v_and_b32_e32 v51, 0xffff0000, v127
	v_pk_add_f32 v[14:15], v[14:15], v[44:45] neg_lo:[0,1] neg_hi:[0,1]
	v_pk_add_f32 v[16:17], v[16:17], v[46:47] neg_lo:[0,1] neg_hi:[0,1]
	v_pk_add_f32 v[18:19], v[18:19], v[48:49] neg_lo:[0,1] neg_hi:[0,1]
	v_pk_add_f32 v[12:13], v[12:13], v[50:51] neg_lo:[0,1] neg_hi:[0,1]
	v_lshl_add_u64 v[10:11], v[10:11], 0, s[26:27]
	v_lshlrev_b32_e32 v44, 16, v132
	v_and_b32_e32 v45, 0xffff0000, v132
	v_lshlrev_b32_e32 v46, 16, v133
	v_and_b32_e32 v47, 0xffff0000, v133
	v_lshlrev_b32_e32 v48, 16, v134
	v_and_b32_e32 v49, 0xffff0000, v134
	v_lshlrev_b32_e32 v50, 16, v135
	v_and_b32_e32 v51, 0xffff0000, v135
	v_pk_add_f32 v[14:15], v[14:15], v[44:45]
	v_pk_add_f32 v[16:17], v[16:17], v[46:47]
	v_pk_add_f32 v[18:19], v[18:19], v[48:49]
	v_pk_add_f32 v[12:13], v[12:13], v[50:51]
	v_pk_fma_f32 v[36:37], v[34:35], v[14:15], v[44:45] op_sel_hi:[0,1,1] neg_lo:[0,0,1] neg_hi:[0,0,1]
	v_pk_fma_f32 v[38:39], v[34:35], v[16:17], v[46:47] op_sel_hi:[0,1,1] neg_lo:[0,0,1] neg_hi:[0,0,1]
	v_pk_fma_f32 v[40:41], v[34:35], v[18:19], v[48:49] op_sel_hi:[0,1,1] neg_lo:[0,0,1] neg_hi:[0,0,1]
	v_pk_fma_f32 v[42:43], v[34:35], v[12:13], v[50:51] op_sel_hi:[0,1,1] neg_lo:[0,0,1] neg_hi:[0,0,1]
	v_cvt_pk_bf16_f32 v28, v36, v37
	v_cvt_pk_bf16_f32 v29, v38, v39
	v_cvt_pk_bf16_f32 v30, v40, v41
	v_cvt_pk_bf16_f32 v31, v42, v43
	global_store_dwordx4 v[10:11], v[28:31], off
	v_lshlrev_b32_e32 v44, 16, v128
	v_and_b32_e32 v45, 0xffff0000, v128
	v_lshlrev_b32_e32 v46, 16, v129
	v_and_b32_e32 v47, 0xffff0000, v129
	v_lshlrev_b32_e32 v48, 16, v130
	v_and_b32_e32 v49, 0xffff0000, v130
	v_lshlrev_b32_e32 v50, 16, v131
	v_and_b32_e32 v51, 0xffff0000, v131
	v_pk_add_f32 v[14:15], v[14:15], v[44:45] neg_lo:[0,1] neg_hi:[0,1]
	v_pk_add_f32 v[16:17], v[16:17], v[46:47] neg_lo:[0,1] neg_hi:[0,1]
	v_pk_add_f32 v[18:19], v[18:19], v[48:49] neg_lo:[0,1] neg_hi:[0,1]
	v_pk_add_f32 v[12:13], v[12:13], v[50:51] neg_lo:[0,1] neg_hi:[0,1]
	v_lshl_add_u64 v[10:11], v[10:11], 0, s[26:27]
	v_lshlrev_b32_e32 v44, 16, v136
	v_and_b32_e32 v45, 0xffff0000, v136
	v_lshlrev_b32_e32 v46, 16, v137
	v_and_b32_e32 v47, 0xffff0000, v137
	v_lshlrev_b32_e32 v48, 16, v138
	v_and_b32_e32 v49, 0xffff0000, v138
	v_lshlrev_b32_e32 v50, 16, v139
	v_and_b32_e32 v51, 0xffff0000, v139
	v_pk_add_f32 v[14:15], v[14:15], v[44:45]
	v_pk_add_f32 v[16:17], v[16:17], v[46:47]
	v_pk_add_f32 v[18:19], v[18:19], v[48:49]
	v_pk_add_f32 v[12:13], v[12:13], v[50:51]
	v_pk_fma_f32 v[36:37], v[34:35], v[14:15], v[44:45] op_sel_hi:[0,1,1] neg_lo:[0,0,1] neg_hi:[0,0,1]
	v_pk_fma_f32 v[38:39], v[34:35], v[16:17], v[46:47] op_sel_hi:[0,1,1] neg_lo:[0,0,1] neg_hi:[0,0,1]
	v_pk_fma_f32 v[40:41], v[34:35], v[18:19], v[48:49] op_sel_hi:[0,1,1] neg_lo:[0,0,1] neg_hi:[0,0,1]
	v_pk_fma_f32 v[42:43], v[34:35], v[12:13], v[50:51] op_sel_hi:[0,1,1] neg_lo:[0,0,1] neg_hi:[0,0,1]
	v_cvt_pk_bf16_f32 v28, v36, v37
	v_cvt_pk_bf16_f32 v29, v38, v39
	v_cvt_pk_bf16_f32 v30, v40, v41
	v_cvt_pk_bf16_f32 v31, v42, v43
	global_store_dwordx4 v[10:11], v[28:31], off
	v_lshlrev_b32_e32 v44, 16, v132
	v_and_b32_e32 v45, 0xffff0000, v132
	v_lshlrev_b32_e32 v46, 16, v133
	v_and_b32_e32 v47, 0xffff0000, v133
; __device__ __forceinline__ unsigned pk2(float lo, float hi) { f32x2 v = {lo, hi}; bf16x2_t b = __builtin_convertvector(v, bf16x2_t); return __builtin_bit_cast(unsigned, b); }
; __device__ __forceinline__ void pool_window(const bf16_t* __restrict__ U  , bf16_t* __restrict__ A3, const int gtid, const int nthr) {
;     ...
;         for (int i = 0; i < 32; ++i) {
;             const int t = t0 + i, s = s0 + i;
;             const u32x4 uu = *(const u32x4*)(U + (size_t)t * LDU + c);
;             float cu[8] = {bflo(uu.x), bfhi(uu.x), bflo(uu.y), bfhi(uu.y), bflo(uu.z), bfhi(uu.z), bflo(uu.w), bfhi(uu.w)};
;             const float rc = 1.0f / (float)((s + 1) < w ? (s + 1) : w);
;             float o[8];
; #pragma unroll
;             for (int e = 0; e < 8; ++e) { sum[e] += cu[e]; o[e] = sum[e] * rc - cu[e]; }
;             u32x4 ww; ww.x = pk2(o[0], o[1]); ww.y = pk2(o[2], o[3]); ww.z = pk2(o[4], o[5]); ww.w = pk2(o[6], o[7]);
;             *(u32x4*)(A3 + (size_t)t * DM + c) = ww;
;             if (s + 1 >= w) { const u32x4 ud = *(const u32x4*)(U + (size_t)(t - w + 1) * LDU + c);
;                 sum[0] -= bflo(ud.x); sum[1] -= bfhi(ud.x); sum[2] -= bflo(ud.y); sum[3] -= bfhi(ud.y); sum[4] -= bflo(ud.z); sum[5] -= bfhi(ud.z); sum[6] -= bflo(ud.w); sum[7] -= bfhi(ud.w); }
;         }
	v_lshlrev_b32_e32 v48, 16, v134
	v_and_b32_e32 v49, 0xffff0000, v134
	v_lshlrev_b32_e32 v50, 16, v135
	v_and_b32_e32 v51, 0xffff0000, v135
	v_pk_add_f32 v[14:15], v[14:15], v[44:45] neg_lo:[0,1] neg_hi:[0,1]
	v_pk_add_f32 v[16:17], v[16:17], v[46:47] neg_lo:[0,1] neg_hi:[0,1]
	v_pk_add_f32 v[18:19], v[18:19], v[48:49] neg_lo:[0,1] neg_hi:[0,1]
	v_pk_add_f32 v[12:13], v[12:13], v[50:51] neg_lo:[0,1] neg_hi:[0,1]
	v_lshl_add_u64 v[10:11], v[10:11], 0, s[26:27]
	v_lshlrev_b32_e32 v44, 16, v140
	v_and_b32_e32 v45, 0xffff0000, v140
	v_lshlrev_b32_e32 v46, 16, v141
	v_and_b32_e32 v47, 0xffff0000, v141
	v_lshlrev_b32_e32 v48, 16, v142
	v_and_b32_e32 v49, 0xffff0000, v142
	v_lshlrev_b32_e32 v50, 16, v143
	v_and_b32_e32 v51, 0xffff0000, v143
	v_pk_add_f32 v[14:15], v[14:15], v[44:45]
	v_pk_add_f32 v[16:17], v[16:17], v[46:47]
	v_pk_add_f32 v[18:19], v[18:19], v[48:49]
	v_pk_add_f32 v[12:13], v[12:13], v[50:51]
	v_pk_fma_f32 v[36:37], v[34:35], v[14:15], v[44:45] op_sel_hi:[0,1,1] neg_lo:[0,0,1] neg_hi:[0,0,1]
	v_pk_fma_f32 v[38:39], v[34:35], v[16:17], v[46:47] op_sel_hi:[0,1,1] neg_lo:[0,0,1] neg_hi:[0,0,1]
	v_pk_fma_f32 v[40:41], v[34:35], v[18:19], v[48:49] op_sel_hi:[0,1,1] neg_lo:[0,0,1] neg_hi:[0,0,1]
	v_pk_fma_f32 v[42:43], v[34:35], v[12:13], v[50:51] op_sel_hi:[0,1,1] neg_lo:[0,0,1] neg_hi:[0,0,1]
	v_cvt_pk_bf16_f32 v28, v36, v37
	v_cvt_pk_bf16_f32 v29, v38, v39
	v_cvt_pk_bf16_f32 v30, v40, v41
	v_cvt_pk_bf16_f32 v31, v42, v43
	global_store_dwordx4 v[10:11], v[28:31], off
	v_lshlrev_b32_e32 v44, 16, v136
	v_and_b32_e32 v45, 0xffff0000, v136
	v_lshlrev_b32_e32 v46, 16, v137
	v_and_b32_e32 v47, 0xffff0000, v137
	v_lshlrev_b32_e32 v48, 16, v138
	v_and_b32_e32 v49, 0xffff0000, v138
	v_lshlrev_b32_e32 v50, 16, v139
	v_and_b32_e32 v51, 0xffff0000, v139
	v_pk_add_f32 v[14:15], v[14:15], v[44:45] neg_lo:[0,1] neg_hi:[0,1]
	v_pk_add_f32 v[16:17], v[16:17], v[46:47] neg_lo:[0,1] neg_hi:[0,1]
	v_pk_add_f32 v[18:19], v[18:19], v[48:49] neg_lo:[0,1] neg_hi:[0,1]
	v_pk_add_f32 v[12:13], v[12:13], v[50:51] neg_lo:[0,1] neg_hi:[0,1]
	v_lshl_add_u64 v[10:11], v[10:11], 0, s[26:27]
	v_lshlrev_b32_e32 v44, 16, v144
	v_and_b32_e32 v45, 0xffff0000, v144
	v_lshlrev_b32_e32 v46, 16, v145
	v_and_b32_e32 v47, 0xffff0000, v145
	v_lshlrev_b32_e32 v48, 16, v146
	v_and_b32_e32 v49, 0xffff0000, v146
	v_lshlrev_b32_e32 v50, 16, v147
	v_and_b32_e32 v51, 0xffff0000, v147
	v_pk_add_f32 v[14:15], v[14:15], v[44:45]
	v_pk_add_f32 v[16:17], v[16:17], v[46:47]
	v_pk_add_f32 v[18:19], v[18:19], v[48:49]
	v_pk_add_f32 v[12:13], v[12:13], v[50:51]
	v_pk_fma_f32 v[36:37], v[34:35], v[14:15], v[44:45] op_sel_hi:[0,1,1] neg_lo:[0,0,1] neg_hi:[0,0,1]
	v_pk_fma_f32 v[38:39], v[34:35], v[16:17], v[46:47] op_sel_hi:[0,1,1] neg_lo:[0,0,1] neg_hi:[0,0,1]
	v_pk_fma_f32 v[40:41], v[34:35], v[18:19], v[48:49] op_sel_hi:[0,1,1] neg_lo:[0,0,1] neg_hi:[0,0,1]
	v_pk_fma_f32 v[42:43], v[34:35], v[12:13], v[50:51] op_sel_hi:[0,1,1] neg_lo:[0,0,1] neg_hi:[0,0,1]
	v_cvt_pk_bf16_f32 v28, v36, v37
	v_cvt_pk_bf16_f32 v29, v38, v39
	v_cvt_pk_bf16_f32 v30, v40, v41
	v_cvt_pk_bf16_f32 v31, v42, v43
	global_store_dwordx4 v[10:11], v[28:31], off
	v_lshlrev_b32_e32 v44, 16, v140
	v_and_b32_e32 v45, 0xffff0000, v140
	v_lshlrev_b32_e32 v46, 16, v141
	v_and_b32_e32 v47, 0xffff0000, v141
	v_lshlrev_b32_e32 v48, 16, v142
	v_and_b32_e32 v49, 0xffff0000, v142
	v_lshlrev_b32_e32 v50, 16, v143
	v_and_b32_e32 v51, 0xffff0000, v143
	v_pk_add_f32 v[14:15], v[14:15], v[44:45] neg_lo:[0,1] neg_hi:[0,1]
	v_pk_add_f32 v[16:17], v[16:17], v[46:47] neg_lo:[0,1] neg_hi:[0,1]
	v_pk_add_f32 v[18:19], v[18:19], v[48:49] neg_lo:[0,1] neg_hi:[0,1]
	v_pk_add_f32 v[12:13], v[12:13], v[50:51] neg_lo:[0,1] neg_hi:[0,1]
	v_lshl_add_u64 v[10:11], v[10:11], 0, s[26:27]
	v_lshlrev_b32_e32 v44, 16, v148
	v_and_b32_e32 v45, 0xffff0000, v148
	v_lshlrev_b32_e32 v46, 16, v149
	v_and_b32_e32 v47, 0xffff0000, v149
	v_lshlrev_b32_e32 v48, 16, v150
	v_and_b32_e32 v49, 0xffff0000, v150
	v_lshlrev_b32_e32 v50, 16, v151
	v_and_b32_e32 v51, 0xffff0000, v151
	v_pk_add_f32 v[14:15], v[14:15], v[44:45]
	v_pk_add_f32 v[16:17], v[16:17], v[46:47]
	v_pk_add_f32 v[18:19], v[18:19], v[48:49]
	v_pk_add_f32 v[12:13], v[12:13], v[50:51]
	v_pk_fma_f32 v[36:37], v[34:35], v[14:15], v[44:45] op_sel_hi:[0,1,1] neg_lo:[0,0,1] neg_hi:[0,0,1]
	v_pk_fma_f32 v[38:39], v[34:35], v[16:17], v[46:47] op_sel_hi:[0,1,1] neg_lo:[0,0,1] neg_hi:[0,0,1]
	v_pk_fma_f32 v[40:41], v[34:35], v[18:19], v[48:49] op_sel_hi:[0,1,1] neg_lo:[0,0,1] neg_hi:[0,0,1]
	v_pk_fma_f32 v[42:43], v[34:35], v[12:13], v[50:51] op_sel_hi:[0,1,1] neg_lo:[0,0,1] neg_hi:[0,0,1]
	v_cvt_pk_bf16_f32 v28, v36, v37
	v_cvt_pk_bf16_f32 v29, v38, v39
	v_cvt_pk_bf16_f32 v30, v40, v41
	v_cvt_pk_bf16_f32 v31, v42, v43
	global_store_dwordx4 v[10:11], v[28:31], off
	v_lshlrev_b32_e32 v44, 16, v144
	v_and_b32_e32 v45, 0xffff0000, v144
	v_lshlrev_b32_e32 v46, 16, v145
	v_and_b32_e32 v47, 0xffff0000, v145
	v_lshlrev_b32_e32 v48, 16, v146
	v_and_b32_e32 v49, 0xffff0000, v146
	v_lshlrev_b32_e32 v50, 16, v147
	v_and_b32_e32 v51, 0xffff0000, v147
	v_pk_add_f32 v[14:15], v[14:15], v[44:45] neg_lo:[0,1] neg_hi:[0,1]
	v_pk_add_f32 v[16:17], v[16:17], v[46:47] neg_lo:[0,1] neg_hi:[0,1]
	v_pk_add_f32 v[18:19], v[18:19], v[48:49] neg_lo:[0,1] neg_hi:[0,1]
	v_pk_add_f32 v[12:13], v[12:13], v[50:51] neg_lo:[0,1] neg_hi:[0,1]
	v_lshl_add_u64 v[10:11], v[10:11], 0, s[26:27]
	v_lshlrev_b32_e32 v44, 16, v152
	v_and_b32_e32 v45, 0xffff0000, v152
	v_lshlrev_b32_e32 v46, 16, v153
	v_and_b32_e32 v47, 0xffff0000, v153
	v_lshlrev_b32_e32 v48, 16, v154
	v_and_b32_e32 v49, 0xffff0000, v154
	v_lshlrev_b32_e32 v50, 16, v155
	v_and_b32_e32 v51, 0xffff0000, v155
; __device__ __forceinline__ unsigned pk2(float lo, float hi) { f32x2 v = {lo, hi}; bf16x2_t b = __builtin_convertvector(v, bf16x2_t); return __builtin_bit_cast(unsigned, b); }
; __device__ __forceinline__ void pool_window(const bf16_t* __restrict__ U  , bf16_t* __restrict__ A3, const int gtid, const int nthr) {
;     ...
;         for (int i = 0; i < 32; ++i) {
;             const int t = t0 + i, s = s0 + i;
;             const u32x4 uu = *(const u32x4*)(U + (size_t)t * LDU + c);
;             float cu[8] = {bflo(uu.x), bfhi(uu.x), bflo(uu.y), bfhi(uu.y), bflo(uu.z), bfhi(uu.z), bflo(uu.w), bfhi(uu.w)};
;             const float rc = 1.0f / (float)((s + 1) < w ? (s + 1) : w);
;             float o[8];
; #pragma unroll
;             for (int e = 0; e < 8; ++e) { sum[e] += cu[e]; o[e] = sum[e] * rc - cu[e]; }
;             u32x4 ww; ww.x = pk2(o[0], o[1]); ww.y = pk2(o[2], o[3]); ww.z = pk2(o[4], o[5]); ww.w = pk2(o[6], o[7]);
;             *(u32x4*)(A3 + (size_t)t * DM + c) = ww;
;             if (s + 1 >= w) { const u32x4 ud = *(const u32x4*)(U + (size_t)(t - w + 1) * LDU + c);
;                 sum[0] -= bflo(ud.x); sum[1] -= bfhi(ud.x); sum[2] -= bflo(ud.y); sum[3] -= bfhi(ud.y); sum[4] -= bflo(ud.z); sum[5] -= bfhi(ud.z); sum[6] -= bflo(ud.w); sum[7] -= bfhi(ud.w); }
;         }
	v_pk_add_f32 v[14:15], v[14:15], v[44:45]
	v_pk_add_f32 v[16:17], v[16:17], v[46:47]
	v_pk_add_f32 v[18:19], v[18:19], v[48:49]
	v_pk_add_f32 v[12:13], v[12:13], v[50:51]
	v_pk_fma_f32 v[36:37], v[34:35], v[14:15], v[44:45] op_sel_hi:[0,1,1] neg_lo:[0,0,1] neg_hi:[0,0,1]
	v_pk_fma_f32 v[38:39], v[34:35], v[16:17], v[46:47] op_sel_hi:[0,1,1] neg_lo:[0,0,1] neg_hi:[0,0,1]
	v_pk_fma_f32 v[40:41], v[34:35], v[18:19], v[48:49] op_sel_hi:[0,1,1] neg_lo:[0,0,1] neg_hi:[0,0,1]
	v_pk_fma_f32 v[42:43], v[34:35], v[12:13], v[50:51] op_sel_hi:[0,1,1] neg_lo:[0,0,1] neg_hi:[0,0,1]
	v_cvt_pk_bf16_f32 v28, v36, v37
	v_cvt_pk_bf16_f32 v29, v38, v39
	v_cvt_pk_bf16_f32 v30, v40, v41
	v_cvt_pk_bf16_f32 v31, v42, v43
	global_store_dwordx4 v[10:11], v[28:31], off
	v_lshlrev_b32_e32 v44, 16, v148
	v_and_b32_e32 v45, 0xffff0000, v148
	v_lshlrev_b32_e32 v46, 16, v149
	v_and_b32_e32 v47, 0xffff0000, v149
	v_lshlrev_b32_e32 v48, 16, v150
	v_and_b32_e32 v49, 0xffff0000, v150
	v_lshlrev_b32_e32 v50, 16, v151
	v_and_b32_e32 v51, 0xffff0000, v151
	v_pk_add_f32 v[14:15], v[14:15], v[44:45] neg_lo:[0,1] neg_hi:[0,1]
	v_pk_add_f32 v[16:17], v[16:17], v[46:47] neg_lo:[0,1] neg_hi:[0,1]
	v_pk_add_f32 v[18:19], v[18:19], v[48:49] neg_lo:[0,1] neg_hi:[0,1]
	v_pk_add_f32 v[12:13], v[12:13], v[50:51] neg_lo:[0,1] neg_hi:[0,1]
	v_lshl_add_u64 v[10:11], v[10:11], 0, s[26:27]
	v_lshlrev_b32_e32 v44, 16, v156
	v_and_b32_e32 v45, 0xffff0000, v156
	v_lshlrev_b32_e32 v46, 16, v157
	v_and_b32_e32 v47, 0xffff0000, v157
	v_lshlrev_b32_e32 v48, 16, v158
	v_and_b32_e32 v49, 0xffff0000, v158
	v_lshlrev_b32_e32 v50, 16, v159
	v_and_b32_e32 v51, 0xffff0000, v159
	v_pk_add_f32 v[14:15], v[14:15], v[44:45]
	v_pk_add_f32 v[16:17], v[16:17], v[46:47]
	v_pk_add_f32 v[18:19], v[18:19], v[48:49]
	v_pk_add_f32 v[12:13], v[12:13], v[50:51]
	v_pk_fma_f32 v[36:37], v[34:35], v[14:15], v[44:45] op_sel_hi:[0,1,1] neg_lo:[0,0,1] neg_hi:[0,0,1]
	v_pk_fma_f32 v[38:39], v[34:35], v[16:17], v[46:47] op_sel_hi:[0,1,1] neg_lo:[0,0,1] neg_hi:[0,0,1]
	v_pk_fma_f32 v[40:41], v[34:35], v[18:19], v[48:49] op_sel_hi:[0,1,1] neg_lo:[0,0,1] neg_hi:[0,0,1]
	v_pk_fma_f32 v[42:43], v[34:35], v[12:13], v[50:51] op_sel_hi:[0,1,1] neg_lo:[0,0,1] neg_hi:[0,0,1]
	v_cvt_pk_bf16_f32 v28, v36, v37
	v_cvt_pk_bf16_f32 v29, v38, v39
	v_cvt_pk_bf16_f32 v30, v40, v41
	v_cvt_pk_bf16_f32 v31, v42, v43
	global_store_dwordx4 v[10:11], v[28:31], off
	v_lshlrev_b32_e32 v44, 16, v152
	v_and_b32_e32 v45, 0xffff0000, v152
	v_lshlrev_b32_e32 v46, 16, v153
	v_and_b32_e32 v47, 0xffff0000, v153
	v_lshlrev_b32_e32 v48, 16, v154
	v_and_b32_e32 v49, 0xffff0000, v154
	v_lshlrev_b32_e32 v50, 16, v155
	v_and_b32_e32 v51, 0xffff0000, v155
	v_pk_add_f32 v[14:15], v[14:15], v[44:45] neg_lo:[0,1] neg_hi:[0,1]
	v_pk_add_f32 v[16:17], v[16:17], v[46:47] neg_lo:[0,1] neg_hi:[0,1]
	v_pk_add_f32 v[18:19], v[18:19], v[48:49] neg_lo:[0,1] neg_hi:[0,1]
	v_pk_add_f32 v[12:13], v[12:13], v[50:51] neg_lo:[0,1] neg_hi:[0,1]
	v_lshl_add_u64 v[10:11], v[10:11], 0, s[26:27]
	v_lshlrev_b32_e32 v44, 16, v160
	v_and_b32_e32 v45, 0xffff0000, v160
	v_lshlrev_b32_e32 v46, 16, v161
	v_and_b32_e32 v47, 0xffff0000, v161
	v_lshlrev_b32_e32 v48, 16, v162
	v_and_b32_e32 v49, 0xffff0000, v162
	v_lshlrev_b32_e32 v50, 16, v163
	v_and_b32_e32 v51, 0xffff0000, v163
	v_pk_add_f32 v[14:15], v[14:15], v[44:45]
	v_pk_add_f32 v[16:17], v[16:17], v[46:47]
	v_pk_add_f32 v[18:19], v[18:19], v[48:49]
	v_pk_add_f32 v[12:13], v[12:13], v[50:51]
	v_pk_fma_f32 v[36:37], v[34:35], v[14:15], v[44:45] op_sel_hi:[0,1,1] neg_lo:[0,0,1] neg_hi:[0,0,1]
	v_pk_fma_f32 v[38:39], v[34:35], v[16:17], v[46:47] op_sel_hi:[0,1,1] neg_lo:[0,0,1] neg_hi:[0,0,1]
	v_pk_fma_f32 v[40:41], v[34:35], v[18:19], v[48:49] op_sel_hi:[0,1,1] neg_lo:[0,0,1] neg_hi:[0,0,1]
	v_pk_fma_f32 v[42:43], v[34:35], v[12:13], v[50:51] op_sel_hi:[0,1,1] neg_lo:[0,0,1] neg_hi:[0,0,1]
	v_cvt_pk_bf16_f32 v28, v36, v37
	v_cvt_pk_bf16_f32 v29, v38, v39
	v_cvt_pk_bf16_f32 v30, v40, v41
	v_cvt_pk_bf16_f32 v31, v42, v43
	global_store_dwordx4 v[10:11], v[28:31], off
	v_lshlrev_b32_e32 v44, 16, v156
	v_and_b32_e32 v45, 0xffff0000, v156
	v_lshlrev_b32_e32 v46, 16, v157
	v_and_b32_e32 v47, 0xffff0000, v157
	v_lshlrev_b32_e32 v48, 16, v158
	v_and_b32_e32 v49, 0xffff0000, v158
	v_lshlrev_b32_e32 v50, 16, v159
	v_and_b32_e32 v51, 0xffff0000, v159
	v_pk_add_f32 v[14:15], v[14:15], v[44:45] neg_lo:[0,1] neg_hi:[0,1]
	v_pk_add_f32 v[16:17], v[16:17], v[46:47] neg_lo:[0,1] neg_hi:[0,1]
	v_pk_add_f32 v[18:19], v[18:19], v[48:49] neg_lo:[0,1] neg_hi:[0,1]
	v_pk_add_f32 v[12:13], v[12:13], v[50:51] neg_lo:[0,1] neg_hi:[0,1]
	v_lshl_add_u64 v[10:11], v[10:11], 0, s[26:27]
	v_lshlrev_b32_e32 v44, 16, v164
	v_and_b32_e32 v45, 0xffff0000, v164
	v_lshlrev_b32_e32 v46, 16, v165
	v_and_b32_e32 v47, 0xffff0000, v165
	v_lshlrev_b32_e32 v48, 16, v166
	v_and_b32_e32 v49, 0xffff0000, v166
	v_lshlrev_b32_e32 v50, 16, v167
	v_and_b32_e32 v51, 0xffff0000, v167
	v_pk_add_f32 v[14:15], v[14:15], v[44:45]
	v_pk_add_f32 v[16:17], v[16:17], v[46:47]
	v_pk_add_f32 v[18:19], v[18:19], v[48:49]
	v_pk_add_f32 v[12:13], v[12:13], v[50:51]
	v_pk_fma_f32 v[36:37], v[34:35], v[14:15], v[44:45] op_sel_hi:[0,1,1] neg_lo:[0,0,1] neg_hi:[0,0,1]
	v_pk_fma_f32 v[38:39], v[34:35], v[16:17], v[46:47] op_sel_hi:[0,1,1] neg_lo:[0,0,1] neg_hi:[0,0,1]
	v_pk_fma_f32 v[40:41], v[34:35], v[18:19], v[48:49] op_sel_hi:[0,1,1] neg_lo:[0,0,1] neg_hi:[0,0,1]
	v_pk_fma_f32 v[42:43], v[34:35], v[12:13], v[50:51] op_sel_hi:[0,1,1] neg_lo:[0,0,1] neg_hi:[0,0,1]
	v_cvt_pk_bf16_f32 v28, v36, v37
	v_cvt_pk_bf16_f32 v29, v38, v39
	v_cvt_pk_bf16_f32 v30, v40, v41
	v_cvt_pk_bf16_f32 v31, v42, v43
; __device__ __forceinline__ unsigned pk2(float lo, float hi) { f32x2 v = {lo, hi}; bf16x2_t b = __builtin_convertvector(v, bf16x2_t); return __builtin_bit_cast(unsigned, b); }
; __device__ __forceinline__ void pool_window(const bf16_t* __restrict__ U  , bf16_t* __restrict__ A3, const int gtid, const int nthr) {
;     ...
;         for (int i = 0; i < 32; ++i) {
;             const int t = t0 + i, s = s0 + i;
;             const u32x4 uu = *(const u32x4*)(U + (size_t)t * LDU + c);
;             float cu[8] = {bflo(uu.x), bfhi(uu.x), bflo(uu.y), bfhi(uu.y), bflo(uu.z), bfhi(uu.z), bflo(uu.w), bfhi(uu.w)};
;             const float rc = 1.0f / (float)((s + 1) < w ? (s + 1) : w);
;             float o[8];
; #pragma unroll
;             for (int e = 0; e < 8; ++e) { sum[e] += cu[e]; o[e] = sum[e] * rc - cu[e]; }
;             u32x4 ww; ww.x = pk2(o[0], o[1]); ww.y = pk2(o[2], o[3]); ww.z = pk2(o[4], o[5]); ww.w = pk2(o[6], o[7]);
;             *(u32x4*)(A3 + (size_t)t * DM + c) = ww;
;             if (s + 1 >= w) { const u32x4 ud = *(const u32x4*)(U + (size_t)(t - w + 1) * LDU + c);
;                 sum[0] -= bflo(ud.x); sum[1] -= bfhi(ud.x); sum[2] -= bflo(ud.y); sum[3] -= bfhi(ud.y); sum[4] -= bflo(ud.z); sum[5] -= bfhi(ud.z); sum[6] -= bflo(ud.w); sum[7] -= bfhi(ud.w); }
;         }
	global_store_dwordx4 v[10:11], v[28:31], off
	v_lshlrev_b32_e32 v44, 16, v160
	v_and_b32_e32 v45, 0xffff0000, v160
	v_lshlrev_b32_e32 v46, 16, v161
	v_and_b32_e32 v47, 0xffff0000, v161
	v_lshlrev_b32_e32 v48, 16, v162
	v_and_b32_e32 v49, 0xffff0000, v162
	v_lshlrev_b32_e32 v50, 16, v163
	v_and_b32_e32 v51, 0xffff0000, v163
	v_pk_add_f32 v[14:15], v[14:15], v[44:45] neg_lo:[0,1] neg_hi:[0,1]
	v_pk_add_f32 v[16:17], v[16:17], v[46:47] neg_lo:[0,1] neg_hi:[0,1]
	v_pk_add_f32 v[18:19], v[18:19], v[48:49] neg_lo:[0,1] neg_hi:[0,1]
	v_pk_add_f32 v[12:13], v[12:13], v[50:51] neg_lo:[0,1] neg_hi:[0,1]
	v_lshl_add_u64 v[10:11], v[10:11], 0, s[26:27]
	v_lshlrev_b32_e32 v44, 16, v168
	v_and_b32_e32 v45, 0xffff0000, v168
	v_lshlrev_b32_e32 v46, 16, v169
	v_and_b32_e32 v47, 0xffff0000, v169
	v_lshlrev_b32_e32 v48, 16, v170
	v_and_b32_e32 v49, 0xffff0000, v170
	v_lshlrev_b32_e32 v50, 16, v171
	v_and_b32_e32 v51, 0xffff0000, v171
	v_pk_add_f32 v[14:15], v[14:15], v[44:45]
	v_pk_add_f32 v[16:17], v[16:17], v[46:47]
	v_pk_add_f32 v[18:19], v[18:19], v[48:49]
	v_pk_add_f32 v[12:13], v[12:13], v[50:51]
	v_pk_fma_f32 v[36:37], v[34:35], v[14:15], v[44:45] op_sel_hi:[0,1,1] neg_lo:[0,0,1] neg_hi:[0,0,1]
	v_pk_fma_f32 v[38:39], v[34:35], v[16:17], v[46:47] op_sel_hi:[0,1,1] neg_lo:[0,0,1] neg_hi:[0,0,1]
	v_pk_fma_f32 v[40:41], v[34:35], v[18:19], v[48:49] op_sel_hi:[0,1,1] neg_lo:[0,0,1] neg_hi:[0,0,1]
	v_pk_fma_f32 v[42:43], v[34:35], v[12:13], v[50:51] op_sel_hi:[0,1,1] neg_lo:[0,0,1] neg_hi:[0,0,1]
	v_cvt_pk_bf16_f32 v28, v36, v37
	v_cvt_pk_bf16_f32 v29, v38, v39
	v_cvt_pk_bf16_f32 v30, v40, v41
	v_cvt_pk_bf16_f32 v31, v42, v43
	global_store_dwordx4 v[10:11], v[28:31], off
	v_lshlrev_b32_e32 v44, 16, v164
	v_and_b32_e32 v45, 0xffff0000, v164
	v_lshlrev_b32_e32 v46, 16, v165
	v_and_b32_e32 v47, 0xffff0000, v165
	v_lshlrev_b32_e32 v48, 16, v166
	v_and_b32_e32 v49, 0xffff0000, v166
	v_lshlrev_b32_e32 v50, 16, v167
	v_and_b32_e32 v51, 0xffff0000, v167
	v_pk_add_f32 v[14:15], v[14:15], v[44:45] neg_lo:[0,1] neg_hi:[0,1]
	v_pk_add_f32 v[16:17], v[16:17], v[46:47] neg_lo:[0,1] neg_hi:[0,1]
	v_pk_add_f32 v[18:19], v[18:19], v[48:49] neg_lo:[0,1] neg_hi:[0,1]
	v_pk_add_f32 v[12:13], v[12:13], v[50:51] neg_lo:[0,1] neg_hi:[0,1]
	v_lshl_add_u64 v[10:11], v[10:11], 0, s[26:27]
	v_lshlrev_b32_e32 v44, 16, v172
	v_and_b32_e32 v45, 0xffff0000, v172
	v_lshlrev_b32_e32 v46, 16, v173
	v_and_b32_e32 v47, 0xffff0000, v173
	v_lshlrev_b32_e32 v48, 16, v174
	v_and_b32_e32 v49, 0xffff0000, v174
	v_lshlrev_b32_e32 v50, 16, v175
	v_and_b32_e32 v51, 0xffff0000, v175
	v_pk_add_f32 v[14:15], v[14:15], v[44:45]
	v_pk_add_f32 v[16:17], v[16:17], v[46:47]
	v_pk_add_f32 v[18:19], v[18:19], v[48:49]
	v_pk_add_f32 v[12:13], v[12:13], v[50:51]
	v_pk_fma_f32 v[36:37], v[34:35], v[14:15], v[44:45] op_sel_hi:[0,1,1] neg_lo:[0,0,1] neg_hi:[0,0,1]
	v_pk_fma_f32 v[38:39], v[34:35], v[16:17], v[46:47] op_sel_hi:[0,1,1] neg_lo:[0,0,1] neg_hi:[0,0,1]
	v_pk_fma_f32 v[40:41], v[34:35], v[18:19], v[48:49] op_sel_hi:[0,1,1] neg_lo:[0,0,1] neg_hi:[0,0,1]
	v_pk_fma_f32 v[42:43], v[34:35], v[12:13], v[50:51] op_sel_hi:[0,1,1] neg_lo:[0,0,1] neg_hi:[0,0,1]
	v_cvt_pk_bf16_f32 v28, v36, v37
	v_cvt_pk_bf16_f32 v29, v38, v39
	v_cvt_pk_bf16_f32 v30, v40, v41
	v_cvt_pk_bf16_f32 v31, v42, v43
	global_store_dwordx4 v[10:11], v[28:31], off
	v_lshlrev_b32_e32 v44, 16, v168
	v_and_b32_e32 v45, 0xffff0000, v168
	v_lshlrev_b32_e32 v46, 16, v169
	v_and_b32_e32 v47, 0xffff0000, v169
	v_lshlrev_b32_e32 v48, 16, v170
	v_and_b32_e32 v49, 0xffff0000, v170
	v_lshlrev_b32_e32 v50, 16, v171
	v_and_b32_e32 v51, 0xffff0000, v171
	v_pk_add_f32 v[14:15], v[14:15], v[44:45] neg_lo:[0,1] neg_hi:[0,1]
	v_pk_add_f32 v[16:17], v[16:17], v[46:47] neg_lo:[0,1] neg_hi:[0,1]
	v_pk_add_f32 v[18:19], v[18:19], v[48:49] neg_lo:[0,1] neg_hi:[0,1]
	v_pk_add_f32 v[12:13], v[12:13], v[50:51] neg_lo:[0,1] neg_hi:[0,1]
	v_lshl_add_u64 v[10:11], v[10:11], 0, s[26:27]
	v_lshlrev_b32_e32 v44, 16, v176
	v_and_b32_e32 v45, 0xffff0000, v176
	v_lshlrev_b32_e32 v46, 16, v177
	v_and_b32_e32 v47, 0xffff0000, v177
	v_lshlrev_b32_e32 v48, 16, v178
	v_and_b32_e32 v49, 0xffff0000, v178
	v_lshlrev_b32_e32 v50, 16, v179
	v_and_b32_e32 v51, 0xffff0000, v179
	v_pk_add_f32 v[14:15], v[14:15], v[44:45]
	v_pk_add_f32 v[16:17], v[16:17], v[46:47]
	v_pk_add_f32 v[18:19], v[18:19], v[48:49]
	v_pk_add_f32 v[12:13], v[12:13], v[50:51]
	v_pk_fma_f32 v[36:37], v[34:35], v[14:15], v[44:45] op_sel_hi:[0,1,1] neg_lo:[0,0,1] neg_hi:[0,0,1]
	v_pk_fma_f32 v[38:39], v[34:35], v[16:17], v[46:47] op_sel_hi:[0,1,1] neg_lo:[0,0,1] neg_hi:[0,0,1]
	v_pk_fma_f32 v[40:41], v[34:35], v[18:19], v[48:49] op_sel_hi:[0,1,1] neg_lo:[0,0,1] neg_hi:[0,0,1]
	v_pk_fma_f32 v[42:43], v[34:35], v[12:13], v[50:51] op_sel_hi:[0,1,1] neg_lo:[0,0,1] neg_hi:[0,0,1]
	v_cvt_pk_bf16_f32 v28, v36, v37
	v_cvt_pk_bf16_f32 v29, v38, v39
	v_cvt_pk_bf16_f32 v30, v40, v41
	v_cvt_pk_bf16_f32 v31, v42, v43
	global_store_dwordx4 v[10:11], v[28:31], off
	v_lshlrev_b32_e32 v44, 16, v172
	v_and_b32_e32 v45, 0xffff0000, v172
	v_lshlrev_b32_e32 v46, 16, v173
	v_and_b32_e32 v47, 0xffff0000, v173
	v_lshlrev_b32_e32 v48, 16, v174
	v_and_b32_e32 v49, 0xffff0000, v174
	v_lshlrev_b32_e32 v50, 16, v175
	v_and_b32_e32 v51, 0xffff0000, v175
	v_pk_add_f32 v[14:15], v[14:15], v[44:45] neg_lo:[0,1] neg_hi:[0,1]
	v_pk_add_f32 v[16:17], v[16:17], v[46:47] neg_lo:[0,1] neg_hi:[0,1]
	v_pk_add_f32 v[18:19], v[18:19], v[48:49] neg_lo:[0,1] neg_hi:[0,1]
	v_pk_add_f32 v[12:13], v[12:13], v[50:51] neg_lo:[0,1] neg_hi:[0,1]
	v_lshl_add_u64 v[10:11], v[10:11], 0, s[26:27]
	v_lshlrev_b32_e32 v44, 16, v180
	v_and_b32_e32 v45, 0xffff0000, v180
; __device__ __forceinline__ unsigned pk2(float lo, float hi) { f32x2 v = {lo, hi}; bf16x2_t b = __builtin_convertvector(v, bf16x2_t); return __builtin_bit_cast(unsigned, b); }
; __device__ __forceinline__ void pool_window(const bf16_t* __restrict__ U  , bf16_t* __restrict__ A3, const int gtid, const int nthr) {
;     ...
;         for (int i = 0; i < 32; ++i) {
;             const int t = t0 + i, s = s0 + i;
;             const u32x4 uu = *(const u32x4*)(U + (size_t)t * LDU + c);
;             float cu[8] = {bflo(uu.x), bfhi(uu.x), bflo(uu.y), bfhi(uu.y), bflo(uu.z), bfhi(uu.z), bflo(uu.w), bfhi(uu.w)};
;             const float rc = 1.0f / (float)((s + 1) < w ? (s + 1) : w);
;             float o[8];
; #pragma unroll
;             for (int e = 0; e < 8; ++e) { sum[e] += cu[e]; o[e] = sum[e] * rc - cu[e]; }
;             u32x4 ww; ww.x = pk2(o[0], o[1]); ww.y = pk2(o[2], o[3]); ww.z = pk2(o[4], o[5]); ww.w = pk2(o[6], o[7]);
;             *(u32x4*)(A3 + (size_t)t * DM + c) = ww;
;             if (s + 1 >= w) { const u32x4 ud = *(const u32x4*)(U + (size_t)(t - w + 1) * LDU + c);
;                 sum[0] -= bflo(ud.x); sum[1] -= bfhi(ud.x); sum[2] -= bflo(ud.y); sum[3] -= bfhi(ud.y); sum[4] -= bflo(ud.z); sum[5] -= bfhi(ud.z); sum[6] -= bflo(ud.w); sum[7] -= bfhi(ud.w); }
;         }
	v_lshlrev_b32_e32 v46, 16, v181
	v_and_b32_e32 v47, 0xffff0000, v181
	v_lshlrev_b32_e32 v48, 16, v182
	v_and_b32_e32 v49, 0xffff0000, v182
	v_lshlrev_b32_e32 v50, 16, v183
	v_and_b32_e32 v51, 0xffff0000, v183
	v_pk_add_f32 v[14:15], v[14:15], v[44:45]
	v_pk_add_f32 v[16:17], v[16:17], v[46:47]
	v_pk_add_f32 v[18:19], v[18:19], v[48:49]
	v_pk_add_f32 v[12:13], v[12:13], v[50:51]
	v_pk_fma_f32 v[36:37], v[34:35], v[14:15], v[44:45] op_sel_hi:[0,1,1] neg_lo:[0,0,1] neg_hi:[0,0,1]
	v_pk_fma_f32 v[38:39], v[34:35], v[16:17], v[46:47] op_sel_hi:[0,1,1] neg_lo:[0,0,1] neg_hi:[0,0,1]
	v_pk_fma_f32 v[40:41], v[34:35], v[18:19], v[48:49] op_sel_hi:[0,1,1] neg_lo:[0,0,1] neg_hi:[0,0,1]
	v_pk_fma_f32 v[42:43], v[34:35], v[12:13], v[50:51] op_sel_hi:[0,1,1] neg_lo:[0,0,1] neg_hi:[0,0,1]
	v_cvt_pk_bf16_f32 v28, v36, v37
	v_cvt_pk_bf16_f32 v29, v38, v39
	v_cvt_pk_bf16_f32 v30, v40, v41
	v_cvt_pk_bf16_f32 v31, v42, v43
	global_store_dwordx4 v[10:11], v[28:31], off
	v_lshlrev_b32_e32 v44, 16, v176
	v_and_b32_e32 v45, 0xffff0000, v176
	v_lshlrev_b32_e32 v46, 16, v177
	v_and_b32_e32 v47, 0xffff0000, v177
	v_lshlrev_b32_e32 v48, 16, v178
	v_and_b32_e32 v49, 0xffff0000, v178
	v_lshlrev_b32_e32 v50, 16, v179
	v_and_b32_e32 v51, 0xffff0000, v179
	v_pk_add_f32 v[14:15], v[14:15], v[44:45] neg_lo:[0,1] neg_hi:[0,1]
	v_pk_add_f32 v[16:17], v[16:17], v[46:47] neg_lo:[0,1] neg_hi:[0,1]
	v_pk_add_f32 v[18:19], v[18:19], v[48:49] neg_lo:[0,1] neg_hi:[0,1]
	v_pk_add_f32 v[12:13], v[12:13], v[50:51] neg_lo:[0,1] neg_hi:[0,1]
	v_lshl_add_u64 v[10:11], v[10:11], 0, s[26:27]
	v_lshlrev_b32_e32 v44, 16, v184
	v_and_b32_e32 v45, 0xffff0000, v184
	v_lshlrev_b32_e32 v46, 16, v185
	v_and_b32_e32 v47, 0xffff0000, v185
	v_lshlrev_b32_e32 v48, 16, v186
	v_and_b32_e32 v49, 0xffff0000, v186
	v_lshlrev_b32_e32 v50, 16, v187
	v_and_b32_e32 v51, 0xffff0000, v187
	v_pk_add_f32 v[14:15], v[14:15], v[44:45]
	v_pk_add_f32 v[16:17], v[16:17], v[46:47]
	v_pk_add_f32 v[18:19], v[18:19], v[48:49]
	v_pk_add_f32 v[12:13], v[12:13], v[50:51]
	v_pk_fma_f32 v[36:37], v[34:35], v[14:15], v[44:45] op_sel_hi:[0,1,1] neg_lo:[0,0,1] neg_hi:[0,0,1]
	v_pk_fma_f32 v[38:39], v[34:35], v[16:17], v[46:47] op_sel_hi:[0,1,1] neg_lo:[0,0,1] neg_hi:[0,0,1]
	v_pk_fma_f32 v[40:41], v[34:35], v[18:19], v[48:49] op_sel_hi:[0,1,1] neg_lo:[0,0,1] neg_hi:[0,0,1]
	v_pk_fma_f32 v[42:43], v[34:35], v[12:13], v[50:51] op_sel_hi:[0,1,1] neg_lo:[0,0,1] neg_hi:[0,0,1]
	v_cvt_pk_bf16_f32 v28, v36, v37
	v_cvt_pk_bf16_f32 v29, v38, v39
	v_cvt_pk_bf16_f32 v30, v40, v41
	v_cvt_pk_bf16_f32 v31, v42, v43
	global_store_dwordx4 v[10:11], v[28:31], off
	v_lshlrev_b32_e32 v44, 16, v180
	v_and_b32_e32 v45, 0xffff0000, v180
	v_lshlrev_b32_e32 v46, 16, v181
	v_and_b32_e32 v47, 0xffff0000, v181
	v_lshlrev_b32_e32 v48, 16, v182
	v_and_b32_e32 v49, 0xffff0000, v182
	v_lshlrev_b32_e32 v50, 16, v183
	v_and_b32_e32 v51, 0xffff0000, v183
	v_pk_add_f32 v[14:15], v[14:15], v[44:45] neg_lo:[0,1] neg_hi:[0,1]
	v_pk_add_f32 v[16:17], v[16:17], v[46:47] neg_lo:[0,1] neg_hi:[0,1]
	v_pk_add_f32 v[18:19], v[18:19], v[48:49] neg_lo:[0,1] neg_hi:[0,1]
	v_pk_add_f32 v[12:13], v[12:13], v[50:51] neg_lo:[0,1] neg_hi:[0,1]
	v_lshl_add_u64 v[10:11], v[10:11], 0, s[26:27]
	v_lshlrev_b32_e32 v44, 16, v188
	v_and_b32_e32 v45, 0xffff0000, v188
	v_lshlrev_b32_e32 v46, 16, v189
	v_and_b32_e32 v47, 0xffff0000, v189
	v_lshlrev_b32_e32 v48, 16, v190
	v_and_b32_e32 v49, 0xffff0000, v190
	v_lshlrev_b32_e32 v50, 16, v191
	v_and_b32_e32 v51, 0xffff0000, v191
	v_pk_add_f32 v[14:15], v[14:15], v[44:45]
	v_pk_add_f32 v[16:17], v[16:17], v[46:47]
	v_pk_add_f32 v[18:19], v[18:19], v[48:49]
	v_pk_add_f32 v[12:13], v[12:13], v[50:51]
	v_pk_fma_f32 v[36:37], v[34:35], v[14:15], v[44:45] op_sel_hi:[0,1,1] neg_lo:[0,0,1] neg_hi:[0,0,1]
	v_pk_fma_f32 v[38:39], v[34:35], v[16:17], v[46:47] op_sel_hi:[0,1,1] neg_lo:[0,0,1] neg_hi:[0,0,1]
	v_pk_fma_f32 v[40:41], v[34:35], v[18:19], v[48:49] op_sel_hi:[0,1,1] neg_lo:[0,0,1] neg_hi:[0,0,1]
	v_pk_fma_f32 v[42:43], v[34:35], v[12:13], v[50:51] op_sel_hi:[0,1,1] neg_lo:[0,0,1] neg_hi:[0,0,1]
	v_cvt_pk_bf16_f32 v28, v36, v37
	v_cvt_pk_bf16_f32 v29, v38, v39
	v_cvt_pk_bf16_f32 v30, v40, v41
	v_cvt_pk_bf16_f32 v31, v42, v43
	global_store_dwordx4 v[10:11], v[28:31], off
	v_lshlrev_b32_e32 v44, 16, v184
	v_and_b32_e32 v45, 0xffff0000, v184
	v_lshlrev_b32_e32 v46, 16, v185
	v_and_b32_e32 v47, 0xffff0000, v185
	v_lshlrev_b32_e32 v48, 16, v186
	v_and_b32_e32 v49, 0xffff0000, v186
	v_lshlrev_b32_e32 v50, 16, v187
	v_and_b32_e32 v51, 0xffff0000, v187
	v_pk_add_f32 v[14:15], v[14:15], v[44:45] neg_lo:[0,1] neg_hi:[0,1]
	v_pk_add_f32 v[16:17], v[16:17], v[46:47] neg_lo:[0,1] neg_hi:[0,1]
	v_pk_add_f32 v[18:19], v[18:19], v[48:49] neg_lo:[0,1] neg_hi:[0,1]
	v_pk_add_f32 v[12:13], v[12:13], v[50:51] neg_lo:[0,1] neg_hi:[0,1]
	v_lshl_add_u64 v[10:11], v[10:11], 0, s[26:27]
	v_lshlrev_b32_e32 v44, 16, v192
	v_and_b32_e32 v45, 0xffff0000, v192
	v_lshlrev_b32_e32 v46, 16, v193
	v_and_b32_e32 v47, 0xffff0000, v193
	v_lshlrev_b32_e32 v48, 16, v194
	v_and_b32_e32 v49, 0xffff0000, v194
	v_lshlrev_b32_e32 v50, 16, v195
	v_and_b32_e32 v51, 0xffff0000, v195
	v_pk_add_f32 v[14:15], v[14:15], v[44:45]
	v_pk_add_f32 v[16:17], v[16:17], v[46:47]
	v_pk_add_f32 v[18:19], v[18:19], v[48:49]
	v_pk_add_f32 v[12:13], v[12:13], v[50:51]
	v_pk_fma_f32 v[36:37], v[34:35], v[14:15], v[44:45] op_sel_hi:[0,1,1] neg_lo:[0,0,1] neg_hi:[0,0,1]
	v_pk_fma_f32 v[38:39], v[34:35], v[16:17], v[46:47] op_sel_hi:[0,1,1] neg_lo:[0,0,1] neg_hi:[0,0,1]
	v_pk_fma_f32 v[40:41], v[34:35], v[18:19], v[48:49] op_sel_hi:[0,1,1] neg_lo:[0,0,1] neg_hi:[0,0,1]
; __device__ __forceinline__ unsigned pk2(float lo, float hi) { f32x2 v = {lo, hi}; bf16x2_t b = __builtin_convertvector(v, bf16x2_t); return __builtin_bit_cast(unsigned, b); }
; __device__ __forceinline__ void pool_window(const bf16_t* __restrict__ U  , bf16_t* __restrict__ A3, const int gtid, const int nthr) {
;     ...
;         for (int i = 0; i < 32; ++i) {
;             const int t = t0 + i, s = s0 + i;
;             const u32x4 uu = *(const u32x4*)(U + (size_t)t * LDU + c);
;             float cu[8] = {bflo(uu.x), bfhi(uu.x), bflo(uu.y), bfhi(uu.y), bflo(uu.z), bfhi(uu.z), bflo(uu.w), bfhi(uu.w)};
;             const float rc = 1.0f / (float)((s + 1) < w ? (s + 1) : w);
;             float o[8];
; #pragma unroll
;             for (int e = 0; e < 8; ++e) { sum[e] += cu[e]; o[e] = sum[e] * rc - cu[e]; }
;             u32x4 ww; ww.x = pk2(o[0], o[1]); ww.y = pk2(o[2], o[3]); ww.z = pk2(o[4], o[5]); ww.w = pk2(o[6], o[7]);
;             *(u32x4*)(A3 + (size_t)t * DM + c) = ww;
;             if (s + 1 >= w) { const u32x4 ud = *(const u32x4*)(U + (size_t)(t - w + 1) * LDU + c);
;                 sum[0] -= bflo(ud.x); sum[1] -= bfhi(ud.x); sum[2] -= bflo(ud.y); sum[3] -= bfhi(ud.y); sum[4] -= bflo(ud.z); sum[5] -= bfhi(ud.z); sum[6] -= bflo(ud.w); sum[7] -= bfhi(ud.w); }
	v_pk_fma_f32 v[42:43], v[34:35], v[12:13], v[50:51] op_sel_hi:[0,1,1] neg_lo:[0,0,1] neg_hi:[0,0,1]
	v_cvt_pk_bf16_f32 v28, v36, v37
	v_cvt_pk_bf16_f32 v29, v38, v39
	v_cvt_pk_bf16_f32 v30, v40, v41
	v_cvt_pk_bf16_f32 v31, v42, v43
	global_store_dwordx4 v[10:11], v[28:31], off
	v_lshlrev_b32_e32 v44, 16, v188
	v_and_b32_e32 v45, 0xffff0000, v188
	v_lshlrev_b32_e32 v46, 16, v189
	v_and_b32_e32 v47, 0xffff0000, v189
	v_lshlrev_b32_e32 v48, 16, v190
	v_and_b32_e32 v49, 0xffff0000, v190
	v_lshlrev_b32_e32 v50, 16, v191
	v_and_b32_e32 v51, 0xffff0000, v191
	v_pk_add_f32 v[14:15], v[14:15], v[44:45] neg_lo:[0,1] neg_hi:[0,1]
	v_pk_add_f32 v[16:17], v[16:17], v[46:47] neg_lo:[0,1] neg_hi:[0,1]
	v_pk_add_f32 v[18:19], v[18:19], v[48:49] neg_lo:[0,1] neg_hi:[0,1]
	v_pk_add_f32 v[12:13], v[12:13], v[50:51] neg_lo:[0,1] neg_hi:[0,1]
	v_lshl_add_u64 v[10:11], v[10:11], 0, s[26:27]
	v_lshlrev_b32_e32 v44, 16, v196
	v_and_b32_e32 v45, 0xffff0000, v196
	v_lshlrev_b32_e32 v46, 16, v197
	v_and_b32_e32 v47, 0xffff0000, v197
	v_lshlrev_b32_e32 v48, 16, v198
	v_and_b32_e32 v49, 0xffff0000, v198
	v_lshlrev_b32_e32 v50, 16, v199
	v_and_b32_e32 v51, 0xffff0000, v199
	v_pk_add_f32 v[14:15], v[14:15], v[44:45]
	v_pk_add_f32 v[16:17], v[16:17], v[46:47]
	v_pk_add_f32 v[18:19], v[18:19], v[48:49]
	v_pk_add_f32 v[12:13], v[12:13], v[50:51]
	v_pk_fma_f32 v[36:37], v[34:35], v[14:15], v[44:45] op_sel_hi:[0,1,1] neg_lo:[0,0,1] neg_hi:[0,0,1]
	v_pk_fma_f32 v[38:39], v[34:35], v[16:17], v[46:47] op_sel_hi:[0,1,1] neg_lo:[0,0,1] neg_hi:[0,0,1]
	v_pk_fma_f32 v[40:41], v[34:35], v[18:19], v[48:49] op_sel_hi:[0,1,1] neg_lo:[0,0,1] neg_hi:[0,0,1]
	v_pk_fma_f32 v[42:43], v[34:35], v[12:13], v[50:51] op_sel_hi:[0,1,1] neg_lo:[0,0,1] neg_hi:[0,0,1]
	v_cvt_pk_bf16_f32 v28, v36, v37
	v_cvt_pk_bf16_f32 v29, v38, v39
	v_cvt_pk_bf16_f32 v30, v40, v41
	v_cvt_pk_bf16_f32 v31, v42, v43
	global_store_dwordx4 v[10:11], v[28:31], off
	v_lshlrev_b32_e32 v44, 16, v192
	v_and_b32_e32 v45, 0xffff0000, v192
	v_lshlrev_b32_e32 v46, 16, v193
	v_and_b32_e32 v47, 0xffff0000, v193
	v_lshlrev_b32_e32 v48, 16, v194
	v_and_b32_e32 v49, 0xffff0000, v194
	v_lshlrev_b32_e32 v50, 16, v195
	v_and_b32_e32 v51, 0xffff0000, v195
	v_pk_add_f32 v[14:15], v[14:15], v[44:45] neg_lo:[0,1] neg_hi:[0,1]
	v_pk_add_f32 v[16:17], v[16:17], v[46:47] neg_lo:[0,1] neg_hi:[0,1]
	v_pk_add_f32 v[18:19], v[18:19], v[48:49] neg_lo:[0,1] neg_hi:[0,1]
	v_pk_add_f32 v[12:13], v[12:13], v[50:51] neg_lo:[0,1] neg_hi:[0,1]
	v_lshl_add_u64 v[10:11], v[10:11], 0, s[26:27]
	v_lshlrev_b32_e32 v44, 16, v200
	v_and_b32_e32 v45, 0xffff0000, v200
	v_lshlrev_b32_e32 v46, 16, v201
	v_and_b32_e32 v47, 0xffff0000, v201
	v_lshlrev_b32_e32 v48, 16, v202
	v_and_b32_e32 v49, 0xffff0000, v202
	v_lshlrev_b32_e32 v50, 16, v203
	v_and_b32_e32 v51, 0xffff0000, v203
	v_pk_add_f32 v[14:15], v[14:15], v[44:45]
	v_pk_add_f32 v[16:17], v[16:17], v[46:47]
	v_pk_add_f32 v[18:19], v[18:19], v[48:49]
	v_pk_add_f32 v[12:13], v[12:13], v[50:51]
	v_pk_fma_f32 v[36:37], v[34:35], v[14:15], v[44:45] op_sel_hi:[0,1,1] neg_lo:[0,0,1] neg_hi:[0,0,1]
	v_pk_fma_f32 v[38:39], v[34:35], v[16:17], v[46:47] op_sel_hi:[0,1,1] neg_lo:[0,0,1] neg_hi:[0,0,1]
	v_pk_fma_f32 v[40:41], v[34:35], v[18:19], v[48:49] op_sel_hi:[0,1,1] neg_lo:[0,0,1] neg_hi:[0,0,1]
	v_pk_fma_f32 v[42:43], v[34:35], v[12:13], v[50:51] op_sel_hi:[0,1,1] neg_lo:[0,0,1] neg_hi:[0,0,1]
	v_cvt_pk_bf16_f32 v28, v36, v37
	v_cvt_pk_bf16_f32 v29, v38, v39
	v_cvt_pk_bf16_f32 v30, v40, v41
	v_cvt_pk_bf16_f32 v31, v42, v43
	global_store_dwordx4 v[10:11], v[28:31], off
	v_lshlrev_b32_e32 v44, 16, v196
	v_and_b32_e32 v45, 0xffff0000, v196
	v_lshlrev_b32_e32 v46, 16, v197
	v_and_b32_e32 v47, 0xffff0000, v197
	v_lshlrev_b32_e32 v48, 16, v198
	v_and_b32_e32 v49, 0xffff0000, v198
	v_lshlrev_b32_e32 v50, 16, v199
	v_and_b32_e32 v51, 0xffff0000, v199
	v_pk_add_f32 v[14:15], v[14:15], v[44:45] neg_lo:[0,1] neg_hi:[0,1]
	v_pk_add_f32 v[16:17], v[16:17], v[46:47] neg_lo:[0,1] neg_hi:[0,1]
	v_pk_add_f32 v[18:19], v[18:19], v[48:49] neg_lo:[0,1] neg_hi:[0,1]
	v_pk_add_f32 v[12:13], v[12:13], v[50:51] neg_lo:[0,1] neg_hi:[0,1]
	v_lshl_add_u64 v[10:11], v[10:11], 0, s[26:27]
	v_lshlrev_b32_e32 v44, 16, v204
	v_and_b32_e32 v45, 0xffff0000, v204
	v_lshlrev_b32_e32 v46, 16, v205
	v_and_b32_e32 v47, 0xffff0000, v205
	v_lshlrev_b32_e32 v48, 16, v206
	v_and_b32_e32 v49, 0xffff0000, v206
	v_lshlrev_b32_e32 v50, 16, v207
	v_and_b32_e32 v51, 0xffff0000, v207
	v_pk_add_f32 v[14:15], v[14:15], v[44:45]
	v_pk_add_f32 v[16:17], v[16:17], v[46:47]
	v_pk_add_f32 v[18:19], v[18:19], v[48:49]
	v_pk_add_f32 v[12:13], v[12:13], v[50:51]
	v_pk_fma_f32 v[36:37], v[34:35], v[14:15], v[44:45] op_sel_hi:[0,1,1] neg_lo:[0,0,1] neg_hi:[0,0,1]
	v_pk_fma_f32 v[38:39], v[34:35], v[16:17], v[46:47] op_sel_hi:[0,1,1] neg_lo:[0,0,1] neg_hi:[0,0,1]
	v_pk_fma_f32 v[40:41], v[34:35], v[18:19], v[48:49] op_sel_hi:[0,1,1] neg_lo:[0,0,1] neg_hi:[0,0,1]
	v_pk_fma_f32 v[42:43], v[34:35], v[12:13], v[50:51] op_sel_hi:[0,1,1] neg_lo:[0,0,1] neg_hi:[0,0,1]
	v_cvt_pk_bf16_f32 v28, v36, v37
	v_cvt_pk_bf16_f32 v29, v38, v39
	v_cvt_pk_bf16_f32 v30, v40, v41
	v_cvt_pk_bf16_f32 v31, v42, v43
	global_store_dwordx4 v[10:11], v[28:31], off
	v_lshlrev_b32_e32 v44, 16, v200
	v_and_b32_e32 v45, 0xffff0000, v200
	v_lshlrev_b32_e32 v46, 16, v201
	v_and_b32_e32 v47, 0xffff0000, v201
	v_lshlrev_b32_e32 v48, 16, v202
	v_and_b32_e32 v49, 0xffff0000, v202
	v_lshlrev_b32_e32 v50, 16, v203
	v_and_b32_e32 v51, 0xffff0000, v203
	v_pk_add_f32 v[14:15], v[14:15], v[44:45] neg_lo:[0,1] neg_hi:[0,1]
	v_pk_add_f32 v[16:17], v[16:17], v[46:47] neg_lo:[0,1] neg_hi:[0,1]
; __device__ __forceinline__ unsigned pk2(float lo, float hi) { f32x2 v = {lo, hi}; bf16x2_t b = __builtin_convertvector(v, bf16x2_t); return __builtin_bit_cast(unsigned, b); }
; __device__ __forceinline__ void pool_window(const bf16_t* __restrict__ U  , bf16_t* __restrict__ A3, const int gtid, const int nthr) {
;     ...
;         for (int i = 0; i < 32; ++i) {
;             const int t = t0 + i, s = s0 + i;
;             const u32x4 uu = *(const u32x4*)(U + (size_t)t * LDU + c);
;             float cu[8] = {bflo(uu.x), bfhi(uu.x), bflo(uu.y), bfhi(uu.y), bflo(uu.z), bfhi(uu.z), bflo(uu.w), bfhi(uu.w)};
;             const float rc = 1.0f / (float)((s + 1) < w ? (s + 1) : w);
;             float o[8];
; #pragma unroll
;             for (int e = 0; e < 8; ++e) { sum[e] += cu[e]; o[e] = sum[e] * rc - cu[e]; }
;             u32x4 ww; ww.x = pk2(o[0], o[1]); ww.y = pk2(o[2], o[3]); ww.z = pk2(o[4], o[5]); ww.w = pk2(o[6], o[7]);
;             *(u32x4*)(A3 + (size_t)t * DM + c) = ww;
;             if (s + 1 >= w) { const u32x4 ud = *(const u32x4*)(U + (size_t)(t - w + 1) * LDU + c);
;                 sum[0] -= bflo(ud.x); sum[1] -= bfhi(ud.x); sum[2] -= bflo(ud.y); sum[3] -= bfhi(ud.y); sum[4] -= bflo(ud.z); sum[5] -= bfhi(ud.z); sum[6] -= bflo(ud.w); sum[7] -= bfhi(ud.w); }
	v_pk_add_f32 v[18:19], v[18:19], v[48:49] neg_lo:[0,1] neg_hi:[0,1]
	v_pk_add_f32 v[12:13], v[12:13], v[50:51] neg_lo:[0,1] neg_hi:[0,1]
	v_lshl_add_u64 v[10:11], v[10:11], 0, s[26:27]
	v_lshlrev_b32_e32 v44, 16, v208
	v_and_b32_e32 v45, 0xffff0000, v208
	v_lshlrev_b32_e32 v46, 16, v209
	v_and_b32_e32 v47, 0xffff0000, v209
	v_lshlrev_b32_e32 v48, 16, v210
	v_and_b32_e32 v49, 0xffff0000, v210
	v_lshlrev_b32_e32 v50, 16, v211
	v_and_b32_e32 v51, 0xffff0000, v211
	v_pk_add_f32 v[14:15], v[14:15], v[44:45]
	v_pk_add_f32 v[16:17], v[16:17], v[46:47]
	v_pk_add_f32 v[18:19], v[18:19], v[48:49]
	v_pk_add_f32 v[12:13], v[12:13], v[50:51]
	v_pk_fma_f32 v[36:37], v[34:35], v[14:15], v[44:45] op_sel_hi:[0,1,1] neg_lo:[0,0,1] neg_hi:[0,0,1]
	v_pk_fma_f32 v[38:39], v[34:35], v[16:17], v[46:47] op_sel_hi:[0,1,1] neg_lo:[0,0,1] neg_hi:[0,0,1]
	v_pk_fma_f32 v[40:41], v[34:35], v[18:19], v[48:49] op_sel_hi:[0,1,1] neg_lo:[0,0,1] neg_hi:[0,0,1]
	v_pk_fma_f32 v[42:43], v[34:35], v[12:13], v[50:51] op_sel_hi:[0,1,1] neg_lo:[0,0,1] neg_hi:[0,0,1]
	v_cvt_pk_bf16_f32 v28, v36, v37
	v_cvt_pk_bf16_f32 v29, v38, v39
	v_cvt_pk_bf16_f32 v30, v40, v41
	v_cvt_pk_bf16_f32 v31, v42, v43
	global_store_dwordx4 v[10:11], v[28:31], off
	v_lshlrev_b32_e32 v44, 16, v204
	v_and_b32_e32 v45, 0xffff0000, v204
	v_lshlrev_b32_e32 v46, 16, v205
	v_and_b32_e32 v47, 0xffff0000, v205
	v_lshlrev_b32_e32 v48, 16, v206
	v_and_b32_e32 v49, 0xffff0000, v206
	v_lshlrev_b32_e32 v50, 16, v207
	v_and_b32_e32 v51, 0xffff0000, v207
	v_pk_add_f32 v[14:15], v[14:15], v[44:45] neg_lo:[0,1] neg_hi:[0,1]
	v_pk_add_f32 v[16:17], v[16:17], v[46:47] neg_lo:[0,1] neg_hi:[0,1]
	v_pk_add_f32 v[18:19], v[18:19], v[48:49] neg_lo:[0,1] neg_hi:[0,1]
	v_pk_add_f32 v[12:13], v[12:13], v[50:51] neg_lo:[0,1] neg_hi:[0,1]
	v_lshl_add_u64 v[10:11], v[10:11], 0, s[26:27]
	v_lshlrev_b32_e32 v44, 16, v214
	v_and_b32_e32 v45, 0xffff0000, v214
	v_lshlrev_b32_e32 v46, 16, v215
	v_and_b32_e32 v47, 0xffff0000, v215
	v_lshlrev_b32_e32 v48, 16, v216
	v_and_b32_e32 v49, 0xffff0000, v216
	v_lshlrev_b32_e32 v50, 16, v217
	v_and_b32_e32 v51, 0xffff0000, v217
	v_pk_add_f32 v[14:15], v[14:15], v[44:45]
	v_pk_add_f32 v[16:17], v[16:17], v[46:47]
	v_pk_add_f32 v[18:19], v[18:19], v[48:49]
	v_pk_add_f32 v[12:13], v[12:13], v[50:51]
	v_pk_fma_f32 v[36:37], v[34:35], v[14:15], v[44:45] op_sel_hi:[0,1,1] neg_lo:[0,0,1] neg_hi:[0,0,1]
	v_pk_fma_f32 v[38:39], v[34:35], v[16:17], v[46:47] op_sel_hi:[0,1,1] neg_lo:[0,0,1] neg_hi:[0,0,1]
	v_pk_fma_f32 v[40:41], v[34:35], v[18:19], v[48:49] op_sel_hi:[0,1,1] neg_lo:[0,0,1] neg_hi:[0,0,1]
	v_pk_fma_f32 v[42:43], v[34:35], v[12:13], v[50:51] op_sel_hi:[0,1,1] neg_lo:[0,0,1] neg_hi:[0,0,1]
	v_cvt_pk_bf16_f32 v28, v36, v37
	v_cvt_pk_bf16_f32 v29, v38, v39
	v_cvt_pk_bf16_f32 v30, v40, v41
	v_cvt_pk_bf16_f32 v31, v42, v43
	global_store_dwordx4 v[10:11], v[28:31], off
	v_lshlrev_b32_e32 v44, 16, v208
	v_and_b32_e32 v45, 0xffff0000, v208
	v_lshlrev_b32_e32 v46, 16, v209
	v_and_b32_e32 v47, 0xffff0000, v209
	v_lshlrev_b32_e32 v48, 16, v210
	v_and_b32_e32 v49, 0xffff0000, v210
	v_lshlrev_b32_e32 v50, 16, v211
	v_and_b32_e32 v51, 0xffff0000, v211
	v_pk_add_f32 v[14:15], v[14:15], v[44:45] neg_lo:[0,1] neg_hi:[0,1]
	v_pk_add_f32 v[16:17], v[16:17], v[46:47] neg_lo:[0,1] neg_hi:[0,1]
	v_pk_add_f32 v[18:19], v[18:19], v[48:49] neg_lo:[0,1] neg_hi:[0,1]
	v_pk_add_f32 v[12:13], v[12:13], v[50:51] neg_lo:[0,1] neg_hi:[0,1]
	v_lshl_add_u64 v[10:11], v[10:11], 0, s[26:27]
	v_lshlrev_b32_e32 v44, 16, v218
	v_and_b32_e32 v45, 0xffff0000, v218
	v_lshlrev_b32_e32 v46, 16, v219
	v_and_b32_e32 v47, 0xffff0000, v219
	v_lshlrev_b32_e32 v48, 16, v220
	v_and_b32_e32 v49, 0xffff0000, v220
	v_lshlrev_b32_e32 v50, 16, v221
	v_and_b32_e32 v51, 0xffff0000, v221
	v_pk_add_f32 v[14:15], v[14:15], v[44:45]
	v_pk_add_f32 v[16:17], v[16:17], v[46:47]
	v_pk_add_f32 v[18:19], v[18:19], v[48:49]
	v_pk_add_f32 v[12:13], v[12:13], v[50:51]
	v_pk_fma_f32 v[36:37], v[34:35], v[14:15], v[44:45] op_sel_hi:[0,1,1] neg_lo:[0,0,1] neg_hi:[0,0,1]
	v_pk_fma_f32 v[38:39], v[34:35], v[16:17], v[46:47] op_sel_hi:[0,1,1] neg_lo:[0,0,1] neg_hi:[0,0,1]
	v_pk_fma_f32 v[40:41], v[34:35], v[18:19], v[48:49] op_sel_hi:[0,1,1] neg_lo:[0,0,1] neg_hi:[0,0,1]
	v_pk_fma_f32 v[42:43], v[34:35], v[12:13], v[50:51] op_sel_hi:[0,1,1] neg_lo:[0,0,1] neg_hi:[0,0,1]
	v_cvt_pk_bf16_f32 v28, v36, v37
	v_cvt_pk_bf16_f32 v29, v38, v39
	v_cvt_pk_bf16_f32 v30, v40, v41
	v_cvt_pk_bf16_f32 v31, v42, v43
	global_store_dwordx4 v[10:11], v[28:31], off
	v_lshlrev_b32_e32 v44, 16, v214
	v_and_b32_e32 v45, 0xffff0000, v214
	v_lshlrev_b32_e32 v46, 16, v215
	v_and_b32_e32 v47, 0xffff0000, v215
	v_lshlrev_b32_e32 v48, 16, v216
	v_and_b32_e32 v49, 0xffff0000, v216
	v_lshlrev_b32_e32 v50, 16, v217
	v_and_b32_e32 v51, 0xffff0000, v217
	v_pk_add_f32 v[14:15], v[14:15], v[44:45] neg_lo:[0,1] neg_hi:[0,1]
	v_pk_add_f32 v[16:17], v[16:17], v[46:47] neg_lo:[0,1] neg_hi:[0,1]
	v_pk_add_f32 v[18:19], v[18:19], v[48:49] neg_lo:[0,1] neg_hi:[0,1]
	v_pk_add_f32 v[12:13], v[12:13], v[50:51] neg_lo:[0,1] neg_hi:[0,1]
	v_lshl_add_u64 v[10:11], v[10:11], 0, s[26:27]
	v_lshlrev_b32_e32 v44, 16, v222
	v_and_b32_e32 v45, 0xffff0000, v222
	v_lshlrev_b32_e32 v46, 16, v223
	v_and_b32_e32 v47, 0xffff0000, v223
	v_lshlrev_b32_e32 v48, 16, v224
	v_and_b32_e32 v49, 0xffff0000, v224
	v_lshlrev_b32_e32 v50, 16, v225
	v_and_b32_e32 v51, 0xffff0000, v225
	v_pk_add_f32 v[14:15], v[14:15], v[44:45]
	v_pk_add_f32 v[16:17], v[16:17], v[46:47]
	v_pk_add_f32 v[18:19], v[18:19], v[48:49]
	v_pk_add_f32 v[12:13], v[12:13], v[50:51]
	v_pk_fma_f32 v[36:37], v[34:35], v[14:15], v[44:45] op_sel_hi:[0,1,1] neg_lo:[0,0,1] neg_hi:[0,0,1]
; __device__ __forceinline__ unsigned pk2(float lo, float hi) { f32x2 v = {lo, hi}; bf16x2_t b = __builtin_convertvector(v, bf16x2_t); return __builtin_bit_cast(unsigned, b); }
; __device__ __forceinline__ void pool_window(const bf16_t* __restrict__ U  , bf16_t* __restrict__ A3, const int gtid, const int nthr) {
;     ...
;         for (int i = 0; i < 32; ++i) {
;             const int t = t0 + i, s = s0 + i;
;             const u32x4 uu = *(const u32x4*)(U + (size_t)t * LDU + c);
;             float cu[8] = {bflo(uu.x), bfhi(uu.x), bflo(uu.y), bfhi(uu.y), bflo(uu.z), bfhi(uu.z), bflo(uu.w), bfhi(uu.w)};
;             const float rc = 1.0f / (float)((s + 1) < w ? (s + 1) : w);
;             float o[8];
; #pragma unroll
;             for (int e = 0; e < 8; ++e) { sum[e] += cu[e]; o[e] = sum[e] * rc - cu[e]; }
;             u32x4 ww; ww.x = pk2(o[0], o[1]); ww.y = pk2(o[2], o[3]); ww.z = pk2(o[4], o[5]); ww.w = pk2(o[6], o[7]);
;             *(u32x4*)(A3 + (size_t)t * DM + c) = ww;
;             if (s + 1 >= w) { const u32x4 ud = *(const u32x4*)(U + (size_t)(t - w + 1) * LDU + c);
;                 sum[0] -= bflo(ud.x); sum[1] -= bfhi(ud.x); sum[2] -= bflo(ud.y); sum[3] -= bfhi(ud.y); sum[4] -= bflo(ud.z); sum[5] -= bfhi(ud.z); sum[6] -= bflo(ud.w); sum[7] -= bfhi(ud.w); }
	v_pk_fma_f32 v[38:39], v[34:35], v[16:17], v[46:47] op_sel_hi:[0,1,1] neg_lo:[0,0,1] neg_hi:[0,0,1]
	v_pk_fma_f32 v[40:41], v[34:35], v[18:19], v[48:49] op_sel_hi:[0,1,1] neg_lo:[0,0,1] neg_hi:[0,0,1]
	v_pk_fma_f32 v[42:43], v[34:35], v[12:13], v[50:51] op_sel_hi:[0,1,1] neg_lo:[0,0,1] neg_hi:[0,0,1]
	v_cvt_pk_bf16_f32 v28, v36, v37
	v_cvt_pk_bf16_f32 v29, v38, v39
	v_cvt_pk_bf16_f32 v30, v40, v41
	v_cvt_pk_bf16_f32 v31, v42, v43
	global_store_dwordx4 v[10:11], v[28:31], off
	v_lshlrev_b32_e32 v44, 16, v218
	v_and_b32_e32 v45, 0xffff0000, v218
	v_lshlrev_b32_e32 v46, 16, v219
	v_and_b32_e32 v47, 0xffff0000, v219
	v_lshlrev_b32_e32 v48, 16, v220
	v_and_b32_e32 v49, 0xffff0000, v220
	v_lshlrev_b32_e32 v50, 16, v221
	v_and_b32_e32 v51, 0xffff0000, v221
	v_pk_add_f32 v[14:15], v[14:15], v[44:45] neg_lo:[0,1] neg_hi:[0,1]
	v_pk_add_f32 v[16:17], v[16:17], v[46:47] neg_lo:[0,1] neg_hi:[0,1]
	v_pk_add_f32 v[18:19], v[18:19], v[48:49] neg_lo:[0,1] neg_hi:[0,1]
	v_pk_add_f32 v[12:13], v[12:13], v[50:51] neg_lo:[0,1] neg_hi:[0,1]
	v_lshl_add_u64 v[10:11], v[10:11], 0, s[26:27]
	v_lshlrev_b32_e32 v44, 16, v226
	v_and_b32_e32 v45, 0xffff0000, v226
	v_lshlrev_b32_e32 v46, 16, v227
	v_and_b32_e32 v47, 0xffff0000, v227
	v_lshlrev_b32_e32 v48, 16, v228
	v_and_b32_e32 v49, 0xffff0000, v228
	v_lshlrev_b32_e32 v50, 16, v229
	v_and_b32_e32 v51, 0xffff0000, v229
	v_pk_add_f32 v[14:15], v[14:15], v[44:45]
	v_pk_add_f32 v[16:17], v[16:17], v[46:47]
	v_pk_add_f32 v[18:19], v[18:19], v[48:49]
	v_pk_add_f32 v[12:13], v[12:13], v[50:51]
	v_pk_fma_f32 v[36:37], v[34:35], v[14:15], v[44:45] op_sel_hi:[0,1,1] neg_lo:[0,0,1] neg_hi:[0,0,1]
	v_pk_fma_f32 v[38:39], v[34:35], v[16:17], v[46:47] op_sel_hi:[0,1,1] neg_lo:[0,0,1] neg_hi:[0,0,1]
	v_pk_fma_f32 v[40:41], v[34:35], v[18:19], v[48:49] op_sel_hi:[0,1,1] neg_lo:[0,0,1] neg_hi:[0,0,1]
	v_pk_fma_f32 v[42:43], v[34:35], v[12:13], v[50:51] op_sel_hi:[0,1,1] neg_lo:[0,0,1] neg_hi:[0,0,1]
	v_cvt_pk_bf16_f32 v28, v36, v37
	v_cvt_pk_bf16_f32 v29, v38, v39
	v_cvt_pk_bf16_f32 v30, v40, v41
	v_cvt_pk_bf16_f32 v31, v42, v43
	global_store_dwordx4 v[10:11], v[28:31], off
	v_lshlrev_b32_e32 v44, 16, v222
	v_and_b32_e32 v45, 0xffff0000, v222
	v_lshlrev_b32_e32 v46, 16, v223
	v_and_b32_e32 v47, 0xffff0000, v223
	v_lshlrev_b32_e32 v48, 16, v224
	v_and_b32_e32 v49, 0xffff0000, v224
	v_lshlrev_b32_e32 v50, 16, v225
	v_and_b32_e32 v51, 0xffff0000, v225
	v_pk_add_f32 v[14:15], v[14:15], v[44:45] neg_lo:[0,1] neg_hi:[0,1]
	v_pk_add_f32 v[16:17], v[16:17], v[46:47] neg_lo:[0,1] neg_hi:[0,1]
	v_pk_add_f32 v[18:19], v[18:19], v[48:49] neg_lo:[0,1] neg_hi:[0,1]
	v_pk_add_f32 v[12:13], v[12:13], v[50:51] neg_lo:[0,1] neg_hi:[0,1]
	v_lshl_add_u64 v[10:11], v[10:11], 0, s[26:27]
	v_lshlrev_b32_e32 v44, 16, v230
	v_and_b32_e32 v45, 0xffff0000, v230
	v_lshlrev_b32_e32 v46, 16, v231
	v_and_b32_e32 v47, 0xffff0000, v231
	v_lshlrev_b32_e32 v48, 16, v232
	v_and_b32_e32 v49, 0xffff0000, v232
	v_lshlrev_b32_e32 v50, 16, v233
	v_and_b32_e32 v51, 0xffff0000, v233
	v_pk_add_f32 v[14:15], v[14:15], v[44:45]
	v_pk_add_f32 v[16:17], v[16:17], v[46:47]
	v_pk_add_f32 v[18:19], v[18:19], v[48:49]
	v_pk_add_f32 v[12:13], v[12:13], v[50:51]
	v_pk_fma_f32 v[36:37], v[34:35], v[14:15], v[44:45] op_sel_hi:[0,1,1] neg_lo:[0,0,1] neg_hi:[0,0,1]
	v_pk_fma_f32 v[38:39], v[34:35], v[16:17], v[46:47] op_sel_hi:[0,1,1] neg_lo:[0,0,1] neg_hi:[0,0,1]
	v_pk_fma_f32 v[40:41], v[34:35], v[18:19], v[48:49] op_sel_hi:[0,1,1] neg_lo:[0,0,1] neg_hi:[0,0,1]
	v_pk_fma_f32 v[42:43], v[34:35], v[12:13], v[50:51] op_sel_hi:[0,1,1] neg_lo:[0,0,1] neg_hi:[0,0,1]
	v_cvt_pk_bf16_f32 v28, v36, v37
	v_cvt_pk_bf16_f32 v29, v38, v39
	v_cvt_pk_bf16_f32 v30, v40, v41
	v_cvt_pk_bf16_f32 v31, v42, v43
	global_store_dwordx4 v[10:11], v[28:31], off
	v_lshlrev_b32_e32 v44, 16, v226
	v_and_b32_e32 v45, 0xffff0000, v226
	v_lshlrev_b32_e32 v46, 16, v227
	v_and_b32_e32 v47, 0xffff0000, v227
	v_lshlrev_b32_e32 v48, 16, v228
	v_and_b32_e32 v49, 0xffff0000, v228
	v_lshlrev_b32_e32 v50, 16, v229
	v_and_b32_e32 v51, 0xffff0000, v229
	v_pk_add_f32 v[14:15], v[14:15], v[44:45] neg_lo:[0,1] neg_hi:[0,1]
	v_pk_add_f32 v[16:17], v[16:17], v[46:47] neg_lo:[0,1] neg_hi:[0,1]
	v_pk_add_f32 v[18:19], v[18:19], v[48:49] neg_lo:[0,1] neg_hi:[0,1]
	v_pk_add_f32 v[12:13], v[12:13], v[50:51] neg_lo:[0,1] neg_hi:[0,1]
	v_lshl_add_u64 v[10:11], v[10:11], 0, s[26:27]
	v_lshlrev_b32_e32 v44, 16, v234
	v_and_b32_e32 v45, 0xffff0000, v234
	v_lshlrev_b32_e32 v46, 16, v235
	v_and_b32_e32 v47, 0xffff0000, v235
	v_lshlrev_b32_e32 v48, 16, v236
	v_and_b32_e32 v49, 0xffff0000, v236
	v_lshlrev_b32_e32 v50, 16, v237
	v_and_b32_e32 v51, 0xffff0000, v237
	v_pk_add_f32 v[14:15], v[14:15], v[44:45]
	v_pk_add_f32 v[16:17], v[16:17], v[46:47]
	v_pk_add_f32 v[18:19], v[18:19], v[48:49]
	v_pk_add_f32 v[12:13], v[12:13], v[50:51]
	v_pk_fma_f32 v[36:37], v[34:35], v[14:15], v[44:45] op_sel_hi:[0,1,1] neg_lo:[0,0,1] neg_hi:[0,0,1]
	v_pk_fma_f32 v[38:39], v[34:35], v[16:17], v[46:47] op_sel_hi:[0,1,1] neg_lo:[0,0,1] neg_hi:[0,0,1]
	v_pk_fma_f32 v[40:41], v[34:35], v[18:19], v[48:49] op_sel_hi:[0,1,1] neg_lo:[0,0,1] neg_hi:[0,0,1]
	v_pk_fma_f32 v[42:43], v[34:35], v[12:13], v[50:51] op_sel_hi:[0,1,1] neg_lo:[0,0,1] neg_hi:[0,0,1]
	v_cvt_pk_bf16_f32 v28, v36, v37
	v_cvt_pk_bf16_f32 v29, v38, v39
	v_cvt_pk_bf16_f32 v30, v40, v41
	v_cvt_pk_bf16_f32 v31, v42, v43
	global_store_dwordx4 v[10:11], v[28:31], off
	v_lshlrev_b32_e32 v44, 16, v230
	v_and_b32_e32 v45, 0xffff0000, v230
	v_lshlrev_b32_e32 v46, 16, v231
	v_and_b32_e32 v47, 0xffff0000, v231
	v_lshlrev_b32_e32 v48, 16, v232
	v_and_b32_e32 v49, 0xffff0000, v232
	v_lshlrev_b32_e32 v50, 16, v233
; __device__ __forceinline__ unsigned pk2(float lo, float hi) { f32x2 v = {lo, hi}; bf16x2_t b = __builtin_convertvector(v, bf16x2_t); return __builtin_bit_cast(unsigned, b); }
; __device__ __forceinline__ void pool_window(const bf16_t* __restrict__ U  , bf16_t* __restrict__ A3, const int gtid, const int nthr) {
;     ...
;         for (int i = 0; i < 32; ++i) {
;             const int t = t0 + i, s = s0 + i;
;             const u32x4 uu = *(const u32x4*)(U + (size_t)t * LDU + c);
;             float cu[8] = {bflo(uu.x), bfhi(uu.x), bflo(uu.y), bfhi(uu.y), bflo(uu.z), bfhi(uu.z), bflo(uu.w), bfhi(uu.w)};
;             const float rc = 1.0f / (float)((s + 1) < w ? (s + 1) : w);
;             float o[8];
; #pragma unroll
;             for (int e = 0; e < 8; ++e) { sum[e] += cu[e]; o[e] = sum[e] * rc - cu[e]; }
;             u32x4 ww; ww.x = pk2(o[0], o[1]); ww.y = pk2(o[2], o[3]); ww.z = pk2(o[4], o[5]); ww.w = pk2(o[6], o[7]);
;             *(u32x4*)(A3 + (size_t)t * DM + c) = ww;
;             if (s + 1 >= w) { const u32x4 ud = *(const u32x4*)(U + (size_t)(t - w + 1) * LDU + c);
;                 sum[0] -= bflo(ud.x); sum[1] -= bfhi(ud.x); sum[2] -= bflo(ud.y); sum[3] -= bfhi(ud.y); sum[4] -= bflo(ud.z); sum[5] -= bfhi(ud.z); sum[6] -= bflo(ud.w); sum[7] -= bfhi(ud.w); }
	v_and_b32_e32 v51, 0xffff0000, v233
	v_pk_add_f32 v[14:15], v[14:15], v[44:45] neg_lo:[0,1] neg_hi:[0,1]
	v_pk_add_f32 v[16:17], v[16:17], v[46:47] neg_lo:[0,1] neg_hi:[0,1]
	v_pk_add_f32 v[18:19], v[18:19], v[48:49] neg_lo:[0,1] neg_hi:[0,1]
	v_pk_add_f32 v[12:13], v[12:13], v[50:51] neg_lo:[0,1] neg_hi:[0,1]
	v_lshl_add_u64 v[10:11], v[10:11], 0, s[26:27]
	v_lshlrev_b32_e32 v44, 16, v238
	v_and_b32_e32 v45, 0xffff0000, v238
	v_lshlrev_b32_e32 v46, 16, v239
	v_and_b32_e32 v47, 0xffff0000, v239
	v_lshlrev_b32_e32 v48, 16, v240
	v_and_b32_e32 v49, 0xffff0000, v240
	v_lshlrev_b32_e32 v50, 16, v241
	v_and_b32_e32 v51, 0xffff0000, v241
	v_pk_add_f32 v[14:15], v[14:15], v[44:45]
	v_pk_add_f32 v[16:17], v[16:17], v[46:47]
	v_pk_add_f32 v[18:19], v[18:19], v[48:49]
	v_pk_add_f32 v[12:13], v[12:13], v[50:51]
	v_pk_fma_f32 v[36:37], v[34:35], v[14:15], v[44:45] op_sel_hi:[0,1,1] neg_lo:[0,0,1] neg_hi:[0,0,1]
	v_pk_fma_f32 v[38:39], v[34:35], v[16:17], v[46:47] op_sel_hi:[0,1,1] neg_lo:[0,0,1] neg_hi:[0,0,1]
	v_pk_fma_f32 v[40:41], v[34:35], v[18:19], v[48:49] op_sel_hi:[0,1,1] neg_lo:[0,0,1] neg_hi:[0,0,1]
	v_pk_fma_f32 v[42:43], v[34:35], v[12:13], v[50:51] op_sel_hi:[0,1,1] neg_lo:[0,0,1] neg_hi:[0,0,1]
	v_cvt_pk_bf16_f32 v28, v36, v37
	v_cvt_pk_bf16_f32 v29, v38, v39
	v_cvt_pk_bf16_f32 v30, v40, v41
	v_cvt_pk_bf16_f32 v31, v42, v43
	global_store_dwordx4 v[10:11], v[28:31], off
	v_lshlrev_b32_e32 v44, 16, v234
	v_and_b32_e32 v45, 0xffff0000, v234
	v_lshlrev_b32_e32 v46, 16, v235
	v_and_b32_e32 v47, 0xffff0000, v235
	v_lshlrev_b32_e32 v48, 16, v236
	v_and_b32_e32 v49, 0xffff0000, v236
	v_lshlrev_b32_e32 v50, 16, v237
	v_and_b32_e32 v51, 0xffff0000, v237
	v_pk_add_f32 v[14:15], v[14:15], v[44:45] neg_lo:[0,1] neg_hi:[0,1]
	v_pk_add_f32 v[16:17], v[16:17], v[46:47] neg_lo:[0,1] neg_hi:[0,1]
	v_pk_add_f32 v[18:19], v[18:19], v[48:49] neg_lo:[0,1] neg_hi:[0,1]
	v_pk_add_f32 v[12:13], v[12:13], v[50:51] neg_lo:[0,1] neg_hi:[0,1]
	v_lshl_add_u64 v[10:11], v[10:11], 0, s[26:27]
	v_lshlrev_b32_e32 v44, 16, v242
	v_and_b32_e32 v45, 0xffff0000, v242
	v_lshlrev_b32_e32 v46, 16, v243
	v_and_b32_e32 v47, 0xffff0000, v243
	v_lshlrev_b32_e32 v48, 16, v244
	v_and_b32_e32 v49, 0xffff0000, v244
	v_lshlrev_b32_e32 v50, 16, v245
	v_and_b32_e32 v51, 0xffff0000, v245
	v_pk_add_f32 v[14:15], v[14:15], v[44:45]
	v_pk_add_f32 v[16:17], v[16:17], v[46:47]
	v_pk_add_f32 v[18:19], v[18:19], v[48:49]
	v_pk_add_f32 v[12:13], v[12:13], v[50:51]
	v_pk_fma_f32 v[36:37], v[34:35], v[14:15], v[44:45] op_sel_hi:[0,1,1] neg_lo:[0,0,1] neg_hi:[0,0,1]
	v_pk_fma_f32 v[38:39], v[34:35], v[16:17], v[46:47] op_sel_hi:[0,1,1] neg_lo:[0,0,1] neg_hi:[0,0,1]
	v_pk_fma_f32 v[40:41], v[34:35], v[18:19], v[48:49] op_sel_hi:[0,1,1] neg_lo:[0,0,1] neg_hi:[0,0,1]
	v_pk_fma_f32 v[42:43], v[34:35], v[12:13], v[50:51] op_sel_hi:[0,1,1] neg_lo:[0,0,1] neg_hi:[0,0,1]
	v_cvt_pk_bf16_f32 v28, v36, v37
	v_cvt_pk_bf16_f32 v29, v38, v39
	v_cvt_pk_bf16_f32 v30, v40, v41
	v_cvt_pk_bf16_f32 v31, v42, v43
	global_store_dwordx4 v[10:11], v[28:31], off
	v_lshlrev_b32_e32 v44, 16, v238
	v_and_b32_e32 v45, 0xffff0000, v238
	v_lshlrev_b32_e32 v46, 16, v239
	v_and_b32_e32 v47, 0xffff0000, v239
	v_lshlrev_b32_e32 v48, 16, v240
	v_and_b32_e32 v49, 0xffff0000, v240
	v_lshlrev_b32_e32 v50, 16, v241
	v_and_b32_e32 v51, 0xffff0000, v241
	v_pk_add_f32 v[14:15], v[14:15], v[44:45] neg_lo:[0,1] neg_hi:[0,1]
	v_pk_add_f32 v[16:17], v[16:17], v[46:47] neg_lo:[0,1] neg_hi:[0,1]
	v_pk_add_f32 v[18:19], v[18:19], v[48:49] neg_lo:[0,1] neg_hi:[0,1]
	v_pk_add_f32 v[12:13], v[12:13], v[50:51] neg_lo:[0,1] neg_hi:[0,1]
	v_lshl_add_u64 v[10:11], v[10:11], 0, s[26:27]
	v_lshlrev_b32_e32 v44, 16, v246
	v_and_b32_e32 v45, 0xffff0000, v246
	v_lshlrev_b32_e32 v46, 16, v247
	v_and_b32_e32 v47, 0xffff0000, v247
	v_lshlrev_b32_e32 v48, 16, v248
	v_and_b32_e32 v49, 0xffff0000, v248
	v_lshlrev_b32_e32 v50, 16, v249
	v_and_b32_e32 v51, 0xffff0000, v249
	v_pk_add_f32 v[14:15], v[14:15], v[44:45]
	v_pk_add_f32 v[16:17], v[16:17], v[46:47]
	v_pk_add_f32 v[18:19], v[18:19], v[48:49]
	v_pk_add_f32 v[12:13], v[12:13], v[50:51]
	v_pk_fma_f32 v[36:37], v[34:35], v[14:15], v[44:45] op_sel_hi:[0,1,1] neg_lo:[0,0,1] neg_hi:[0,0,1]
	v_pk_fma_f32 v[38:39], v[34:35], v[16:17], v[46:47] op_sel_hi:[0,1,1] neg_lo:[0,0,1] neg_hi:[0,0,1]
	v_pk_fma_f32 v[40:41], v[34:35], v[18:19], v[48:49] op_sel_hi:[0,1,1] neg_lo:[0,0,1] neg_hi:[0,0,1]
	v_pk_fma_f32 v[42:43], v[34:35], v[12:13], v[50:51] op_sel_hi:[0,1,1] neg_lo:[0,0,1] neg_hi:[0,0,1]
	v_cvt_pk_bf16_f32 v28, v36, v37
	v_cvt_pk_bf16_f32 v29, v38, v39
	v_cvt_pk_bf16_f32 v30, v40, v41
	v_cvt_pk_bf16_f32 v31, v42, v43
	global_store_dwordx4 v[10:11], v[28:31], off
	v_lshlrev_b32_e32 v44, 16, v242
	v_and_b32_e32 v45, 0xffff0000, v242
	v_lshlrev_b32_e32 v46, 16, v243
	v_and_b32_e32 v47, 0xffff0000, v243
	v_lshlrev_b32_e32 v48, 16, v244
	v_and_b32_e32 v49, 0xffff0000, v244
	v_lshlrev_b32_e32 v50, 16, v245
	v_and_b32_e32 v51, 0xffff0000, v245
	v_pk_add_f32 v[14:15], v[14:15], v[44:45] neg_lo:[0,1] neg_hi:[0,1]
	v_pk_add_f32 v[16:17], v[16:17], v[46:47] neg_lo:[0,1] neg_hi:[0,1]
	v_pk_add_f32 v[18:19], v[18:19], v[48:49] neg_lo:[0,1] neg_hi:[0,1]
	v_pk_add_f32 v[12:13], v[12:13], v[50:51] neg_lo:[0,1] neg_hi:[0,1]
	v_lshl_add_u64 v[10:11], v[10:11], 0, s[26:27]
	v_lshlrev_b32_e32 v44, 16, v250
	v_and_b32_e32 v45, 0xffff0000, v250
	v_lshlrev_b32_e32 v46, 16, v251
	v_and_b32_e32 v47, 0xffff0000, v251
	v_lshlrev_b32_e32 v48, 16, v252
	v_and_b32_e32 v49, 0xffff0000, v252
	v_lshlrev_b32_e32 v50, 16, v253
	v_and_b32_e32 v51, 0xffff0000, v253
	v_pk_add_f32 v[14:15], v[14:15], v[44:45]
	v_pk_add_f32 v[16:17], v[16:17], v[46:47]
	v_pk_add_f32 v[18:19], v[18:19], v[48:49]
	v_pk_add_f32 v[12:13], v[12:13], v[50:51]
	v_pk_fma_f32 v[36:37], v[34:35], v[14:15], v[44:45] op_sel_hi:[0,1,1] neg_lo:[0,0,1] neg_hi:[0,0,1]
	v_pk_fma_f32 v[38:39], v[34:35], v[16:17], v[46:47] op_sel_hi:[0,1,1] neg_lo:[0,0,1] neg_hi:[0,0,1]
	v_pk_fma_f32 v[40:41], v[34:35], v[18:19], v[48:49] op_sel_hi:[0,1,1] neg_lo:[0,0,1] neg_hi:[0,0,1]
	v_pk_fma_f32 v[42:43], v[34:35], v[12:13], v[50:51] op_sel_hi:[0,1,1] neg_lo:[0,0,1] neg_hi:[0,0,1]
	v_cvt_pk_bf16_f32 v28, v36, v37
	v_cvt_pk_bf16_f32 v29, v38, v39
	v_cvt_pk_bf16_f32 v30, v40, v41
	v_cvt_pk_bf16_f32 v31, v42, v43
	global_store_dwordx4 v[10:11], v[28:31], off
	v_lshlrev_b32_e32 v44, 16, v246
	v_and_b32_e32 v45, 0xffff0000, v246
	v_lshlrev_b32_e32 v46, 16, v247
	v_and_b32_e32 v47, 0xffff0000, v247
	v_lshlrev_b32_e32 v48, 16, v248
	v_and_b32_e32 v49, 0xffff0000, v248
	v_lshlrev_b32_e32 v50, 16, v249
	v_and_b32_e32 v51, 0xffff0000, v249
	v_pk_add_f32 v[14:15], v[14:15], v[44:45] neg_lo:[0,1] neg_hi:[0,1]
	v_pk_add_f32 v[16:17], v[16:17], v[46:47] neg_lo:[0,1] neg_hi:[0,1]
	v_pk_add_f32 v[18:19], v[18:19], v[48:49] neg_lo:[0,1] neg_hi:[0,1]
	v_pk_add_f32 v[12:13], v[12:13], v[50:51] neg_lo:[0,1] neg_hi:[0,1]
	s_branch .LBB0_1331
; __device__ __forceinline__ unsigned pk2(float lo, float hi) { f32x2 v = {lo, hi}; bf16x2_t b = __builtin_convertvector(v, bf16x2_t); return __builtin_bit_cast(unsigned, b); }
; __device__ __forceinline__ void pool_window(const bf16_t* __restrict__ U  , bf16_t* __restrict__ A3, const int gtid, const int nthr) {
;     ...
;         for (int i = 0; i < 32; ++i) {
;             const int t = t0 + i, s = s0 + i;
;             const u32x4 uu = *(const u32x4*)(U + (size_t)t * LDU + c);
;             float cu[8] = {bflo(uu.x), bfhi(uu.x), bflo(uu.y), bfhi(uu.y), bflo(uu.z), bfhi(uu.z), bflo(uu.w), bfhi(uu.w)};
;             const float rc = 1.0f / (float)((s + 1) < w ? (s + 1) : w);
;             float o[8];
; #pragma unroll
;             for (int e = 0; e < 8; ++e) { sum[e] += cu[e]; o[e] = sum[e] * rc - cu[e]; }
;             u32x4 ww; ww.x = pk2(o[0], o[1]); ww.y = pk2(o[2], o[3]); ww.z = pk2(o[4], o[5]); ww.w = pk2(o[6], o[7]);
;             *(u32x4*)(A3 + (size_t)t * DM + c) = ww;
;             if (s + 1 >= w) { const u32x4 ud = *(const u32x4*)(U + (size_t)(t - w + 1) * LDU + c);
;                 sum[0] -= bflo(ud.x); sum[1] -= bfhi(ud.x); sum[2] -= bflo(ud.y); sum[3] -= bfhi(ud.y); sum[4] -= bflo(ud.z); sum[5] -= bfhi(ud.z); sum[6] -= bflo(ud.w); sum[7] -= bfhi(ud.w); }
.Lpw0_w4:
	v_mov_b32_e32 v34, 0x3e800000
	s_waitcnt vmcnt(0)
	v_mov_b32_e32 v34, 0x3f800000
	v_lshlrev_b32_e32 v44, 16, v124
	v_and_b32_e32 v45, 0xffff0000, v124
	v_lshlrev_b32_e32 v46, 16, v125
	v_and_b32_e32 v47, 0xffff0000, v125
	v_lshlrev_b32_e32 v48, 16, v126
	v_and_b32_e32 v49, 0xffff0000, v126
	v_lshlrev_b32_e32 v50, 16, v127
	v_and_b32_e32 v51, 0xffff0000, v127
	v_pk_add_f32 v[14:15], v[14:15], v[44:45]
	v_pk_add_f32 v[16:17], v[16:17], v[46:47]
	v_pk_add_f32 v[18:19], v[18:19], v[48:49]
	v_pk_add_f32 v[12:13], v[12:13], v[50:51]
	v_pk_fma_f32 v[36:37], v[34:35], v[14:15], v[44:45] op_sel_hi:[0,1,1] neg_lo:[0,0,1] neg_hi:[0,0,1]
	v_pk_fma_f32 v[38:39], v[34:35], v[16:17], v[46:47] op_sel_hi:[0,1,1] neg_lo:[0,0,1] neg_hi:[0,0,1]
	v_pk_fma_f32 v[40:41], v[34:35], v[18:19], v[48:49] op_sel_hi:[0,1,1] neg_lo:[0,0,1] neg_hi:[0,0,1]
	v_pk_fma_f32 v[42:43], v[34:35], v[12:13], v[50:51] op_sel_hi:[0,1,1] neg_lo:[0,0,1] neg_hi:[0,0,1]
	v_cvt_pk_bf16_f32 v28, v36, v37
	v_cvt_pk_bf16_f32 v29, v38, v39
	v_cvt_pk_bf16_f32 v30, v40, v41
	v_cvt_pk_bf16_f32 v31, v42, v43
	global_store_dwordx4 v[10:11], v[28:31], off
	v_lshl_add_u64 v[10:11], v[10:11], 0, s[26:27]
	v_mov_b32_e32 v34, 0x3f000000
	v_lshlrev_b32_e32 v44, 16, v128
	v_and_b32_e32 v45, 0xffff0000, v128
	v_lshlrev_b32_e32 v46, 16, v129
	v_and_b32_e32 v47, 0xffff0000, v129
	v_lshlrev_b32_e32 v48, 16, v130
	v_and_b32_e32 v49, 0xffff0000, v130
	v_lshlrev_b32_e32 v50, 16, v131
	v_and_b32_e32 v51, 0xffff0000, v131
	v_pk_add_f32 v[14:15], v[14:15], v[44:45]
	v_pk_add_f32 v[16:17], v[16:17], v[46:47]
	v_pk_add_f32 v[18:19], v[18:19], v[48:49]
	v_pk_add_f32 v[12:13], v[12:13], v[50:51]
	v_pk_fma_f32 v[36:37], v[34:35], v[14:15], v[44:45] op_sel_hi:[0,1,1] neg_lo:[0,0,1] neg_hi:[0,0,1]
	v_pk_fma_f32 v[38:39], v[34:35], v[16:17], v[46:47] op_sel_hi:[0,1,1] neg_lo:[0,0,1] neg_hi:[0,0,1]
	v_pk_fma_f32 v[40:41], v[34:35], v[18:19], v[48:49] op_sel_hi:[0,1,1] neg_lo:[0,0,1] neg_hi:[0,0,1]
	v_pk_fma_f32 v[42:43], v[34:35], v[12:13], v[50:51] op_sel_hi:[0,1,1] neg_lo:[0,0,1] neg_hi:[0,0,1]
	v_cvt_pk_bf16_f32 v28, v36, v37
	v_cvt_pk_bf16_f32 v29, v38, v39
	v_cvt_pk_bf16_f32 v30, v40, v41
	v_cvt_pk_bf16_f32 v31, v42, v43
	global_store_dwordx4 v[10:11], v[28:31], off
	v_lshl_add_u64 v[10:11], v[10:11], 0, s[26:27]
	v_mov_b32_e32 v34, 0x3eaaaaab
	v_lshlrev_b32_e32 v44, 16, v132
	v_and_b32_e32 v45, 0xffff0000, v132
	v_lshlrev_b32_e32 v46, 16, v133
	v_and_b32_e32 v47, 0xffff0000, v133
	v_lshlrev_b32_e32 v48, 16, v134
	v_and_b32_e32 v49, 0xffff0000, v134
	v_lshlrev_b32_e32 v50, 16, v135
	v_and_b32_e32 v51, 0xffff0000, v135
	v_pk_add_f32 v[14:15], v[14:15], v[44:45]
	v_pk_add_f32 v[16:17], v[16:17], v[46:47]
	v_pk_add_f32 v[18:19], v[18:19], v[48:49]
	v_pk_add_f32 v[12:13], v[12:13], v[50:51]
	v_pk_fma_f32 v[36:37], v[34:35], v[14:15], v[44:45] op_sel_hi:[0,1,1] neg_lo:[0,0,1] neg_hi:[0,0,1]
	v_pk_fma_f32 v[38:39], v[34:35], v[16:17], v[46:47] op_sel_hi:[0,1,1] neg_lo:[0,0,1] neg_hi:[0,0,1]
	v_pk_fma_f32 v[40:41], v[34:35], v[18:19], v[48:49] op_sel_hi:[0,1,1] neg_lo:[0,0,1] neg_hi:[0,0,1]
	v_pk_fma_f32 v[42:43], v[34:35], v[12:13], v[50:51] op_sel_hi:[0,1,1] neg_lo:[0,0,1] neg_hi:[0,0,1]
	v_cvt_pk_bf16_f32 v28, v36, v37
	v_cvt_pk_bf16_f32 v29, v38, v39
	v_cvt_pk_bf16_f32 v30, v40, v41
	v_cvt_pk_bf16_f32 v31, v42, v43
	global_store_dwordx4 v[10:11], v[28:31], off
	v_lshl_add_u64 v[10:11], v[10:11], 0, s[26:27]
	v_mov_b32_e32 v34, 0x3e800000
	v_lshlrev_b32_e32 v44, 16, v136
	v_and_b32_e32 v45, 0xffff0000, v136
	v_lshlrev_b32_e32 v46, 16, v137
	v_and_b32_e32 v47, 0xffff0000, v137
	v_lshlrev_b32_e32 v48, 16, v138
	v_and_b32_e32 v49, 0xffff0000, v138
	v_lshlrev_b32_e32 v50, 16, v139
	v_and_b32_e32 v51, 0xffff0000, v139
	v_pk_add_f32 v[14:15], v[14:15], v[44:45]
	v_pk_add_f32 v[16:17], v[16:17], v[46:47]
	v_pk_add_f32 v[18:19], v[18:19], v[48:49]
	v_pk_add_f32 v[12:13], v[12:13], v[50:51]
	v_pk_fma_f32 v[36:37], v[34:35], v[14:15], v[44:45] op_sel_hi:[0,1,1] neg_lo:[0,0,1] neg_hi:[0,0,1]
	v_pk_fma_f32 v[38:39], v[34:35], v[16:17], v[46:47] op_sel_hi:[0,1,1] neg_lo:[0,0,1] neg_hi:[0,0,1]
	v_pk_fma_f32 v[40:41], v[34:35], v[18:19], v[48:49] op_sel_hi:[0,1,1] neg_lo:[0,0,1] neg_hi:[0,0,1]
	v_pk_fma_f32 v[42:43], v[34:35], v[12:13], v[50:51] op_sel_hi:[0,1,1] neg_lo:[0,0,1] neg_hi:[0,0,1]
	v_cvt_pk_bf16_f32 v28, v36, v37
	v_cvt_pk_bf16_f32 v29, v38, v39
	v_cvt_pk_bf16_f32 v30, v40, v41
	v_cvt_pk_bf16_f32 v31, v42, v43
	global_store_dwordx4 v[10:11], v[28:31], off
	v_lshlrev_b32_e32 v44, 16, v124
	v_and_b32_e32 v45, 0xffff0000, v124
	v_lshlrev_b32_e32 v46, 16, v125
	v_and_b32_e32 v47, 0xffff0000, v125
	v_lshlrev_b32_e32 v48, 16, v126
	v_and_b32_e32 v49, 0xffff0000, v126
	v_lshlrev_b32_e32 v50, 16, v127
	v_and_b32_e32 v51, 0xffff0000, v127
	v_pk_add_f32 v[14:15], v[14:15], v[44:45] neg_lo:[0,1] neg_hi:[0,1]
	v_pk_add_f32 v[16:17], v[16:17], v[46:47] neg_lo:[0,1] neg_hi:[0,1]
	v_pk_add_f32 v[18:19], v[18:19], v[48:49] neg_lo:[0,1] neg_hi:[0,1]
	v_pk_add_f32 v[12:13], v[12:13], v[50:51] neg_lo:[0,1] neg_hi:[0,1]
	v_lshl_add_u64 v[10:11], v[10:11], 0, s[26:27]
	v_lshlrev_b32_e32 v44, 16, v140
	v_and_b32_e32 v45, 0xffff0000, v140
	v_lshlrev_b32_e32 v46, 16, v141
	v_and_b32_e32 v47, 0xffff0000, v141
	v_lshlrev_b32_e32 v48, 16, v142
	v_and_b32_e32 v49, 0xffff0000, v142
	v_lshlrev_b32_e32 v50, 16, v143
	v_and_b32_e32 v51, 0xffff0000, v143
	v_pk_add_f32 v[14:15], v[14:15], v[44:45]
	v_pk_add_f32 v[16:17], v[16:17], v[46:47]
	v_pk_add_f32 v[18:19], v[18:19], v[48:49]
	v_pk_add_f32 v[12:13], v[12:13], v[50:51]
	v_pk_fma_f32 v[36:37], v[34:35], v[14:15], v[44:45] op_sel_hi:[0,1,1] neg_lo:[0,0,1] neg_hi:[0,0,1]
; __device__ __forceinline__ unsigned pk2(float lo, float hi) { f32x2 v = {lo, hi}; bf16x2_t b = __builtin_convertvector(v, bf16x2_t); return __builtin_bit_cast(unsigned, b); }
; __device__ __forceinline__ void pool_window(const bf16_t* __restrict__ U  , bf16_t* __restrict__ A3, const int gtid, const int nthr) {
;     ...
;         for (int i = 0; i < 32; ++i) {
;             const int t = t0 + i, s = s0 + i;
;             const u32x4 uu = *(const u32x4*)(U + (size_t)t * LDU + c);
;             float cu[8] = {bflo(uu.x), bfhi(uu.x), bflo(uu.y), bfhi(uu.y), bflo(uu.z), bfhi(uu.z), bflo(uu.w), bfhi(uu.w)};
;             const float rc = 1.0f / (float)((s + 1) < w ? (s + 1) : w);
;             float o[8];
; #pragma unroll
;             for (int e = 0; e < 8; ++e) { sum[e] += cu[e]; o[e] = sum[e] * rc - cu[e]; }
;             u32x4 ww; ww.x = pk2(o[0], o[1]); ww.y = pk2(o[2], o[3]); ww.z = pk2(o[4], o[5]); ww.w = pk2(o[6], o[7]);
;             *(u32x4*)(A3 + (size_t)t * DM + c) = ww;
;             if (s + 1 >= w) { const u32x4 ud = *(const u32x4*)(U + (size_t)(t - w + 1) * LDU + c);
;                 sum[0] -= bflo(ud.x); sum[1] -= bfhi(ud.x); sum[2] -= bflo(ud.y); sum[3] -= bfhi(ud.y); sum[4] -= bflo(ud.z); sum[5] -= bfhi(ud.z); sum[6] -= bflo(ud.w); sum[7] -= bfhi(ud.w); }
	v_pk_fma_f32 v[38:39], v[34:35], v[16:17], v[46:47] op_sel_hi:[0,1,1] neg_lo:[0,0,1] neg_hi:[0,0,1]
	v_pk_fma_f32 v[40:41], v[34:35], v[18:19], v[48:49] op_sel_hi:[0,1,1] neg_lo:[0,0,1] neg_hi:[0,0,1]
	v_pk_fma_f32 v[42:43], v[34:35], v[12:13], v[50:51] op_sel_hi:[0,1,1] neg_lo:[0,0,1] neg_hi:[0,0,1]
	v_cvt_pk_bf16_f32 v28, v36, v37
	v_cvt_pk_bf16_f32 v29, v38, v39
	v_cvt_pk_bf16_f32 v30, v40, v41
	v_cvt_pk_bf16_f32 v31, v42, v43
	global_store_dwordx4 v[10:11], v[28:31], off
	v_lshlrev_b32_e32 v44, 16, v128
	v_and_b32_e32 v45, 0xffff0000, v128
	v_lshlrev_b32_e32 v46, 16, v129
	v_and_b32_e32 v47, 0xffff0000, v129
	v_lshlrev_b32_e32 v48, 16, v130
	v_and_b32_e32 v49, 0xffff0000, v130
	v_lshlrev_b32_e32 v50, 16, v131
	v_and_b32_e32 v51, 0xffff0000, v131
	v_pk_add_f32 v[14:15], v[14:15], v[44:45] neg_lo:[0,1] neg_hi:[0,1]
	v_pk_add_f32 v[16:17], v[16:17], v[46:47] neg_lo:[0,1] neg_hi:[0,1]
	v_pk_add_f32 v[18:19], v[18:19], v[48:49] neg_lo:[0,1] neg_hi:[0,1]
	v_pk_add_f32 v[12:13], v[12:13], v[50:51] neg_lo:[0,1] neg_hi:[0,1]
	v_lshl_add_u64 v[10:11], v[10:11], 0, s[26:27]
	v_lshlrev_b32_e32 v44, 16, v144
	v_and_b32_e32 v45, 0xffff0000, v144
	v_lshlrev_b32_e32 v46, 16, v145
	v_and_b32_e32 v47, 0xffff0000, v145
	v_lshlrev_b32_e32 v48, 16, v146
	v_and_b32_e32 v49, 0xffff0000, v146
	v_lshlrev_b32_e32 v50, 16, v147
	v_and_b32_e32 v51, 0xffff0000, v147
	v_pk_add_f32 v[14:15], v[14:15], v[44:45]
	v_pk_add_f32 v[16:17], v[16:17], v[46:47]
	v_pk_add_f32 v[18:19], v[18:19], v[48:49]
	v_pk_add_f32 v[12:13], v[12:13], v[50:51]
	v_pk_fma_f32 v[36:37], v[34:35], v[14:15], v[44:45] op_sel_hi:[0,1,1] neg_lo:[0,0,1] neg_hi:[0,0,1]
	v_pk_fma_f32 v[38:39], v[34:35], v[16:17], v[46:47] op_sel_hi:[0,1,1] neg_lo:[0,0,1] neg_hi:[0,0,1]
	v_pk_fma_f32 v[40:41], v[34:35], v[18:19], v[48:49] op_sel_hi:[0,1,1] neg_lo:[0,0,1] neg_hi:[0,0,1]
	v_pk_fma_f32 v[42:43], v[34:35], v[12:13], v[50:51] op_sel_hi:[0,1,1] neg_lo:[0,0,1] neg_hi:[0,0,1]
	v_cvt_pk_bf16_f32 v28, v36, v37
	v_cvt_pk_bf16_f32 v29, v38, v39
	v_cvt_pk_bf16_f32 v30, v40, v41
	v_cvt_pk_bf16_f32 v31, v42, v43
	global_store_dwordx4 v[10:11], v[28:31], off
	v_lshlrev_b32_e32 v44, 16, v132
	v_and_b32_e32 v45, 0xffff0000, v132
	v_lshlrev_b32_e32 v46, 16, v133
	v_and_b32_e32 v47, 0xffff0000, v133
	v_lshlrev_b32_e32 v48, 16, v134
	v_and_b32_e32 v49, 0xffff0000, v134
	v_lshlrev_b32_e32 v50, 16, v135
	v_and_b32_e32 v51, 0xffff0000, v135
	v_pk_add_f32 v[14:15], v[14:15], v[44:45] neg_lo:[0,1] neg_hi:[0,1]
	v_pk_add_f32 v[16:17], v[16:17], v[46:47] neg_lo:[0,1] neg_hi:[0,1]
	v_pk_add_f32 v[18:19], v[18:19], v[48:49] neg_lo:[0,1] neg_hi:[0,1]
	v_pk_add_f32 v[12:13], v[12:13], v[50:51] neg_lo:[0,1] neg_hi:[0,1]
	v_lshl_add_u64 v[10:11], v[10:11], 0, s[26:27]
	v_lshlrev_b32_e32 v44, 16, v148
	v_and_b32_e32 v45, 0xffff0000, v148
	v_lshlrev_b32_e32 v46, 16, v149
	v_and_b32_e32 v47, 0xffff0000, v149
	v_lshlrev_b32_e32 v48, 16, v150
	v_and_b32_e32 v49, 0xffff0000, v150
	v_lshlrev_b32_e32 v50, 16, v151
	v_and_b32_e32 v51, 0xffff0000, v151
	v_pk_add_f32 v[14:15], v[14:15], v[44:45]
	v_pk_add_f32 v[16:17], v[16:17], v[46:47]
	v_pk_add_f32 v[18:19], v[18:19], v[48:49]
	v_pk_add_f32 v[12:13], v[12:13], v[50:51]
	v_pk_fma_f32 v[36:37], v[34:35], v[14:15], v[44:45] op_sel_hi:[0,1,1] neg_lo:[0,0,1] neg_hi:[0,0,1]
	v_pk_fma_f32 v[38:39], v[34:35], v[16:17], v[46:47] op_sel_hi:[0,1,1] neg_lo:[0,0,1] neg_hi:[0,0,1]
	v_pk_fma_f32 v[40:41], v[34:35], v[18:19], v[48:49] op_sel_hi:[0,1,1] neg_lo:[0,0,1] neg_hi:[0,0,1]
	v_pk_fma_f32 v[42:43], v[34:35], v[12:13], v[50:51] op_sel_hi:[0,1,1] neg_lo:[0,0,1] neg_hi:[0,0,1]
	v_cvt_pk_bf16_f32 v28, v36, v37
	v_cvt_pk_bf16_f32 v29, v38, v39
	v_cvt_pk_bf16_f32 v30, v40, v41
	v_cvt_pk_bf16_f32 v31, v42, v43
	global_store_dwordx4 v[10:11], v[28:31], off
	v_lshlrev_b32_e32 v44, 16, v136
	v_and_b32_e32 v45, 0xffff0000, v136
	v_lshlrev_b32_e32 v46, 16, v137
	v_and_b32_e32 v47, 0xffff0000, v137
	v_lshlrev_b32_e32 v48, 16, v138
	v_and_b32_e32 v49, 0xffff0000, v138
	v_lshlrev_b32_e32 v50, 16, v139
	v_and_b32_e32 v51, 0xffff0000, v139
	v_pk_add_f32 v[14:15], v[14:15], v[44:45] neg_lo:[0,1] neg_hi:[0,1]
	v_pk_add_f32 v[16:17], v[16:17], v[46:47] neg_lo:[0,1] neg_hi:[0,1]
	v_pk_add_f32 v[18:19], v[18:19], v[48:49] neg_lo:[0,1] neg_hi:[0,1]
	v_pk_add_f32 v[12:13], v[12:13], v[50:51] neg_lo:[0,1] neg_hi:[0,1]
	v_lshl_add_u64 v[10:11], v[10:11], 0, s[26:27]
	v_lshlrev_b32_e32 v44, 16, v152
	v_and_b32_e32 v45, 0xffff0000, v152
	v_lshlrev_b32_e32 v46, 16, v153
	v_and_b32_e32 v47, 0xffff0000, v153
	v_lshlrev_b32_e32 v48, 16, v154
	v_and_b32_e32 v49, 0xffff0000, v154
	v_lshlrev_b32_e32 v50, 16, v155
	v_and_b32_e32 v51, 0xffff0000, v155
	v_pk_add_f32 v[14:15], v[14:15], v[44:45]
	v_pk_add_f32 v[16:17], v[16:17], v[46:47]
	v_pk_add_f32 v[18:19], v[18:19], v[48:49]
	v_pk_add_f32 v[12:13], v[12:13], v[50:51]
	v_pk_fma_f32 v[36:37], v[34:35], v[14:15], v[44:45] op_sel_hi:[0,1,1] neg_lo:[0,0,1] neg_hi:[0,0,1]
	v_pk_fma_f32 v[38:39], v[34:35], v[16:17], v[46:47] op_sel_hi:[0,1,1] neg_lo:[0,0,1] neg_hi:[0,0,1]
	v_pk_fma_f32 v[40:41], v[34:35], v[18:19], v[48:49] op_sel_hi:[0,1,1] neg_lo:[0,0,1] neg_hi:[0,0,1]
	v_pk_fma_f32 v[42:43], v[34:35], v[12:13], v[50:51] op_sel_hi:[0,1,1] neg_lo:[0,0,1] neg_hi:[0,0,1]
	v_cvt_pk_bf16_f32 v28, v36, v37
	v_cvt_pk_bf16_f32 v29, v38, v39
	v_cvt_pk_bf16_f32 v30, v40, v41
	v_cvt_pk_bf16_f32 v31, v42, v43
	global_store_dwordx4 v[10:11], v[28:31], off
	v_lshlrev_b32_e32 v44, 16, v140
	v_and_b32_e32 v45, 0xffff0000, v140
	v_lshlrev_b32_e32 v46, 16, v141
	v_and_b32_e32 v47, 0xffff0000, v141
	v_lshlrev_b32_e32 v48, 16, v142
	v_and_b32_e32 v49, 0xffff0000, v142
	v_lshlrev_b32_e32 v50, 16, v143
; __device__ __forceinline__ unsigned pk2(float lo, float hi) { f32x2 v = {lo, hi}; bf16x2_t b = __builtin_convertvector(v, bf16x2_t); return __builtin_bit_cast(unsigned, b); }
; __device__ __forceinline__ void pool_window(const bf16_t* __restrict__ U  , bf16_t* __restrict__ A3, const int gtid, const int nthr) {
;     ...
;         for (int i = 0; i < 32; ++i) {
;             const int t = t0 + i, s = s0 + i;
;             const u32x4 uu = *(const u32x4*)(U + (size_t)t * LDU + c);
;             float cu[8] = {bflo(uu.x), bfhi(uu.x), bflo(uu.y), bfhi(uu.y), bflo(uu.z), bfhi(uu.z), bflo(uu.w), bfhi(uu.w)};
;             const float rc = 1.0f / (float)((s + 1) < w ? (s + 1) : w);
;             float o[8];
; #pragma unroll
;             for (int e = 0; e < 8; ++e) { sum[e] += cu[e]; o[e] = sum[e] * rc - cu[e]; }
;             u32x4 ww; ww.x = pk2(o[0], o[1]); ww.y = pk2(o[2], o[3]); ww.z = pk2(o[4], o[5]); ww.w = pk2(o[6], o[7]);
;             *(u32x4*)(A3 + (size_t)t * DM + c) = ww;
;             if (s + 1 >= w) { const u32x4 ud = *(const u32x4*)(U + (size_t)(t - w + 1) * LDU + c);
;                 sum[0] -= bflo(ud.x); sum[1] -= bfhi(ud.x); sum[2] -= bflo(ud.y); sum[3] -= bfhi(ud.y); sum[4] -= bflo(ud.z); sum[5] -= bfhi(ud.z); sum[6] -= bflo(ud.w); sum[7] -= bfhi(ud.w); }
	v_and_b32_e32 v51, 0xffff0000, v143
	v_pk_add_f32 v[14:15], v[14:15], v[44:45] neg_lo:[0,1] neg_hi:[0,1]
	v_pk_add_f32 v[16:17], v[16:17], v[46:47] neg_lo:[0,1] neg_hi:[0,1]
	v_pk_add_f32 v[18:19], v[18:19], v[48:49] neg_lo:[0,1] neg_hi:[0,1]
	v_pk_add_f32 v[12:13], v[12:13], v[50:51] neg_lo:[0,1] neg_hi:[0,1]
	v_lshl_add_u64 v[10:11], v[10:11], 0, s[26:27]
	v_lshlrev_b32_e32 v44, 16, v156
	v_and_b32_e32 v45, 0xffff0000, v156
	v_lshlrev_b32_e32 v46, 16, v157
	v_and_b32_e32 v47, 0xffff0000, v157
	v_lshlrev_b32_e32 v48, 16, v158
	v_and_b32_e32 v49, 0xffff0000, v158
	v_lshlrev_b32_e32 v50, 16, v159
	v_and_b32_e32 v51, 0xffff0000, v159
	v_pk_add_f32 v[14:15], v[14:15], v[44:45]
	v_pk_add_f32 v[16:17], v[16:17], v[46:47]
	v_pk_add_f32 v[18:19], v[18:19], v[48:49]
	v_pk_add_f32 v[12:13], v[12:13], v[50:51]
	v_pk_fma_f32 v[36:37], v[34:35], v[14:15], v[44:45] op_sel_hi:[0,1,1] neg_lo:[0,0,1] neg_hi:[0,0,1]
	v_pk_fma_f32 v[38:39], v[34:35], v[16:17], v[46:47] op_sel_hi:[0,1,1] neg_lo:[0,0,1] neg_hi:[0,0,1]
	v_pk_fma_f32 v[40:41], v[34:35], v[18:19], v[48:49] op_sel_hi:[0,1,1] neg_lo:[0,0,1] neg_hi:[0,0,1]
	v_pk_fma_f32 v[42:43], v[34:35], v[12:13], v[50:51] op_sel_hi:[0,1,1] neg_lo:[0,0,1] neg_hi:[0,0,1]
	v_cvt_pk_bf16_f32 v28, v36, v37
	v_cvt_pk_bf16_f32 v29, v38, v39
	v_cvt_pk_bf16_f32 v30, v40, v41
	v_cvt_pk_bf16_f32 v31, v42, v43
	global_store_dwordx4 v[10:11], v[28:31], off
	v_lshlrev_b32_e32 v44, 16, v144
	v_and_b32_e32 v45, 0xffff0000, v144
	v_lshlrev_b32_e32 v46, 16, v145
	v_and_b32_e32 v47, 0xffff0000, v145
	v_lshlrev_b32_e32 v48, 16, v146
	v_and_b32_e32 v49, 0xffff0000, v146
	v_lshlrev_b32_e32 v50, 16, v147
	v_and_b32_e32 v51, 0xffff0000, v147
	v_pk_add_f32 v[14:15], v[14:15], v[44:45] neg_lo:[0,1] neg_hi:[0,1]
	v_pk_add_f32 v[16:17], v[16:17], v[46:47] neg_lo:[0,1] neg_hi:[0,1]
	v_pk_add_f32 v[18:19], v[18:19], v[48:49] neg_lo:[0,1] neg_hi:[0,1]
	v_pk_add_f32 v[12:13], v[12:13], v[50:51] neg_lo:[0,1] neg_hi:[0,1]
	v_lshl_add_u64 v[10:11], v[10:11], 0, s[26:27]
	v_lshlrev_b32_e32 v44, 16, v160
	v_and_b32_e32 v45, 0xffff0000, v160
	v_lshlrev_b32_e32 v46, 16, v161
	v_and_b32_e32 v47, 0xffff0000, v161
	v_lshlrev_b32_e32 v48, 16, v162
	v_and_b32_e32 v49, 0xffff0000, v162
	v_lshlrev_b32_e32 v50, 16, v163
	v_and_b32_e32 v51, 0xffff0000, v163
	v_pk_add_f32 v[14:15], v[14:15], v[44:45]
	v_pk_add_f32 v[16:17], v[16:17], v[46:47]
	v_pk_add_f32 v[18:19], v[18:19], v[48:49]
	v_pk_add_f32 v[12:13], v[12:13], v[50:51]
	v_pk_fma_f32 v[36:37], v[34:35], v[14:15], v[44:45] op_sel_hi:[0,1,1] neg_lo:[0,0,1] neg_hi:[0,0,1]
	v_pk_fma_f32 v[38:39], v[34:35], v[16:17], v[46:47] op_sel_hi:[0,1,1] neg_lo:[0,0,1] neg_hi:[0,0,1]
	v_pk_fma_f32 v[40:41], v[34:35], v[18:19], v[48:49] op_sel_hi:[0,1,1] neg_lo:[0,0,1] neg_hi:[0,0,1]
	v_pk_fma_f32 v[42:43], v[34:35], v[12:13], v[50:51] op_sel_hi:[0,1,1] neg_lo:[0,0,1] neg_hi:[0,0,1]
	v_cvt_pk_bf16_f32 v28, v36, v37
	v_cvt_pk_bf16_f32 v29, v38, v39
	v_cvt_pk_bf16_f32 v30, v40, v41
	v_cvt_pk_bf16_f32 v31, v42, v43
	global_store_dwordx4 v[10:11], v[28:31], off
	v_lshlrev_b32_e32 v44, 16, v148
	v_and_b32_e32 v45, 0xffff0000, v148
	v_lshlrev_b32_e32 v46, 16, v149
	v_and_b32_e32 v47, 0xffff0000, v149
	v_lshlrev_b32_e32 v48, 16, v150
	v_and_b32_e32 v49, 0xffff0000, v150
	v_lshlrev_b32_e32 v50, 16, v151
	v_and_b32_e32 v51, 0xffff0000, v151
	v_pk_add_f32 v[14:15], v[14:15], v[44:45] neg_lo:[0,1] neg_hi:[0,1]
	v_pk_add_f32 v[16:17], v[16:17], v[46:47] neg_lo:[0,1] neg_hi:[0,1]
	v_pk_add_f32 v[18:19], v[18:19], v[48:49] neg_lo:[0,1] neg_hi:[0,1]
	v_pk_add_f32 v[12:13], v[12:13], v[50:51] neg_lo:[0,1] neg_hi:[0,1]
	v_lshl_add_u64 v[10:11], v[10:11], 0, s[26:27]
	v_lshlrev_b32_e32 v44, 16, v164
	v_and_b32_e32 v45, 0xffff0000, v164
	v_lshlrev_b32_e32 v46, 16, v165
	v_and_b32_e32 v47, 0xffff0000, v165
	v_lshlrev_b32_e32 v48, 16, v166
	v_and_b32_e32 v49, 0xffff0000, v166
	v_lshlrev_b32_e32 v50, 16, v167
	v_and_b32_e32 v51, 0xffff0000, v167
	v_pk_add_f32 v[14:15], v[14:15], v[44:45]
	v_pk_add_f32 v[16:17], v[16:17], v[46:47]
	v_pk_add_f32 v[18:19], v[18:19], v[48:49]
	v_pk_add_f32 v[12:13], v[12:13], v[50:51]
	v_pk_fma_f32 v[36:37], v[34:35], v[14:15], v[44:45] op_sel_hi:[0,1,1] neg_lo:[0,0,1] neg_hi:[0,0,1]
	v_pk_fma_f32 v[38:39], v[34:35], v[16:17], v[46:47] op_sel_hi:[0,1,1] neg_lo:[0,0,1] neg_hi:[0,0,1]
	v_pk_fma_f32 v[40:41], v[34:35], v[18:19], v[48:49] op_sel_hi:[0,1,1] neg_lo:[0,0,1] neg_hi:[0,0,1]
	v_pk_fma_f32 v[42:43], v[34:35], v[12:13], v[50:51] op_sel_hi:[0,1,1] neg_lo:[0,0,1] neg_hi:[0,0,1]
	v_cvt_pk_bf16_f32 v28, v36, v37
	v_cvt_pk_bf16_f32 v29, v38, v39
	v_cvt_pk_bf16_f32 v30, v40, v41
	v_cvt_pk_bf16_f32 v31, v42, v43
	global_store_dwordx4 v[10:11], v[28:31], off
	v_lshlrev_b32_e32 v44, 16, v152
	v_and_b32_e32 v45, 0xffff0000, v152
	v_lshlrev_b32_e32 v46, 16, v153
	v_and_b32_e32 v47, 0xffff0000, v153
	v_lshlrev_b32_e32 v48, 16, v154
	v_and_b32_e32 v49, 0xffff0000, v154
	v_lshlrev_b32_e32 v50, 16, v155
	v_and_b32_e32 v51, 0xffff0000, v155
	v_pk_add_f32 v[14:15], v[14:15], v[44:45] neg_lo:[0,1] neg_hi:[0,1]
	v_pk_add_f32 v[16:17], v[16:17], v[46:47] neg_lo:[0,1] neg_hi:[0,1]
	v_pk_add_f32 v[18:19], v[18:19], v[48:49] neg_lo:[0,1] neg_hi:[0,1]
	v_pk_add_f32 v[12:13], v[12:13], v[50:51] neg_lo:[0,1] neg_hi:[0,1]
	v_lshl_add_u64 v[10:11], v[10:11], 0, s[26:27]
	v_lshlrev_b32_e32 v44, 16, v168
	v_and_b32_e32 v45, 0xffff0000, v168
	v_lshlrev_b32_e32 v46, 16, v169
	v_and_b32_e32 v47, 0xffff0000, v169
	v_lshlrev_b32_e32 v48, 16, v170
	v_and_b32_e32 v49, 0xffff0000, v170
	v_lshlrev_b32_e32 v50, 16, v171
	v_and_b32_e32 v51, 0xffff0000, v171
	v_pk_add_f32 v[14:15], v[14:15], v[44:45]
	v_pk_add_f32 v[16:17], v[16:17], v[46:47]
; __device__ __forceinline__ unsigned pk2(float lo, float hi) { f32x2 v = {lo, hi}; bf16x2_t b = __builtin_convertvector(v, bf16x2_t); return __builtin_bit_cast(unsigned, b); }
; __device__ __forceinline__ void pool_window(const bf16_t* __restrict__ U  , bf16_t* __restrict__ A3, const int gtid, const int nthr) {
;     ...
;         for (int i = 0; i < 32; ++i) {
;             const int t = t0 + i, s = s0 + i;
;             const u32x4 uu = *(const u32x4*)(U + (size_t)t * LDU + c);
;             float cu[8] = {bflo(uu.x), bfhi(uu.x), bflo(uu.y), bfhi(uu.y), bflo(uu.z), bfhi(uu.z), bflo(uu.w), bfhi(uu.w)};
;             const float rc = 1.0f / (float)((s + 1) < w ? (s + 1) : w);
;             float o[8];
; #pragma unroll
;             for (int e = 0; e < 8; ++e) { sum[e] += cu[e]; o[e] = sum[e] * rc - cu[e]; }
;             u32x4 ww; ww.x = pk2(o[0], o[1]); ww.y = pk2(o[2], o[3]); ww.z = pk2(o[4], o[5]); ww.w = pk2(o[6], o[7]);
;             *(u32x4*)(A3 + (size_t)t * DM + c) = ww;
;             if (s + 1 >= w) { const u32x4 ud = *(const u32x4*)(U + (size_t)(t - w + 1) * LDU + c);
;                 sum[0] -= bflo(ud.x); sum[1] -= bfhi(ud.x); sum[2] -= bflo(ud.y); sum[3] -= bfhi(ud.y); sum[4] -= bflo(ud.z); sum[5] -= bfhi(ud.z); sum[6] -= bflo(ud.w); sum[7] -= bfhi(ud.w); }
	v_pk_add_f32 v[18:19], v[18:19], v[48:49]
	v_pk_add_f32 v[12:13], v[12:13], v[50:51]
	v_pk_fma_f32 v[36:37], v[34:35], v[14:15], v[44:45] op_sel_hi:[0,1,1] neg_lo:[0,0,1] neg_hi:[0,0,1]
	v_pk_fma_f32 v[38:39], v[34:35], v[16:17], v[46:47] op_sel_hi:[0,1,1] neg_lo:[0,0,1] neg_hi:[0,0,1]
	v_pk_fma_f32 v[40:41], v[34:35], v[18:19], v[48:49] op_sel_hi:[0,1,1] neg_lo:[0,0,1] neg_hi:[0,0,1]
	v_pk_fma_f32 v[42:43], v[34:35], v[12:13], v[50:51] op_sel_hi:[0,1,1] neg_lo:[0,0,1] neg_hi:[0,0,1]
	v_cvt_pk_bf16_f32 v28, v36, v37
	v_cvt_pk_bf16_f32 v29, v38, v39
	v_cvt_pk_bf16_f32 v30, v40, v41
	v_cvt_pk_bf16_f32 v31, v42, v43
	global_store_dwordx4 v[10:11], v[28:31], off
	v_lshlrev_b32_e32 v44, 16, v156
	v_and_b32_e32 v45, 0xffff0000, v156
	v_lshlrev_b32_e32 v46, 16, v157
	v_and_b32_e32 v47, 0xffff0000, v157
	v_lshlrev_b32_e32 v48, 16, v158
	v_and_b32_e32 v49, 0xffff0000, v158
	v_lshlrev_b32_e32 v50, 16, v159
	v_and_b32_e32 v51, 0xffff0000, v159
	v_pk_add_f32 v[14:15], v[14:15], v[44:45] neg_lo:[0,1] neg_hi:[0,1]
	v_pk_add_f32 v[16:17], v[16:17], v[46:47] neg_lo:[0,1] neg_hi:[0,1]
	v_pk_add_f32 v[18:19], v[18:19], v[48:49] neg_lo:[0,1] neg_hi:[0,1]
	v_pk_add_f32 v[12:13], v[12:13], v[50:51] neg_lo:[0,1] neg_hi:[0,1]
	v_lshl_add_u64 v[10:11], v[10:11], 0, s[26:27]
	v_lshlrev_b32_e32 v44, 16, v172
	v_and_b32_e32 v45, 0xffff0000, v172
	v_lshlrev_b32_e32 v46, 16, v173
	v_and_b32_e32 v47, 0xffff0000, v173
	v_lshlrev_b32_e32 v48, 16, v174
	v_and_b32_e32 v49, 0xffff0000, v174
	v_lshlrev_b32_e32 v50, 16, v175
	v_and_b32_e32 v51, 0xffff0000, v175
	v_pk_add_f32 v[14:15], v[14:15], v[44:45]
	v_pk_add_f32 v[16:17], v[16:17], v[46:47]
	v_pk_add_f32 v[18:19], v[18:19], v[48:49]
	v_pk_add_f32 v[12:13], v[12:13], v[50:51]
	v_pk_fma_f32 v[36:37], v[34:35], v[14:15], v[44:45] op_sel_hi:[0,1,1] neg_lo:[0,0,1] neg_hi:[0,0,1]
	v_pk_fma_f32 v[38:39], v[34:35], v[16:17], v[46:47] op_sel_hi:[0,1,1] neg_lo:[0,0,1] neg_hi:[0,0,1]
	v_pk_fma_f32 v[40:41], v[34:35], v[18:19], v[48:49] op_sel_hi:[0,1,1] neg_lo:[0,0,1] neg_hi:[0,0,1]
	v_pk_fma_f32 v[42:43], v[34:35], v[12:13], v[50:51] op_sel_hi:[0,1,1] neg_lo:[0,0,1] neg_hi:[0,0,1]
	v_cvt_pk_bf16_f32 v28, v36, v37
	v_cvt_pk_bf16_f32 v29, v38, v39
	v_cvt_pk_bf16_f32 v30, v40, v41
	v_cvt_pk_bf16_f32 v31, v42, v43
	global_store_dwordx4 v[10:11], v[28:31], off
	v_lshlrev_b32_e32 v44, 16, v160
	v_and_b32_e32 v45, 0xffff0000, v160
	v_lshlrev_b32_e32 v46, 16, v161
	v_and_b32_e32 v47, 0xffff0000, v161
	v_lshlrev_b32_e32 v48, 16, v162
	v_and_b32_e32 v49, 0xffff0000, v162
	v_lshlrev_b32_e32 v50, 16, v163
	v_and_b32_e32 v51, 0xffff0000, v163
	v_pk_add_f32 v[14:15], v[14:15], v[44:45] neg_lo:[0,1] neg_hi:[0,1]
	v_pk_add_f32 v[16:17], v[16:17], v[46:47] neg_lo:[0,1] neg_hi:[0,1]
	v_pk_add_f32 v[18:19], v[18:19], v[48:49] neg_lo:[0,1] neg_hi:[0,1]
	v_pk_add_f32 v[12:13], v[12:13], v[50:51] neg_lo:[0,1] neg_hi:[0,1]
	v_lshl_add_u64 v[10:11], v[10:11], 0, s[26:27]
	v_lshlrev_b32_e32 v44, 16, v176
	v_and_b32_e32 v45, 0xffff0000, v176
	v_lshlrev_b32_e32 v46, 16, v177
	v_and_b32_e32 v47, 0xffff0000, v177
	v_lshlrev_b32_e32 v48, 16, v178
	v_and_b32_e32 v49, 0xffff0000, v178
	v_lshlrev_b32_e32 v50, 16, v179
	v_and_b32_e32 v51, 0xffff0000, v179
	v_pk_add_f32 v[14:15], v[14:15], v[44:45]
	v_pk_add_f32 v[16:17], v[16:17], v[46:47]
	v_pk_add_f32 v[18:19], v[18:19], v[48:49]
	v_pk_add_f32 v[12:13], v[12:13], v[50:51]
	v_pk_fma_f32 v[36:37], v[34:35], v[14:15], v[44:45] op_sel_hi:[0,1,1] neg_lo:[0,0,1] neg_hi:[0,0,1]
	v_pk_fma_f32 v[38:39], v[34:35], v[16:17], v[46:47] op_sel_hi:[0,1,1] neg_lo:[0,0,1] neg_hi:[0,0,1]
	v_pk_fma_f32 v[40:41], v[34:35], v[18:19], v[48:49] op_sel_hi:[0,1,1] neg_lo:[0,0,1] neg_hi:[0,0,1]
	v_pk_fma_f32 v[42:43], v[34:35], v[12:13], v[50:51] op_sel_hi:[0,1,1] neg_lo:[0,0,1] neg_hi:[0,0,1]
	v_cvt_pk_bf16_f32 v28, v36, v37
	v_cvt_pk_bf16_f32 v29, v38, v39
	v_cvt_pk_bf16_f32 v30, v40, v41
	v_cvt_pk_bf16_f32 v31, v42, v43
	global_store_dwordx4 v[10:11], v[28:31], off
	v_lshlrev_b32_e32 v44, 16, v164
	v_and_b32_e32 v45, 0xffff0000, v164
	v_lshlrev_b32_e32 v46, 16, v165
	v_and_b32_e32 v47, 0xffff0000, v165
	v_lshlrev_b32_e32 v48, 16, v166
	v_and_b32_e32 v49, 0xffff0000, v166
	v_lshlrev_b32_e32 v50, 16, v167
	v_and_b32_e32 v51, 0xffff0000, v167
	v_pk_add_f32 v[14:15], v[14:15], v[44:45] neg_lo:[0,1] neg_hi:[0,1]
	v_pk_add_f32 v[16:17], v[16:17], v[46:47] neg_lo:[0,1] neg_hi:[0,1]
	v_pk_add_f32 v[18:19], v[18:19], v[48:49] neg_lo:[0,1] neg_hi:[0,1]
	v_pk_add_f32 v[12:13], v[12:13], v[50:51] neg_lo:[0,1] neg_hi:[0,1]
	v_lshl_add_u64 v[10:11], v[10:11], 0, s[26:27]
	v_lshlrev_b32_e32 v44, 16, v180
	v_and_b32_e32 v45, 0xffff0000, v180
	v_lshlrev_b32_e32 v46, 16, v181
	v_and_b32_e32 v47, 0xffff0000, v181
	v_lshlrev_b32_e32 v48, 16, v182
	v_and_b32_e32 v49, 0xffff0000, v182
	v_lshlrev_b32_e32 v50, 16, v183
	v_and_b32_e32 v51, 0xffff0000, v183
	v_pk_add_f32 v[14:15], v[14:15], v[44:45]
	v_pk_add_f32 v[16:17], v[16:17], v[46:47]
	v_pk_add_f32 v[18:19], v[18:19], v[48:49]
	v_pk_add_f32 v[12:13], v[12:13], v[50:51]
	v_pk_fma_f32 v[36:37], v[34:35], v[14:15], v[44:45] op_sel_hi:[0,1,1] neg_lo:[0,0,1] neg_hi:[0,0,1]
	v_pk_fma_f32 v[38:39], v[34:35], v[16:17], v[46:47] op_sel_hi:[0,1,1] neg_lo:[0,0,1] neg_hi:[0,0,1]
	v_pk_fma_f32 v[40:41], v[34:35], v[18:19], v[48:49] op_sel_hi:[0,1,1] neg_lo:[0,0,1] neg_hi:[0,0,1]
	v_pk_fma_f32 v[42:43], v[34:35], v[12:13], v[50:51] op_sel_hi:[0,1,1] neg_lo:[0,0,1] neg_hi:[0,0,1]
	v_cvt_pk_bf16_f32 v28, v36, v37
	v_cvt_pk_bf16_f32 v29, v38, v39
	v_cvt_pk_bf16_f32 v30, v40, v41
	v_cvt_pk_bf16_f32 v31, v42, v43
	global_store_dwordx4 v[10:11], v[28:31], off
	v_lshlrev_b32_e32 v44, 16, v168
	v_and_b32_e32 v45, 0xffff0000, v168
; __device__ __forceinline__ unsigned pk2(float lo, float hi) { f32x2 v = {lo, hi}; bf16x2_t b = __builtin_convertvector(v, bf16x2_t); return __builtin_bit_cast(unsigned, b); }
; __device__ __forceinline__ void pool_window(const bf16_t* __restrict__ U  , bf16_t* __restrict__ A3, const int gtid, const int nthr) {
;     ...
;         for (int i = 0; i < 32; ++i) {
;             const int t = t0 + i, s = s0 + i;
;             const u32x4 uu = *(const u32x4*)(U + (size_t)t * LDU + c);
;             float cu[8] = {bflo(uu.x), bfhi(uu.x), bflo(uu.y), bfhi(uu.y), bflo(uu.z), bfhi(uu.z), bflo(uu.w), bfhi(uu.w)};
;             const float rc = 1.0f / (float)((s + 1) < w ? (s + 1) : w);
;             float o[8];
; #pragma unroll
;             for (int e = 0; e < 8; ++e) { sum[e] += cu[e]; o[e] = sum[e] * rc - cu[e]; }
;             u32x4 ww; ww.x = pk2(o[0], o[1]); ww.y = pk2(o[2], o[3]); ww.z = pk2(o[4], o[5]); ww.w = pk2(o[6], o[7]);
;             *(u32x4*)(A3 + (size_t)t * DM + c) = ww;
;             if (s + 1 >= w) { const u32x4 ud = *(const u32x4*)(U + (size_t)(t - w + 1) * LDU + c);
;                 sum[0] -= bflo(ud.x); sum[1] -= bfhi(ud.x); sum[2] -= bflo(ud.y); sum[3] -= bfhi(ud.y); sum[4] -= bflo(ud.z); sum[5] -= bfhi(ud.z); sum[6] -= bflo(ud.w); sum[7] -= bfhi(ud.w); }
	v_lshlrev_b32_e32 v46, 16, v169
	v_and_b32_e32 v47, 0xffff0000, v169
	v_lshlrev_b32_e32 v48, 16, v170
	v_and_b32_e32 v49, 0xffff0000, v170
	v_lshlrev_b32_e32 v50, 16, v171
	v_and_b32_e32 v51, 0xffff0000, v171
	v_pk_add_f32 v[14:15], v[14:15], v[44:45] neg_lo:[0,1] neg_hi:[0,1]
	v_pk_add_f32 v[16:17], v[16:17], v[46:47] neg_lo:[0,1] neg_hi:[0,1]
	v_pk_add_f32 v[18:19], v[18:19], v[48:49] neg_lo:[0,1] neg_hi:[0,1]
	v_pk_add_f32 v[12:13], v[12:13], v[50:51] neg_lo:[0,1] neg_hi:[0,1]
	v_lshl_add_u64 v[10:11], v[10:11], 0, s[26:27]
	v_lshlrev_b32_e32 v44, 16, v184
	v_and_b32_e32 v45, 0xffff0000, v184
	v_lshlrev_b32_e32 v46, 16, v185
	v_and_b32_e32 v47, 0xffff0000, v185
	v_lshlrev_b32_e32 v48, 16, v186
	v_and_b32_e32 v49, 0xffff0000, v186
	v_lshlrev_b32_e32 v50, 16, v187
	v_and_b32_e32 v51, 0xffff0000, v187
	v_pk_add_f32 v[14:15], v[14:15], v[44:45]
	v_pk_add_f32 v[16:17], v[16:17], v[46:47]
	v_pk_add_f32 v[18:19], v[18:19], v[48:49]
	v_pk_add_f32 v[12:13], v[12:13], v[50:51]
	v_pk_fma_f32 v[36:37], v[34:35], v[14:15], v[44:45] op_sel_hi:[0,1,1] neg_lo:[0,0,1] neg_hi:[0,0,1]
	v_pk_fma_f32 v[38:39], v[34:35], v[16:17], v[46:47] op_sel_hi:[0,1,1] neg_lo:[0,0,1] neg_hi:[0,0,1]
	v_pk_fma_f32 v[40:41], v[34:35], v[18:19], v[48:49] op_sel_hi:[0,1,1] neg_lo:[0,0,1] neg_hi:[0,0,1]
	v_pk_fma_f32 v[42:43], v[34:35], v[12:13], v[50:51] op_sel_hi:[0,1,1] neg_lo:[0,0,1] neg_hi:[0,0,1]
	v_cvt_pk_bf16_f32 v28, v36, v37
	v_cvt_pk_bf16_f32 v29, v38, v39
	v_cvt_pk_bf16_f32 v30, v40, v41
	v_cvt_pk_bf16_f32 v31, v42, v43
	global_store_dwordx4 v[10:11], v[28:31], off
	v_lshlrev_b32_e32 v44, 16, v172
	v_and_b32_e32 v45, 0xffff0000, v172
	v_lshlrev_b32_e32 v46, 16, v173
	v_and_b32_e32 v47, 0xffff0000, v173
	v_lshlrev_b32_e32 v48, 16, v174
	v_and_b32_e32 v49, 0xffff0000, v174
	v_lshlrev_b32_e32 v50, 16, v175
	v_and_b32_e32 v51, 0xffff0000, v175
	v_pk_add_f32 v[14:15], v[14:15], v[44:45] neg_lo:[0,1] neg_hi:[0,1]
	v_pk_add_f32 v[16:17], v[16:17], v[46:47] neg_lo:[0,1] neg_hi:[0,1]
	v_pk_add_f32 v[18:19], v[18:19], v[48:49] neg_lo:[0,1] neg_hi:[0,1]
	v_pk_add_f32 v[12:13], v[12:13], v[50:51] neg_lo:[0,1] neg_hi:[0,1]
	v_lshl_add_u64 v[10:11], v[10:11], 0, s[26:27]
	v_lshlrev_b32_e32 v44, 16, v188
	v_and_b32_e32 v45, 0xffff0000, v188
	v_lshlrev_b32_e32 v46, 16, v189
	v_and_b32_e32 v47, 0xffff0000, v189
	v_lshlrev_b32_e32 v48, 16, v190
	v_and_b32_e32 v49, 0xffff0000, v190
	v_lshlrev_b32_e32 v50, 16, v191
	v_and_b32_e32 v51, 0xffff0000, v191
	v_pk_add_f32 v[14:15], v[14:15], v[44:45]
	v_pk_add_f32 v[16:17], v[16:17], v[46:47]
	v_pk_add_f32 v[18:19], v[18:19], v[48:49]
	v_pk_add_f32 v[12:13], v[12:13], v[50:51]
	v_pk_fma_f32 v[36:37], v[34:35], v[14:15], v[44:45] op_sel_hi:[0,1,1] neg_lo:[0,0,1] neg_hi:[0,0,1]
	v_pk_fma_f32 v[38:39], v[34:35], v[16:17], v[46:47] op_sel_hi:[0,1,1] neg_lo:[0,0,1] neg_hi:[0,0,1]
	v_pk_fma_f32 v[40:41], v[34:35], v[18:19], v[48:49] op_sel_hi:[0,1,1] neg_lo:[0,0,1] neg_hi:[0,0,1]
	v_pk_fma_f32 v[42:43], v[34:35], v[12:13], v[50:51] op_sel_hi:[0,1,1] neg_lo:[0,0,1] neg_hi:[0,0,1]
	v_cvt_pk_bf16_f32 v28, v36, v37
	v_cvt_pk_bf16_f32 v29, v38, v39
	v_cvt_pk_bf16_f32 v30, v40, v41
	v_cvt_pk_bf16_f32 v31, v42, v43
	global_store_dwordx4 v[10:11], v[28:31], off
	v_lshlrev_b32_e32 v44, 16, v176
	v_and_b32_e32 v45, 0xffff0000, v176
	v_lshlrev_b32_e32 v46, 16, v177
	v_and_b32_e32 v47, 0xffff0000, v177
	v_lshlrev_b32_e32 v48, 16, v178
	v_and_b32_e32 v49, 0xffff0000, v178
	v_lshlrev_b32_e32 v50, 16, v179
	v_and_b32_e32 v51, 0xffff0000, v179
	v_pk_add_f32 v[14:15], v[14:15], v[44:45] neg_lo:[0,1] neg_hi:[0,1]
	v_pk_add_f32 v[16:17], v[16:17], v[46:47] neg_lo:[0,1] neg_hi:[0,1]
	v_pk_add_f32 v[18:19], v[18:19], v[48:49] neg_lo:[0,1] neg_hi:[0,1]
	v_pk_add_f32 v[12:13], v[12:13], v[50:51] neg_lo:[0,1] neg_hi:[0,1]
	v_lshl_add_u64 v[10:11], v[10:11], 0, s[26:27]
	v_lshlrev_b32_e32 v44, 16, v192
	v_and_b32_e32 v45, 0xffff0000, v192
	v_lshlrev_b32_e32 v46, 16, v193
	v_and_b32_e32 v47, 0xffff0000, v193
	v_lshlrev_b32_e32 v48, 16, v194
	v_and_b32_e32 v49, 0xffff0000, v194
	v_lshlrev_b32_e32 v50, 16, v195
	v_and_b32_e32 v51, 0xffff0000, v195
	v_pk_add_f32 v[14:15], v[14:15], v[44:45]
	v_pk_add_f32 v[16:17], v[16:17], v[46:47]
	v_pk_add_f32 v[18:19], v[18:19], v[48:49]
	v_pk_add_f32 v[12:13], v[12:13], v[50:51]
	v_pk_fma_f32 v[36:37], v[34:35], v[14:15], v[44:45] op_sel_hi:[0,1,1] neg_lo:[0,0,1] neg_hi:[0,0,1]
	v_pk_fma_f32 v[38:39], v[34:35], v[16:17], v[46:47] op_sel_hi:[0,1,1] neg_lo:[0,0,1] neg_hi:[0,0,1]
	v_pk_fma_f32 v[40:41], v[34:35], v[18:19], v[48:49] op_sel_hi:[0,1,1] neg_lo:[0,0,1] neg_hi:[0,0,1]
	v_pk_fma_f32 v[42:43], v[34:35], v[12:13], v[50:51] op_sel_hi:[0,1,1] neg_lo:[0,0,1] neg_hi:[0,0,1]
	v_cvt_pk_bf16_f32 v28, v36, v37
	v_cvt_pk_bf16_f32 v29, v38, v39
	v_cvt_pk_bf16_f32 v30, v40, v41
	v_cvt_pk_bf16_f32 v31, v42, v43
	global_store_dwordx4 v[10:11], v[28:31], off
	v_lshlrev_b32_e32 v44, 16, v180
	v_and_b32_e32 v45, 0xffff0000, v180
	v_lshlrev_b32_e32 v46, 16, v181
	v_and_b32_e32 v47, 0xffff0000, v181
	v_lshlrev_b32_e32 v48, 16, v182
	v_and_b32_e32 v49, 0xffff0000, v182
	v_lshlrev_b32_e32 v50, 16, v183
	v_and_b32_e32 v51, 0xffff0000, v183
	v_pk_add_f32 v[14:15], v[14:15], v[44:45] neg_lo:[0,1] neg_hi:[0,1]
	v_pk_add_f32 v[16:17], v[16:17], v[46:47] neg_lo:[0,1] neg_hi:[0,1]
	v_pk_add_f32 v[18:19], v[18:19], v[48:49] neg_lo:[0,1] neg_hi:[0,1]
	v_pk_add_f32 v[12:13], v[12:13], v[50:51] neg_lo:[0,1] neg_hi:[0,1]
	v_lshl_add_u64 v[10:11], v[10:11], 0, s[26:27]
	v_lshlrev_b32_e32 v44, 16, v196
	v_and_b32_e32 v45, 0xffff0000, v196
	v_lshlrev_b32_e32 v46, 16, v197
	v_and_b32_e32 v47, 0xffff0000, v197
	v_lshlrev_b32_e32 v48, 16, v198
	v_and_b32_e32 v49, 0xffff0000, v198
; __device__ __forceinline__ unsigned pk2(float lo, float hi) { f32x2 v = {lo, hi}; bf16x2_t b = __builtin_convertvector(v, bf16x2_t); return __builtin_bit_cast(unsigned, b); }
; __device__ __forceinline__ void pool_window(const bf16_t* __restrict__ U  , bf16_t* __restrict__ A3, const int gtid, const int nthr) {
;     ...
;         for (int i = 0; i < 32; ++i) {
;             const int t = t0 + i, s = s0 + i;
;             const u32x4 uu = *(const u32x4*)(U + (size_t)t * LDU + c);
;             float cu[8] = {bflo(uu.x), bfhi(uu.x), bflo(uu.y), bfhi(uu.y), bflo(uu.z), bfhi(uu.z), bflo(uu.w), bfhi(uu.w)};
;             const float rc = 1.0f / (float)((s + 1) < w ? (s + 1) : w);
;             float o[8];
; #pragma unroll
;             for (int e = 0; e < 8; ++e) { sum[e] += cu[e]; o[e] = sum[e] * rc - cu[e]; }
;             u32x4 ww; ww.x = pk2(o[0], o[1]); ww.y = pk2(o[2], o[3]); ww.z = pk2(o[4], o[5]); ww.w = pk2(o[6], o[7]);
;             *(u32x4*)(A3 + (size_t)t * DM + c) = ww;
;             if (s + 1 >= w) { const u32x4 ud = *(const u32x4*)(U + (size_t)(t - w + 1) * LDU + c);
;                 sum[0] -= bflo(ud.x); sum[1] -= bfhi(ud.x); sum[2] -= bflo(ud.y); sum[3] -= bfhi(ud.y); sum[4] -= bflo(ud.z); sum[5] -= bfhi(ud.z); sum[6] -= bflo(ud.w); sum[7] -= bfhi(ud.w); }
	v_lshlrev_b32_e32 v50, 16, v199
	v_and_b32_e32 v51, 0xffff0000, v199
	v_pk_add_f32 v[14:15], v[14:15], v[44:45]
	v_pk_add_f32 v[16:17], v[16:17], v[46:47]
	v_pk_add_f32 v[18:19], v[18:19], v[48:49]
	v_pk_add_f32 v[12:13], v[12:13], v[50:51]
	v_pk_fma_f32 v[36:37], v[34:35], v[14:15], v[44:45] op_sel_hi:[0,1,1] neg_lo:[0,0,1] neg_hi:[0,0,1]
	v_pk_fma_f32 v[38:39], v[34:35], v[16:17], v[46:47] op_sel_hi:[0,1,1] neg_lo:[0,0,1] neg_hi:[0,0,1]
	v_pk_fma_f32 v[40:41], v[34:35], v[18:19], v[48:49] op_sel_hi:[0,1,1] neg_lo:[0,0,1] neg_hi:[0,0,1]
	v_pk_fma_f32 v[42:43], v[34:35], v[12:13], v[50:51] op_sel_hi:[0,1,1] neg_lo:[0,0,1] neg_hi:[0,0,1]
	v_cvt_pk_bf16_f32 v28, v36, v37
	v_cvt_pk_bf16_f32 v29, v38, v39
	v_cvt_pk_bf16_f32 v30, v40, v41
	v_cvt_pk_bf16_f32 v31, v42, v43
	global_store_dwordx4 v[10:11], v[28:31], off
	v_lshlrev_b32_e32 v44, 16, v184
	v_and_b32_e32 v45, 0xffff0000, v184
	v_lshlrev_b32_e32 v46, 16, v185
	v_and_b32_e32 v47, 0xffff0000, v185
	v_lshlrev_b32_e32 v48, 16, v186
	v_and_b32_e32 v49, 0xffff0000, v186
	v_lshlrev_b32_e32 v50, 16, v187
	v_and_b32_e32 v51, 0xffff0000, v187
	v_pk_add_f32 v[14:15], v[14:15], v[44:45] neg_lo:[0,1] neg_hi:[0,1]
	v_pk_add_f32 v[16:17], v[16:17], v[46:47] neg_lo:[0,1] neg_hi:[0,1]
	v_pk_add_f32 v[18:19], v[18:19], v[48:49] neg_lo:[0,1] neg_hi:[0,1]
	v_pk_add_f32 v[12:13], v[12:13], v[50:51] neg_lo:[0,1] neg_hi:[0,1]
	v_lshl_add_u64 v[10:11], v[10:11], 0, s[26:27]
	v_lshlrev_b32_e32 v44, 16, v200
	v_and_b32_e32 v45, 0xffff0000, v200
	v_lshlrev_b32_e32 v46, 16, v201
	v_and_b32_e32 v47, 0xffff0000, v201
	v_lshlrev_b32_e32 v48, 16, v202
	v_and_b32_e32 v49, 0xffff0000, v202
	v_lshlrev_b32_e32 v50, 16, v203
	v_and_b32_e32 v51, 0xffff0000, v203
	v_pk_add_f32 v[14:15], v[14:15], v[44:45]
	v_pk_add_f32 v[16:17], v[16:17], v[46:47]
	v_pk_add_f32 v[18:19], v[18:19], v[48:49]
	v_pk_add_f32 v[12:13], v[12:13], v[50:51]
	v_pk_fma_f32 v[36:37], v[34:35], v[14:15], v[44:45] op_sel_hi:[0,1,1] neg_lo:[0,0,1] neg_hi:[0,0,1]
	v_pk_fma_f32 v[38:39], v[34:35], v[16:17], v[46:47] op_sel_hi:[0,1,1] neg_lo:[0,0,1] neg_hi:[0,0,1]
	v_pk_fma_f32 v[40:41], v[34:35], v[18:19], v[48:49] op_sel_hi:[0,1,1] neg_lo:[0,0,1] neg_hi:[0,0,1]
	v_pk_fma_f32 v[42:43], v[34:35], v[12:13], v[50:51] op_sel_hi:[0,1,1] neg_lo:[0,0,1] neg_hi:[0,0,1]
	v_cvt_pk_bf16_f32 v28, v36, v37
	v_cvt_pk_bf16_f32 v29, v38, v39
	v_cvt_pk_bf16_f32 v30, v40, v41
	v_cvt_pk_bf16_f32 v31, v42, v43
	global_store_dwordx4 v[10:11], v[28:31], off
	v_lshlrev_b32_e32 v44, 16, v188
	v_and_b32_e32 v45, 0xffff0000, v188
	v_lshlrev_b32_e32 v46, 16, v189
	v_and_b32_e32 v47, 0xffff0000, v189
	v_lshlrev_b32_e32 v48, 16, v190
	v_and_b32_e32 v49, 0xffff0000, v190
	v_lshlrev_b32_e32 v50, 16, v191
	v_and_b32_e32 v51, 0xffff0000, v191
	v_pk_add_f32 v[14:15], v[14:15], v[44:45] neg_lo:[0,1] neg_hi:[0,1]
	v_pk_add_f32 v[16:17], v[16:17], v[46:47] neg_lo:[0,1] neg_hi:[0,1]
	v_pk_add_f32 v[18:19], v[18:19], v[48:49] neg_lo:[0,1] neg_hi:[0,1]
	v_pk_add_f32 v[12:13], v[12:13], v[50:51] neg_lo:[0,1] neg_hi:[0,1]
	v_lshl_add_u64 v[10:11], v[10:11], 0, s[26:27]
	v_lshlrev_b32_e32 v44, 16, v204
	v_and_b32_e32 v45, 0xffff0000, v204
	v_lshlrev_b32_e32 v46, 16, v205
	v_and_b32_e32 v47, 0xffff0000, v205
	v_lshlrev_b32_e32 v48, 16, v206
	v_and_b32_e32 v49, 0xffff0000, v206
	v_lshlrev_b32_e32 v50, 16, v207
	v_and_b32_e32 v51, 0xffff0000, v207
	v_pk_add_f32 v[14:15], v[14:15], v[44:45]
	v_pk_add_f32 v[16:17], v[16:17], v[46:47]
	v_pk_add_f32 v[18:19], v[18:19], v[48:49]
	v_pk_add_f32 v[12:13], v[12:13], v[50:51]
	v_pk_fma_f32 v[36:37], v[34:35], v[14:15], v[44:45] op_sel_hi:[0,1,1] neg_lo:[0,0,1] neg_hi:[0,0,1]
	v_pk_fma_f32 v[38:39], v[34:35], v[16:17], v[46:47] op_sel_hi:[0,1,1] neg_lo:[0,0,1] neg_hi:[0,0,1]
	v_pk_fma_f32 v[40:41], v[34:35], v[18:19], v[48:49] op_sel_hi:[0,1,1] neg_lo:[0,0,1] neg_hi:[0,0,1]
	v_pk_fma_f32 v[42:43], v[34:35], v[12:13], v[50:51] op_sel_hi:[0,1,1] neg_lo:[0,0,1] neg_hi:[0,0,1]
	v_cvt_pk_bf16_f32 v28, v36, v37
	v_cvt_pk_bf16_f32 v29, v38, v39
	v_cvt_pk_bf16_f32 v30, v40, v41
	v_cvt_pk_bf16_f32 v31, v42, v43
	global_store_dwordx4 v[10:11], v[28:31], off
	v_lshlrev_b32_e32 v44, 16, v192
	v_and_b32_e32 v45, 0xffff0000, v192
	v_lshlrev_b32_e32 v46, 16, v193
	v_and_b32_e32 v47, 0xffff0000, v193
	v_lshlrev_b32_e32 v48, 16, v194
	v_and_b32_e32 v49, 0xffff0000, v194
	v_lshlrev_b32_e32 v50, 16, v195
	v_and_b32_e32 v51, 0xffff0000, v195
	v_pk_add_f32 v[14:15], v[14:15], v[44:45] neg_lo:[0,1] neg_hi:[0,1]
	v_pk_add_f32 v[16:17], v[16:17], v[46:47] neg_lo:[0,1] neg_hi:[0,1]
	v_pk_add_f32 v[18:19], v[18:19], v[48:49] neg_lo:[0,1] neg_hi:[0,1]
	v_pk_add_f32 v[12:13], v[12:13], v[50:51] neg_lo:[0,1] neg_hi:[0,1]
	v_lshl_add_u64 v[10:11], v[10:11], 0, s[26:27]
	v_lshlrev_b32_e32 v44, 16, v208
	v_and_b32_e32 v45, 0xffff0000, v208
	v_lshlrev_b32_e32 v46, 16, v209
	v_and_b32_e32 v47, 0xffff0000, v209
	v_lshlrev_b32_e32 v48, 16, v210
	v_and_b32_e32 v49, 0xffff0000, v210
	v_lshlrev_b32_e32 v50, 16, v211
	v_and_b32_e32 v51, 0xffff0000, v211
	v_pk_add_f32 v[14:15], v[14:15], v[44:45]
	v_pk_add_f32 v[16:17], v[16:17], v[46:47]
	v_pk_add_f32 v[18:19], v[18:19], v[48:49]
	v_pk_add_f32 v[12:13], v[12:13], v[50:51]
	v_pk_fma_f32 v[36:37], v[34:35], v[14:15], v[44:45] op_sel_hi:[0,1,1] neg_lo:[0,0,1] neg_hi:[0,0,1]
	v_pk_fma_f32 v[38:39], v[34:35], v[16:17], v[46:47] op_sel_hi:[0,1,1] neg_lo:[0,0,1] neg_hi:[0,0,1]
	v_pk_fma_f32 v[40:41], v[34:35], v[18:19], v[48:49] op_sel_hi:[0,1,1] neg_lo:[0,0,1] neg_hi:[0,0,1]
	v_pk_fma_f32 v[42:43], v[34:35], v[12:13], v[50:51] op_sel_hi:[0,1,1] neg_lo:[0,0,1] neg_hi:[0,0,1]
	v_cvt_pk_bf16_f32 v28, v36, v37
	v_cvt_pk_bf16_f32 v29, v38, v39
; __device__ __forceinline__ unsigned pk2(float lo, float hi) { f32x2 v = {lo, hi}; bf16x2_t b = __builtin_convertvector(v, bf16x2_t); return __builtin_bit_cast(unsigned, b); }
; __device__ __forceinline__ void pool_window(const bf16_t* __restrict__ U  , bf16_t* __restrict__ A3, const int gtid, const int nthr) {
;     ...
;         for (int i = 0; i < 32; ++i) {
;             const int t = t0 + i, s = s0 + i;
;             const u32x4 uu = *(const u32x4*)(U + (size_t)t * LDU + c);
;             float cu[8] = {bflo(uu.x), bfhi(uu.x), bflo(uu.y), bfhi(uu.y), bflo(uu.z), bfhi(uu.z), bflo(uu.w), bfhi(uu.w)};
;             const float rc = 1.0f / (float)((s + 1) < w ? (s + 1) : w);
;             float o[8];
; #pragma unroll
;             for (int e = 0; e < 8; ++e) { sum[e] += cu[e]; o[e] = sum[e] * rc - cu[e]; }
;             u32x4 ww; ww.x = pk2(o[0], o[1]); ww.y = pk2(o[2], o[3]); ww.z = pk2(o[4], o[5]); ww.w = pk2(o[6], o[7]);
;             *(u32x4*)(A3 + (size_t)t * DM + c) = ww;
;             if (s + 1 >= w) { const u32x4 ud = *(const u32x4*)(U + (size_t)(t - w + 1) * LDU + c);
;                 sum[0] -= bflo(ud.x); sum[1] -= bfhi(ud.x); sum[2] -= bflo(ud.y); sum[3] -= bfhi(ud.y); sum[4] -= bflo(ud.z); sum[5] -= bfhi(ud.z); sum[6] -= bflo(ud.w); sum[7] -= bfhi(ud.w); }
	v_cvt_pk_bf16_f32 v30, v40, v41
	v_cvt_pk_bf16_f32 v31, v42, v43
	global_store_dwordx4 v[10:11], v[28:31], off
	v_lshlrev_b32_e32 v44, 16, v196
	v_and_b32_e32 v45, 0xffff0000, v196
	v_lshlrev_b32_e32 v46, 16, v197
	v_and_b32_e32 v47, 0xffff0000, v197
	v_lshlrev_b32_e32 v48, 16, v198
	v_and_b32_e32 v49, 0xffff0000, v198
	v_lshlrev_b32_e32 v50, 16, v199
	v_and_b32_e32 v51, 0xffff0000, v199
	v_pk_add_f32 v[14:15], v[14:15], v[44:45] neg_lo:[0,1] neg_hi:[0,1]
	v_pk_add_f32 v[16:17], v[16:17], v[46:47] neg_lo:[0,1] neg_hi:[0,1]
	v_pk_add_f32 v[18:19], v[18:19], v[48:49] neg_lo:[0,1] neg_hi:[0,1]
	v_pk_add_f32 v[12:13], v[12:13], v[50:51] neg_lo:[0,1] neg_hi:[0,1]
	v_lshl_add_u64 v[10:11], v[10:11], 0, s[26:27]
	v_lshlrev_b32_e32 v44, 16, v214
	v_and_b32_e32 v45, 0xffff0000, v214
	v_lshlrev_b32_e32 v46, 16, v215
	v_and_b32_e32 v47, 0xffff0000, v215
	v_lshlrev_b32_e32 v48, 16, v216
	v_and_b32_e32 v49, 0xffff0000, v216
	v_lshlrev_b32_e32 v50, 16, v217
	v_and_b32_e32 v51, 0xffff0000, v217
	v_pk_add_f32 v[14:15], v[14:15], v[44:45]
	v_pk_add_f32 v[16:17], v[16:17], v[46:47]
	v_pk_add_f32 v[18:19], v[18:19], v[48:49]
	v_pk_add_f32 v[12:13], v[12:13], v[50:51]
	v_pk_fma_f32 v[36:37], v[34:35], v[14:15], v[44:45] op_sel_hi:[0,1,1] neg_lo:[0,0,1] neg_hi:[0,0,1]
	v_pk_fma_f32 v[38:39], v[34:35], v[16:17], v[46:47] op_sel_hi:[0,1,1] neg_lo:[0,0,1] neg_hi:[0,0,1]
	v_pk_fma_f32 v[40:41], v[34:35], v[18:19], v[48:49] op_sel_hi:[0,1,1] neg_lo:[0,0,1] neg_hi:[0,0,1]
	v_pk_fma_f32 v[42:43], v[34:35], v[12:13], v[50:51] op_sel_hi:[0,1,1] neg_lo:[0,0,1] neg_hi:[0,0,1]
	v_cvt_pk_bf16_f32 v28, v36, v37
	v_cvt_pk_bf16_f32 v29, v38, v39
	v_cvt_pk_bf16_f32 v30, v40, v41
	v_cvt_pk_bf16_f32 v31, v42, v43
	global_store_dwordx4 v[10:11], v[28:31], off
	v_lshlrev_b32_e32 v44, 16, v200
	v_and_b32_e32 v45, 0xffff0000, v200
	v_lshlrev_b32_e32 v46, 16, v201
	v_and_b32_e32 v47, 0xffff0000, v201
	v_lshlrev_b32_e32 v48, 16, v202
	v_and_b32_e32 v49, 0xffff0000, v202
	v_lshlrev_b32_e32 v50, 16, v203
	v_and_b32_e32 v51, 0xffff0000, v203
	v_pk_add_f32 v[14:15], v[14:15], v[44:45] neg_lo:[0,1] neg_hi:[0,1]
	v_pk_add_f32 v[16:17], v[16:17], v[46:47] neg_lo:[0,1] neg_hi:[0,1]
	v_pk_add_f32 v[18:19], v[18:19], v[48:49] neg_lo:[0,1] neg_hi:[0,1]
	v_pk_add_f32 v[12:13], v[12:13], v[50:51] neg_lo:[0,1] neg_hi:[0,1]
	v_lshl_add_u64 v[10:11], v[10:11], 0, s[26:27]
	v_lshlrev_b32_e32 v44, 16, v218
	v_and_b32_e32 v45, 0xffff0000, v218
	v_lshlrev_b32_e32 v46, 16, v219
	v_and_b32_e32 v47, 0xffff0000, v219
	v_lshlrev_b32_e32 v48, 16, v220
	v_and_b32_e32 v49, 0xffff0000, v220
	v_lshlrev_b32_e32 v50, 16, v221
	v_and_b32_e32 v51, 0xffff0000, v221
	v_pk_add_f32 v[14:15], v[14:15], v[44:45]
	v_pk_add_f32 v[16:17], v[16:17], v[46:47]
	v_pk_add_f32 v[18:19], v[18:19], v[48:49]
	v_pk_add_f32 v[12:13], v[12:13], v[50:51]
	v_pk_fma_f32 v[36:37], v[34:35], v[14:15], v[44:45] op_sel_hi:[0,1,1] neg_lo:[0,0,1] neg_hi:[0,0,1]
	v_pk_fma_f32 v[38:39], v[34:35], v[16:17], v[46:47] op_sel_hi:[0,1,1] neg_lo:[0,0,1] neg_hi:[0,0,1]
	v_pk_fma_f32 v[40:41], v[34:35], v[18:19], v[48:49] op_sel_hi:[0,1,1] neg_lo:[0,0,1] neg_hi:[0,0,1]
	v_pk_fma_f32 v[42:43], v[34:35], v[12:13], v[50:51] op_sel_hi:[0,1,1] neg_lo:[0,0,1] neg_hi:[0,0,1]
	v_cvt_pk_bf16_f32 v28, v36, v37
	v_cvt_pk_bf16_f32 v29, v38, v39
	v_cvt_pk_bf16_f32 v30, v40, v41
	v_cvt_pk_bf16_f32 v31, v42, v43
	global_store_dwordx4 v[10:11], v[28:31], off
	v_lshlrev_b32_e32 v44, 16, v204
	v_and_b32_e32 v45, 0xffff0000, v204
	v_lshlrev_b32_e32 v46, 16, v205
	v_and_b32_e32 v47, 0xffff0000, v205
	v_lshlrev_b32_e32 v48, 16, v206
	v_and_b32_e32 v49, 0xffff0000, v206
	v_lshlrev_b32_e32 v50, 16, v207
	v_and_b32_e32 v51, 0xffff0000, v207
	v_pk_add_f32 v[14:15], v[14:15], v[44:45] neg_lo:[0,1] neg_hi:[0,1]
	v_pk_add_f32 v[16:17], v[16:17], v[46:47] neg_lo:[0,1] neg_hi:[0,1]
	v_pk_add_f32 v[18:19], v[18:19], v[48:49] neg_lo:[0,1] neg_hi:[0,1]
	v_pk_add_f32 v[12:13], v[12:13], v[50:51] neg_lo:[0,1] neg_hi:[0,1]
	v_lshl_add_u64 v[10:11], v[10:11], 0, s[26:27]
	v_lshlrev_b32_e32 v44, 16, v222
	v_and_b32_e32 v45, 0xffff0000, v222
	v_lshlrev_b32_e32 v46, 16, v223
	v_and_b32_e32 v47, 0xffff0000, v223
	v_lshlrev_b32_e32 v48, 16, v224
	v_and_b32_e32 v49, 0xffff0000, v224
	v_lshlrev_b32_e32 v50, 16, v225
	v_and_b32_e32 v51, 0xffff0000, v225
	v_pk_add_f32 v[14:15], v[14:15], v[44:45]
	v_pk_add_f32 v[16:17], v[16:17], v[46:47]
	v_pk_add_f32 v[18:19], v[18:19], v[48:49]
	v_pk_add_f32 v[12:13], v[12:13], v[50:51]
	v_pk_fma_f32 v[36:37], v[34:35], v[14:15], v[44:45] op_sel_hi:[0,1,1] neg_lo:[0,0,1] neg_hi:[0,0,1]
	v_pk_fma_f32 v[38:39], v[34:35], v[16:17], v[46:47] op_sel_hi:[0,1,1] neg_lo:[0,0,1] neg_hi:[0,0,1]
	v_pk_fma_f32 v[40:41], v[34:35], v[18:19], v[48:49] op_sel_hi:[0,1,1] neg_lo:[0,0,1] neg_hi:[0,0,1]
	v_pk_fma_f32 v[42:43], v[34:35], v[12:13], v[50:51] op_sel_hi:[0,1,1] neg_lo:[0,0,1] neg_hi:[0,0,1]
	v_cvt_pk_bf16_f32 v28, v36, v37
	v_cvt_pk_bf16_f32 v29, v38, v39
	v_cvt_pk_bf16_f32 v30, v40, v41
	v_cvt_pk_bf16_f32 v31, v42, v43
	global_store_dwordx4 v[10:11], v[28:31], off
	v_lshlrev_b32_e32 v44, 16, v208
	v_and_b32_e32 v45, 0xffff0000, v208
	v_lshlrev_b32_e32 v46, 16, v209
	v_and_b32_e32 v47, 0xffff0000, v209
	v_lshlrev_b32_e32 v48, 16, v210
	v_and_b32_e32 v49, 0xffff0000, v210
	v_lshlrev_b32_e32 v50, 16, v211
	v_and_b32_e32 v51, 0xffff0000, v211
	v_pk_add_f32 v[14:15], v[14:15], v[44:45] neg_lo:[0,1] neg_hi:[0,1]
	v_pk_add_f32 v[16:17], v[16:17], v[46:47] neg_lo:[0,1] neg_hi:[0,1]
	v_pk_add_f32 v[18:19], v[18:19], v[48:49] neg_lo:[0,1] neg_hi:[0,1]
	v_pk_add_f32 v[12:13], v[12:13], v[50:51] neg_lo:[0,1] neg_hi:[0,1]
	v_lshl_add_u64 v[10:11], v[10:11], 0, s[26:27]
; __device__ __forceinline__ unsigned pk2(float lo, float hi) { f32x2 v = {lo, hi}; bf16x2_t b = __builtin_convertvector(v, bf16x2_t); return __builtin_bit_cast(unsigned, b); }
; __device__ __forceinline__ void pool_window(const bf16_t* __restrict__ U  , bf16_t* __restrict__ A3, const int gtid, const int nthr) {
;     ...
;         for (int i = 0; i < 32; ++i) {
;             const int t = t0 + i, s = s0 + i;
;             const u32x4 uu = *(const u32x4*)(U + (size_t)t * LDU + c);
;             float cu[8] = {bflo(uu.x), bfhi(uu.x), bflo(uu.y), bfhi(uu.y), bflo(uu.z), bfhi(uu.z), bflo(uu.w), bfhi(uu.w)};
;             const float rc = 1.0f / (float)((s + 1) < w ? (s + 1) : w);
;             float o[8];
; #pragma unroll
;             for (int e = 0; e < 8; ++e) { sum[e] += cu[e]; o[e] = sum[e] * rc - cu[e]; }
;             u32x4 ww; ww.x = pk2(o[0], o[1]); ww.y = pk2(o[2], o[3]); ww.z = pk2(o[4], o[5]); ww.w = pk2(o[6], o[7]);
;             *(u32x4*)(A3 + (size_t)t * DM + c) = ww;
;             if (s + 1 >= w) { const u32x4 ud = *(const u32x4*)(U + (size_t)(t - w + 1) * LDU + c);
;                 sum[0] -= bflo(ud.x); sum[1] -= bfhi(ud.x); sum[2] -= bflo(ud.y); sum[3] -= bfhi(ud.y); sum[4] -= bflo(ud.z); sum[5] -= bfhi(ud.z); sum[6] -= bflo(ud.w); sum[7] -= bfhi(ud.w); }
	v_lshlrev_b32_e32 v44, 16, v226
	v_and_b32_e32 v45, 0xffff0000, v226
	v_lshlrev_b32_e32 v46, 16, v227
	v_and_b32_e32 v47, 0xffff0000, v227
	v_lshlrev_b32_e32 v48, 16, v228
	v_and_b32_e32 v49, 0xffff0000, v228
	v_lshlrev_b32_e32 v50, 16, v229
	v_and_b32_e32 v51, 0xffff0000, v229
	v_pk_add_f32 v[14:15], v[14:15], v[44:45]
	v_pk_add_f32 v[16:17], v[16:17], v[46:47]
	v_pk_add_f32 v[18:19], v[18:19], v[48:49]
	v_pk_add_f32 v[12:13], v[12:13], v[50:51]
	v_pk_fma_f32 v[36:37], v[34:35], v[14:15], v[44:45] op_sel_hi:[0,1,1] neg_lo:[0,0,1] neg_hi:[0,0,1]
	v_pk_fma_f32 v[38:39], v[34:35], v[16:17], v[46:47] op_sel_hi:[0,1,1] neg_lo:[0,0,1] neg_hi:[0,0,1]
	v_pk_fma_f32 v[40:41], v[34:35], v[18:19], v[48:49] op_sel_hi:[0,1,1] neg_lo:[0,0,1] neg_hi:[0,0,1]
	v_pk_fma_f32 v[42:43], v[34:35], v[12:13], v[50:51] op_sel_hi:[0,1,1] neg_lo:[0,0,1] neg_hi:[0,0,1]
	v_cvt_pk_bf16_f32 v28, v36, v37
	v_cvt_pk_bf16_f32 v29, v38, v39
	v_cvt_pk_bf16_f32 v30, v40, v41
	v_cvt_pk_bf16_f32 v31, v42, v43
	global_store_dwordx4 v[10:11], v[28:31], off
	v_lshlrev_b32_e32 v44, 16, v214
	v_and_b32_e32 v45, 0xffff0000, v214
	v_lshlrev_b32_e32 v46, 16, v215
	v_and_b32_e32 v47, 0xffff0000, v215
	v_lshlrev_b32_e32 v48, 16, v216
	v_and_b32_e32 v49, 0xffff0000, v216
	v_lshlrev_b32_e32 v50, 16, v217
	v_and_b32_e32 v51, 0xffff0000, v217
	v_pk_add_f32 v[14:15], v[14:15], v[44:45] neg_lo:[0,1] neg_hi:[0,1]
	v_pk_add_f32 v[16:17], v[16:17], v[46:47] neg_lo:[0,1] neg_hi:[0,1]
	v_pk_add_f32 v[18:19], v[18:19], v[48:49] neg_lo:[0,1] neg_hi:[0,1]
	v_pk_add_f32 v[12:13], v[12:13], v[50:51] neg_lo:[0,1] neg_hi:[0,1]
	v_lshl_add_u64 v[10:11], v[10:11], 0, s[26:27]
	v_lshlrev_b32_e32 v44, 16, v230
	v_and_b32_e32 v45, 0xffff0000, v230
	v_lshlrev_b32_e32 v46, 16, v231
	v_and_b32_e32 v47, 0xffff0000, v231
	v_lshlrev_b32_e32 v48, 16, v232
	v_and_b32_e32 v49, 0xffff0000, v232
	v_lshlrev_b32_e32 v50, 16, v233
	v_and_b32_e32 v51, 0xffff0000, v233
	v_pk_add_f32 v[14:15], v[14:15], v[44:45]
	v_pk_add_f32 v[16:17], v[16:17], v[46:47]
	v_pk_add_f32 v[18:19], v[18:19], v[48:49]
	v_pk_add_f32 v[12:13], v[12:13], v[50:51]
	v_pk_fma_f32 v[36:37], v[34:35], v[14:15], v[44:45] op_sel_hi:[0,1,1] neg_lo:[0,0,1] neg_hi:[0,0,1]
	v_pk_fma_f32 v[38:39], v[34:35], v[16:17], v[46:47] op_sel_hi:[0,1,1] neg_lo:[0,0,1] neg_hi:[0,0,1]
	v_pk_fma_f32 v[40:41], v[34:35], v[18:19], v[48:49] op_sel_hi:[0,1,1] neg_lo:[0,0,1] neg_hi:[0,0,1]
	v_pk_fma_f32 v[42:43], v[34:35], v[12:13], v[50:51] op_sel_hi:[0,1,1] neg_lo:[0,0,1] neg_hi:[0,0,1]
	v_cvt_pk_bf16_f32 v28, v36, v37
	v_cvt_pk_bf16_f32 v29, v38, v39
	v_cvt_pk_bf16_f32 v30, v40, v41
	v_cvt_pk_bf16_f32 v31, v42, v43
	global_store_dwordx4 v[10:11], v[28:31], off
	v_lshlrev_b32_e32 v44, 16, v218
	v_and_b32_e32 v45, 0xffff0000, v218
	v_lshlrev_b32_e32 v46, 16, v219
	v_and_b32_e32 v47, 0xffff0000, v219
	v_lshlrev_b32_e32 v48, 16, v220
	v_and_b32_e32 v49, 0xffff0000, v220
	v_lshlrev_b32_e32 v50, 16, v221
	v_and_b32_e32 v51, 0xffff0000, v221
	v_pk_add_f32 v[14:15], v[14:15], v[44:45] neg_lo:[0,1] neg_hi:[0,1]
	v_pk_add_f32 v[16:17], v[16:17], v[46:47] neg_lo:[0,1] neg_hi:[0,1]
	v_pk_add_f32 v[18:19], v[18:19], v[48:49] neg_lo:[0,1] neg_hi:[0,1]
	v_pk_add_f32 v[12:13], v[12:13], v[50:51] neg_lo:[0,1] neg_hi:[0,1]
	v_lshl_add_u64 v[10:11], v[10:11], 0, s[26:27]
	v_lshlrev_b32_e32 v44, 16, v234
	v_and_b32_e32 v45, 0xffff0000, v234
	v_lshlrev_b32_e32 v46, 16, v235
	v_and_b32_e32 v47, 0xffff0000, v235
	v_lshlrev_b32_e32 v48, 16, v236
	v_and_b32_e32 v49, 0xffff0000, v236
	v_lshlrev_b32_e32 v50, 16, v237
	v_and_b32_e32 v51, 0xffff0000, v237
	v_pk_add_f32 v[14:15], v[14:15], v[44:45]
	v_pk_add_f32 v[16:17], v[16:17], v[46:47]
	v_pk_add_f32 v[18:19], v[18:19], v[48:49]
	v_pk_add_f32 v[12:13], v[12:13], v[50:51]
	v_pk_fma_f32 v[36:37], v[34:35], v[14:15], v[44:45] op_sel_hi:[0,1,1] neg_lo:[0,0,1] neg_hi:[0,0,1]
	v_pk_fma_f32 v[38:39], v[34:35], v[16:17], v[46:47] op_sel_hi:[0,1,1] neg_lo:[0,0,1] neg_hi:[0,0,1]
	v_pk_fma_f32 v[40:41], v[34:35], v[18:19], v[48:49] op_sel_hi:[0,1,1] neg_lo:[0,0,1] neg_hi:[0,0,1]
	v_pk_fma_f32 v[42:43], v[34:35], v[12:13], v[50:51] op_sel_hi:[0,1,1] neg_lo:[0,0,1] neg_hi:[0,0,1]
	v_cvt_pk_bf16_f32 v28, v36, v37
	v_cvt_pk_bf16_f32 v29, v38, v39
	v_cvt_pk_bf16_f32 v30, v40, v41
	v_cvt_pk_bf16_f32 v31, v42, v43
	global_store_dwordx4 v[10:11], v[28:31], off
	v_lshlrev_b32_e32 v44, 16, v222
	v_and_b32_e32 v45, 0xffff0000, v222
	v_lshlrev_b32_e32 v46, 16, v223
	v_and_b32_e32 v47, 0xffff0000, v223
	v_lshlrev_b32_e32 v48, 16, v224
	v_and_b32_e32 v49, 0xffff0000, v224
	v_lshlrev_b32_e32 v50, 16, v225
	v_and_b32_e32 v51, 0xffff0000, v225
	v_pk_add_f32 v[14:15], v[14:15], v[44:45] neg_lo:[0,1] neg_hi:[0,1]
	v_pk_add_f32 v[16:17], v[16:17], v[46:47] neg_lo:[0,1] neg_hi:[0,1]
	v_pk_add_f32 v[18:19], v[18:19], v[48:49] neg_lo:[0,1] neg_hi:[0,1]
	v_pk_add_f32 v[12:13], v[12:13], v[50:51] neg_lo:[0,1] neg_hi:[0,1]
	v_lshl_add_u64 v[10:11], v[10:11], 0, s[26:27]
	v_lshlrev_b32_e32 v44, 16, v238
	v_and_b32_e32 v45, 0xffff0000, v238
	v_lshlrev_b32_e32 v46, 16, v239
	v_and_b32_e32 v47, 0xffff0000, v239
	v_lshlrev_b32_e32 v48, 16, v240
	v_and_b32_e32 v49, 0xffff0000, v240
	v_lshlrev_b32_e32 v50, 16, v241
	v_and_b32_e32 v51, 0xffff0000, v241
	v_pk_add_f32 v[14:15], v[14:15], v[44:45]
	v_pk_add_f32 v[16:17], v[16:17], v[46:47]
	v_pk_add_f32 v[18:19], v[18:19], v[48:49]
	v_pk_add_f32 v[12:13], v[12:13], v[50:51]
	v_pk_fma_f32 v[36:37], v[34:35], v[14:15], v[44:45] op_sel_hi:[0,1,1] neg_lo:[0,0,1] neg_hi:[0,0,1]
	v_pk_fma_f32 v[38:39], v[34:35], v[16:17], v[46:47] op_sel_hi:[0,1,1] neg_lo:[0,0,1] neg_hi:[0,0,1]
	v_pk_fma_f32 v[40:41], v[34:35], v[18:19], v[48:49] op_sel_hi:[0,1,1] neg_lo:[0,0,1] neg_hi:[0,0,1]
; __device__ __forceinline__ unsigned pk2(float lo, float hi) { f32x2 v = {lo, hi}; bf16x2_t b = __builtin_convertvector(v, bf16x2_t); return __builtin_bit_cast(unsigned, b); }
; __device__ __forceinline__ void pool_window(const bf16_t* __restrict__ U  , bf16_t* __restrict__ A3, const int gtid, const int nthr) {
;     ...
;         for (int i = 0; i < 32; ++i) {
;             const int t = t0 + i, s = s0 + i;
;             const u32x4 uu = *(const u32x4*)(U + (size_t)t * LDU + c);
;             float cu[8] = {bflo(uu.x), bfhi(uu.x), bflo(uu.y), bfhi(uu.y), bflo(uu.z), bfhi(uu.z), bflo(uu.w), bfhi(uu.w)};
;             const float rc = 1.0f / (float)((s + 1) < w ? (s + 1) : w);
;             float o[8];
; #pragma unroll
;             for (int e = 0; e < 8; ++e) { sum[e] += cu[e]; o[e] = sum[e] * rc - cu[e]; }
;             u32x4 ww; ww.x = pk2(o[0], o[1]); ww.y = pk2(o[2], o[3]); ww.z = pk2(o[4], o[5]); ww.w = pk2(o[6], o[7]);
;             *(u32x4*)(A3 + (size_t)t * DM + c) = ww;
;             if (s + 1 >= w) { const u32x4 ud = *(const u32x4*)(U + (size_t)(t - w + 1) * LDU + c);
;                 sum[0] -= bflo(ud.x); sum[1] -= bfhi(ud.x); sum[2] -= bflo(ud.y); sum[3] -= bfhi(ud.y); sum[4] -= bflo(ud.z); sum[5] -= bfhi(ud.z); sum[6] -= bflo(ud.w); sum[7] -= bfhi(ud.w); }
	v_pk_fma_f32 v[42:43], v[34:35], v[12:13], v[50:51] op_sel_hi:[0,1,1] neg_lo:[0,0,1] neg_hi:[0,0,1]
	v_cvt_pk_bf16_f32 v28, v36, v37
	v_cvt_pk_bf16_f32 v29, v38, v39
	v_cvt_pk_bf16_f32 v30, v40, v41
	v_cvt_pk_bf16_f32 v31, v42, v43
	global_store_dwordx4 v[10:11], v[28:31], off
	v_lshlrev_b32_e32 v44, 16, v226
	v_and_b32_e32 v45, 0xffff0000, v226
	v_lshlrev_b32_e32 v46, 16, v227
	v_and_b32_e32 v47, 0xffff0000, v227
	v_lshlrev_b32_e32 v48, 16, v228
	v_and_b32_e32 v49, 0xffff0000, v228
	v_lshlrev_b32_e32 v50, 16, v229
	v_and_b32_e32 v51, 0xffff0000, v229
	v_pk_add_f32 v[14:15], v[14:15], v[44:45] neg_lo:[0,1] neg_hi:[0,1]
	v_pk_add_f32 v[16:17], v[16:17], v[46:47] neg_lo:[0,1] neg_hi:[0,1]
	v_pk_add_f32 v[18:19], v[18:19], v[48:49] neg_lo:[0,1] neg_hi:[0,1]
	v_pk_add_f32 v[12:13], v[12:13], v[50:51] neg_lo:[0,1] neg_hi:[0,1]
	v_lshl_add_u64 v[10:11], v[10:11], 0, s[26:27]
	v_lshlrev_b32_e32 v44, 16, v242
	v_and_b32_e32 v45, 0xffff0000, v242
	v_lshlrev_b32_e32 v46, 16, v243
	v_and_b32_e32 v47, 0xffff0000, v243
	v_lshlrev_b32_e32 v48, 16, v244
	v_and_b32_e32 v49, 0xffff0000, v244
	v_lshlrev_b32_e32 v50, 16, v245
	v_and_b32_e32 v51, 0xffff0000, v245
	v_pk_add_f32 v[14:15], v[14:15], v[44:45]
	v_pk_add_f32 v[16:17], v[16:17], v[46:47]
	v_pk_add_f32 v[18:19], v[18:19], v[48:49]
	v_pk_add_f32 v[12:13], v[12:13], v[50:51]
	v_pk_fma_f32 v[36:37], v[34:35], v[14:15], v[44:45] op_sel_hi:[0,1,1] neg_lo:[0,0,1] neg_hi:[0,0,1]
	v_pk_fma_f32 v[38:39], v[34:35], v[16:17], v[46:47] op_sel_hi:[0,1,1] neg_lo:[0,0,1] neg_hi:[0,0,1]
	v_pk_fma_f32 v[40:41], v[34:35], v[18:19], v[48:49] op_sel_hi:[0,1,1] neg_lo:[0,0,1] neg_hi:[0,0,1]
	v_pk_fma_f32 v[42:43], v[34:35], v[12:13], v[50:51] op_sel_hi:[0,1,1] neg_lo:[0,0,1] neg_hi:[0,0,1]
	v_cvt_pk_bf16_f32 v28, v36, v37
	v_cvt_pk_bf16_f32 v29, v38, v39
	v_cvt_pk_bf16_f32 v30, v40, v41
	v_cvt_pk_bf16_f32 v31, v42, v43
	global_store_dwordx4 v[10:11], v[28:31], off
	v_lshlrev_b32_e32 v44, 16, v230
	v_and_b32_e32 v45, 0xffff0000, v230
	v_lshlrev_b32_e32 v46, 16, v231
	v_and_b32_e32 v47, 0xffff0000, v231
	v_lshlrev_b32_e32 v48, 16, v232
	v_and_b32_e32 v49, 0xffff0000, v232
	v_lshlrev_b32_e32 v50, 16, v233
	v_and_b32_e32 v51, 0xffff0000, v233
	v_pk_add_f32 v[14:15], v[14:15], v[44:45] neg_lo:[0,1] neg_hi:[0,1]
	v_pk_add_f32 v[16:17], v[16:17], v[46:47] neg_lo:[0,1] neg_hi:[0,1]
	v_pk_add_f32 v[18:19], v[18:19], v[48:49] neg_lo:[0,1] neg_hi:[0,1]
	v_pk_add_f32 v[12:13], v[12:13], v[50:51] neg_lo:[0,1] neg_hi:[0,1]
	v_lshl_add_u64 v[10:11], v[10:11], 0, s[26:27]
	v_lshlrev_b32_e32 v44, 16, v246
	v_and_b32_e32 v45, 0xffff0000, v246
	v_lshlrev_b32_e32 v46, 16, v247
	v_and_b32_e32 v47, 0xffff0000, v247
	v_lshlrev_b32_e32 v48, 16, v248
	v_and_b32_e32 v49, 0xffff0000, v248
	v_lshlrev_b32_e32 v50, 16, v249
	v_and_b32_e32 v51, 0xffff0000, v249
	v_pk_add_f32 v[14:15], v[14:15], v[44:45]
	v_pk_add_f32 v[16:17], v[16:17], v[46:47]
	v_pk_add_f32 v[18:19], v[18:19], v[48:49]
	v_pk_add_f32 v[12:13], v[12:13], v[50:51]
	v_pk_fma_f32 v[36:37], v[34:35], v[14:15], v[44:45] op_sel_hi:[0,1,1] neg_lo:[0,0,1] neg_hi:[0,0,1]
	v_pk_fma_f32 v[38:39], v[34:35], v[16:17], v[46:47] op_sel_hi:[0,1,1] neg_lo:[0,0,1] neg_hi:[0,0,1]
	v_pk_fma_f32 v[40:41], v[34:35], v[18:19], v[48:49] op_sel_hi:[0,1,1] neg_lo:[0,0,1] neg_hi:[0,0,1]
	v_pk_fma_f32 v[42:43], v[34:35], v[12:13], v[50:51] op_sel_hi:[0,1,1] neg_lo:[0,0,1] neg_hi:[0,0,1]
	v_cvt_pk_bf16_f32 v28, v36, v37
	v_cvt_pk_bf16_f32 v29, v38, v39
	v_cvt_pk_bf16_f32 v30, v40, v41
	v_cvt_pk_bf16_f32 v31, v42, v43
	global_store_dwordx4 v[10:11], v[28:31], off
	v_lshlrev_b32_e32 v44, 16, v234
	v_and_b32_e32 v45, 0xffff0000, v234
	v_lshlrev_b32_e32 v46, 16, v235
	v_and_b32_e32 v47, 0xffff0000, v235
	v_lshlrev_b32_e32 v48, 16, v236
	v_and_b32_e32 v49, 0xffff0000, v236
	v_lshlrev_b32_e32 v50, 16, v237
	v_and_b32_e32 v51, 0xffff0000, v237
	v_pk_add_f32 v[14:15], v[14:15], v[44:45] neg_lo:[0,1] neg_hi:[0,1]
	v_pk_add_f32 v[16:17], v[16:17], v[46:47] neg_lo:[0,1] neg_hi:[0,1]
	v_pk_add_f32 v[18:19], v[18:19], v[48:49] neg_lo:[0,1] neg_hi:[0,1]
	v_pk_add_f32 v[12:13], v[12:13], v[50:51] neg_lo:[0,1] neg_hi:[0,1]
	v_lshl_add_u64 v[10:11], v[10:11], 0, s[26:27]
	v_lshlrev_b32_e32 v44, 16, v250
	v_and_b32_e32 v45, 0xffff0000, v250
	v_lshlrev_b32_e32 v46, 16, v251
	v_and_b32_e32 v47, 0xffff0000, v251
	v_lshlrev_b32_e32 v48, 16, v252
	v_and_b32_e32 v49, 0xffff0000, v252
	v_lshlrev_b32_e32 v50, 16, v253
	v_and_b32_e32 v51, 0xffff0000, v253
	v_pk_add_f32 v[14:15], v[14:15], v[44:45]
	v_pk_add_f32 v[16:17], v[16:17], v[46:47]
	v_pk_add_f32 v[18:19], v[18:19], v[48:49]
	v_pk_add_f32 v[12:13], v[12:13], v[50:51]
	v_pk_fma_f32 v[36:37], v[34:35], v[14:15], v[44:45] op_sel_hi:[0,1,1] neg_lo:[0,0,1] neg_hi:[0,0,1]
	v_pk_fma_f32 v[38:39], v[34:35], v[16:17], v[46:47] op_sel_hi:[0,1,1] neg_lo:[0,0,1] neg_hi:[0,0,1]
	v_pk_fma_f32 v[40:41], v[34:35], v[18:19], v[48:49] op_sel_hi:[0,1,1] neg_lo:[0,0,1] neg_hi:[0,0,1]
	v_pk_fma_f32 v[42:43], v[34:35], v[12:13], v[50:51] op_sel_hi:[0,1,1] neg_lo:[0,0,1] neg_hi:[0,0,1]
	v_cvt_pk_bf16_f32 v28, v36, v37
	v_cvt_pk_bf16_f32 v29, v38, v39
	v_cvt_pk_bf16_f32 v30, v40, v41
	v_cvt_pk_bf16_f32 v31, v42, v43
	global_store_dwordx4 v[10:11], v[28:31], off
	v_lshlrev_b32_e32 v44, 16, v238
	v_and_b32_e32 v45, 0xffff0000, v238
	v_lshlrev_b32_e32 v46, 16, v239
	v_and_b32_e32 v47, 0xffff0000, v239
	v_lshlrev_b32_e32 v48, 16, v240
	v_and_b32_e32 v49, 0xffff0000, v240
	v_lshlrev_b32_e32 v50, 16, v241
	v_and_b32_e32 v51, 0xffff0000, v241
	v_pk_add_f32 v[14:15], v[14:15], v[44:45] neg_lo:[0,1] neg_hi:[0,1]
	v_pk_add_f32 v[16:17], v[16:17], v[46:47] neg_lo:[0,1] neg_hi:[0,1]
	v_pk_add_f32 v[18:19], v[18:19], v[48:49] neg_lo:[0,1] neg_hi:[0,1]
	v_pk_add_f32 v[12:13], v[12:13], v[50:51] neg_lo:[0,1] neg_hi:[0,1]
	s_branch .LBB0_1331
; __device__ __forceinline__ unsigned pk2(float lo, float hi) { f32x2 v = {lo, hi}; bf16x2_t b = __builtin_convertvector(v, bf16x2_t); return __builtin_bit_cast(unsigned, b); }
; __device__ __forceinline__ void pool_window(const bf16_t* __restrict__ U  , bf16_t* __restrict__ A3, const int gtid, const int nthr) {
;     ...
;         for (int i = 0; i < 32; ++i) {
;             const int t = t0 + i, s = s0 + i;
;             const u32x4 uu = *(const u32x4*)(U + (size_t)t * LDU + c);
;             float cu[8] = {bflo(uu.x), bfhi(uu.x), bflo(uu.y), bfhi(uu.y), bflo(uu.z), bfhi(uu.z), bflo(uu.w), bfhi(uu.w)};
;             const float rc = 1.0f / (float)((s + 1) < w ? (s + 1) : w);
;             float o[8];
; #pragma unroll
;             for (int e = 0; e < 8; ++e) { sum[e] += cu[e]; o[e] = sum[e] * rc - cu[e]; }
;             u32x4 ww; ww.x = pk2(o[0], o[1]); ww.y = pk2(o[2], o[3]); ww.z = pk2(o[4], o[5]); ww.w = pk2(o[6], o[7]);
;             *(u32x4*)(A3 + (size_t)t * DM + c) = ww;
;             if (s + 1 >= w) { const u32x4 ud = *(const u32x4*)(U + (size_t)(t - w + 1) * LDU + c);
;                 sum[0] -= bflo(ud.x); sum[1] -= bfhi(ud.x); sum[2] -= bflo(ud.y); sum[3] -= bfhi(ud.y); sum[4] -= bflo(ud.z); sum[5] -= bfhi(ud.z); sum[6] -= bflo(ud.w); sum[7] -= bfhi(ud.w); }
.Lpw0_w8:
	v_mov_b32_e32 v34, 0x3e000000
	s_waitcnt vmcnt(0)
	v_mov_b32_e32 v34, 0x3f800000
	v_lshlrev_b32_e32 v44, 16, v124
	v_and_b32_e32 v45, 0xffff0000, v124
	v_lshlrev_b32_e32 v46, 16, v125
	v_and_b32_e32 v47, 0xffff0000, v125
	v_lshlrev_b32_e32 v48, 16, v126
	v_and_b32_e32 v49, 0xffff0000, v126
	v_lshlrev_b32_e32 v50, 16, v127
	v_and_b32_e32 v51, 0xffff0000, v127
	v_pk_add_f32 v[14:15], v[14:15], v[44:45]
	v_pk_add_f32 v[16:17], v[16:17], v[46:47]
	v_pk_add_f32 v[18:19], v[18:19], v[48:49]
	v_pk_add_f32 v[12:13], v[12:13], v[50:51]
	v_pk_fma_f32 v[36:37], v[34:35], v[14:15], v[44:45] op_sel_hi:[0,1,1] neg_lo:[0,0,1] neg_hi:[0,0,1]
	v_pk_fma_f32 v[38:39], v[34:35], v[16:17], v[46:47] op_sel_hi:[0,1,1] neg_lo:[0,0,1] neg_hi:[0,0,1]
	v_pk_fma_f32 v[40:41], v[34:35], v[18:19], v[48:49] op_sel_hi:[0,1,1] neg_lo:[0,0,1] neg_hi:[0,0,1]
	v_pk_fma_f32 v[42:43], v[34:35], v[12:13], v[50:51] op_sel_hi:[0,1,1] neg_lo:[0,0,1] neg_hi:[0,0,1]
	v_cvt_pk_bf16_f32 v28, v36, v37
	v_cvt_pk_bf16_f32 v29, v38, v39
	v_cvt_pk_bf16_f32 v30, v40, v41
	v_cvt_pk_bf16_f32 v31, v42, v43
	global_store_dwordx4 v[10:11], v[28:31], off
	v_lshl_add_u64 v[10:11], v[10:11], 0, s[26:27]
	v_mov_b32_e32 v34, 0x3f000000
	v_lshlrev_b32_e32 v44, 16, v128
	v_and_b32_e32 v45, 0xffff0000, v128
	v_lshlrev_b32_e32 v46, 16, v129
	v_and_b32_e32 v47, 0xffff0000, v129
	v_lshlrev_b32_e32 v48, 16, v130
	v_and_b32_e32 v49, 0xffff0000, v130
	v_lshlrev_b32_e32 v50, 16, v131
	v_and_b32_e32 v51, 0xffff0000, v131
	v_pk_add_f32 v[14:15], v[14:15], v[44:45]
	v_pk_add_f32 v[16:17], v[16:17], v[46:47]
	v_pk_add_f32 v[18:19], v[18:19], v[48:49]
	v_pk_add_f32 v[12:13], v[12:13], v[50:51]
	v_pk_fma_f32 v[36:37], v[34:35], v[14:15], v[44:45] op_sel_hi:[0,1,1] neg_lo:[0,0,1] neg_hi:[0,0,1]
	v_pk_fma_f32 v[38:39], v[34:35], v[16:17], v[46:47] op_sel_hi:[0,1,1] neg_lo:[0,0,1] neg_hi:[0,0,1]
	v_pk_fma_f32 v[40:41], v[34:35], v[18:19], v[48:49] op_sel_hi:[0,1,1] neg_lo:[0,0,1] neg_hi:[0,0,1]
	v_pk_fma_f32 v[42:43], v[34:35], v[12:13], v[50:51] op_sel_hi:[0,1,1] neg_lo:[0,0,1] neg_hi:[0,0,1]
	v_cvt_pk_bf16_f32 v28, v36, v37
	v_cvt_pk_bf16_f32 v29, v38, v39
	v_cvt_pk_bf16_f32 v30, v40, v41
	v_cvt_pk_bf16_f32 v31, v42, v43
	global_store_dwordx4 v[10:11], v[28:31], off
	v_lshl_add_u64 v[10:11], v[10:11], 0, s[26:27]
	v_mov_b32_e32 v34, 0x3eaaaaab
	v_lshlrev_b32_e32 v44, 16, v132
	v_and_b32_e32 v45, 0xffff0000, v132
	v_lshlrev_b32_e32 v46, 16, v133
	v_and_b32_e32 v47, 0xffff0000, v133
	v_lshlrev_b32_e32 v48, 16, v134
	v_and_b32_e32 v49, 0xffff0000, v134
	v_lshlrev_b32_e32 v50, 16, v135
	v_and_b32_e32 v51, 0xffff0000, v135
	v_pk_add_f32 v[14:15], v[14:15], v[44:45]
	v_pk_add_f32 v[16:17], v[16:17], v[46:47]
	v_pk_add_f32 v[18:19], v[18:19], v[48:49]
	v_pk_add_f32 v[12:13], v[12:13], v[50:51]
	v_pk_fma_f32 v[36:37], v[34:35], v[14:15], v[44:45] op_sel_hi:[0,1,1] neg_lo:[0,0,1] neg_hi:[0,0,1]
	v_pk_fma_f32 v[38:39], v[34:35], v[16:17], v[46:47] op_sel_hi:[0,1,1] neg_lo:[0,0,1] neg_hi:[0,0,1]
	v_pk_fma_f32 v[40:41], v[34:35], v[18:19], v[48:49] op_sel_hi:[0,1,1] neg_lo:[0,0,1] neg_hi:[0,0,1]
	v_pk_fma_f32 v[42:43], v[34:35], v[12:13], v[50:51] op_sel_hi:[0,1,1] neg_lo:[0,0,1] neg_hi:[0,0,1]
	v_cvt_pk_bf16_f32 v28, v36, v37
	v_cvt_pk_bf16_f32 v29, v38, v39
	v_cvt_pk_bf16_f32 v30, v40, v41
	v_cvt_pk_bf16_f32 v31, v42, v43
	global_store_dwordx4 v[10:11], v[28:31], off
	v_lshl_add_u64 v[10:11], v[10:11], 0, s[26:27]
	v_mov_b32_e32 v34, 0x3e800000
	v_lshlrev_b32_e32 v44, 16, v136
	v_and_b32_e32 v45, 0xffff0000, v136
	v_lshlrev_b32_e32 v46, 16, v137
	v_and_b32_e32 v47, 0xffff0000, v137
	v_lshlrev_b32_e32 v48, 16, v138
	v_and_b32_e32 v49, 0xffff0000, v138
	v_lshlrev_b32_e32 v50, 16, v139
	v_and_b32_e32 v51, 0xffff0000, v139
	v_pk_add_f32 v[14:15], v[14:15], v[44:45]
	v_pk_add_f32 v[16:17], v[16:17], v[46:47]
	v_pk_add_f32 v[18:19], v[18:19], v[48:49]
	v_pk_add_f32 v[12:13], v[12:13], v[50:51]
	v_pk_fma_f32 v[36:37], v[34:35], v[14:15], v[44:45] op_sel_hi:[0,1,1] neg_lo:[0,0,1] neg_hi:[0,0,1]
	v_pk_fma_f32 v[38:39], v[34:35], v[16:17], v[46:47] op_sel_hi:[0,1,1] neg_lo:[0,0,1] neg_hi:[0,0,1]
	v_pk_fma_f32 v[40:41], v[34:35], v[18:19], v[48:49] op_sel_hi:[0,1,1] neg_lo:[0,0,1] neg_hi:[0,0,1]
	v_pk_fma_f32 v[42:43], v[34:35], v[12:13], v[50:51] op_sel_hi:[0,1,1] neg_lo:[0,0,1] neg_hi:[0,0,1]
	v_cvt_pk_bf16_f32 v28, v36, v37
	v_cvt_pk_bf16_f32 v29, v38, v39
	v_cvt_pk_bf16_f32 v30, v40, v41
	v_cvt_pk_bf16_f32 v31, v42, v43
	global_store_dwordx4 v[10:11], v[28:31], off
	v_lshl_add_u64 v[10:11], v[10:11], 0, s[26:27]
	v_mov_b32_e32 v34, 0x3e4ccccd
	v_lshlrev_b32_e32 v44, 16, v140
	v_and_b32_e32 v45, 0xffff0000, v140
	v_lshlrev_b32_e32 v46, 16, v141
	v_and_b32_e32 v47, 0xffff0000, v141
	v_lshlrev_b32_e32 v48, 16, v142
	v_and_b32_e32 v49, 0xffff0000, v142
	v_lshlrev_b32_e32 v50, 16, v143
	v_and_b32_e32 v51, 0xffff0000, v143
	v_pk_add_f32 v[14:15], v[14:15], v[44:45]
	v_pk_add_f32 v[16:17], v[16:17], v[46:47]
	v_pk_add_f32 v[18:19], v[18:19], v[48:49]
	v_pk_add_f32 v[12:13], v[12:13], v[50:51]
	v_pk_fma_f32 v[36:37], v[34:35], v[14:15], v[44:45] op_sel_hi:[0,1,1] neg_lo:[0,0,1] neg_hi:[0,0,1]
	v_pk_fma_f32 v[38:39], v[34:35], v[16:17], v[46:47] op_sel_hi:[0,1,1] neg_lo:[0,0,1] neg_hi:[0,0,1]
	v_pk_fma_f32 v[40:41], v[34:35], v[18:19], v[48:49] op_sel_hi:[0,1,1] neg_lo:[0,0,1] neg_hi:[0,0,1]
	v_pk_fma_f32 v[42:43], v[34:35], v[12:13], v[50:51] op_sel_hi:[0,1,1] neg_lo:[0,0,1] neg_hi:[0,0,1]
	v_cvt_pk_bf16_f32 v28, v36, v37
	v_cvt_pk_bf16_f32 v29, v38, v39
	v_cvt_pk_bf16_f32 v30, v40, v41
	v_cvt_pk_bf16_f32 v31, v42, v43
	global_store_dwordx4 v[10:11], v[28:31], off
	v_lshl_add_u64 v[10:11], v[10:11], 0, s[26:27]
; __device__ __forceinline__ unsigned pk2(float lo, float hi) { f32x2 v = {lo, hi}; bf16x2_t b = __builtin_convertvector(v, bf16x2_t); return __builtin_bit_cast(unsigned, b); }
; __device__ __forceinline__ void pool_window(const bf16_t* __restrict__ U  , bf16_t* __restrict__ A3, const int gtid, const int nthr) {
;     ...
;         for (int i = 0; i < 32; ++i) {
;             const int t = t0 + i, s = s0 + i;
;             const u32x4 uu = *(const u32x4*)(U + (size_t)t * LDU + c);
;             float cu[8] = {bflo(uu.x), bfhi(uu.x), bflo(uu.y), bfhi(uu.y), bflo(uu.z), bfhi(uu.z), bflo(uu.w), bfhi(uu.w)};
;             const float rc = 1.0f / (float)((s + 1) < w ? (s + 1) : w);
;             float o[8];
; #pragma unroll
;             for (int e = 0; e < 8; ++e) { sum[e] += cu[e]; o[e] = sum[e] * rc - cu[e]; }
;             u32x4 ww; ww.x = pk2(o[0], o[1]); ww.y = pk2(o[2], o[3]); ww.z = pk2(o[4], o[5]); ww.w = pk2(o[6], o[7]);
;             *(u32x4*)(A3 + (size_t)t * DM + c) = ww;
;             if (s + 1 >= w) { const u32x4 ud = *(const u32x4*)(U + (size_t)(t - w + 1) * LDU + c);
;                 sum[0] -= bflo(ud.x); sum[1] -= bfhi(ud.x); sum[2] -= bflo(ud.y); sum[3] -= bfhi(ud.y); sum[4] -= bflo(ud.z); sum[5] -= bfhi(ud.z); sum[6] -= bflo(ud.w); sum[7] -= bfhi(ud.w); }
	v_mov_b32_e32 v34, 0x3e2aaaab
	v_lshlrev_b32_e32 v44, 16, v144
	v_and_b32_e32 v45, 0xffff0000, v144
	v_lshlrev_b32_e32 v46, 16, v145
	v_and_b32_e32 v47, 0xffff0000, v145
	v_lshlrev_b32_e32 v48, 16, v146
	v_and_b32_e32 v49, 0xffff0000, v146
	v_lshlrev_b32_e32 v50, 16, v147
	v_and_b32_e32 v51, 0xffff0000, v147
	v_pk_add_f32 v[14:15], v[14:15], v[44:45]
	v_pk_add_f32 v[16:17], v[16:17], v[46:47]
	v_pk_add_f32 v[18:19], v[18:19], v[48:49]
	v_pk_add_f32 v[12:13], v[12:13], v[50:51]
	v_pk_fma_f32 v[36:37], v[34:35], v[14:15], v[44:45] op_sel_hi:[0,1,1] neg_lo:[0,0,1] neg_hi:[0,0,1]
	v_pk_fma_f32 v[38:39], v[34:35], v[16:17], v[46:47] op_sel_hi:[0,1,1] neg_lo:[0,0,1] neg_hi:[0,0,1]
	v_pk_fma_f32 v[40:41], v[34:35], v[18:19], v[48:49] op_sel_hi:[0,1,1] neg_lo:[0,0,1] neg_hi:[0,0,1]
	v_pk_fma_f32 v[42:43], v[34:35], v[12:13], v[50:51] op_sel_hi:[0,1,1] neg_lo:[0,0,1] neg_hi:[0,0,1]
	v_cvt_pk_bf16_f32 v28, v36, v37
	v_cvt_pk_bf16_f32 v29, v38, v39
	v_cvt_pk_bf16_f32 v30, v40, v41
	v_cvt_pk_bf16_f32 v31, v42, v43
	global_store_dwordx4 v[10:11], v[28:31], off
	v_lshl_add_u64 v[10:11], v[10:11], 0, s[26:27]
	v_mov_b32_e32 v34, 0x3e124925
	v_lshlrev_b32_e32 v44, 16, v148
	v_and_b32_e32 v45, 0xffff0000, v148
	v_lshlrev_b32_e32 v46, 16, v149
	v_and_b32_e32 v47, 0xffff0000, v149
	v_lshlrev_b32_e32 v48, 16, v150
	v_and_b32_e32 v49, 0xffff0000, v150
	v_lshlrev_b32_e32 v50, 16, v151
	v_and_b32_e32 v51, 0xffff0000, v151
	v_pk_add_f32 v[14:15], v[14:15], v[44:45]
	v_pk_add_f32 v[16:17], v[16:17], v[46:47]
	v_pk_add_f32 v[18:19], v[18:19], v[48:49]
	v_pk_add_f32 v[12:13], v[12:13], v[50:51]
	v_pk_fma_f32 v[36:37], v[34:35], v[14:15], v[44:45] op_sel_hi:[0,1,1] neg_lo:[0,0,1] neg_hi:[0,0,1]
	v_pk_fma_f32 v[38:39], v[34:35], v[16:17], v[46:47] op_sel_hi:[0,1,1] neg_lo:[0,0,1] neg_hi:[0,0,1]
	v_pk_fma_f32 v[40:41], v[34:35], v[18:19], v[48:49] op_sel_hi:[0,1,1] neg_lo:[0,0,1] neg_hi:[0,0,1]
	v_pk_fma_f32 v[42:43], v[34:35], v[12:13], v[50:51] op_sel_hi:[0,1,1] neg_lo:[0,0,1] neg_hi:[0,0,1]
	v_cvt_pk_bf16_f32 v28, v36, v37
	v_cvt_pk_bf16_f32 v29, v38, v39
	v_cvt_pk_bf16_f32 v30, v40, v41
	v_cvt_pk_bf16_f32 v31, v42, v43
	global_store_dwordx4 v[10:11], v[28:31], off
	v_lshl_add_u64 v[10:11], v[10:11], 0, s[26:27]
	v_mov_b32_e32 v34, 0x3e000000
	v_lshlrev_b32_e32 v44, 16, v152
	v_and_b32_e32 v45, 0xffff0000, v152
	v_lshlrev_b32_e32 v46, 16, v153
	v_and_b32_e32 v47, 0xffff0000, v153
	v_lshlrev_b32_e32 v48, 16, v154
	v_and_b32_e32 v49, 0xffff0000, v154
	v_lshlrev_b32_e32 v50, 16, v155
	v_and_b32_e32 v51, 0xffff0000, v155
	v_pk_add_f32 v[14:15], v[14:15], v[44:45]
	v_pk_add_f32 v[16:17], v[16:17], v[46:47]
	v_pk_add_f32 v[18:19], v[18:19], v[48:49]
	v_pk_add_f32 v[12:13], v[12:13], v[50:51]
	v_pk_fma_f32 v[36:37], v[34:35], v[14:15], v[44:45] op_sel_hi:[0,1,1] neg_lo:[0,0,1] neg_hi:[0,0,1]
	v_pk_fma_f32 v[38:39], v[34:35], v[16:17], v[46:47] op_sel_hi:[0,1,1] neg_lo:[0,0,1] neg_hi:[0,0,1]
	v_pk_fma_f32 v[40:41], v[34:35], v[18:19], v[48:49] op_sel_hi:[0,1,1] neg_lo:[0,0,1] neg_hi:[0,0,1]
	v_pk_fma_f32 v[42:43], v[34:35], v[12:13], v[50:51] op_sel_hi:[0,1,1] neg_lo:[0,0,1] neg_hi:[0,0,1]
	v_cvt_pk_bf16_f32 v28, v36, v37
	v_cvt_pk_bf16_f32 v29, v38, v39
	v_cvt_pk_bf16_f32 v30, v40, v41
	v_cvt_pk_bf16_f32 v31, v42, v43
	global_store_dwordx4 v[10:11], v[28:31], off
	v_lshlrev_b32_e32 v44, 16, v124
	v_and_b32_e32 v45, 0xffff0000, v124
	v_lshlrev_b32_e32 v46, 16, v125
	v_and_b32_e32 v47, 0xffff0000, v125
	v_lshlrev_b32_e32 v48, 16, v126
	v_and_b32_e32 v49, 0xffff0000, v126
	v_lshlrev_b32_e32 v50, 16, v127
	v_and_b32_e32 v51, 0xffff0000, v127
	v_pk_add_f32 v[14:15], v[14:15], v[44:45] neg_lo:[0,1] neg_hi:[0,1]
	v_pk_add_f32 v[16:17], v[16:17], v[46:47] neg_lo:[0,1] neg_hi:[0,1]
	v_pk_add_f32 v[18:19], v[18:19], v[48:49] neg_lo:[0,1] neg_hi:[0,1]
	v_pk_add_f32 v[12:13], v[12:13], v[50:51] neg_lo:[0,1] neg_hi:[0,1]
	v_lshl_add_u64 v[10:11], v[10:11], 0, s[26:27]
	v_lshlrev_b32_e32 v44, 16, v156
	v_and_b32_e32 v45, 0xffff0000, v156
	v_lshlrev_b32_e32 v46, 16, v157
	v_and_b32_e32 v47, 0xffff0000, v157
	v_lshlrev_b32_e32 v48, 16, v158
	v_and_b32_e32 v49, 0xffff0000, v158
	v_lshlrev_b32_e32 v50, 16, v159
	v_and_b32_e32 v51, 0xffff0000, v159
	v_pk_add_f32 v[14:15], v[14:15], v[44:45]
	v_pk_add_f32 v[16:17], v[16:17], v[46:47]
	v_pk_add_f32 v[18:19], v[18:19], v[48:49]
	v_pk_add_f32 v[12:13], v[12:13], v[50:51]
	v_pk_fma_f32 v[36:37], v[34:35], v[14:15], v[44:45] op_sel_hi:[0,1,1] neg_lo:[0,0,1] neg_hi:[0,0,1]
	v_pk_fma_f32 v[38:39], v[34:35], v[16:17], v[46:47] op_sel_hi:[0,1,1] neg_lo:[0,0,1] neg_hi:[0,0,1]
	v_pk_fma_f32 v[40:41], v[34:35], v[18:19], v[48:49] op_sel_hi:[0,1,1] neg_lo:[0,0,1] neg_hi:[0,0,1]
	v_pk_fma_f32 v[42:43], v[34:35], v[12:13], v[50:51] op_sel_hi:[0,1,1] neg_lo:[0,0,1] neg_hi:[0,0,1]
	v_cvt_pk_bf16_f32 v28, v36, v37
	v_cvt_pk_bf16_f32 v29, v38, v39
	v_cvt_pk_bf16_f32 v30, v40, v41
	v_cvt_pk_bf16_f32 v31, v42, v43
	global_store_dwordx4 v[10:11], v[28:31], off
	v_lshlrev_b32_e32 v44, 16, v128
	v_and_b32_e32 v45, 0xffff0000, v128
	v_lshlrev_b32_e32 v46, 16, v129
	v_and_b32_e32 v47, 0xffff0000, v129
	v_lshlrev_b32_e32 v48, 16, v130
	v_and_b32_e32 v49, 0xffff0000, v130
	v_lshlrev_b32_e32 v50, 16, v131
	v_and_b32_e32 v51, 0xffff0000, v131
	v_pk_add_f32 v[14:15], v[14:15], v[44:45] neg_lo:[0,1] neg_hi:[0,1]
	v_pk_add_f32 v[16:17], v[16:17], v[46:47] neg_lo:[0,1] neg_hi:[0,1]
	v_pk_add_f32 v[18:19], v[18:19], v[48:49] neg_lo:[0,1] neg_hi:[0,1]
	v_pk_add_f32 v[12:13], v[12:13], v[50:51] neg_lo:[0,1] neg_hi:[0,1]
	v_lshl_add_u64 v[10:11], v[10:11], 0, s[26:27]
	v_lshlrev_b32_e32 v44, 16, v160
	v_and_b32_e32 v45, 0xffff0000, v160
	v_lshlrev_b32_e32 v46, 16, v161
; __device__ __forceinline__ unsigned pk2(float lo, float hi) { f32x2 v = {lo, hi}; bf16x2_t b = __builtin_convertvector(v, bf16x2_t); return __builtin_bit_cast(unsigned, b); }
; __device__ __forceinline__ void pool_window(const bf16_t* __restrict__ U  , bf16_t* __restrict__ A3, const int gtid, const int nthr) {
;     ...
;         for (int i = 0; i < 32; ++i) {
;             const int t = t0 + i, s = s0 + i;
;             const u32x4 uu = *(const u32x4*)(U + (size_t)t * LDU + c);
;             float cu[8] = {bflo(uu.x), bfhi(uu.x), bflo(uu.y), bfhi(uu.y), bflo(uu.z), bfhi(uu.z), bflo(uu.w), bfhi(uu.w)};
;             const float rc = 1.0f / (float)((s + 1) < w ? (s + 1) : w);
;             float o[8];
; #pragma unroll
;             for (int e = 0; e < 8; ++e) { sum[e] += cu[e]; o[e] = sum[e] * rc - cu[e]; }
;             u32x4 ww; ww.x = pk2(o[0], o[1]); ww.y = pk2(o[2], o[3]); ww.z = pk2(o[4], o[5]); ww.w = pk2(o[6], o[7]);
;             *(u32x4*)(A3 + (size_t)t * DM + c) = ww;
;             if (s + 1 >= w) { const u32x4 ud = *(const u32x4*)(U + (size_t)(t - w + 1) * LDU + c);
;                 sum[0] -= bflo(ud.x); sum[1] -= bfhi(ud.x); sum[2] -= bflo(ud.y); sum[3] -= bfhi(ud.y); sum[4] -= bflo(ud.z); sum[5] -= bfhi(ud.z); sum[6] -= bflo(ud.w); sum[7] -= bfhi(ud.w); }
	v_and_b32_e32 v47, 0xffff0000, v161
	v_lshlrev_b32_e32 v48, 16, v162
	v_and_b32_e32 v49, 0xffff0000, v162
	v_lshlrev_b32_e32 v50, 16, v163
	v_and_b32_e32 v51, 0xffff0000, v163
	v_pk_add_f32 v[14:15], v[14:15], v[44:45]
	v_pk_add_f32 v[16:17], v[16:17], v[46:47]
	v_pk_add_f32 v[18:19], v[18:19], v[48:49]
	v_pk_add_f32 v[12:13], v[12:13], v[50:51]
	v_pk_fma_f32 v[36:37], v[34:35], v[14:15], v[44:45] op_sel_hi:[0,1,1] neg_lo:[0,0,1] neg_hi:[0,0,1]
	v_pk_fma_f32 v[38:39], v[34:35], v[16:17], v[46:47] op_sel_hi:[0,1,1] neg_lo:[0,0,1] neg_hi:[0,0,1]
	v_pk_fma_f32 v[40:41], v[34:35], v[18:19], v[48:49] op_sel_hi:[0,1,1] neg_lo:[0,0,1] neg_hi:[0,0,1]
	v_pk_fma_f32 v[42:43], v[34:35], v[12:13], v[50:51] op_sel_hi:[0,1,1] neg_lo:[0,0,1] neg_hi:[0,0,1]
	v_cvt_pk_bf16_f32 v28, v36, v37
	v_cvt_pk_bf16_f32 v29, v38, v39
	v_cvt_pk_bf16_f32 v30, v40, v41
	v_cvt_pk_bf16_f32 v31, v42, v43
	global_store_dwordx4 v[10:11], v[28:31], off
	v_lshlrev_b32_e32 v44, 16, v132
	v_and_b32_e32 v45, 0xffff0000, v132
	v_lshlrev_b32_e32 v46, 16, v133
	v_and_b32_e32 v47, 0xffff0000, v133
	v_lshlrev_b32_e32 v48, 16, v134
	v_and_b32_e32 v49, 0xffff0000, v134
	v_lshlrev_b32_e32 v50, 16, v135
	v_and_b32_e32 v51, 0xffff0000, v135
	v_pk_add_f32 v[14:15], v[14:15], v[44:45] neg_lo:[0,1] neg_hi:[0,1]
	v_pk_add_f32 v[16:17], v[16:17], v[46:47] neg_lo:[0,1] neg_hi:[0,1]
	v_pk_add_f32 v[18:19], v[18:19], v[48:49] neg_lo:[0,1] neg_hi:[0,1]
	v_pk_add_f32 v[12:13], v[12:13], v[50:51] neg_lo:[0,1] neg_hi:[0,1]
	v_lshl_add_u64 v[10:11], v[10:11], 0, s[26:27]
	v_lshlrev_b32_e32 v44, 16, v164
	v_and_b32_e32 v45, 0xffff0000, v164
	v_lshlrev_b32_e32 v46, 16, v165
	v_and_b32_e32 v47, 0xffff0000, v165
	v_lshlrev_b32_e32 v48, 16, v166
	v_and_b32_e32 v49, 0xffff0000, v166
	v_lshlrev_b32_e32 v50, 16, v167
	v_and_b32_e32 v51, 0xffff0000, v167
	v_pk_add_f32 v[14:15], v[14:15], v[44:45]
	v_pk_add_f32 v[16:17], v[16:17], v[46:47]
	v_pk_add_f32 v[18:19], v[18:19], v[48:49]
	v_pk_add_f32 v[12:13], v[12:13], v[50:51]
	v_pk_fma_f32 v[36:37], v[34:35], v[14:15], v[44:45] op_sel_hi:[0,1,1] neg_lo:[0,0,1] neg_hi:[0,0,1]
	v_pk_fma_f32 v[38:39], v[34:35], v[16:17], v[46:47] op_sel_hi:[0,1,1] neg_lo:[0,0,1] neg_hi:[0,0,1]
	v_pk_fma_f32 v[40:41], v[34:35], v[18:19], v[48:49] op_sel_hi:[0,1,1] neg_lo:[0,0,1] neg_hi:[0,0,1]
	v_pk_fma_f32 v[42:43], v[34:35], v[12:13], v[50:51] op_sel_hi:[0,1,1] neg_lo:[0,0,1] neg_hi:[0,0,1]
	v_cvt_pk_bf16_f32 v28, v36, v37
	v_cvt_pk_bf16_f32 v29, v38, v39
	v_cvt_pk_bf16_f32 v30, v40, v41
	v_cvt_pk_bf16_f32 v31, v42, v43
	global_store_dwordx4 v[10:11], v[28:31], off
	v_lshlrev_b32_e32 v44, 16, v136
	v_and_b32_e32 v45, 0xffff0000, v136
	v_lshlrev_b32_e32 v46, 16, v137
	v_and_b32_e32 v47, 0xffff0000, v137
	v_lshlrev_b32_e32 v48, 16, v138
	v_and_b32_e32 v49, 0xffff0000, v138
	v_lshlrev_b32_e32 v50, 16, v139
	v_and_b32_e32 v51, 0xffff0000, v139
	v_pk_add_f32 v[14:15], v[14:15], v[44:45] neg_lo:[0,1] neg_hi:[0,1]
	v_pk_add_f32 v[16:17], v[16:17], v[46:47] neg_lo:[0,1] neg_hi:[0,1]
	v_pk_add_f32 v[18:19], v[18:19], v[48:49] neg_lo:[0,1] neg_hi:[0,1]
	v_pk_add_f32 v[12:13], v[12:13], v[50:51] neg_lo:[0,1] neg_hi:[0,1]
	v_lshl_add_u64 v[10:11], v[10:11], 0, s[26:27]
	v_lshlrev_b32_e32 v44, 16, v168
	v_and_b32_e32 v45, 0xffff0000, v168
	v_lshlrev_b32_e32 v46, 16, v169
	v_and_b32_e32 v47, 0xffff0000, v169
	v_lshlrev_b32_e32 v48, 16, v170
	v_and_b32_e32 v49, 0xffff0000, v170
	v_lshlrev_b32_e32 v50, 16, v171
	v_and_b32_e32 v51, 0xffff0000, v171
	v_pk_add_f32 v[14:15], v[14:15], v[44:45]
	v_pk_add_f32 v[16:17], v[16:17], v[46:47]
	v_pk_add_f32 v[18:19], v[18:19], v[48:49]
	v_pk_add_f32 v[12:13], v[12:13], v[50:51]
	v_pk_fma_f32 v[36:37], v[34:35], v[14:15], v[44:45] op_sel_hi:[0,1,1] neg_lo:[0,0,1] neg_hi:[0,0,1]
	v_pk_fma_f32 v[38:39], v[34:35], v[16:17], v[46:47] op_sel_hi:[0,1,1] neg_lo:[0,0,1] neg_hi:[0,0,1]
	v_pk_fma_f32 v[40:41], v[34:35], v[18:19], v[48:49] op_sel_hi:[0,1,1] neg_lo:[0,0,1] neg_hi:[0,0,1]
	v_pk_fma_f32 v[42:43], v[34:35], v[12:13], v[50:51] op_sel_hi:[0,1,1] neg_lo:[0,0,1] neg_hi:[0,0,1]
	v_cvt_pk_bf16_f32 v28, v36, v37
	v_cvt_pk_bf16_f32 v29, v38, v39
	v_cvt_pk_bf16_f32 v30, v40, v41
	v_cvt_pk_bf16_f32 v31, v42, v43
	global_store_dwordx4 v[10:11], v[28:31], off
	v_lshlrev_b32_e32 v44, 16, v140
	v_and_b32_e32 v45, 0xffff0000, v140
	v_lshlrev_b32_e32 v46, 16, v141
	v_and_b32_e32 v47, 0xffff0000, v141
	v_lshlrev_b32_e32 v48, 16, v142
	v_and_b32_e32 v49, 0xffff0000, v142
	v_lshlrev_b32_e32 v50, 16, v143
	v_and_b32_e32 v51, 0xffff0000, v143
	v_pk_add_f32 v[14:15], v[14:15], v[44:45] neg_lo:[0,1] neg_hi:[0,1]
	v_pk_add_f32 v[16:17], v[16:17], v[46:47] neg_lo:[0,1] neg_hi:[0,1]
	v_pk_add_f32 v[18:19], v[18:19], v[48:49] neg_lo:[0,1] neg_hi:[0,1]
	v_pk_add_f32 v[12:13], v[12:13], v[50:51] neg_lo:[0,1] neg_hi:[0,1]
	v_lshl_add_u64 v[10:11], v[10:11], 0, s[26:27]
	v_lshlrev_b32_e32 v44, 16, v172
	v_and_b32_e32 v45, 0xffff0000, v172
	v_lshlrev_b32_e32 v46, 16, v173
	v_and_b32_e32 v47, 0xffff0000, v173
	v_lshlrev_b32_e32 v48, 16, v174
	v_and_b32_e32 v49, 0xffff0000, v174
	v_lshlrev_b32_e32 v50, 16, v175
	v_and_b32_e32 v51, 0xffff0000, v175
	v_pk_add_f32 v[14:15], v[14:15], v[44:45]
	v_pk_add_f32 v[16:17], v[16:17], v[46:47]
	v_pk_add_f32 v[18:19], v[18:19], v[48:49]
	v_pk_add_f32 v[12:13], v[12:13], v[50:51]
	v_pk_fma_f32 v[36:37], v[34:35], v[14:15], v[44:45] op_sel_hi:[0,1,1] neg_lo:[0,0,1] neg_hi:[0,0,1]
	v_pk_fma_f32 v[38:39], v[34:35], v[16:17], v[46:47] op_sel_hi:[0,1,1] neg_lo:[0,0,1] neg_hi:[0,0,1]
	v_pk_fma_f32 v[40:41], v[34:35], v[18:19], v[48:49] op_sel_hi:[0,1,1] neg_lo:[0,0,1] neg_hi:[0,0,1]
	v_pk_fma_f32 v[42:43], v[34:35], v[12:13], v[50:51] op_sel_hi:[0,1,1] neg_lo:[0,0,1] neg_hi:[0,0,1]
; __device__ __forceinline__ unsigned pk2(float lo, float hi) { f32x2 v = {lo, hi}; bf16x2_t b = __builtin_convertvector(v, bf16x2_t); return __builtin_bit_cast(unsigned, b); }
; __device__ __forceinline__ void pool_window(const bf16_t* __restrict__ U  , bf16_t* __restrict__ A3, const int gtid, const int nthr) {
;     ...
;         for (int i = 0; i < 32; ++i) {
;             const int t = t0 + i, s = s0 + i;
;             const u32x4 uu = *(const u32x4*)(U + (size_t)t * LDU + c);
;             float cu[8] = {bflo(uu.x), bfhi(uu.x), bflo(uu.y), bfhi(uu.y), bflo(uu.z), bfhi(uu.z), bflo(uu.w), bfhi(uu.w)};
;             const float rc = 1.0f / (float)((s + 1) < w ? (s + 1) : w);
;             float o[8];
; #pragma unroll
;             for (int e = 0; e < 8; ++e) { sum[e] += cu[e]; o[e] = sum[e] * rc - cu[e]; }
;             u32x4 ww; ww.x = pk2(o[0], o[1]); ww.y = pk2(o[2], o[3]); ww.z = pk2(o[4], o[5]); ww.w = pk2(o[6], o[7]);
;             *(u32x4*)(A3 + (size_t)t * DM + c) = ww;
;             if (s + 1 >= w) { const u32x4 ud = *(const u32x4*)(U + (size_t)(t - w + 1) * LDU + c);
;                 sum[0] -= bflo(ud.x); sum[1] -= bfhi(ud.x); sum[2] -= bflo(ud.y); sum[3] -= bfhi(ud.y); sum[4] -= bflo(ud.z); sum[5] -= bfhi(ud.z); sum[6] -= bflo(ud.w); sum[7] -= bfhi(ud.w); }
	v_cvt_pk_bf16_f32 v28, v36, v37
	v_cvt_pk_bf16_f32 v29, v38, v39
	v_cvt_pk_bf16_f32 v30, v40, v41
	v_cvt_pk_bf16_f32 v31, v42, v43
	global_store_dwordx4 v[10:11], v[28:31], off
	v_lshlrev_b32_e32 v44, 16, v144
	v_and_b32_e32 v45, 0xffff0000, v144
	v_lshlrev_b32_e32 v46, 16, v145
	v_and_b32_e32 v47, 0xffff0000, v145
	v_lshlrev_b32_e32 v48, 16, v146
	v_and_b32_e32 v49, 0xffff0000, v146
	v_lshlrev_b32_e32 v50, 16, v147
	v_and_b32_e32 v51, 0xffff0000, v147
	v_pk_add_f32 v[14:15], v[14:15], v[44:45] neg_lo:[0,1] neg_hi:[0,1]
	v_pk_add_f32 v[16:17], v[16:17], v[46:47] neg_lo:[0,1] neg_hi:[0,1]
	v_pk_add_f32 v[18:19], v[18:19], v[48:49] neg_lo:[0,1] neg_hi:[0,1]
	v_pk_add_f32 v[12:13], v[12:13], v[50:51] neg_lo:[0,1] neg_hi:[0,1]
	v_lshl_add_u64 v[10:11], v[10:11], 0, s[26:27]
	v_lshlrev_b32_e32 v44, 16, v176
	v_and_b32_e32 v45, 0xffff0000, v176
	v_lshlrev_b32_e32 v46, 16, v177
	v_and_b32_e32 v47, 0xffff0000, v177
	v_lshlrev_b32_e32 v48, 16, v178
	v_and_b32_e32 v49, 0xffff0000, v178
	v_lshlrev_b32_e32 v50, 16, v179
	v_and_b32_e32 v51, 0xffff0000, v179
	v_pk_add_f32 v[14:15], v[14:15], v[44:45]
	v_pk_add_f32 v[16:17], v[16:17], v[46:47]
	v_pk_add_f32 v[18:19], v[18:19], v[48:49]
	v_pk_add_f32 v[12:13], v[12:13], v[50:51]
	v_pk_fma_f32 v[36:37], v[34:35], v[14:15], v[44:45] op_sel_hi:[0,1,1] neg_lo:[0,0,1] neg_hi:[0,0,1]
	v_pk_fma_f32 v[38:39], v[34:35], v[16:17], v[46:47] op_sel_hi:[0,1,1] neg_lo:[0,0,1] neg_hi:[0,0,1]
	v_pk_fma_f32 v[40:41], v[34:35], v[18:19], v[48:49] op_sel_hi:[0,1,1] neg_lo:[0,0,1] neg_hi:[0,0,1]
	v_pk_fma_f32 v[42:43], v[34:35], v[12:13], v[50:51] op_sel_hi:[0,1,1] neg_lo:[0,0,1] neg_hi:[0,0,1]
	v_cvt_pk_bf16_f32 v28, v36, v37
	v_cvt_pk_bf16_f32 v29, v38, v39
	v_cvt_pk_bf16_f32 v30, v40, v41
	v_cvt_pk_bf16_f32 v31, v42, v43
	global_store_dwordx4 v[10:11], v[28:31], off
	v_lshlrev_b32_e32 v44, 16, v148
	v_and_b32_e32 v45, 0xffff0000, v148
	v_lshlrev_b32_e32 v46, 16, v149
	v_and_b32_e32 v47, 0xffff0000, v149
	v_lshlrev_b32_e32 v48, 16, v150
	v_and_b32_e32 v49, 0xffff0000, v150
	v_lshlrev_b32_e32 v50, 16, v151
	v_and_b32_e32 v51, 0xffff0000, v151
	v_pk_add_f32 v[14:15], v[14:15], v[44:45] neg_lo:[0,1] neg_hi:[0,1]
	v_pk_add_f32 v[16:17], v[16:17], v[46:47] neg_lo:[0,1] neg_hi:[0,1]
	v_pk_add_f32 v[18:19], v[18:19], v[48:49] neg_lo:[0,1] neg_hi:[0,1]
	v_pk_add_f32 v[12:13], v[12:13], v[50:51] neg_lo:[0,1] neg_hi:[0,1]
	v_lshl_add_u64 v[10:11], v[10:11], 0, s[26:27]
	v_lshlrev_b32_e32 v44, 16, v180
	v_and_b32_e32 v45, 0xffff0000, v180
	v_lshlrev_b32_e32 v46, 16, v181
	v_and_b32_e32 v47, 0xffff0000, v181
	v_lshlrev_b32_e32 v48, 16, v182
	v_and_b32_e32 v49, 0xffff0000, v182
	v_lshlrev_b32_e32 v50, 16, v183
	v_and_b32_e32 v51, 0xffff0000, v183
	v_pk_add_f32 v[14:15], v[14:15], v[44:45]
	v_pk_add_f32 v[16:17], v[16:17], v[46:47]
	v_pk_add_f32 v[18:19], v[18:19], v[48:49]
	v_pk_add_f32 v[12:13], v[12:13], v[50:51]
	v_pk_fma_f32 v[36:37], v[34:35], v[14:15], v[44:45] op_sel_hi:[0,1,1] neg_lo:[0,0,1] neg_hi:[0,0,1]
	v_pk_fma_f32 v[38:39], v[34:35], v[16:17], v[46:47] op_sel_hi:[0,1,1] neg_lo:[0,0,1] neg_hi:[0,0,1]
	v_pk_fma_f32 v[40:41], v[34:35], v[18:19], v[48:49] op_sel_hi:[0,1,1] neg_lo:[0,0,1] neg_hi:[0,0,1]
	v_pk_fma_f32 v[42:43], v[34:35], v[12:13], v[50:51] op_sel_hi:[0,1,1] neg_lo:[0,0,1] neg_hi:[0,0,1]
	v_cvt_pk_bf16_f32 v28, v36, v37
	v_cvt_pk_bf16_f32 v29, v38, v39
	v_cvt_pk_bf16_f32 v30, v40, v41
	v_cvt_pk_bf16_f32 v31, v42, v43
	global_store_dwordx4 v[10:11], v[28:31], off
	v_lshlrev_b32_e32 v44, 16, v152
	v_and_b32_e32 v45, 0xffff0000, v152
	v_lshlrev_b32_e32 v46, 16, v153
	v_and_b32_e32 v47, 0xffff0000, v153
	v_lshlrev_b32_e32 v48, 16, v154
	v_and_b32_e32 v49, 0xffff0000, v154
	v_lshlrev_b32_e32 v50, 16, v155
	v_and_b32_e32 v51, 0xffff0000, v155
	v_pk_add_f32 v[14:15], v[14:15], v[44:45] neg_lo:[0,1] neg_hi:[0,1]
	v_pk_add_f32 v[16:17], v[16:17], v[46:47] neg_lo:[0,1] neg_hi:[0,1]
	v_pk_add_f32 v[18:19], v[18:19], v[48:49] neg_lo:[0,1] neg_hi:[0,1]
	v_pk_add_f32 v[12:13], v[12:13], v[50:51] neg_lo:[0,1] neg_hi:[0,1]
	v_lshl_add_u64 v[10:11], v[10:11], 0, s[26:27]
	v_lshlrev_b32_e32 v44, 16, v184
	v_and_b32_e32 v45, 0xffff0000, v184
	v_lshlrev_b32_e32 v46, 16, v185
	v_and_b32_e32 v47, 0xffff0000, v185
	v_lshlrev_b32_e32 v48, 16, v186
	v_and_b32_e32 v49, 0xffff0000, v186
	v_lshlrev_b32_e32 v50, 16, v187
	v_and_b32_e32 v51, 0xffff0000, v187
	v_pk_add_f32 v[14:15], v[14:15], v[44:45]
	v_pk_add_f32 v[16:17], v[16:17], v[46:47]
	v_pk_add_f32 v[18:19], v[18:19], v[48:49]
	v_pk_add_f32 v[12:13], v[12:13], v[50:51]
	v_pk_fma_f32 v[36:37], v[34:35], v[14:15], v[44:45] op_sel_hi:[0,1,1] neg_lo:[0,0,1] neg_hi:[0,0,1]
	v_pk_fma_f32 v[38:39], v[34:35], v[16:17], v[46:47] op_sel_hi:[0,1,1] neg_lo:[0,0,1] neg_hi:[0,0,1]
	v_pk_fma_f32 v[40:41], v[34:35], v[18:19], v[48:49] op_sel_hi:[0,1,1] neg_lo:[0,0,1] neg_hi:[0,0,1]
	v_pk_fma_f32 v[42:43], v[34:35], v[12:13], v[50:51] op_sel_hi:[0,1,1] neg_lo:[0,0,1] neg_hi:[0,0,1]
	v_cvt_pk_bf16_f32 v28, v36, v37
	v_cvt_pk_bf16_f32 v29, v38, v39
	v_cvt_pk_bf16_f32 v30, v40, v41
	v_cvt_pk_bf16_f32 v31, v42, v43
	global_store_dwordx4 v[10:11], v[28:31], off
	v_lshlrev_b32_e32 v44, 16, v156
	v_and_b32_e32 v45, 0xffff0000, v156
	v_lshlrev_b32_e32 v46, 16, v157
	v_and_b32_e32 v47, 0xffff0000, v157
	v_lshlrev_b32_e32 v48, 16, v158
	v_and_b32_e32 v49, 0xffff0000, v158
	v_lshlrev_b32_e32 v50, 16, v159
	v_and_b32_e32 v51, 0xffff0000, v159
	v_pk_add_f32 v[14:15], v[14:15], v[44:45] neg_lo:[0,1] neg_hi:[0,1]
	v_pk_add_f32 v[16:17], v[16:17], v[46:47] neg_lo:[0,1] neg_hi:[0,1]
	v_pk_add_f32 v[18:19], v[18:19], v[48:49] neg_lo:[0,1] neg_hi:[0,1]
	v_pk_add_f32 v[12:13], v[12:13], v[50:51] neg_lo:[0,1] neg_hi:[0,1]
; __device__ __forceinline__ unsigned pk2(float lo, float hi) { f32x2 v = {lo, hi}; bf16x2_t b = __builtin_convertvector(v, bf16x2_t); return __builtin_bit_cast(unsigned, b); }
; __device__ __forceinline__ void pool_window(const bf16_t* __restrict__ U  , bf16_t* __restrict__ A3, const int gtid, const int nthr) {
;     ...
;         for (int i = 0; i < 32; ++i) {
;             const int t = t0 + i, s = s0 + i;
;             const u32x4 uu = *(const u32x4*)(U + (size_t)t * LDU + c);
;             float cu[8] = {bflo(uu.x), bfhi(uu.x), bflo(uu.y), bfhi(uu.y), bflo(uu.z), bfhi(uu.z), bflo(uu.w), bfhi(uu.w)};
;             const float rc = 1.0f / (float)((s + 1) < w ? (s + 1) : w);
;             float o[8];
; #pragma unroll
;             for (int e = 0; e < 8; ++e) { sum[e] += cu[e]; o[e] = sum[e] * rc - cu[e]; }
;             u32x4 ww; ww.x = pk2(o[0], o[1]); ww.y = pk2(o[2], o[3]); ww.z = pk2(o[4], o[5]); ww.w = pk2(o[6], o[7]);
;             *(u32x4*)(A3 + (size_t)t * DM + c) = ww;
;             if (s + 1 >= w) { const u32x4 ud = *(const u32x4*)(U + (size_t)(t - w + 1) * LDU + c);
;                 sum[0] -= bflo(ud.x); sum[1] -= bfhi(ud.x); sum[2] -= bflo(ud.y); sum[3] -= bfhi(ud.y); sum[4] -= bflo(ud.z); sum[5] -= bfhi(ud.z); sum[6] -= bflo(ud.w); sum[7] -= bfhi(ud.w); }
	v_lshl_add_u64 v[10:11], v[10:11], 0, s[26:27]
	v_lshlrev_b32_e32 v44, 16, v188
	v_and_b32_e32 v45, 0xffff0000, v188
	v_lshlrev_b32_e32 v46, 16, v189
	v_and_b32_e32 v47, 0xffff0000, v189
	v_lshlrev_b32_e32 v48, 16, v190
	v_and_b32_e32 v49, 0xffff0000, v190
	v_lshlrev_b32_e32 v50, 16, v191
	v_and_b32_e32 v51, 0xffff0000, v191
	v_pk_add_f32 v[14:15], v[14:15], v[44:45]
	v_pk_add_f32 v[16:17], v[16:17], v[46:47]
	v_pk_add_f32 v[18:19], v[18:19], v[48:49]
	v_pk_add_f32 v[12:13], v[12:13], v[50:51]
	v_pk_fma_f32 v[36:37], v[34:35], v[14:15], v[44:45] op_sel_hi:[0,1,1] neg_lo:[0,0,1] neg_hi:[0,0,1]
	v_pk_fma_f32 v[38:39], v[34:35], v[16:17], v[46:47] op_sel_hi:[0,1,1] neg_lo:[0,0,1] neg_hi:[0,0,1]
	v_pk_fma_f32 v[40:41], v[34:35], v[18:19], v[48:49] op_sel_hi:[0,1,1] neg_lo:[0,0,1] neg_hi:[0,0,1]
	v_pk_fma_f32 v[42:43], v[34:35], v[12:13], v[50:51] op_sel_hi:[0,1,1] neg_lo:[0,0,1] neg_hi:[0,0,1]
	v_cvt_pk_bf16_f32 v28, v36, v37
	v_cvt_pk_bf16_f32 v29, v38, v39
	v_cvt_pk_bf16_f32 v30, v40, v41
	v_cvt_pk_bf16_f32 v31, v42, v43
	global_store_dwordx4 v[10:11], v[28:31], off
	v_lshlrev_b32_e32 v44, 16, v160
	v_and_b32_e32 v45, 0xffff0000, v160
	v_lshlrev_b32_e32 v46, 16, v161
	v_and_b32_e32 v47, 0xffff0000, v161
	v_lshlrev_b32_e32 v48, 16, v162
	v_and_b32_e32 v49, 0xffff0000, v162
	v_lshlrev_b32_e32 v50, 16, v163
	v_and_b32_e32 v51, 0xffff0000, v163
	v_pk_add_f32 v[14:15], v[14:15], v[44:45] neg_lo:[0,1] neg_hi:[0,1]
	v_pk_add_f32 v[16:17], v[16:17], v[46:47] neg_lo:[0,1] neg_hi:[0,1]
	v_pk_add_f32 v[18:19], v[18:19], v[48:49] neg_lo:[0,1] neg_hi:[0,1]
	v_pk_add_f32 v[12:13], v[12:13], v[50:51] neg_lo:[0,1] neg_hi:[0,1]
	v_lshl_add_u64 v[10:11], v[10:11], 0, s[26:27]
	v_lshlrev_b32_e32 v44, 16, v192
	v_and_b32_e32 v45, 0xffff0000, v192
	v_lshlrev_b32_e32 v46, 16, v193
	v_and_b32_e32 v47, 0xffff0000, v193
	v_lshlrev_b32_e32 v48, 16, v194
	v_and_b32_e32 v49, 0xffff0000, v194
	v_lshlrev_b32_e32 v50, 16, v195
	v_and_b32_e32 v51, 0xffff0000, v195
	v_pk_add_f32 v[14:15], v[14:15], v[44:45]
	v_pk_add_f32 v[16:17], v[16:17], v[46:47]
	v_pk_add_f32 v[18:19], v[18:19], v[48:49]
	v_pk_add_f32 v[12:13], v[12:13], v[50:51]
	v_pk_fma_f32 v[36:37], v[34:35], v[14:15], v[44:45] op_sel_hi:[0,1,1] neg_lo:[0,0,1] neg_hi:[0,0,1]
	v_pk_fma_f32 v[38:39], v[34:35], v[16:17], v[46:47] op_sel_hi:[0,1,1] neg_lo:[0,0,1] neg_hi:[0,0,1]
	v_pk_fma_f32 v[40:41], v[34:35], v[18:19], v[48:49] op_sel_hi:[0,1,1] neg_lo:[0,0,1] neg_hi:[0,0,1]
	v_pk_fma_f32 v[42:43], v[34:35], v[12:13], v[50:51] op_sel_hi:[0,1,1] neg_lo:[0,0,1] neg_hi:[0,0,1]
	v_cvt_pk_bf16_f32 v28, v36, v37
	v_cvt_pk_bf16_f32 v29, v38, v39
	v_cvt_pk_bf16_f32 v30, v40, v41
	v_cvt_pk_bf16_f32 v31, v42, v43
	global_store_dwordx4 v[10:11], v[28:31], off
	v_lshlrev_b32_e32 v44, 16, v164
	v_and_b32_e32 v45, 0xffff0000, v164
	v_lshlrev_b32_e32 v46, 16, v165
	v_and_b32_e32 v47, 0xffff0000, v165
	v_lshlrev_b32_e32 v48, 16, v166
	v_and_b32_e32 v49, 0xffff0000, v166
	v_lshlrev_b32_e32 v50, 16, v167
	v_and_b32_e32 v51, 0xffff0000, v167
	v_pk_add_f32 v[14:15], v[14:15], v[44:45] neg_lo:[0,1] neg_hi:[0,1]
	v_pk_add_f32 v[16:17], v[16:17], v[46:47] neg_lo:[0,1] neg_hi:[0,1]
	v_pk_add_f32 v[18:19], v[18:19], v[48:49] neg_lo:[0,1] neg_hi:[0,1]
	v_pk_add_f32 v[12:13], v[12:13], v[50:51] neg_lo:[0,1] neg_hi:[0,1]
	v_lshl_add_u64 v[10:11], v[10:11], 0, s[26:27]
	v_lshlrev_b32_e32 v44, 16, v196
	v_and_b32_e32 v45, 0xffff0000, v196
	v_lshlrev_b32_e32 v46, 16, v197
	v_and_b32_e32 v47, 0xffff0000, v197
	v_lshlrev_b32_e32 v48, 16, v198
	v_and_b32_e32 v49, 0xffff0000, v198
	v_lshlrev_b32_e32 v50, 16, v199
	v_and_b32_e32 v51, 0xffff0000, v199
	v_pk_add_f32 v[14:15], v[14:15], v[44:45]
	v_pk_add_f32 v[16:17], v[16:17], v[46:47]
	v_pk_add_f32 v[18:19], v[18:19], v[48:49]
	v_pk_add_f32 v[12:13], v[12:13], v[50:51]
	v_pk_fma_f32 v[36:37], v[34:35], v[14:15], v[44:45] op_sel_hi:[0,1,1] neg_lo:[0,0,1] neg_hi:[0,0,1]
	v_pk_fma_f32 v[38:39], v[34:35], v[16:17], v[46:47] op_sel_hi:[0,1,1] neg_lo:[0,0,1] neg_hi:[0,0,1]
	v_pk_fma_f32 v[40:41], v[34:35], v[18:19], v[48:49] op_sel_hi:[0,1,1] neg_lo:[0,0,1] neg_hi:[0,0,1]
	v_pk_fma_f32 v[42:43], v[34:35], v[12:13], v[50:51] op_sel_hi:[0,1,1] neg_lo:[0,0,1] neg_hi:[0,0,1]
	v_cvt_pk_bf16_f32 v28, v36, v37
	v_cvt_pk_bf16_f32 v29, v38, v39
	v_cvt_pk_bf16_f32 v30, v40, v41
	v_cvt_pk_bf16_f32 v31, v42, v43
	global_store_dwordx4 v[10:11], v[28:31], off
	v_lshlrev_b32_e32 v44, 16, v168
	v_and_b32_e32 v45, 0xffff0000, v168
	v_lshlrev_b32_e32 v46, 16, v169
	v_and_b32_e32 v47, 0xffff0000, v169
	v_lshlrev_b32_e32 v48, 16, v170
	v_and_b32_e32 v49, 0xffff0000, v170
	v_lshlrev_b32_e32 v50, 16, v171
	v_and_b32_e32 v51, 0xffff0000, v171
	v_pk_add_f32 v[14:15], v[14:15], v[44:45] neg_lo:[0,1] neg_hi:[0,1]
	v_pk_add_f32 v[16:17], v[16:17], v[46:47] neg_lo:[0,1] neg_hi:[0,1]
	v_pk_add_f32 v[18:19], v[18:19], v[48:49] neg_lo:[0,1] neg_hi:[0,1]
	v_pk_add_f32 v[12:13], v[12:13], v[50:51] neg_lo:[0,1] neg_hi:[0,1]
	v_lshl_add_u64 v[10:11], v[10:11], 0, s[26:27]
	v_lshlrev_b32_e32 v44, 16, v200
	v_and_b32_e32 v45, 0xffff0000, v200
	v_lshlrev_b32_e32 v46, 16, v201
	v_and_b32_e32 v47, 0xffff0000, v201
	v_lshlrev_b32_e32 v48, 16, v202
	v_and_b32_e32 v49, 0xffff0000, v202
	v_lshlrev_b32_e32 v50, 16, v203
	v_and_b32_e32 v51, 0xffff0000, v203
	v_pk_add_f32 v[14:15], v[14:15], v[44:45]
	v_pk_add_f32 v[16:17], v[16:17], v[46:47]
	v_pk_add_f32 v[18:19], v[18:19], v[48:49]
	v_pk_add_f32 v[12:13], v[12:13], v[50:51]
	v_pk_fma_f32 v[36:37], v[34:35], v[14:15], v[44:45] op_sel_hi:[0,1,1] neg_lo:[0,0,1] neg_hi:[0,0,1]
	v_pk_fma_f32 v[38:39], v[34:35], v[16:17], v[46:47] op_sel_hi:[0,1,1] neg_lo:[0,0,1] neg_hi:[0,0,1]
; __device__ __forceinline__ unsigned pk2(float lo, float hi) { f32x2 v = {lo, hi}; bf16x2_t b = __builtin_convertvector(v, bf16x2_t); return __builtin_bit_cast(unsigned, b); }
; __device__ __forceinline__ void pool_window(const bf16_t* __restrict__ U  , bf16_t* __restrict__ A3, const int gtid, const int nthr) {
;     ...
;         for (int i = 0; i < 32; ++i) {
;             const int t = t0 + i, s = s0 + i;
;             const u32x4 uu = *(const u32x4*)(U + (size_t)t * LDU + c);
;             float cu[8] = {bflo(uu.x), bfhi(uu.x), bflo(uu.y), bfhi(uu.y), bflo(uu.z), bfhi(uu.z), bflo(uu.w), bfhi(uu.w)};
;             const float rc = 1.0f / (float)((s + 1) < w ? (s + 1) : w);
;             float o[8];
; #pragma unroll
;             for (int e = 0; e < 8; ++e) { sum[e] += cu[e]; o[e] = sum[e] * rc - cu[e]; }
;             u32x4 ww; ww.x = pk2(o[0], o[1]); ww.y = pk2(o[2], o[3]); ww.z = pk2(o[4], o[5]); ww.w = pk2(o[6], o[7]);
;             *(u32x4*)(A3 + (size_t)t * DM + c) = ww;
;             if (s + 1 >= w) { const u32x4 ud = *(const u32x4*)(U + (size_t)(t - w + 1) * LDU + c);
;                 sum[0] -= bflo(ud.x); sum[1] -= bfhi(ud.x); sum[2] -= bflo(ud.y); sum[3] -= bfhi(ud.y); sum[4] -= bflo(ud.z); sum[5] -= bfhi(ud.z); sum[6] -= bflo(ud.w); sum[7] -= bfhi(ud.w); }
	v_pk_fma_f32 v[40:41], v[34:35], v[18:19], v[48:49] op_sel_hi:[0,1,1] neg_lo:[0,0,1] neg_hi:[0,0,1]
	v_pk_fma_f32 v[42:43], v[34:35], v[12:13], v[50:51] op_sel_hi:[0,1,1] neg_lo:[0,0,1] neg_hi:[0,0,1]
	v_cvt_pk_bf16_f32 v28, v36, v37
	v_cvt_pk_bf16_f32 v29, v38, v39
	v_cvt_pk_bf16_f32 v30, v40, v41
	v_cvt_pk_bf16_f32 v31, v42, v43
	global_store_dwordx4 v[10:11], v[28:31], off
	v_lshlrev_b32_e32 v44, 16, v172
	v_and_b32_e32 v45, 0xffff0000, v172
	v_lshlrev_b32_e32 v46, 16, v173
	v_and_b32_e32 v47, 0xffff0000, v173
	v_lshlrev_b32_e32 v48, 16, v174
	v_and_b32_e32 v49, 0xffff0000, v174
	v_lshlrev_b32_e32 v50, 16, v175
	v_and_b32_e32 v51, 0xffff0000, v175
	v_pk_add_f32 v[14:15], v[14:15], v[44:45] neg_lo:[0,1] neg_hi:[0,1]
	v_pk_add_f32 v[16:17], v[16:17], v[46:47] neg_lo:[0,1] neg_hi:[0,1]
	v_pk_add_f32 v[18:19], v[18:19], v[48:49] neg_lo:[0,1] neg_hi:[0,1]
	v_pk_add_f32 v[12:13], v[12:13], v[50:51] neg_lo:[0,1] neg_hi:[0,1]
	v_lshl_add_u64 v[10:11], v[10:11], 0, s[26:27]
	v_lshlrev_b32_e32 v44, 16, v204
	v_and_b32_e32 v45, 0xffff0000, v204
	v_lshlrev_b32_e32 v46, 16, v205
	v_and_b32_e32 v47, 0xffff0000, v205
	v_lshlrev_b32_e32 v48, 16, v206
	v_and_b32_e32 v49, 0xffff0000, v206
	v_lshlrev_b32_e32 v50, 16, v207
	v_and_b32_e32 v51, 0xffff0000, v207
	v_pk_add_f32 v[14:15], v[14:15], v[44:45]
	v_pk_add_f32 v[16:17], v[16:17], v[46:47]
	v_pk_add_f32 v[18:19], v[18:19], v[48:49]
	v_pk_add_f32 v[12:13], v[12:13], v[50:51]
	v_pk_fma_f32 v[36:37], v[34:35], v[14:15], v[44:45] op_sel_hi:[0,1,1] neg_lo:[0,0,1] neg_hi:[0,0,1]
	v_pk_fma_f32 v[38:39], v[34:35], v[16:17], v[46:47] op_sel_hi:[0,1,1] neg_lo:[0,0,1] neg_hi:[0,0,1]
	v_pk_fma_f32 v[40:41], v[34:35], v[18:19], v[48:49] op_sel_hi:[0,1,1] neg_lo:[0,0,1] neg_hi:[0,0,1]
	v_pk_fma_f32 v[42:43], v[34:35], v[12:13], v[50:51] op_sel_hi:[0,1,1] neg_lo:[0,0,1] neg_hi:[0,0,1]
	v_cvt_pk_bf16_f32 v28, v36, v37
	v_cvt_pk_bf16_f32 v29, v38, v39
	v_cvt_pk_bf16_f32 v30, v40, v41
	v_cvt_pk_bf16_f32 v31, v42, v43
	global_store_dwordx4 v[10:11], v[28:31], off
	v_lshlrev_b32_e32 v44, 16, v176
	v_and_b32_e32 v45, 0xffff0000, v176
	v_lshlrev_b32_e32 v46, 16, v177
	v_and_b32_e32 v47, 0xffff0000, v177
	v_lshlrev_b32_e32 v48, 16, v178
	v_and_b32_e32 v49, 0xffff0000, v178
	v_lshlrev_b32_e32 v50, 16, v179
	v_and_b32_e32 v51, 0xffff0000, v179
	v_pk_add_f32 v[14:15], v[14:15], v[44:45] neg_lo:[0,1] neg_hi:[0,1]
	v_pk_add_f32 v[16:17], v[16:17], v[46:47] neg_lo:[0,1] neg_hi:[0,1]
	v_pk_add_f32 v[18:19], v[18:19], v[48:49] neg_lo:[0,1] neg_hi:[0,1]
	v_pk_add_f32 v[12:13], v[12:13], v[50:51] neg_lo:[0,1] neg_hi:[0,1]
	v_lshl_add_u64 v[10:11], v[10:11], 0, s[26:27]
	v_lshlrev_b32_e32 v44, 16, v208
	v_and_b32_e32 v45, 0xffff0000, v208
	v_lshlrev_b32_e32 v46, 16, v209
	v_and_b32_e32 v47, 0xffff0000, v209
	v_lshlrev_b32_e32 v48, 16, v210
	v_and_b32_e32 v49, 0xffff0000, v210
	v_lshlrev_b32_e32 v50, 16, v211
	v_and_b32_e32 v51, 0xffff0000, v211
	v_pk_add_f32 v[14:15], v[14:15], v[44:45]
	v_pk_add_f32 v[16:17], v[16:17], v[46:47]
	v_pk_add_f32 v[18:19], v[18:19], v[48:49]
	v_pk_add_f32 v[12:13], v[12:13], v[50:51]
	v_pk_fma_f32 v[36:37], v[34:35], v[14:15], v[44:45] op_sel_hi:[0,1,1] neg_lo:[0,0,1] neg_hi:[0,0,1]
	v_pk_fma_f32 v[38:39], v[34:35], v[16:17], v[46:47] op_sel_hi:[0,1,1] neg_lo:[0,0,1] neg_hi:[0,0,1]
	v_pk_fma_f32 v[40:41], v[34:35], v[18:19], v[48:49] op_sel_hi:[0,1,1] neg_lo:[0,0,1] neg_hi:[0,0,1]
	v_pk_fma_f32 v[42:43], v[34:35], v[12:13], v[50:51] op_sel_hi:[0,1,1] neg_lo:[0,0,1] neg_hi:[0,0,1]
	v_cvt_pk_bf16_f32 v28, v36, v37
	v_cvt_pk_bf16_f32 v29, v38, v39
	v_cvt_pk_bf16_f32 v30, v40, v41
	v_cvt_pk_bf16_f32 v31, v42, v43
	global_store_dwordx4 v[10:11], v[28:31], off
	v_lshlrev_b32_e32 v44, 16, v180
	v_and_b32_e32 v45, 0xffff0000, v180
	v_lshlrev_b32_e32 v46, 16, v181
	v_and_b32_e32 v47, 0xffff0000, v181
	v_lshlrev_b32_e32 v48, 16, v182
	v_and_b32_e32 v49, 0xffff0000, v182
	v_lshlrev_b32_e32 v50, 16, v183
	v_and_b32_e32 v51, 0xffff0000, v183
	v_pk_add_f32 v[14:15], v[14:15], v[44:45] neg_lo:[0,1] neg_hi:[0,1]
	v_pk_add_f32 v[16:17], v[16:17], v[46:47] neg_lo:[0,1] neg_hi:[0,1]
	v_pk_add_f32 v[18:19], v[18:19], v[48:49] neg_lo:[0,1] neg_hi:[0,1]
	v_pk_add_f32 v[12:13], v[12:13], v[50:51] neg_lo:[0,1] neg_hi:[0,1]
	v_lshl_add_u64 v[10:11], v[10:11], 0, s[26:27]
	v_lshlrev_b32_e32 v44, 16, v214
	v_and_b32_e32 v45, 0xffff0000, v214
	v_lshlrev_b32_e32 v46, 16, v215
	v_and_b32_e32 v47, 0xffff0000, v215
	v_lshlrev_b32_e32 v48, 16, v216
	v_and_b32_e32 v49, 0xffff0000, v216
	v_lshlrev_b32_e32 v50, 16, v217
	v_and_b32_e32 v51, 0xffff0000, v217
	v_pk_add_f32 v[14:15], v[14:15], v[44:45]
	v_pk_add_f32 v[16:17], v[16:17], v[46:47]
	v_pk_add_f32 v[18:19], v[18:19], v[48:49]
	v_pk_add_f32 v[12:13], v[12:13], v[50:51]
	v_pk_fma_f32 v[36:37], v[34:35], v[14:15], v[44:45] op_sel_hi:[0,1,1] neg_lo:[0,0,1] neg_hi:[0,0,1]
	v_pk_fma_f32 v[38:39], v[34:35], v[16:17], v[46:47] op_sel_hi:[0,1,1] neg_lo:[0,0,1] neg_hi:[0,0,1]
	v_pk_fma_f32 v[40:41], v[34:35], v[18:19], v[48:49] op_sel_hi:[0,1,1] neg_lo:[0,0,1] neg_hi:[0,0,1]
	v_pk_fma_f32 v[42:43], v[34:35], v[12:13], v[50:51] op_sel_hi:[0,1,1] neg_lo:[0,0,1] neg_hi:[0,0,1]
	v_cvt_pk_bf16_f32 v28, v36, v37
	v_cvt_pk_bf16_f32 v29, v38, v39
	v_cvt_pk_bf16_f32 v30, v40, v41
	v_cvt_pk_bf16_f32 v31, v42, v43
	global_store_dwordx4 v[10:11], v[28:31], off
	v_lshlrev_b32_e32 v44, 16, v184
	v_and_b32_e32 v45, 0xffff0000, v184
	v_lshlrev_b32_e32 v46, 16, v185
	v_and_b32_e32 v47, 0xffff0000, v185
	v_lshlrev_b32_e32 v48, 16, v186
	v_and_b32_e32 v49, 0xffff0000, v186
	v_lshlrev_b32_e32 v50, 16, v187
	v_and_b32_e32 v51, 0xffff0000, v187
	v_pk_add_f32 v[14:15], v[14:15], v[44:45] neg_lo:[0,1] neg_hi:[0,1]
; __device__ __forceinline__ unsigned pk2(float lo, float hi) { f32x2 v = {lo, hi}; bf16x2_t b = __builtin_convertvector(v, bf16x2_t); return __builtin_bit_cast(unsigned, b); }
; __device__ __forceinline__ void pool_window(const bf16_t* __restrict__ U  , bf16_t* __restrict__ A3, const int gtid, const int nthr) {
;     ...
;         for (int i = 0; i < 32; ++i) {
;             const int t = t0 + i, s = s0 + i;
;             const u32x4 uu = *(const u32x4*)(U + (size_t)t * LDU + c);
;             float cu[8] = {bflo(uu.x), bfhi(uu.x), bflo(uu.y), bfhi(uu.y), bflo(uu.z), bfhi(uu.z), bflo(uu.w), bfhi(uu.w)};
;             const float rc = 1.0f / (float)((s + 1) < w ? (s + 1) : w);
;             float o[8];
; #pragma unroll
;             for (int e = 0; e < 8; ++e) { sum[e] += cu[e]; o[e] = sum[e] * rc - cu[e]; }
;             u32x4 ww; ww.x = pk2(o[0], o[1]); ww.y = pk2(o[2], o[3]); ww.z = pk2(o[4], o[5]); ww.w = pk2(o[6], o[7]);
;             *(u32x4*)(A3 + (size_t)t * DM + c) = ww;
;             if (s + 1 >= w) { const u32x4 ud = *(const u32x4*)(U + (size_t)(t - w + 1) * LDU + c);
;                 sum[0] -= bflo(ud.x); sum[1] -= bfhi(ud.x); sum[2] -= bflo(ud.y); sum[3] -= bfhi(ud.y); sum[4] -= bflo(ud.z); sum[5] -= bfhi(ud.z); sum[6] -= bflo(ud.w); sum[7] -= bfhi(ud.w); }
	v_pk_add_f32 v[16:17], v[16:17], v[46:47] neg_lo:[0,1] neg_hi:[0,1]
	v_pk_add_f32 v[18:19], v[18:19], v[48:49] neg_lo:[0,1] neg_hi:[0,1]
	v_pk_add_f32 v[12:13], v[12:13], v[50:51] neg_lo:[0,1] neg_hi:[0,1]
	v_lshl_add_u64 v[10:11], v[10:11], 0, s[26:27]
	v_lshlrev_b32_e32 v44, 16, v218
	v_and_b32_e32 v45, 0xffff0000, v218
	v_lshlrev_b32_e32 v46, 16, v219
	v_and_b32_e32 v47, 0xffff0000, v219
	v_lshlrev_b32_e32 v48, 16, v220
	v_and_b32_e32 v49, 0xffff0000, v220
	v_lshlrev_b32_e32 v50, 16, v221
	v_and_b32_e32 v51, 0xffff0000, v221
	v_pk_add_f32 v[14:15], v[14:15], v[44:45]
	v_pk_add_f32 v[16:17], v[16:17], v[46:47]
	v_pk_add_f32 v[18:19], v[18:19], v[48:49]
	v_pk_add_f32 v[12:13], v[12:13], v[50:51]
	v_pk_fma_f32 v[36:37], v[34:35], v[14:15], v[44:45] op_sel_hi:[0,1,1] neg_lo:[0,0,1] neg_hi:[0,0,1]
	v_pk_fma_f32 v[38:39], v[34:35], v[16:17], v[46:47] op_sel_hi:[0,1,1] neg_lo:[0,0,1] neg_hi:[0,0,1]
	v_pk_fma_f32 v[40:41], v[34:35], v[18:19], v[48:49] op_sel_hi:[0,1,1] neg_lo:[0,0,1] neg_hi:[0,0,1]
	v_pk_fma_f32 v[42:43], v[34:35], v[12:13], v[50:51] op_sel_hi:[0,1,1] neg_lo:[0,0,1] neg_hi:[0,0,1]
	v_cvt_pk_bf16_f32 v28, v36, v37
	v_cvt_pk_bf16_f32 v29, v38, v39
	v_cvt_pk_bf16_f32 v30, v40, v41
	v_cvt_pk_bf16_f32 v31, v42, v43
	global_store_dwordx4 v[10:11], v[28:31], off
	v_lshlrev_b32_e32 v44, 16, v188
	v_and_b32_e32 v45, 0xffff0000, v188
	v_lshlrev_b32_e32 v46, 16, v189
	v_and_b32_e32 v47, 0xffff0000, v189
	v_lshlrev_b32_e32 v48, 16, v190
	v_and_b32_e32 v49, 0xffff0000, v190
	v_lshlrev_b32_e32 v50, 16, v191
	v_and_b32_e32 v51, 0xffff0000, v191
	v_pk_add_f32 v[14:15], v[14:15], v[44:45] neg_lo:[0,1] neg_hi:[0,1]
	v_pk_add_f32 v[16:17], v[16:17], v[46:47] neg_lo:[0,1] neg_hi:[0,1]
	v_pk_add_f32 v[18:19], v[18:19], v[48:49] neg_lo:[0,1] neg_hi:[0,1]
	v_pk_add_f32 v[12:13], v[12:13], v[50:51] neg_lo:[0,1] neg_hi:[0,1]
	v_lshl_add_u64 v[10:11], v[10:11], 0, s[26:27]
	v_lshlrev_b32_e32 v44, 16, v222
	v_and_b32_e32 v45, 0xffff0000, v222
	v_lshlrev_b32_e32 v46, 16, v223
	v_and_b32_e32 v47, 0xffff0000, v223
	v_lshlrev_b32_e32 v48, 16, v224
	v_and_b32_e32 v49, 0xffff0000, v224
	v_lshlrev_b32_e32 v50, 16, v225
	v_and_b32_e32 v51, 0xffff0000, v225
	v_pk_add_f32 v[14:15], v[14:15], v[44:45]
	v_pk_add_f32 v[16:17], v[16:17], v[46:47]
	v_pk_add_f32 v[18:19], v[18:19], v[48:49]
	v_pk_add_f32 v[12:13], v[12:13], v[50:51]
	v_pk_fma_f32 v[36:37], v[34:35], v[14:15], v[44:45] op_sel_hi:[0,1,1] neg_lo:[0,0,1] neg_hi:[0,0,1]
	v_pk_fma_f32 v[38:39], v[34:35], v[16:17], v[46:47] op_sel_hi:[0,1,1] neg_lo:[0,0,1] neg_hi:[0,0,1]
	v_pk_fma_f32 v[40:41], v[34:35], v[18:19], v[48:49] op_sel_hi:[0,1,1] neg_lo:[0,0,1] neg_hi:[0,0,1]
	v_pk_fma_f32 v[42:43], v[34:35], v[12:13], v[50:51] op_sel_hi:[0,1,1] neg_lo:[0,0,1] neg_hi:[0,0,1]
	v_cvt_pk_bf16_f32 v28, v36, v37
	v_cvt_pk_bf16_f32 v29, v38, v39
	v_cvt_pk_bf16_f32 v30, v40, v41
	v_cvt_pk_bf16_f32 v31, v42, v43
	global_store_dwordx4 v[10:11], v[28:31], off
	v_lshlrev_b32_e32 v44, 16, v192
	v_and_b32_e32 v45, 0xffff0000, v192
	v_lshlrev_b32_e32 v46, 16, v193
	v_and_b32_e32 v47, 0xffff0000, v193
	v_lshlrev_b32_e32 v48, 16, v194
	v_and_b32_e32 v49, 0xffff0000, v194
	v_lshlrev_b32_e32 v50, 16, v195
	v_and_b32_e32 v51, 0xffff0000, v195
	v_pk_add_f32 v[14:15], v[14:15], v[44:45] neg_lo:[0,1] neg_hi:[0,1]
	v_pk_add_f32 v[16:17], v[16:17], v[46:47] neg_lo:[0,1] neg_hi:[0,1]
	v_pk_add_f32 v[18:19], v[18:19], v[48:49] neg_lo:[0,1] neg_hi:[0,1]
	v_pk_add_f32 v[12:13], v[12:13], v[50:51] neg_lo:[0,1] neg_hi:[0,1]
	v_lshl_add_u64 v[10:11], v[10:11], 0, s[26:27]
	v_lshlrev_b32_e32 v44, 16, v226
	v_and_b32_e32 v45, 0xffff0000, v226
	v_lshlrev_b32_e32 v46, 16, v227
	v_and_b32_e32 v47, 0xffff0000, v227
	v_lshlrev_b32_e32 v48, 16, v228
	v_and_b32_e32 v49, 0xffff0000, v228
	v_lshlrev_b32_e32 v50, 16, v229
	v_and_b32_e32 v51, 0xffff0000, v229
	v_pk_add_f32 v[14:15], v[14:15], v[44:45]
	v_pk_add_f32 v[16:17], v[16:17], v[46:47]
	v_pk_add_f32 v[18:19], v[18:19], v[48:49]
	v_pk_add_f32 v[12:13], v[12:13], v[50:51]
	v_pk_fma_f32 v[36:37], v[34:35], v[14:15], v[44:45] op_sel_hi:[0,1,1] neg_lo:[0,0,1] neg_hi:[0,0,1]
	v_pk_fma_f32 v[38:39], v[34:35], v[16:17], v[46:47] op_sel_hi:[0,1,1] neg_lo:[0,0,1] neg_hi:[0,0,1]
	v_pk_fma_f32 v[40:41], v[34:35], v[18:19], v[48:49] op_sel_hi:[0,1,1] neg_lo:[0,0,1] neg_hi:[0,0,1]
	v_pk_fma_f32 v[42:43], v[34:35], v[12:13], v[50:51] op_sel_hi:[0,1,1] neg_lo:[0,0,1] neg_hi:[0,0,1]
	v_cvt_pk_bf16_f32 v28, v36, v37
	v_cvt_pk_bf16_f32 v29, v38, v39
	v_cvt_pk_bf16_f32 v30, v40, v41
	v_cvt_pk_bf16_f32 v31, v42, v43
	global_store_dwordx4 v[10:11], v[28:31], off
	v_lshlrev_b32_e32 v44, 16, v196
	v_and_b32_e32 v45, 0xffff0000, v196
	v_lshlrev_b32_e32 v46, 16, v197
	v_and_b32_e32 v47, 0xffff0000, v197
	v_lshlrev_b32_e32 v48, 16, v198
	v_and_b32_e32 v49, 0xffff0000, v198
	v_lshlrev_b32_e32 v50, 16, v199
	v_and_b32_e32 v51, 0xffff0000, v199
	v_pk_add_f32 v[14:15], v[14:15], v[44:45] neg_lo:[0,1] neg_hi:[0,1]
	v_pk_add_f32 v[16:17], v[16:17], v[46:47] neg_lo:[0,1] neg_hi:[0,1]
	v_pk_add_f32 v[18:19], v[18:19], v[48:49] neg_lo:[0,1] neg_hi:[0,1]
	v_pk_add_f32 v[12:13], v[12:13], v[50:51] neg_lo:[0,1] neg_hi:[0,1]
	v_lshl_add_u64 v[10:11], v[10:11], 0, s[26:27]
	v_lshlrev_b32_e32 v44, 16, v230
	v_and_b32_e32 v45, 0xffff0000, v230
	v_lshlrev_b32_e32 v46, 16, v231
	v_and_b32_e32 v47, 0xffff0000, v231
	v_lshlrev_b32_e32 v48, 16, v232
	v_and_b32_e32 v49, 0xffff0000, v232
	v_lshlrev_b32_e32 v50, 16, v233
	v_and_b32_e32 v51, 0xffff0000, v233
	v_pk_add_f32 v[14:15], v[14:15], v[44:45]
	v_pk_add_f32 v[16:17], v[16:17], v[46:47]
	v_pk_add_f32 v[18:19], v[18:19], v[48:49]
	v_pk_add_f32 v[12:13], v[12:13], v[50:51]
; __device__ __forceinline__ unsigned pk2(float lo, float hi) { f32x2 v = {lo, hi}; bf16x2_t b = __builtin_convertvector(v, bf16x2_t); return __builtin_bit_cast(unsigned, b); }
; __device__ __forceinline__ void pool_window(const bf16_t* __restrict__ U  , bf16_t* __restrict__ A3, const int gtid, const int nthr) {
;     ...
;         for (int i = 0; i < 32; ++i) {
;             const int t = t0 + i, s = s0 + i;
;             const u32x4 uu = *(const u32x4*)(U + (size_t)t * LDU + c);
;             float cu[8] = {bflo(uu.x), bfhi(uu.x), bflo(uu.y), bfhi(uu.y), bflo(uu.z), bfhi(uu.z), bflo(uu.w), bfhi(uu.w)};
;             const float rc = 1.0f / (float)((s + 1) < w ? (s + 1) : w);
;             float o[8];
; #pragma unroll
;             for (int e = 0; e < 8; ++e) { sum[e] += cu[e]; o[e] = sum[e] * rc - cu[e]; }
;             u32x4 ww; ww.x = pk2(o[0], o[1]); ww.y = pk2(o[2], o[3]); ww.z = pk2(o[4], o[5]); ww.w = pk2(o[6], o[7]);
;             *(u32x4*)(A3 + (size_t)t * DM + c) = ww;
;             if (s + 1 >= w) { const u32x4 ud = *(const u32x4*)(U + (size_t)(t - w + 1) * LDU + c);
;                 sum[0] -= bflo(ud.x); sum[1] -= bfhi(ud.x); sum[2] -= bflo(ud.y); sum[3] -= bfhi(ud.y); sum[4] -= bflo(ud.z); sum[5] -= bfhi(ud.z); sum[6] -= bflo(ud.w); sum[7] -= bfhi(ud.w); }
	v_pk_fma_f32 v[36:37], v[34:35], v[14:15], v[44:45] op_sel_hi:[0,1,1] neg_lo:[0,0,1] neg_hi:[0,0,1]
	v_pk_fma_f32 v[38:39], v[34:35], v[16:17], v[46:47] op_sel_hi:[0,1,1] neg_lo:[0,0,1] neg_hi:[0,0,1]
	v_pk_fma_f32 v[40:41], v[34:35], v[18:19], v[48:49] op_sel_hi:[0,1,1] neg_lo:[0,0,1] neg_hi:[0,0,1]
	v_pk_fma_f32 v[42:43], v[34:35], v[12:13], v[50:51] op_sel_hi:[0,1,1] neg_lo:[0,0,1] neg_hi:[0,0,1]
	v_cvt_pk_bf16_f32 v28, v36, v37
	v_cvt_pk_bf16_f32 v29, v38, v39
	v_cvt_pk_bf16_f32 v30, v40, v41
	v_cvt_pk_bf16_f32 v31, v42, v43
	global_store_dwordx4 v[10:11], v[28:31], off
	v_lshlrev_b32_e32 v44, 16, v200
	v_and_b32_e32 v45, 0xffff0000, v200
	v_lshlrev_b32_e32 v46, 16, v201
	v_and_b32_e32 v47, 0xffff0000, v201
	v_lshlrev_b32_e32 v48, 16, v202
	v_and_b32_e32 v49, 0xffff0000, v202
	v_lshlrev_b32_e32 v50, 16, v203
	v_and_b32_e32 v51, 0xffff0000, v203
	v_pk_add_f32 v[14:15], v[14:15], v[44:45] neg_lo:[0,1] neg_hi:[0,1]
	v_pk_add_f32 v[16:17], v[16:17], v[46:47] neg_lo:[0,1] neg_hi:[0,1]
	v_pk_add_f32 v[18:19], v[18:19], v[48:49] neg_lo:[0,1] neg_hi:[0,1]
	v_pk_add_f32 v[12:13], v[12:13], v[50:51] neg_lo:[0,1] neg_hi:[0,1]
	v_lshl_add_u64 v[10:11], v[10:11], 0, s[26:27]
	v_lshlrev_b32_e32 v44, 16, v234
	v_and_b32_e32 v45, 0xffff0000, v234
	v_lshlrev_b32_e32 v46, 16, v235
	v_and_b32_e32 v47, 0xffff0000, v235
	v_lshlrev_b32_e32 v48, 16, v236
	v_and_b32_e32 v49, 0xffff0000, v236
	v_lshlrev_b32_e32 v50, 16, v237
	v_and_b32_e32 v51, 0xffff0000, v237
	v_pk_add_f32 v[14:15], v[14:15], v[44:45]
	v_pk_add_f32 v[16:17], v[16:17], v[46:47]
	v_pk_add_f32 v[18:19], v[18:19], v[48:49]
	v_pk_add_f32 v[12:13], v[12:13], v[50:51]
	v_pk_fma_f32 v[36:37], v[34:35], v[14:15], v[44:45] op_sel_hi:[0,1,1] neg_lo:[0,0,1] neg_hi:[0,0,1]
	v_pk_fma_f32 v[38:39], v[34:35], v[16:17], v[46:47] op_sel_hi:[0,1,1] neg_lo:[0,0,1] neg_hi:[0,0,1]
	v_pk_fma_f32 v[40:41], v[34:35], v[18:19], v[48:49] op_sel_hi:[0,1,1] neg_lo:[0,0,1] neg_hi:[0,0,1]
	v_pk_fma_f32 v[42:43], v[34:35], v[12:13], v[50:51] op_sel_hi:[0,1,1] neg_lo:[0,0,1] neg_hi:[0,0,1]
	v_cvt_pk_bf16_f32 v28, v36, v37
	v_cvt_pk_bf16_f32 v29, v38, v39
	v_cvt_pk_bf16_f32 v30, v40, v41
	v_cvt_pk_bf16_f32 v31, v42, v43
	global_store_dwordx4 v[10:11], v[28:31], off
	v_lshlrev_b32_e32 v44, 16, v204
	v_and_b32_e32 v45, 0xffff0000, v204
	v_lshlrev_b32_e32 v46, 16, v205
	v_and_b32_e32 v47, 0xffff0000, v205
	v_lshlrev_b32_e32 v48, 16, v206
	v_and_b32_e32 v49, 0xffff0000, v206
	v_lshlrev_b32_e32 v50, 16, v207
	v_and_b32_e32 v51, 0xffff0000, v207
	v_pk_add_f32 v[14:15], v[14:15], v[44:45] neg_lo:[0,1] neg_hi:[0,1]
	v_pk_add_f32 v[16:17], v[16:17], v[46:47] neg_lo:[0,1] neg_hi:[0,1]
	v_pk_add_f32 v[18:19], v[18:19], v[48:49] neg_lo:[0,1] neg_hi:[0,1]
	v_pk_add_f32 v[12:13], v[12:13], v[50:51] neg_lo:[0,1] neg_hi:[0,1]
	v_lshl_add_u64 v[10:11], v[10:11], 0, s[26:27]
	v_lshlrev_b32_e32 v44, 16, v238
	v_and_b32_e32 v45, 0xffff0000, v238
	v_lshlrev_b32_e32 v46, 16, v239
	v_and_b32_e32 v47, 0xffff0000, v239
	v_lshlrev_b32_e32 v48, 16, v240
	v_and_b32_e32 v49, 0xffff0000, v240
	v_lshlrev_b32_e32 v50, 16, v241
	v_and_b32_e32 v51, 0xffff0000, v241
	v_pk_add_f32 v[14:15], v[14:15], v[44:45]
	v_pk_add_f32 v[16:17], v[16:17], v[46:47]
	v_pk_add_f32 v[18:19], v[18:19], v[48:49]
	v_pk_add_f32 v[12:13], v[12:13], v[50:51]
	v_pk_fma_f32 v[36:37], v[34:35], v[14:15], v[44:45] op_sel_hi:[0,1,1] neg_lo:[0,0,1] neg_hi:[0,0,1]
	v_pk_fma_f32 v[38:39], v[34:35], v[16:17], v[46:47] op_sel_hi:[0,1,1] neg_lo:[0,0,1] neg_hi:[0,0,1]
	v_pk_fma_f32 v[40:41], v[34:35], v[18:19], v[48:49] op_sel_hi:[0,1,1] neg_lo:[0,0,1] neg_hi:[0,0,1]
	v_pk_fma_f32 v[42:43], v[34:35], v[12:13], v[50:51] op_sel_hi:[0,1,1] neg_lo:[0,0,1] neg_hi:[0,0,1]
	v_cvt_pk_bf16_f32 v28, v36, v37
	v_cvt_pk_bf16_f32 v29, v38, v39
	v_cvt_pk_bf16_f32 v30, v40, v41
	v_cvt_pk_bf16_f32 v31, v42, v43
	global_store_dwordx4 v[10:11], v[28:31], off
	v_lshlrev_b32_e32 v44, 16, v208
	v_and_b32_e32 v45, 0xffff0000, v208
	v_lshlrev_b32_e32 v46, 16, v209
	v_and_b32_e32 v47, 0xffff0000, v209
	v_lshlrev_b32_e32 v48, 16, v210
	v_and_b32_e32 v49, 0xffff0000, v210
	v_lshlrev_b32_e32 v50, 16, v211
	v_and_b32_e32 v51, 0xffff0000, v211
	v_pk_add_f32 v[14:15], v[14:15], v[44:45] neg_lo:[0,1] neg_hi:[0,1]
	v_pk_add_f32 v[16:17], v[16:17], v[46:47] neg_lo:[0,1] neg_hi:[0,1]
	v_pk_add_f32 v[18:19], v[18:19], v[48:49] neg_lo:[0,1] neg_hi:[0,1]
	v_pk_add_f32 v[12:13], v[12:13], v[50:51] neg_lo:[0,1] neg_hi:[0,1]
	v_lshl_add_u64 v[10:11], v[10:11], 0, s[26:27]
	v_lshlrev_b32_e32 v44, 16, v242
	v_and_b32_e32 v45, 0xffff0000, v242
	v_lshlrev_b32_e32 v46, 16, v243
	v_and_b32_e32 v47, 0xffff0000, v243
	v_lshlrev_b32_e32 v48, 16, v244
	v_and_b32_e32 v49, 0xffff0000, v244
; __device__ __forceinline__ unsigned pk2(float lo, float hi) { f32x2 v = {lo, hi}; bf16x2_t b = __builtin_convertvector(v, bf16x2_t); return __builtin_bit_cast(unsigned, b); }
; __device__ __forceinline__ void pool_window(const bf16_t* __restrict__ U  , bf16_t* __restrict__ A3, const int gtid, const int nthr) {
;     ...
;         for (int i = 0; i < 32; ++i) {
;             const int t = t0 + i, s = s0 + i;
;             const u32x4 uu = *(const u32x4*)(U + (size_t)t * LDU + c);
;             float cu[8] = {bflo(uu.x), bfhi(uu.x), bflo(uu.y), bfhi(uu.y), bflo(uu.z), bfhi(uu.z), bflo(uu.w), bfhi(uu.w)};
;             const float rc = 1.0f / (float)((s + 1) < w ? (s + 1) : w);
;             float o[8];
; #pragma unroll
;             for (int e = 0; e < 8; ++e) { sum[e] += cu[e]; o[e] = sum[e] * rc - cu[e]; }
;             u32x4 ww; ww.x = pk2(o[0], o[1]); ww.y = pk2(o[2], o[3]); ww.z = pk2(o[4], o[5]); ww.w = pk2(o[6], o[7]);
;             *(u32x4*)(A3 + (size_t)t * DM + c) = ww;
;             if (s + 1 >= w) { const u32x4 ud = *(const u32x4*)(U + (size_t)(t - w + 1) * LDU + c);
;                 sum[0] -= bflo(ud.x); sum[1] -= bfhi(ud.x); sum[2] -= bflo(ud.y); sum[3] -= bfhi(ud.y); sum[4] -= bflo(ud.z); sum[5] -= bfhi(ud.z); sum[6] -= bflo(ud.w); sum[7] -= bfhi(ud.w); }
	v_lshlrev_b32_e32 v50, 16, v245
	v_and_b32_e32 v51, 0xffff0000, v245
	v_pk_add_f32 v[14:15], v[14:15], v[44:45]
	v_pk_add_f32 v[16:17], v[16:17], v[46:47]
	v_pk_add_f32 v[18:19], v[18:19], v[48:49]
	v_pk_add_f32 v[12:13], v[12:13], v[50:51]
	v_pk_fma_f32 v[36:37], v[34:35], v[14:15], v[44:45] op_sel_hi:[0,1,1] neg_lo:[0,0,1] neg_hi:[0,0,1]
	v_pk_fma_f32 v[38:39], v[34:35], v[16:17], v[46:47] op_sel_hi:[0,1,1] neg_lo:[0,0,1] neg_hi:[0,0,1]
	v_pk_fma_f32 v[40:41], v[34:35], v[18:19], v[48:49] op_sel_hi:[0,1,1] neg_lo:[0,0,1] neg_hi:[0,0,1]
	v_pk_fma_f32 v[42:43], v[34:35], v[12:13], v[50:51] op_sel_hi:[0,1,1] neg_lo:[0,0,1] neg_hi:[0,0,1]
	v_cvt_pk_bf16_f32 v28, v36, v37
	v_cvt_pk_bf16_f32 v29, v38, v39
	v_cvt_pk_bf16_f32 v30, v40, v41
	v_cvt_pk_bf16_f32 v31, v42, v43
	global_store_dwordx4 v[10:11], v[28:31], off
	v_lshlrev_b32_e32 v44, 16, v214
	v_and_b32_e32 v45, 0xffff0000, v214
	v_lshlrev_b32_e32 v46, 16, v215
	v_and_b32_e32 v47, 0xffff0000, v215
	v_lshlrev_b32_e32 v48, 16, v216
	v_and_b32_e32 v49, 0xffff0000, v216
	v_lshlrev_b32_e32 v50, 16, v217
	v_and_b32_e32 v51, 0xffff0000, v217
	v_pk_add_f32 v[14:15], v[14:15], v[44:45] neg_lo:[0,1] neg_hi:[0,1]
	v_pk_add_f32 v[16:17], v[16:17], v[46:47] neg_lo:[0,1] neg_hi:[0,1]
	v_pk_add_f32 v[18:19], v[18:19], v[48:49] neg_lo:[0,1] neg_hi:[0,1]
	v_pk_add_f32 v[12:13], v[12:13], v[50:51] neg_lo:[0,1] neg_hi:[0,1]
	v_lshl_add_u64 v[10:11], v[10:11], 0, s[26:27]
	v_lshlrev_b32_e32 v44, 16, v246
	v_and_b32_e32 v45, 0xffff0000, v246
	v_lshlrev_b32_e32 v46, 16, v247
	v_and_b32_e32 v47, 0xffff0000, v247
	v_lshlrev_b32_e32 v48, 16, v248
	v_and_b32_e32 v49, 0xffff0000, v248
	v_lshlrev_b32_e32 v50, 16, v249
	v_and_b32_e32 v51, 0xffff0000, v249
	v_pk_add_f32 v[14:15], v[14:15], v[44:45]
	v_pk_add_f32 v[16:17], v[16:17], v[46:47]
	v_pk_add_f32 v[18:19], v[18:19], v[48:49]
	v_pk_add_f32 v[12:13], v[12:13], v[50:51]
	v_pk_fma_f32 v[36:37], v[34:35], v[14:15], v[44:45] op_sel_hi:[0,1,1] neg_lo:[0,0,1] neg_hi:[0,0,1]
	v_pk_fma_f32 v[38:39], v[34:35], v[16:17], v[46:47] op_sel_hi:[0,1,1] neg_lo:[0,0,1] neg_hi:[0,0,1]
	v_pk_fma_f32 v[40:41], v[34:35], v[18:19], v[48:49] op_sel_hi:[0,1,1] neg_lo:[0,0,1] neg_hi:[0,0,1]
	v_pk_fma_f32 v[42:43], v[34:35], v[12:13], v[50:51] op_sel_hi:[0,1,1] neg_lo:[0,0,1] neg_hi:[0,0,1]
	v_cvt_pk_bf16_f32 v28, v36, v37
	v_cvt_pk_bf16_f32 v29, v38, v39
	v_cvt_pk_bf16_f32 v30, v40, v41
	v_cvt_pk_bf16_f32 v31, v42, v43
	global_store_dwordx4 v[10:11], v[28:31], off
	v_lshlrev_b32_e32 v44, 16, v218
	v_and_b32_e32 v45, 0xffff0000, v218
	v_lshlrev_b32_e32 v46, 16, v219
	v_and_b32_e32 v47, 0xffff0000, v219
	v_lshlrev_b32_e32 v48, 16, v220
	v_and_b32_e32 v49, 0xffff0000, v220
	v_lshlrev_b32_e32 v50, 16, v221
	v_and_b32_e32 v51, 0xffff0000, v221
	v_pk_add_f32 v[14:15], v[14:15], v[44:45] neg_lo:[0,1] neg_hi:[0,1]
	v_pk_add_f32 v[16:17], v[16:17], v[46:47] neg_lo:[0,1] neg_hi:[0,1]
	v_pk_add_f32 v[18:19], v[18:19], v[48:49] neg_lo:[0,1] neg_hi:[0,1]
	v_pk_add_f32 v[12:13], v[12:13], v[50:51] neg_lo:[0,1] neg_hi:[0,1]
	v_lshl_add_u64 v[10:11], v[10:11], 0, s[26:27]
	v_lshlrev_b32_e32 v44, 16, v250
	v_and_b32_e32 v45, 0xffff0000, v250
	v_lshlrev_b32_e32 v46, 16, v251
	v_and_b32_e32 v47, 0xffff0000, v251
	v_lshlrev_b32_e32 v48, 16, v252
	v_and_b32_e32 v49, 0xffff0000, v252
	v_lshlrev_b32_e32 v50, 16, v253
	v_and_b32_e32 v51, 0xffff0000, v253
	v_pk_add_f32 v[14:15], v[14:15], v[44:45]
	v_pk_add_f32 v[16:17], v[16:17], v[46:47]
	v_pk_add_f32 v[18:19], v[18:19], v[48:49]
	v_pk_add_f32 v[12:13], v[12:13], v[50:51]
	v_pk_fma_f32 v[36:37], v[34:35], v[14:15], v[44:45] op_sel_hi:[0,1,1] neg_lo:[0,0,1] neg_hi:[0,0,1]
	v_pk_fma_f32 v[38:39], v[34:35], v[16:17], v[46:47] op_sel_hi:[0,1,1] neg_lo:[0,0,1] neg_hi:[0,0,1]
	v_pk_fma_f32 v[40:41], v[34:35], v[18:19], v[48:49] op_sel_hi:[0,1,1] neg_lo:[0,0,1] neg_hi:[0,0,1]
	v_pk_fma_f32 v[42:43], v[34:35], v[12:13], v[50:51] op_sel_hi:[0,1,1] neg_lo:[0,0,1] neg_hi:[0,0,1]
	v_cvt_pk_bf16_f32 v28, v36, v37
	v_cvt_pk_bf16_f32 v29, v38, v39
	v_cvt_pk_bf16_f32 v30, v40, v41
	v_cvt_pk_bf16_f32 v31, v42, v43
	global_store_dwordx4 v[10:11], v[28:31], off
	v_lshlrev_b32_e32 v44, 16, v222
	v_and_b32_e32 v45, 0xffff0000, v222
	v_lshlrev_b32_e32 v46, 16, v223
	v_and_b32_e32 v47, 0xffff0000, v223
	v_lshlrev_b32_e32 v48, 16, v224
	v_and_b32_e32 v49, 0xffff0000, v224
	v_lshlrev_b32_e32 v50, 16, v225
	v_and_b32_e32 v51, 0xffff0000, v225
	v_pk_add_f32 v[14:15], v[14:15], v[44:45] neg_lo:[0,1] neg_hi:[0,1]
	v_pk_add_f32 v[16:17], v[16:17], v[46:47] neg_lo:[0,1] neg_hi:[0,1]
	v_pk_add_f32 v[18:19], v[18:19], v[48:49] neg_lo:[0,1] neg_hi:[0,1]
	v_pk_add_f32 v[12:13], v[12:13], v[50:51] neg_lo:[0,1] neg_hi:[0,1]
	s_branch .LBB0_1331
